# div-by-1.0 IEEE sequences replaced by v_rcp_f32 (f32, sigmoid/gelu epilogues); sample-attention tile loop: waves 4-7 run convert+load block before PV+norms to break SIMD lockstep
# speedup vs baseline: 1.0116x; 1.0116x over previous
; DI unsigned f2bf(float f) { unsigned u = __builtin_bit_cast(unsigned, f); return (u + 0x7fffu + ((u >> 16) & 1u)) >> 16; }
; DI float sigmoidf_(float x) { return 1.f / (1.f + __expf(-x)); }
; DI void gla_sample_phase(const Args& a, LAS unsigned char* lds, int vcu, int G, int tid, int lane, int wave) {
;     ...
;             float ss = wave_sum(o * o); if (lane == 0) rsum[wave] = ss;
;             __syncthreads();
;             const float tot = rsum[2 * t] + rsum[2 * t + 1]; const float rn = __builtin_amdgcn_rsqf(tot * (1.f / 128.f) + EPS);
;             const float g = bf2f(Z[(row0 + t) * ZW + ZC_GR + h * 128 + dv]);
;             MIX[(row0 + t) * DM + 512 + h * 128 + dv] = (bf16)f2bf(o * rn * go[dv] * g * sigmoidf_(g)); }
.LBB0_688:
	s_or_b64 exec, exec, s[4:5]
	s_waitcnt lgkmcnt(0)
	v_lshl_add_u64 v[18:19], s[20:21], 0, v[6:7]
	v_mov_b64_e32 v[20:21], s[18:19]
	v_mad_u64_u32 v[20:21], s[4:5], v18, s37, v[20:21]
	v_mad_i32_i24 v21, v19, s37, v21
	s_lshl_b32 s6, s47, 8
	v_lshl_add_u64 v[20:21], v[20:21], 0, s[6:7]
	v_lshl_add_u64 v[20:21], v[20:21], 0, v[2:3]
	v_add_co_u32_e32 v20, vcc, s38, v20
	s_nop 1
	v_addc_co_u32_e32 v21, vcc, 0, v21, vcc
	s_barrier
	global_load_ushort v17, v[20:21], off offset:256
	global_load_dword v22, v[8:9], off
	ds_read_b64 v[20:21], v41 offset:16960
	v_lshlrev_b64 v[18:19], 11, v[18:19]
	v_lshl_add_u64 v[18:19], s[10:11], 0, v[18:19]
	s_add_i32 s46, s46, s91
	s_add_i32 s45, s45, s91
	s_waitcnt lgkmcnt(0)
	v_add_f32_e32 v20, v20, v21
	v_fmamk_f32 v20, v20, 0x3c000000, v42
	v_rsq_f32_e32 v20, v20
	v_lshl_add_u64 v[18:19], v[18:19], 0, s[6:7]
	v_lshl_add_u64 v[18:19], v[18:19], 0, v[2:3]
	s_cmpk_lt_i32 s46, 0x200
	v_mul_f32_e32 v16, v16, v20
	s_waitcnt vmcnt(1)
	v_lshlrev_b32_e32 v17, 16, v17
	v_mul_f32_e32 v21, 0xbfb8aa3b, v17
	v_exp_f32_e32 v21, v21
	s_waitcnt vmcnt(0)
	v_mul_f32_e32 v16, v22, v16
	v_mul_f32_e32 v16, v16, v17
	v_add_f32_e32 v20, 1.0, v21
	v_div_scale_f32 v21, s[4:5], v20, v20, 1.0
	v_rcp_f32_e32 v22, v21
	s_nop 0
	v_fma_f32 v23, -v21, v22, 1.0
	v_fmac_f32_e32 v22, v23, v22
	v_rcp_f32_e32 v17, v20
	s_nop 0
	v_mul_f32_e32 v16, v16, v17
	v_bfe_u32 v17, v16, 16, 1
	v_add3_u32 v16, v16, v17, s44
	global_store_short_d16_hi v[18:19], v16, off
	s_cbranch_scc0 .LBB0_703

; DI unsigned pk2(float lo, float hi) { f32x2 v = {lo, hi}; bf16x2_t b = __builtin_convertvector(v, bf16x2_t); return __builtin_bit_cast(unsigned, b); }
; DI void attn_prompt_unit(const Args& a, LAS unsigned char* lds, int b, int h, int qb, float cB, int tid, int lane, int wave) {
;     ...
;     lsum += __shfl_xor(lsum, 32);
;     const float inv = 1.f / lsum;
;     bf16* op = MIX + qrow * DM + h * 64;
; #pragma unroll
;     for (int q = 0; q < 4; ++q) { const int dv = 8 * q + 4 * h2;
;         u32x2 w0, w1; w0.x = pk2(o0[4 * q] * inv, o0[4 * q + 1] * inv); w0.y = pk2(o0[4 * q + 2] * inv, o0[4 * q + 3] * inv);
;         w1.x = pk2(o1[4 * q] * inv, o1[4 * q + 1] * inv); w1.y = pk2(o1[4 * q + 2] * inv, o1[4 * q + 3] * inv);
;         *(u32x2*)(op + dv) = w0; *(u32x2*)(op + 32 + dv) = w1; }
.LBB0_832:
	ds_bpermute_b32 v50, v143, v1
	s_lshl_b32 s6, s6, 1
	v_mov_b32_e32 v161, v127
	s_waitcnt lgkmcnt(0)
	s_barrier
	v_add_f32_e32 v1, v1, v50
	v_div_scale_f32 v50, s[4:5], v1, v1, 1.0
	v_rcp_f32_e32 v51, v50
	v_div_scale_f32 v52, vcc, 1.0, v1, 1.0
	v_fma_f32 v53, -v50, v51, 1.0
	v_fmac_f32_e32 v51, v53, v51
	v_rcp_f32_e32 v50, v1
	v_lshlrev_b64 v[52:53], 11, v[176:177]
	v_lshl_add_u64 v[52:53], s[10:11], 0, v[52:53]
	v_pk_mul_f32 v[18:19], v[18:19], v[50:51] op_sel_hi:[1,0]
	v_pk_mul_f32 v[20:21], v[20:21], v[50:51] op_sel_hi:[1,0]
	v_lshl_add_u64 v[52:53], v[52:53], 0, s[6:7]
	v_cvt_pk_bf16_f32 v18, v18, v19
	v_cvt_pk_bf16_f32 v19, v20, v21
	v_pk_mul_f32 v[20:21], v[34:35], v[50:51] op_sel_hi:[1,0]
	v_pk_mul_f32 v[34:35], v[36:37], v[50:51] op_sel_hi:[1,0]
	v_cvt_pk_bf16_f32 v20, v20, v21
	v_cvt_pk_bf16_f32 v21, v34, v35
	v_lshl_add_u64 v[34:35], v[52:53], 0, v[160:161]
	global_store_dwordx2 v[34:35], v[18:19], off
	global_store_dwordx2 v[34:35], v[20:21], off offset:64
	v_pk_mul_f32 v[18:19], v[22:23], v[50:51] op_sel_hi:[1,0]
	v_pk_mul_f32 v[20:21], v[24:25], v[50:51] op_sel_hi:[1,0]
	v_cvt_pk_bf16_f32 v18, v18, v19
	v_cvt_pk_bf16_f32 v19, v20, v21
	v_pk_mul_f32 v[20:21], v[38:39], v[50:51] op_sel_hi:[1,0]
	v_pk_mul_f32 v[22:23], v[40:41], v[50:51] op_sel_hi:[1,0]
	v_cvt_pk_bf16_f32 v20, v20, v21
	v_cvt_pk_bf16_f32 v21, v22, v23
	global_store_dwordx2 v[34:35], v[18:19], off offset:16
	global_store_dwordx2 v[34:35], v[20:21], off offset:80
	v_pk_mul_f32 v[18:19], v[26:27], v[50:51] op_sel_hi:[1,0]
	v_pk_mul_f32 v[20:21], v[28:29], v[50:51] op_sel_hi:[1,0]
	v_cvt_pk_bf16_f32 v18, v18, v19
	v_cvt_pk_bf16_f32 v19, v20, v21
	v_pk_mul_f32 v[20:21], v[42:43], v[50:51] op_sel_hi:[1,0]
	v_pk_mul_f32 v[22:23], v[44:45], v[50:51] op_sel_hi:[1,0]
	v_cvt_pk_bf16_f32 v20, v20, v21
	v_cvt_pk_bf16_f32 v21, v22, v23
	global_store_dwordx2 v[34:35], v[18:19], off offset:32
	global_store_dwordx2 v[34:35], v[20:21], off offset:96
	v_pk_mul_f32 v[18:19], v[30:31], v[50:51] op_sel_hi:[1,0]
	v_pk_mul_f32 v[20:21], v[32:33], v[50:51] op_sel_hi:[1,0]
	v_cvt_pk_bf16_f32 v18, v18, v19
	v_cvt_pk_bf16_f32 v19, v20, v21
	v_pk_mul_f32 v[20:21], v[46:47], v[50:51] op_sel_hi:[1,0]
	v_pk_mul_f32 v[22:23], v[48:49], v[50:51] op_sel_hi:[1,0]
	s_add_i32 s26, s26, s91
	s_add_i32 s25, s25, s91
	v_cvt_pk_bf16_f32 v20, v20, v21
	v_cvt_pk_bf16_f32 v21, v22, v23
	s_cmpk_lt_i32 s26, 0x100
	global_store_dwordx2 v[34:35], v[18:19], off offset:48
	global_store_dwordx2 v[34:35], v[20:21], off offset:112
	s_cbranch_scc0 .LBB0_861

; DI unsigned pk2(float lo, float hi) { f32x2 v = {lo, hi}; bf16x2_t b = __builtin_convertvector(v, bf16x2_t); return __builtin_bit_cast(unsigned, b); }
; DI void attn_prompt_unit(const Args& a, LAS unsigned char* lds, int b, int h, int qb, float cB, int tid, int lane, int wave) {
;     ...
;     { const bf16* QR = (const bf16*)(a.ws + WS_QRAW); const float* gq = (const float*)a.in[I_GQH]; const float* rc = (const float*)(a.ws + WS_ROPE); const float* rs = rc + 8200 * 16;
;         u32x4 wq[6]; float ss = 0.f;
; #pragma unroll
;         for (int s = 0; s < 6; ++s) { wq[s] = *(const u32x4*)(QR + qrow * 768 + h * 96 + 16 * s + 8 * h2);
;             const float e0 = bflo(wq[s].x), e1 = bfhi(wq[s].x), e2 = bflo(wq[s].y), e3 = bfhi(wq[s].y), e4 = bflo(wq[s].z), e5 = bfhi(wq[s].z), e6 = bflo(wq[s].w), e7 = bfhi(wq[s].w);
;             ss += ((e0 * e0 + e1 * e1) + (e2 * e2 + e3 * e3)) + ((e4 * e4 + e5 * e5) + (e6 * e6 + e7 * e7)); }
;     ...
;     lsum += __shfl_xor(lsum, 32);
;     const float inv = 1.f / lsum;
;     bf16* op = MIX + qrow * DM + h * 64;
; #pragma unroll
;     for (int q = 0; q < 4; ++q) { const int dv = 8 * q + 4 * h2;
;         u32x2 w0, w1; w0.x = pk2(o0[4 * q] * inv, o0[4 * q + 1] * inv); w0.y = pk2(o0[4 * q + 2] * inv, o0[4 * q + 3] * inv);
;         w1.x = pk2(o1[4 * q] * inv, o1[4 * q + 1] * inv); w1.y = pk2(o1[4 * q + 2] * inv, o1[4 * q + 3] * inv);
;         *(u32x2*)(op + dv) = w0; *(u32x2*)(op + 32 + dv) = w1; }
.LBB0_847:
	ds_bpermute_b32 v50, v143, v1
	v_mov_b32_e32 v161, v127
	s_waitcnt lgkmcnt(0)
	s_barrier
	v_add_f32_e32 v1, v1, v50
	v_div_scale_f32 v50, s[4:5], v1, v1, 1.0
	v_rcp_f32_e32 v51, v50
	v_div_scale_f32 v52, vcc, 1.0, v1, 1.0
	s_lshl_b32 s4, s27, 7
	v_fma_f32 v53, -v50, v51, 1.0
	v_fmac_f32_e32 v51, v53, v51
	v_rcp_f32_e32 v50, v1
	v_lshlrev_b64 v[52:53], 11, v[176:177]
	v_lshl_add_u64 v[52:53], s[10:11], 0, v[52:53]
	s_mov_b32 s5, s7
	v_pk_mul_f32 v[18:19], v[18:19], v[50:51] op_sel_hi:[1,0]
	v_pk_mul_f32 v[20:21], v[20:21], v[50:51] op_sel_hi:[1,0]
	v_lshl_add_u64 v[52:53], v[52:53], 0, s[4:5]
	v_cvt_pk_bf16_f32 v18, v18, v19
	v_cvt_pk_bf16_f32 v19, v20, v21
	v_pk_mul_f32 v[20:21], v[34:35], v[50:51] op_sel_hi:[1,0]
	v_pk_mul_f32 v[34:35], v[36:37], v[50:51] op_sel_hi:[1,0]
	v_cvt_pk_bf16_f32 v20, v20, v21
	v_cvt_pk_bf16_f32 v21, v34, v35
	v_lshl_add_u64 v[34:35], v[52:53], 0, v[160:161]
	global_store_dwordx2 v[34:35], v[18:19], off
	global_store_dwordx2 v[34:35], v[20:21], off offset:64
	v_pk_mul_f32 v[18:19], v[22:23], v[50:51] op_sel_hi:[1,0]
	v_pk_mul_f32 v[20:21], v[24:25], v[50:51] op_sel_hi:[1,0]
	v_cvt_pk_bf16_f32 v18, v18, v19
	v_cvt_pk_bf16_f32 v19, v20, v21
	v_pk_mul_f32 v[20:21], v[38:39], v[50:51] op_sel_hi:[1,0]
	v_pk_mul_f32 v[22:23], v[40:41], v[50:51] op_sel_hi:[1,0]
	v_cvt_pk_bf16_f32 v20, v20, v21
	v_cvt_pk_bf16_f32 v21, v22, v23
	global_store_dwordx2 v[34:35], v[18:19], off offset:16
	global_store_dwordx2 v[34:35], v[20:21], off offset:80
	v_pk_mul_f32 v[18:19], v[26:27], v[50:51] op_sel_hi:[1,0]
	v_pk_mul_f32 v[20:21], v[28:29], v[50:51] op_sel_hi:[1,0]
	v_cvt_pk_bf16_f32 v18, v18, v19
	v_cvt_pk_bf16_f32 v19, v20, v21
	v_pk_mul_f32 v[20:21], v[42:43], v[50:51] op_sel_hi:[1,0]
	v_pk_mul_f32 v[22:23], v[44:45], v[50:51] op_sel_hi:[1,0]
	s_lshl_b32 s20, s28, 8
	v_cvt_pk_bf16_f32 v20, v20, v21
	v_cvt_pk_bf16_f32 v21, v22, v23
	s_add_i32 s20, s20, s46
	global_store_dwordx2 v[34:35], v[18:19], off offset:32
	global_store_dwordx2 v[34:35], v[20:21], off offset:96
	v_pk_mul_f32 v[18:19], v[30:31], v[50:51] op_sel_hi:[1,0]
	v_pk_mul_f32 v[20:21], v[32:33], v[50:51] op_sel_hi:[1,0]
	v_or_b32_e32 v178, s20, v210
	v_cvt_pk_bf16_f32 v18, v18, v19
	v_cvt_pk_bf16_f32 v19, v20, v21
	v_pk_mul_f32 v[20:21], v[46:47], v[50:51] op_sel_hi:[1,0]
	v_pk_mul_f32 v[22:23], v[48:49], v[50:51] op_sel_hi:[1,0]
	v_ashrrev_i32_e32 v179, 31, v178
	v_cvt_pk_bf16_f32 v20, v20, v21
	v_cvt_pk_bf16_f32 v21, v22, v23
	global_store_dwordx2 v[34:35], v[18:19], off offset:48
	global_store_dwordx2 v[34:35], v[20:21], off offset:112
	v_lshl_add_u64 v[176:177], s[18:19], 0, v[178:179]
	v_mov_b64_e32 v[18:19], s[8:9]
	v_mad_u64_u32 v[18:19], s[4:5], v176, s22, v[18:19]
	v_mad_i32_i24 v19, v177, s22, v19
	v_lshl_add_u64 v[18:19], v[18:19], 0, s[6:7]
	v_lshl_add_u64 v[18:19], v[18:19], 0, v[126:127]
	global_load_dwordx4 v[22:25], v[18:19], off offset:128
	global_load_dwordx4 v[26:29], v[18:19], off offset:160
	global_load_dwordx4 v[30:33], v[18:19], off offset:96
	global_load_dwordx4 v[58:61], v[18:19], off offset:64
	v_lshlrev_b32_e32 v20, 4, v178
	v_ashrrev_i32_e32 v21, 31, v20
	v_lshlrev_b64 v[90:91], 2, v[20:21]
	global_load_dwordx4 v[82:85], v[18:19], off offset:32
	v_lshl_add_u64 v[92:93], v[146:147], 0, v[90:91]
	global_load_dwordx4 v[232:235], v[18:19], off
	s_nop 0
	global_load_dwordx4 v[18:21], v[92:93], off
	global_load_dwordx4 v[78:81], v[144:145], off offset:16
	global_load_dwordx4 v[86:89], v[144:145], off
	global_load_dwordx4 v[70:73], v[144:145], off offset:80
	global_load_dwordx4 v[74:77], v[144:145], off offset:64
	global_load_dwordx4 v[62:65], v[144:145], off offset:144
	global_load_dwordx4 v[66:69], v[144:145], off offset:128
	global_load_dwordx4 v[38:41], v[144:145], off offset:208
	global_load_dwordx4 v[50:53], v[144:145], off offset:192
	global_load_dwordx4 v[46:49], v[144:145], off offset:272
	global_load_dwordx4 v[54:57], v[144:145], off offset:256
	global_load_dwordx4 v[34:37], v[144:145], off offset:336
	global_load_dwordx4 v[42:45], v[144:145], off offset:320
	s_waitcnt vmcnt(18)
	v_lshlrev_b32_e32 v106, 16, v22
	v_and_b32_e32 v107, 0xffff0000, v22
	s_waitcnt vmcnt(16)
; DI void attn_prompt_unit(const Args& a, LAS unsigned char* lds, int b, int h, int qb, float cB, int tid, int lane, int wave) {
;     ...
;         for (int s = 0; s < 6; ++s) { wq[s] = *(const u32x4*)(QR + qrow * 768 + h * 96 + 16 * s + 8 * h2);
;             const float e0 = bflo(wq[s].x), e1 = bfhi(wq[s].x), e2 = bflo(wq[s].y), e3 = bfhi(wq[s].y), e4 = bflo(wq[s].z), e5 = bfhi(wq[s].z), e6 = bflo(wq[s].w), e7 = bfhi(wq[s].w);
;             ss += ((e0 * e0 + e1 * e1) + (e2 * e2 + e3 * e3)) + ((e4 * e4 + e5 * e5) + (e6 * e6 + e7 * e7)); }
;         ss += __shfl_xor(ss, 32);
;         const float r = __builtin_amdgcn_rsqf(ss * (1.f / 96.f) + EPS) * QSCALE;
; #pragma unroll
;         for (int s = 0; s < 4; ++s) { const f32x4 g0 = *(const f32x4*)(gq + 16 * s + 8 * h2) * r, g1 = *(const f32x4*)(gq + 16 * s + 8 * h2 + 4) * r;
;             u32x4 o; o.x = pk2(bflo(wq[s].x) * g0.x, bfhi(wq[s].x) * g0.y); o.y = pk2(bflo(wq[s].y) * g0.z, bfhi(wq[s].y) * g0.w); o.z = pk2(bflo(wq[s].z) * g1.x, bfhi(wq[s].z) * g1.y); o.w = pk2(bflo(wq[s].w) * g1.z, bfhi(wq[s].w) * g1.w);
;             qf[s] = __builtin_bit_cast(bf16x8, o); }
;         { const f32x4 ga0 = *(const f32x4*)(gq + 64 + 8 * h2) * r, ga1 = *(const f32x4*)(gq + 64 + 8 * h2 + 4) * r, gb0 = *(const f32x4*)(gq + 80 + 8 * h2) * r, gb1 = *(const f32x4*)(gq + 80 + 8 * h2 + 4) * r;
;             const f32x4 c0 = *(const f32x4*)(rc + qloc * 16 + 8 * h2), c1 = *(const f32x4*)(rc + qloc * 16 + 8 * h2 + 4), s0 = *(const f32x4*)(rs + qloc * 16 + 8 * h2), s1 = *(const f32x4*)(rs + qloc * 16 + 8 * h2 + 4);
;             const f32x4 xa0 = (f32x4){bflo(wq[4].x), bfhi(wq[4].x), bflo(wq[4].y), bfhi(wq[4].y)} * ga0, xa1 = (f32x4){bflo(wq[4].z), bfhi(wq[4].z), bflo(wq[4].w), bfhi(wq[4].w)} * ga1;
;             const f32x4 xb0 = (f32x4){bflo(wq[5].x), bfhi(wq[5].x), bflo(wq[5].y), bfhi(wq[5].y)} * gb0, xb1 = (f32x4){bflo(wq[5].z), bfhi(wq[5].z), bflo(wq[5].w), bfhi(wq[5].w)} * gb1;
;             const f32x4 ra0 = xa0 * c0 - xb0 * s0, ra1 = xa1 * c1 - xb1 * s1, rb0 = xb0 * c0 + xa0 * s0, rb1 = xb1 * c1 + xa1 * s1;
;             u32x4 o4, o5; o4.x = pk2(ra0.x, ra0.y); o4.y = pk2(ra0.z, ra0.w); o4.z = pk2(ra1.x, ra1.y); o4.w = pk2(ra1.z, ra1.w); o5.x = pk2(rb0.x, rb0.y); o5.y = pk2(rb0.z, rb0.w); o5.z = pk2(rb1.x, rb1.y); o5.w = pk2(rb1.z, rb1.w);
	v_and_b32_e32 v1, 0xffff0000, v32
	v_lshlrev_b32_e32 v180, 16, v33
	v_and_b32_e32 v97, 0xffff0000, v33
	v_mov_b32_e32 v96, v1
	v_and_b32_e32 v119, 0xffff0000, v30
	v_lshlrev_b32_e32 v112, 16, v23
	v_and_b32_e32 v113, 0xffff0000, v23
	v_lshlrev_b32_e32 v100, 16, v32
	v_mov_b32_e32 v101, v180
	v_pk_mul_f32 v[22:23], v[96:97], v[96:97]
	v_lshlrev_b32_e32 v182, 16, v31
	v_and_b32_e32 v185, 0xffff0000, v31
	v_mov_b32_e32 v184, v119
	v_pk_fma_f32 v[236:237], v[100:101], v[100:101], v[22:23]
	v_lshlrev_b32_e32 v98, 16, v30
	v_mov_b32_e32 v99, v182
	v_pk_mul_f32 v[22:23], v[184:185], v[184:185]
	v_lshl_add_u64 v[30:31], v[148:149], 0, v[90:91]
	v_lshlrev_b32_e32 v110, 16, v24
	v_and_b32_e32 v111, 0xffff0000, v24
	v_lshlrev_b32_e32 v114, 16, v25
	v_and_b32_e32 v115, 0xffff0000, v25
	v_lshlrev_b32_e32 v104, 16, v26
	v_and_b32_e32 v105, 0xffff0000, v26
	v_lshlrev_b32_e32 v116, 16, v27
	v_and_b32_e32 v117, 0xffff0000, v27
	v_lshlrev_b32_e32 v102, 16, v28
	v_and_b32_e32 v103, 0xffff0000, v28
	v_lshlrev_b32_e32 v108, 16, v29
	v_and_b32_e32 v109, 0xffff0000, v29
	v_pk_fma_f32 v[238:239], v[98:99], v[98:99], v[22:23]
	global_load_dwordx4 v[22:25], v[30:31], off offset:16
	global_load_dwordx4 v[26:29], v[92:93], off offset:16
	s_nop 0
	global_load_dwordx4 v[30:33], v[30:31], off
	s_nop 0
	global_load_dwordx4 v[90:93], v[172:173], off
	s_waitcnt vmcnt(19)
	v_and_b32_e32 v121, 0xffff0000, v59
	v_and_b32_e32 v129, 0xffff0000, v58
	v_lshlrev_b32_e32 v184, 16, v61
	v_and_b32_e32 v191, 0xffff0000, v61
	v_lshlrev_b32_e32 v96, 16, v60
	v_and_b32_e32 v189, 0xffff0000, v60
	v_mov_b32_e32 v190, v121
	v_mov_b32_e32 v188, v129
	v_lshlrev_b32_e32 v186, 16, v59
	v_lshlrev_b32_e32 v94, 16, v58
	v_mov_b32_e32 v187, v184
	v_pk_mul_f32 v[58:59], v[190:191], v[190:191]
	v_mov_b32_e32 v95, v96
	v_pk_mul_f32 v[60:61], v[188:189], v[188:189]
	s_waitcnt vmcnt(17)
	v_and_b32_e32 v139, 0xffff0000, v235
	v_and_b32_e32 v133, 0xffff0000, v234
	v_pk_fma_f32 v[58:59], v[186:187], v[186:187], v[58:59]
	v_pk_fma_f32 v[60:61], v[94:95], v[94:95], v[60:61]
	v_lshlrev_b32_e32 v172, 16, v85
	v_and_b32_e32 v209, 0xffff0000, v85
	v_lshlrev_b32_e32 v188, 16, v84
	v_and_b32_e32 v207, 0xffff0000, v84
	v_mov_b32_e32 v208, v139
	v_mov_b32_e32 v206, v133
	v_pk_add_f32 v[58:59], v[60:61], v[58:59]
	v_lshlrev_b32_e32 v190, 16, v83
	v_and_b32_e32 v205, 0xffff0000, v83
	v_lshlrev_b32_e32 v192, 16, v82
	v_and_b32_e32 v203, 0xffff0000, v82
	v_lshlrev_b32_e32 v194, 16, v235
	v_lshlrev_b32_e32 v196, 16, v234
	v_and_b32_e32 v135, 0xffff0000, v233
	v_and_b32_e32 v137, 0xffff0000, v232
	v_mov_b32_e32 v195, v172
	v_pk_mul_f32 v[60:61], v[208:209], v[208:209]
	v_mov_b32_e32 v197, v188
	v_pk_mul_f32 v[82:83], v[206:207], v[206:207]
	v_pk_fma_f32 v[60:61], v[194:195], v[194:195], v[60:61]
	v_pk_fma_f32 v[82:83], v[196:197], v[196:197], v[82:83]
	v_mov_b32_e32 v204, v135
	v_mov_b32_e32 v202, v137
	v_lshlrev_b32_e32 v198, 16, v233
	v_lshlrev_b32_e32 v200, 16, v232
	v_pk_add_f32 v[60:61], v[82:83], v[60:61]
	v_mov_b32_e32 v199, v190
	v_pk_mul_f32 v[82:83], v[204:205], v[204:205]
	v_mov_b32_e32 v201, v192
	v_pk_mul_f32 v[84:85], v[202:203], v[202:203]
	v_pk_fma_f32 v[82:83], v[198:199], v[198:199], v[82:83]
	v_pk_fma_f32 v[84:85], v[200:201], v[200:201], v[84:85]
	v_mul_f32_e32 v171, v102, v102
	v_pk_add_f32 v[82:83], v[84:85], v[82:83]
	v_mul_f32_e32 v84, v113, v113
	v_pk_add_f32 v[60:61], v[82:83], v[60:61]
	v_mul_f32_e32 v82, v107, v107
	v_mul_f32_e32 v179, v103, v103
	v_pk_fma_f32 v[82:83], v[106:107], v[106:107], v[82:83] op_sel_hi:[1,1,0]
	v_pk_fma_f32 v[84:85], v[112:113], v[112:113], v[84:85] op_sel_hi:[1,1,0]
	v_mov_b32_e32 v83, v171
	v_mov_b32_e32 v85, v179
	v_pk_add_f32 v[82:83], v[82:83], v[84:85]
	v_mul_f32_e32 v84, v111, v111
	v_mul_f32_e32 v202, v115, v115
	v_mul_f32_e32 v181, v108, v108
	v_mul_f32_e32 v183, v109, v109
	v_pk_fma_f32 v[84:85], v[110:111], v[110:111], v[84:85] op_sel_hi:[1,1,0]
	v_pk_fma_f32 v[232:233], v[114:115], v[114:115], v[202:203] op_sel_hi:[1,1,0]
	v_mov_b32_e32 v85, v181
	v_mov_b32_e32 v233, v183
	v_pk_add_f32 v[84:85], v[84:85], v[232:233]
	v_mul_f32_e32 v157, v104, v104
	v_mul_f32_e32 v159, v105, v105
	v_mul_f32_e32 v161, v116, v116
	v_mul_f32_e32 v169, v117, v117
	v_pk_add_f32 v[82:83], v[82:83], v[84:85]
	v_pk_add_f32 v[84:85], v[238:239], v[238:239] op_sel:[0,1] op_sel_hi:[1,0]
	v_pk_add_f32 v[232:233], v[236:237], v[236:237] op_sel:[0,1] op_sel_hi:[1,0]
	v_pk_add_f32 v[60:61], v[60:61], v[60:61] op_sel:[0,1] op_sel_hi:[1,0]
	v_pk_add_f32 v[58:59], v[58:59], v[58:59] op_sel:[0,1] op_sel_hi:[1,0]
	v_mov_b32_e32 v85, v161
	v_mov_b32_e32 v233, v169
	v_mov_b32_e32 v61, v157
	v_mov_b32_e32 v59, v159
	v_pk_add_f32 v[84:85], v[84:85], v[232:233]
	v_pk_add_f32 v[58:59], v[60:61], v[58:59]
	s_nop 0
	v_pk_add_f32 v[58:59], v[58:59], v[84:85]
	v_mov_b32_e32 v84, v127
	v_pk_add_f32 v[58:59], v[58:59], v[82:83]
	v_mov_b32_e32 v82, v127
	v_add_f32_e32 v157, v58, v59
	ds_bpermute_b32 v159, v143, v157
	v_mov_b32_e32 v83, v127
	v_mov_b32_e32 v85, v127
	s_and_saveexec_b64 s[4:5], s[2:3]
	s_cbranch_execz .LBB0_849
	v_mov_b32_e32 v171, v127
	v_lshl_add_u64 v[58:59], s[16:17], 0, v[170:171]
	v_mov_b32_e32 v169, v127
	v_lshl_add_u64 v[58:59], v[58:59], 0, v[168:169]
	global_load_dwordx4 v[82:85], v[58:59], off

; DI unsigned pk2(float lo, float hi) { f32x2 v = {lo, hi}; bf16x2_t b = __builtin_convertvector(v, bf16x2_t); return __builtin_bit_cast(unsigned, b); }
; DI float sigmoidf_(float x) { return 1.f / (1.f + __expf(-x)); }
; DI void gla_c_phase(const Args& a, LAS unsigned char* lds, int vcu, int G, int tid, int lane, int wave) {
;     ...
;         const int t = tb * 32 + r32; const float tot = (RS[t] + RS[64 + t]) + (RS[128 + t] + RS[192 + t]);
;         const float rn = __builtin_amdgcn_rsqf(tot * (1.f / 128.f) + EPS);
;         const size_t row = (size_t)row0 + t;
; #pragma unroll
;         for (int q = 0; q < 4; ++q) { const int dv = dvb * 32 + 8 * q + 4 * h2; const f32x4 g4 = *(const f32x4*)(go + dv);
;             const u32x2 gw = *(const u32x2*)(Z + row * ZW + ZC_GR + h * 128 + dv); const float g0 = bflo(gw.x), g1 = bfhi(gw.x), g2 = bflo(gw.y), g3 = bfhi(gw.y);
;             const float v0 = o[4 * q + 0] * rn * g4.x * g0 * sigmoidf_(g0), v1 = o[4 * q + 1] * rn * g4.y * g1 * sigmoidf_(g1), v2 = o[4 * q + 2] * rn * g4.z * g2 * sigmoidf_(g2), v3 = o[4 * q + 3] * rn * g4.w * g3 * sigmoidf_(g3);
;             u32x2 w; w.x = pk2(v0, v1); w.y = pk2(v2, v3); *(u32x2*)(MIX + row * DM + 512 + h * 128 + dv) = w; }
.LBB0_863:
	s_or_b64 exec, exec, s[62:63]
	s_waitcnt lgkmcnt(0)
	s_barrier
	ds_read2st64_b32 v[32:33], v110 offset1:1
	ds_read2st64_b32 v[34:35], v110 offset0:2 offset1:3
	s_lshl_b32 s96, s52, 1
	s_ashr_i32 s53, s88, 31
	v_mov_b32_e32 v97, v11
	s_waitcnt lgkmcnt(1)
	v_mov_b32_e32 v36, v32
	s_waitcnt lgkmcnt(0)
	v_mov_b32_e32 v37, v34
	v_mov_b32_e32 v34, v33
	v_pk_add_f32 v[32:33], v[36:37], v[34:35]
	v_mov_b64_e32 v[36:37], s[94:95]
	v_add_f32_e32 v32, v32, v33
	v_fmamk_f32 v32, v32, 0x3c000000, v135
	v_rsq_f32_e32 v34, v32
	v_or_b32_e32 v32, s88, v84
	v_mad_i64_i32 v[36:37], s[54:55], v32, s47, v[36:37]
	v_lshl_add_u64 v[36:37], v[36:37], 0, s[96:97]
	v_mov_b32_e32 v33, s53
	v_lshl_add_u64 v[42:43], v[36:37], 0, v[96:97]
	s_mov_b64 s[52:53], 0x1100
	v_lshl_add_u64 v[36:37], v[42:43], 0, s[52:53]
	s_movk_i32 s52, 0x1000
	v_add_co_u32_e32 v42, vcc, s52, v42
	global_load_dwordx4 v[38:41], v[86:87], off
	s_nop 0
	v_addc_co_u32_e32 v43, vcc, 0, v43, vcc
	global_load_dwordx2 v[42:43], v[42:43], off offset:256
	v_lshlrev_b64 v[32:33], 11, v[32:33]
	v_lshl_add_u64 v[32:33], s[50:51], 0, v[32:33]
	v_lshl_add_u64 v[32:33], v[32:33], 0, s[96:97]
	s_add_i32 s84, s84, s91
	s_cmpk_lt_i32 s84, 0x400
	s_waitcnt vmcnt(0)
	v_lshlrev_b32_e32 v44, 16, v42
	v_and_b32_e32 v45, 0xffff0000, v42
	v_mul_f32_e32 v35, 0xbfb8aa3b, v44
	v_exp_f32_e32 v46, v35
	v_pk_mul_f32 v[16:17], v[16:17], v[34:35] op_sel_hi:[1,0]
	v_mul_f32_e32 v35, 0xbfb8aa3b, v45
	v_exp_f32_e32 v47, v35
	v_pk_mul_f32 v[16:17], v[38:39], v[16:17]
	v_pk_add_f32 v[38:39], v[46:47], 1.0 op_sel_hi:[1,0]
	s_nop 0
	v_pk_mul_f32 v[16:17], v[16:17], v[44:45]
	v_rcp_f32_e32 v39, v39
	v_div_scale_f32 v35, s[52:53], v38, v38, 1.0
	v_rcp_f32_e32 v42, v35
	s_nop 0
	v_fma_f32 v44, -v35, v42, 1.0
	v_fmac_f32_e32 v42, v44, v42
	v_div_scale_f32 v44, vcc, 1.0, v38, 1.0
	v_mul_f32_e32 v45, v44, v42
	v_fma_f32 v46, -v35, v45, v44
	v_fmac_f32_e32 v45, v46, v42
	v_rcp_f32_e32 v38, v38
	s_nop 0
	v_pk_mul_f32 v[16:17], v[16:17], v[38:39]
	v_lshlrev_b32_e32 v38, 16, v43
	v_and_b32_e32 v39, 0xffff0000, v43
	v_mul_f32_e32 v35, 0xbfb8aa3b, v38
	v_exp_f32_e32 v42, v35
	v_pk_mul_f32 v[18:19], v[18:19], v[34:35] op_sel_hi:[1,0]
	v_mul_f32_e32 v35, 0xbfb8aa3b, v39
	v_exp_f32_e32 v43, v35
	v_pk_mul_f32 v[18:19], v[40:41], v[18:19]
	v_cvt_pk_bf16_f32 v16, v16, v17
	v_pk_mul_f32 v[18:19], v[18:19], v[38:39]
	v_pk_add_f32 v[38:39], v[42:43], 1.0 op_sel_hi:[1,0]
	s_nop 0
	s_nop 0
	v_rcp_f32_e32 v39, v39
	s_mov_b64 s[52:53], 0x1d600400
	v_rcp_f32_e32 v38, v38
	s_nop 0
	v_pk_mul_f32 v[18:19], v[18:19], v[38:39]
	s_nop 0
	v_cvt_pk_bf16_f32 v17, v18, v19
	v_lshl_add_u64 v[18:19], v[32:33], 0, v[96:97]
	v_lshl_add_u64 v[32:33], v[18:19], 0, s[52:53]
	s_mov_b32 s52, 0x1d600000
	v_add_co_u32_e32 v18, vcc, s52, v18
	s_nop 1
	v_addc_co_u32_e32 v19, vcc, 0, v19, vcc
	global_store_dwordx2 v[18:19], v[16:17], off offset:1024
	global_load_dwordx4 v[16:19], v[86:87], off offset:32
	s_nop 0
	global_load_dwordx2 v[38:39], v[36:37], off offset:16
	s_waitcnt vmcnt(0)
	v_lshlrev_b32_e32 v40, 16, v38
	v_mul_f32_e32 v35, 0xbfb8aa3b, v40
	v_and_b32_e32 v41, 0xffff0000, v38
	v_pk_mul_f32 v[20:21], v[20:21], v[34:35] op_sel_hi:[1,0]
	v_exp_f32_e32 v42, v35
	v_pk_mul_f32 v[16:17], v[16:17], v[20:21]
	v_mul_f32_e32 v20, 0xbfb8aa3b, v41
	v_exp_f32_e32 v43, v20
	v_pk_mul_f32 v[16:17], v[16:17], v[40:41]
	v_pk_add_f32 v[20:21], v[42:43], 1.0 op_sel_hi:[1,0]
	s_nop 0
	s_nop 0
	v_rcp_f32_e32 v21, v21
	s_nop 0
	v_rcp_f32_e32 v20, v20
	s_nop 0
	v_pk_mul_f32 v[16:17], v[16:17], v[20:21]
	v_lshlrev_b32_e32 v20, 16, v39
	v_mul_f32_e32 v35, 0xbfb8aa3b, v20
	v_pk_mul_f32 v[22:23], v[22:23], v[34:35] op_sel_hi:[1,0]
	v_and_b32_e32 v21, 0xffff0000, v39
	v_pk_mul_f32 v[18:19], v[18:19], v[22:23]
	v_exp_f32_e32 v38, v35
	v_pk_mul_f32 v[18:19], v[18:19], v[20:21]
	v_mul_f32_e32 v20, 0xbfb8aa3b, v21
	v_exp_f32_e32 v39, v20
	v_cvt_pk_bf16_f32 v16, v16, v17
	v_pk_add_f32 v[20:21], v[38:39], 1.0 op_sel_hi:[1,0]
	s_nop 0
	s_nop 0
	v_rcp_f32_e32 v21, v21
	s_nop 0
	v_div_scale_f32 v35, vcc, 1.0, v20, 1.0
	v_rcp_f32_e32 v20, v20
	s_nop 0
	v_pk_mul_f32 v[18:19], v[18:19], v[20:21]
	v_pk_mul_f32 v[24:25], v[24:25], v[34:35] op_sel_hi:[1,0]
	v_cvt_pk_bf16_f32 v17, v18, v19
	global_store_dwordx2 v[32:33], v[16:17], off offset:16
	global_load_dwordx4 v[16:19], v[86:87], off offset:64
	s_nop 0
	global_load_dwordx2 v[20:21], v[36:37], off offset:32
	s_waitcnt vmcnt(1)
; DI unsigned pk2(float lo, float hi) { f32x2 v = {lo, hi}; bf16x2_t b = __builtin_convertvector(v, bf16x2_t); return __builtin_bit_cast(unsigned, b); }
; DI float sigmoidf_(float x) { return 1.f / (1.f + __expf(-x)); }
; DI void gla_c_phase(const Args& a, LAS unsigned char* lds, int vcu, int G, int tid, int lane, int wave) {
;     ...
;         for (int q = 0; q < 4; ++q) { const int dv = dvb * 32 + 8 * q + 4 * h2; const f32x4 g4 = *(const f32x4*)(go + dv);
;             const u32x2 gw = *(const u32x2*)(Z + row * ZW + ZC_GR + h * 128 + dv); const float g0 = bflo(gw.x), g1 = bfhi(gw.x), g2 = bflo(gw.y), g3 = bfhi(gw.y);
;             const float v0 = o[4 * q + 0] * rn * g4.x * g0 * sigmoidf_(g0), v1 = o[4 * q + 1] * rn * g4.y * g1 * sigmoidf_(g1), v2 = o[4 * q + 2] * rn * g4.z * g2 * sigmoidf_(g2), v3 = o[4 * q + 3] * rn * g4.w * g3 * sigmoidf_(g3);
;             u32x2 w; w.x = pk2(v0, v1); w.y = pk2(v2, v3); *(u32x2*)(MIX + row * DM + 512 + h * 128 + dv) = w; }
	v_pk_mul_f32 v[16:17], v[24:25], v[16:17]
	s_waitcnt vmcnt(0)
	v_lshlrev_b32_e32 v22, 16, v20
	v_and_b32_e32 v23, 0xffff0000, v20
	v_mul_f32_e32 v20, 0xbfb8aa3b, v22
	v_exp_f32_e32 v38, v20
	v_mul_f32_e32 v20, 0xbfb8aa3b, v23
	v_exp_f32_e32 v39, v20
	v_pk_mul_f32 v[16:17], v[16:17], v[22:23]
	v_pk_add_f32 v[22:23], v[38:39], 1.0 op_sel_hi:[1,0]
	s_nop 0
	s_nop 0
	v_rcp_f32_e32 v23, v23
	v_div_scale_f32 v20, s[52:53], v22, v22, 1.0
	v_rcp_f32_e32 v24, v20
	s_nop 0
	v_fma_f32 v25, -v20, v24, 1.0
	v_fmac_f32_e32 v24, v25, v24
	v_div_scale_f32 v25, vcc, 1.0, v22, 1.0
	v_mul_f32_e32 v35, v25, v24
	v_fma_f32 v38, -v20, v35, v25
	v_fmac_f32_e32 v35, v38, v24
	v_pk_mul_f32 v[24:25], v[26:27], v[34:35] op_sel_hi:[1,0]
	v_rcp_f32_e32 v22, v22
	v_lshlrev_b32_e32 v20, 16, v21
	v_and_b32_e32 v21, 0xffff0000, v21
	v_pk_mul_f32 v[18:19], v[24:25], v[18:19]
	v_pk_mul_f32 v[16:17], v[16:17], v[22:23]
	v_mul_f32_e32 v22, 0xbfb8aa3b, v20
	v_pk_mul_f32 v[18:19], v[18:19], v[20:21]
	v_mul_f32_e32 v20, 0xbfb8aa3b, v21
	v_exp_f32_e32 v22, v22
	v_exp_f32_e32 v23, v20
	v_cvt_pk_bf16_f32 v16, v16, v17
	v_pk_add_f32 v[20:21], v[22:23], 1.0 op_sel_hi:[1,0]
	s_nop 0
	s_nop 0
	v_rcp_f32_e32 v21, v21
	s_nop 0
	v_rcp_f32_e32 v20, v20
	s_nop 0
	v_pk_mul_f32 v[18:19], v[18:19], v[20:21]
	v_pk_mul_f32 v[26:27], v[28:29], v[34:35] op_sel_hi:[1,0]
	v_cvt_pk_bf16_f32 v17, v18, v19
	global_store_dwordx2 v[32:33], v[16:17], off offset:32
	global_load_dwordx4 v[16:19], v[86:87], off offset:96
	s_nop 0
	global_load_dwordx2 v[20:21], v[36:37], off offset:48
	s_waitcnt vmcnt(1)
	v_pk_mul_f32 v[16:17], v[26:27], v[16:17]
	s_waitcnt vmcnt(0)
	v_lshlrev_b32_e32 v22, 16, v20
	v_and_b32_e32 v23, 0xffff0000, v20
	v_mul_f32_e32 v20, 0xbfb8aa3b, v22
	v_exp_f32_e32 v24, v20
	v_mul_f32_e32 v20, 0xbfb8aa3b, v23
	v_exp_f32_e32 v25, v20
	v_pk_mul_f32 v[16:17], v[16:17], v[22:23]
	v_pk_add_f32 v[22:23], v[24:25], 1.0 op_sel_hi:[1,0]
	s_nop 0
	s_nop 0
	v_rcp_f32_e32 v23, v23
	s_nop 0
	v_pk_mul_f32 v[24:25], v[30:31], v[34:35] op_sel_hi:[1,0]
	v_rcp_f32_e32 v22, v22
	v_lshlrev_b32_e32 v20, 16, v21
	v_and_b32_e32 v21, 0xffff0000, v21
	v_pk_mul_f32 v[18:19], v[24:25], v[18:19]
	v_pk_mul_f32 v[16:17], v[16:17], v[22:23]
	v_mul_f32_e32 v22, 0xbfb8aa3b, v20
	v_pk_mul_f32 v[18:19], v[18:19], v[20:21]
	v_mul_f32_e32 v20, 0xbfb8aa3b, v21
	v_exp_f32_e32 v22, v22
	v_exp_f32_e32 v23, v20
	v_cvt_pk_bf16_f32 v16, v16, v17
	v_pk_add_f32 v[20:21], v[22:23], 1.0 op_sel_hi:[1,0]
	s_nop 0
	s_nop 0
	v_rcp_f32_e32 v21, v21
	v_div_scale_f32 v22, s[52:53], v20, v20, 1.0
	v_rcp_f32_e32 v23, v22
	s_nop 0
	v_fma_f32 v24, -v22, v23, 1.0
	v_fmac_f32_e32 v23, v24, v23
	v_div_scale_f32 v24, vcc, 1.0, v20, 1.0
	v_mul_f32_e32 v25, v24, v23
	v_fma_f32 v26, -v22, v25, v24
	v_fmac_f32_e32 v25, v26, v23
	v_fma_f32 v22, -v22, v25, v24
	v_div_fmas_f32 v22, v22, v23, v25
	v_rcp_f32_e32 v20, v20
	s_nop 0
	v_pk_mul_f32 v[18:19], v[18:19], v[20:21]
	s_nop 0
	v_cvt_pk_bf16_f32 v17, v18, v19
	global_store_dwordx2 v[32:33], v[16:17], off offset:48
	s_cbranch_scc0 .LBB0_882

; DI void attn_sample_phase(const Args& a, LAS unsigned char* lds, int vcu, int G, int tid, int lane, int wave) {
;     ...
;         for (int j = 0; j < 128; ++j) {
;             const int c3n = (c3 == 2) ? 0 : c3 + 1, c3p = (c3 == 0) ? 2 : c3 - 1;
;             if (j > 0) SA_PV(c3p);
.LBB0_902:
	s_mov_b32 s98, s17
	s_add_i32 s26, s25, -2
	s_cmp_lg_u64 s[2:3], 0
	s_cbranch_scc1 .Lsa_a4
.Lsa_front:
	s_cmp_eq_u32 s25, 2
	s_cbranch_scc1 .LBB0_904
	s_mul_i32 s8, s98, 0x2500
	s_addk_i32 s8, 0xdb00
	s_cmp_lg_u32 s98, 0
	s_cselect_b32 s8, s8, 0x4a00
	v_lshl_add_u32 v2, s8, 1, v201
	ds_read_b64_tr_b16 v[136:137], v2
	ds_read_b64_tr_b16 v[138:139], v2 offset:2368
	ds_read_b128 v[212:215], v196
	ds_read_b128 v[216:219], v196 offset:32
	ds_read_b64_tr_b16 v[220:221], v2 offset:9472
	ds_read_b64_tr_b16 v[222:223], v2 offset:11840
	s_waitcnt lgkmcnt(3)
	v_mfma_f32_32x32x16_bf16 v[4:19], v[136:139], v[212:215], v[4:19]
	s_waitcnt lgkmcnt(0)
	v_mfma_f32_32x32x16_bf16 v[4:19], v[220:223], v[216:219], v[4:19]

; #define LAS __attribute__((address_space(3)))
; #define MFMA16(a, b, c) __builtin_amdgcn_mfma_f32_16x16x32_bf16((a), (b), (c), 0, 0, 0)
; DI void attn_sample_phase(const Args& a, LAS unsigned char* lds, int vcu, int G, int tid, int lane, int wave) {
;     ...
;             f32x4 sa = {0.f, 0.f, 0.f, 0.f};
;             if (wave < 4) { const int kb = wave >> 1, nb2 = wave & 1; const LAS bf16* cb = Cs + c3 * (32 * CSW);
; #pragma unroll
;                 for (int s9 = 0; s9 < 9; ++s9) { const bf16x8 af = *(const LAS bf16x8*)(cb + (kb * 16 + r16) * CSW + 32 * s9 + 8 * q4);
;                     sa = MFMA16(af, qfr[s9], sa); } (void)nb2; }
;             if (j + 1 < 128) { SA_CONVERT(j + 1, c3n, a0, a1, a2, a3, aka, akb); if (j + 2 < 128) SA_LOAD(j + 2, a0, a1, a2, a3, aka, akb); }
.LBB0_908:
	s_or_b64 exec, exec, s[8:9]
	v_cndmask_b32_e64 v2, 0, 1, s[10:11]
	v_mov_b32_e32 v136, 0
	v_cmp_ne_u32_e64 s[8:9], 1, v2
	s_andn2_b64 vcc, exec, s[10:11]
	v_mov_b32_e32 v137, 0
	v_mov_b32_e32 v138, 0
	v_mov_b32_e32 v139, 0
	s_cbranch_vccnz .LBB0_910
	s_mul_i32 s18, s98, 0x4a00
	v_add_u32_e32 v2, s18, v197
	ds_read_b128 v[136:139], v2
	ds_read_b128 v[212:215], v2 offset:64
	ds_read_b128 v[216:219], v2 offset:128
	s_waitcnt lgkmcnt(2)
	v_mfma_f32_16x16x32_bf16 v[136:139], v[136:139], v[84:87], 0
	s_waitcnt lgkmcnt(1)
	v_mfma_f32_16x16x32_bf16 v[136:139], v[212:215], v[88:91], v[136:139]
	ds_read_b128 v[212:215], v2 offset:192
	s_waitcnt lgkmcnt(1)
	v_mfma_f32_16x16x32_bf16 v[136:139], v[216:219], v[92:95], v[136:139]
	ds_read_b128 v[216:219], v2 offset:256
	s_waitcnt lgkmcnt(1)
	v_mfma_f32_16x16x32_bf16 v[136:139], v[212:215], v[96:99], v[136:139]
	ds_read_b128 v[212:215], v2 offset:320
	s_waitcnt lgkmcnt(1)
	v_mfma_f32_16x16x32_bf16 v[136:139], v[216:219], v[100:103], v[136:139]
	ds_read_b128 v[216:219], v2 offset:384
	s_waitcnt lgkmcnt(1)
	v_mfma_f32_16x16x32_bf16 v[136:139], v[212:215], v[104:107], v[136:139]
	ds_read_b128 v[212:215], v2 offset:448
	s_waitcnt lgkmcnt(1)
	v_mfma_f32_16x16x32_bf16 v[136:139], v[216:219], v[108:111], v[136:139]
	s_waitcnt lgkmcnt(0)
	v_mfma_f32_16x16x32_bf16 v[136:139], v[212:215], v[112:115], v[136:139]
	ds_read_b128 v[212:215], v2 offset:512
	s_waitcnt lgkmcnt(0)
	v_mfma_f32_16x16x32_bf16 v[136:139], v[212:215], v[116:119], v[136:139]
.LBB0_910:
	s_cmp_lg_u64 s[2:3], 0
	s_cbranch_scc1 .LBB0_919

; DI unsigned pk2(float lo, float hi) { f32x2 v = {lo, hi}; bf16x2_t b = __builtin_convertvector(v, bf16x2_t); return __builtin_bit_cast(unsigned, b); }
; DI float sigmoidf_(float x) { return 1.f / (1.f + __expf(-x)); }
;     DI void operator()(const f32x4 (&acc)[2][2][4][2], const Unit& u, int wr, int wc, int fr, int fq) const {
;     ...
;             for (int m = 0; m < 4; ++m) { const int row = row0 + ai * HALF + m * 16;
;                 const float* bp = (row < MP) ? base0 + (size_t)row * DM : base1 + (size_t)(row - MP) * DM;
;                 float r = 1.f; if (MODE == 1) r = __builtin_amdgcn_rsqf(ssin[row] * (1.f / DM) + EPS);
;                 float s = 0.f;
; #pragma unroll
;                 for (int bj = 0; bj < 2; ++bj)
; #pragma unroll
;                     for (int n = 0; n < 2; ++n) { const int col = col0 + bj * HALF + n * 16;
;                         f32x4 v = acc[ai][bj][m][n];
;                         if (MODE == 1) { const u32x2 pw = *(const u32x2*)(PP + (size_t)row * DM + col);
;                             v[0] = sigmoidf_(v[0] * r) * bflo(pw.x); v[1] = sigmoidf_(v[1] * r) * bfhi(pw.x); v[2] = sigmoidf_(v[2] * r) * bflo(pw.y); v[3] = sigmoidf_(v[3] * r) * bfhi(pw.y); }
;                         f32x4 h;
;                         if (baseb) { const u32x2 bw = *(const u32x2*)(baseb + (size_t)row * DM + col); h = (f32x4){bflo(bw.x), bfhi(bw.x), bflo(bw.y), bfhi(bw.y)} + v; }
;                         else h = *(const f32x4*)(bp + col) + v;
;                         if (H) *(f32x4*)(H + (size_t)row * DM + col) = h;
;                         if (XB) { u32x2 w; w.x = pk2(h[0], h[1]); w.y = pk2(h[2], h[3]); *(u32x2*)(XB + (size_t)row * DM + col) = w; }
;                         s += (h[0] * h[0] + h[1] * h[1]) + (h[2] * h[2] + h[3] * h[3]); }
;                 if (ssout) { s += __shfl_xor(s, 16); s += __shfl_xor(s, 32); if (fq == 0) atomicAdd(ssout + row, s); } }
.LBB0_1423:
	v_lshl_add_u32 v148, s4, 8, v1
	v_ashrrev_i32_e32 v147, 31, v148
	v_cmp_gt_i32_e32 vcc, s52, v148
	v_lshl_or_b32 v146, s6, 8, v143
	s_nop 0
	v_cndmask_b32_e32 v149, 0, v147, vcc
	v_lshl_add_u64 v[150:151], v[148:149], 2, s[16:17]
	global_load_dword v173, v[150:151], off
	v_lshlrev_b64 v[150:151], 11, v[148:149]
	v_ashrrev_i32_e32 v147, 31, v146
	v_lshl_add_u64 v[152:153], s[18:19], 0, v[150:151]
	v_lshlrev_b64 v[146:147], 1, v[146:147]
	v_lshl_add_u64 v[154:155], v[152:153], 0, v[146:147]
	v_lshl_add_u64 v[152:153], s[92:93], 0, v[150:151]
	v_lshl_add_u64 v[152:153], v[152:153], 0, v[146:147]
	global_load_dwordx2 v[158:159], v[154:155], off
	global_load_dwordx2 v[164:165], v[152:153], off
	global_load_dwordx2 v[156:157], v[154:155], off offset:32
	global_load_dwordx2 v[160:161], v[154:155], off offset:256
	global_load_dwordx2 v[162:163], v[152:153], off offset:32
	global_load_dwordx2 v[166:167], v[152:153], off offset:256
	s_nop 0
	global_load_dwordx2 v[154:155], v[154:155], off offset:288
	v_lshl_add_u64 v[150:151], s[14:15], 0, v[150:151]
	v_lshl_add_u64 v[150:151], v[150:151], 0, v[146:147]
	s_waitcnt vmcnt(0)
	v_fmamk_f32 v173, v173, 0x3a800000, v171
	v_rsq_f32_e32 v173, v173
	v_lshlrev_b32_e32 v174, 16, v158
	v_mul_f32_e32 v126, v126, v173
	v_mul_f32_e32 v127, v127, v173
	v_mul_f32_e32 v122, v122, v173
	v_mul_f32_e32 v123, v123, v173
	v_mul_f32_e32 v126, 0xbfb8aa3b, v126
	v_mul_f32_e32 v127, 0xbfb8aa3b, v127
	v_mul_f32_e32 v178, 0xbfb8aa3b, v122
	v_mul_f32_e32 v179, 0xbfb8aa3b, v123
	v_exp_f32_e32 v122, v126
	v_exp_f32_e32 v123, v127
	v_mul_f32_e32 v128, v128, v173
	v_mul_f32_e32 v129, v129, v173
	v_mul_f32_e32 v128, 0xbfb8aa3b, v128
	v_pk_add_f32 v[122:123], v[122:123], 1.0 op_sel_hi:[1,0]
	v_mul_f32_e32 v129, 0xbfb8aa3b, v129
	v_exp_f32_e32 v126, v128
	v_exp_f32_e32 v128, v178
	v_exp_f32_e32 v127, v129
	s_nop 0
	v_pk_add_f32 v[126:127], v[126:127], 1.0 op_sel_hi:[1,0]
	v_exp_f32_e32 v129, v179
	v_rcp_f32_e32 v123, v123
	v_and_b32_e32 v175, 0xffff0000, v158
	v_lshlrev_b32_e32 v176, 16, v164
	v_and_b32_e32 v177, 0xffff0000, v164
	v_rcp_f32_e32 v122, v122
	s_nop 0
	v_pk_fma_f32 v[122:123], v[122:123], v[174:175], v[176:177]
	v_mul_f32_e32 v176, v123, v123
	v_cvt_pk_bf16_f32 v174, v122, v123
	v_fmac_f32_e32 v176, v122, v122
	v_pk_add_f32 v[122:123], v[128:129], 1.0 op_sel_hi:[1,0]
	v_rcp_f32_e32 v127, v127
	v_lshlrev_b32_e32 v158, 16, v159
	v_and_b32_e32 v159, 0xffff0000, v159
	v_lshlrev_b32_e32 v164, 16, v165
	v_and_b32_e32 v165, 0xffff0000, v165
	v_rcp_f32_e32 v126, v126
	s_nop 0
	v_pk_fma_f32 v[126:127], v[126:127], v[158:159], v[164:165]
	v_mul_f32_e32 v124, v124, v173
	v_cvt_pk_bf16_f32 v175, v126, v127
	v_mul_f32_e32 v127, v127, v127
	v_fmac_f32_e32 v127, v126, v126
	v_add_f32_e32 v164, v176, v127
	v_mul_f32_e32 v125, v125, v173
	v_rcp_f32_e32 v127, v123
	v_mul_f32_e32 v124, 0xbfb8aa3b, v124
	v_mul_f32_e32 v125, 0xbfb8aa3b, v125
	v_exp_f32_e32 v124, v124
	v_exp_f32_e32 v125, v125
	s_nop 0
	v_pk_add_f32 v[124:125], v[124:125], 1.0 op_sel_hi:[1,0]
	v_rcp_f32_e32 v126, v122
	v_lshlrev_b32_e32 v128, 16, v156
	v_and_b32_e32 v129, 0xffff0000, v156
	v_rcp_f32_e32 v123, v125
	v_mul_f32_e32 v118, v118, v173
	v_mul_f32_e32 v119, v119, v173
	v_mul_f32_e32 v118, 0xbfb8aa3b, v118
	v_mul_f32_e32 v119, 0xbfb8aa3b, v119
	v_exp_f32_e32 v118, v118
	v_exp_f32_e32 v119, v119
	v_rcp_f32_e32 v122, v124
	v_lshlrev_b32_e32 v124, 16, v157
	v_and_b32_e32 v125, 0xffff0000, v157
	v_lshlrev_b32_e32 v156, 16, v162
	v_and_b32_e32 v157, 0xffff0000, v162
	v_lshlrev_b32_e32 v158, 16, v163
	v_and_b32_e32 v159, 0xffff0000, v163
	v_pk_fma_f32 v[126:127], v[126:127], v[128:129], v[156:157]
	v_pk_add_f32 v[118:119], v[118:119], 1.0 op_sel_hi:[1,0]
	v_pk_fma_f32 v[122:123], v[122:123], v[124:125], v[158:159]
	v_cvt_pk_bf16_f32 v124, v126, v127
	v_mul_f32_e32 v125, v127, v127
	v_fmac_f32_e32 v125, v126, v126
	v_mul_f32_e32 v126, v123, v123
	v_fmac_f32_e32 v126, v122, v122
	v_add_f32_e32 v125, v125, v126
	v_mul_f32_e32 v120, v120, v173
	v_mul_f32_e32 v121, v121, v173
	v_rcp_f32_e32 v119, v119
	v_mul_f32_e32 v120, 0xbfb8aa3b, v120
	v_mul_f32_e32 v121, 0xbfb8aa3b, v121
	v_exp_f32_e32 v120, v120
	v_exp_f32_e32 v121, v121
	s_nop 0
	v_pk_add_f32 v[120:121], v[120:121], 1.0 op_sel_hi:[1,0]
	v_rcp_f32_e32 v118, v118
	v_lshlrev_b32_e32 v126, 16, v160
	v_and_b32_e32 v127, 0xffff0000, v160
	v_rcp_f32_e32 v121, v121
	v_mul_f32_e32 v114, v114, v173
	v_lshlrev_b32_e32 v156, 16, v166
	v_and_b32_e32 v157, 0xffff0000, v166
	v_pk_fma_f32 v[118:119], v[118:119], v[126:127], v[156:157]
	global_load_dwordx2 v[126:127], v[152:153], off offset:288
	v_mul_f32_e32 v115, v115, v173
	v_mul_f32_e32 v114, 0xbfb8aa3b, v114
	v_mul_f32_e32 v115, 0xbfb8aa3b, v115
	v_exp_f32_e32 v114, v114
	v_exp_f32_e32 v115, v115
	v_rcp_f32_e32 v120, v120
	v_lshlrev_b32_e32 v128, 16, v161
	v_pk_add_f32 v[114:115], v[114:115], 1.0 op_sel_hi:[1,0]
	v_and_b32_e32 v129, 0xffff0000, v161
	v_lshlrev_b32_e32 v158, 16, v167
	v_and_b32_e32 v159, 0xffff0000, v167
	v_pk_fma_f32 v[120:121], v[120:121], v[128:129], v[158:159]
	v_mul_f32_e32 v128, v119, v119
	v_mul_f32_e32 v129, v121, v121
	v_fmac_f32_e32 v128, v118, v118
	v_fmac_f32_e32 v129, v120, v120
	v_add_f32_e32 v125, v164, v125
	v_add_f32_e32 v128, v128, v129
	v_add_f32_e32 v125, v125, v128
	v_mul_f32_e32 v116, v116, v173
	v_mul_f32_e32 v117, v117, v173
	v_mul_f32_e32 v116, 0xbfb8aa3b, v116
	v_mul_f32_e32 v117, 0xbfb8aa3b, v117
	v_rcp_f32_e32 v115, v115
	v_exp_f32_e32 v116, v116
	v_exp_f32_e32 v117, v117
	s_nop 0
	v_pk_add_f32 v[116:117], v[116:117], 1.0 op_sel_hi:[1,0]
	v_rcp_f32_e32 v114, v114
	v_lshlrev_b32_e32 v128, 16, v154
	v_and_b32_e32 v129, 0xffff0000, v154
	v_rcp_f32_e32 v117, v117
	v_cvt_pk_bf16_f32 v118, v118, v119
	v_div_scale_f32 v152, vcc, 1.0, v116, 1.0
	v_rcp_f32_e32 v116, v116
	v_lshlrev_b32_e32 v152, 16, v155
	v_and_b32_e32 v153, 0xffff0000, v155
	s_waitcnt vmcnt(0)
; DI float sigmoidf_(float x) { return 1.f / (1.f + __expf(-x)); }
;     DI void operator()(const f32x4 (&acc)[2][2][4][2], const Unit& u, int wr, int wc, int fr, int fq) const {
;     ...
;             for (int m = 0; m < 4; ++m) { const int row = row0 + ai * HALF + m * 16;
;                 const float* bp = (row < MP) ? base0 + (size_t)row * DM : base1 + (size_t)(row - MP) * DM;
;                 float r = 1.f; if (MODE == 1) r = __builtin_amdgcn_rsqf(ssin[row] * (1.f / DM) + EPS);
;                 float s = 0.f;
; #pragma unroll
;                 for (int bj = 0; bj < 2; ++bj)
; #pragma unroll
;                     for (int n = 0; n < 2; ++n) { const int col = col0 + bj * HALF + n * 16;
;                         f32x4 v = acc[ai][bj][m][n];
;                         if (MODE == 1) { const u32x2 pw = *(const u32x2*)(PP + (size_t)row * DM + col);
;                             v[0] = sigmoidf_(v[0] * r) * bflo(pw.x); v[1] = sigmoidf_(v[1] * r) * bfhi(pw.x); v[2] = sigmoidf_(v[2] * r) * bflo(pw.y); v[3] = sigmoidf_(v[3] * r) * bfhi(pw.y); }
;     ...
;                         s += (h[0] * h[0] + h[1] * h[1]) + (h[2] * h[2] + h[3] * h[3]); }
;                 if (ssout) { s += __shfl_xor(s, 16); s += __shfl_xor(s, 32); if (fq == 0) atomicAdd(ssout + row, s); } }
	v_lshlrev_b32_e32 v154, 16, v126
	v_and_b32_e32 v155, 0xffff0000, v126
	v_lshlrev_b32_e32 v126, 16, v127
	v_and_b32_e32 v127, 0xffff0000, v127
	v_pk_fma_f32 v[116:117], v[116:117], v[152:153], v[126:127]
	v_pk_fma_f32 v[126:127], v[114:115], v[128:129], v[154:155]
	v_mul_f32_e32 v115, v117, v117
	v_mul_f32_e32 v114, v127, v127
	v_fmac_f32_e32 v114, v126, v126
	v_fmac_f32_e32 v115, v116, v116
	v_add_f32_e32 v114, v114, v115
	v_add_f32_e32 v114, v125, v114
	v_and_b32_e32 v125, 64, v172
	v_xor_b32_e32 v115, 16, v172
	v_add_u32_e32 v128, 64, v125
	v_cmp_lt_i32_e32 vcc, v115, v128
	v_cvt_pk_bf16_f32 v119, v120, v121
	v_cvt_pk_bf16_f32 v125, v122, v123
	v_cndmask_b32_e32 v115, v172, v115, vcc
	v_lshlrev_b32_e32 v154, 2, v115
	ds_bpermute_b32 v115, v154, v114
	global_store_dwordx2 v[150:151], v[118:119], off offset:256
	v_cvt_pk_bf16_f32 v118, v126, v127
	v_cvt_pk_bf16_f32 v119, v116, v117
	global_store_dwordx2 v[150:151], v[174:175], off
	s_waitcnt lgkmcnt(0)
	v_add_f32_e32 v114, v114, v115
	v_xor_b32_e32 v115, 32, v172
	v_cmp_lt_i32_e32 vcc, v115, v128
	global_store_dwordx2 v[150:151], v[124:125], off offset:32
	global_store_dwordx2 v[150:151], v[118:119], off offset:288
	v_cndmask_b32_e32 v115, v172, v115, vcc
	v_lshlrev_b32_e32 v155, 2, v115
	ds_bpermute_b32 v115, v155, v114
	s_and_saveexec_b64 s[4:5], s[0:1]
	s_cbranch_execz .LBB0_1425
	v_lshl_add_u64 v[116:117], v[148:149], 2, s[12:13]
	s_waitcnt lgkmcnt(0)
	v_add_f32_e32 v114, v114, v115
	global_atomic_add_f32 v[116:117], v114, off
.LBB0_1425:
	s_or_b64 exec, exec, s[4:5]
	v_or_b32_e32 v114, 16, v148
	s_waitcnt lgkmcnt(0)
	v_ashrrev_i32_e32 v115, 31, v114
	v_cmp_gt_i32_e32 vcc, s52, v114
	s_nop 1
	v_cndmask_b32_e32 v115, 0, v115, vcc
	v_lshl_add_u64 v[116:117], v[114:115], 2, s[16:17]
	global_load_dword v149, v[116:117], off
	v_lshlrev_b64 v[116:117], 11, v[114:115]
	v_lshl_add_u64 v[118:119], s[18:19], 0, v[116:117]
	v_lshl_add_u64 v[120:121], v[118:119], 0, v[146:147]
	v_lshl_add_u64 v[118:119], s[92:93], 0, v[116:117]
	v_lshl_add_u64 v[118:119], v[118:119], 0, v[146:147]
	global_load_dwordx2 v[124:125], v[120:121], off
	global_load_dwordx2 v[128:129], v[118:119], off
	global_load_dwordx2 v[122:123], v[120:121], off offset:32
	global_load_dwordx2 v[126:127], v[120:121], off offset:256
	global_load_dwordx2 v[150:151], v[118:119], off offset:32
	global_load_dwordx2 v[152:153], v[118:119], off offset:256
	s_nop 0
	global_load_dwordx2 v[120:121], v[120:121], off offset:288
	v_lshl_add_u64 v[116:117], s[14:15], 0, v[116:117]
	v_lshl_add_u64 v[116:117], v[116:117], 0, v[146:147]
	s_waitcnt vmcnt(7)
	v_fmamk_f32 v149, v149, 0x3a800000, v171
	v_rsq_f32_e32 v149, v149
	s_waitcnt vmcnt(6)
	v_lshlrev_b32_e32 v156, 16, v124
	v_mul_f32_e32 v110, v110, v149
	v_mul_f32_e32 v111, v111, v149
	v_mul_f32_e32 v106, v106, v149
	v_mul_f32_e32 v107, v107, v149
	v_mul_f32_e32 v110, 0xbfb8aa3b, v110
	v_mul_f32_e32 v111, 0xbfb8aa3b, v111
	v_mul_f32_e32 v160, 0xbfb8aa3b, v106
	v_mul_f32_e32 v161, 0xbfb8aa3b, v107
	v_exp_f32_e32 v106, v110
	v_exp_f32_e32 v107, v111
	v_mul_f32_e32 v112, v112, v149
	v_mul_f32_e32 v113, v113, v149
	v_mul_f32_e32 v112, 0xbfb8aa3b, v112
	v_mul_f32_e32 v113, 0xbfb8aa3b, v113
	v_exp_f32_e32 v110, v112
	v_exp_f32_e32 v111, v113
	v_pk_add_f32 v[106:107], v[106:107], 1.0 op_sel_hi:[1,0]
	v_exp_f32_e32 v112, v160
	v_pk_add_f32 v[110:111], v[110:111], 1.0 op_sel_hi:[1,0]
	v_exp_f32_e32 v113, v161
	v_rcp_f32_e32 v107, v107
	v_and_b32_e32 v157, 0xffff0000, v124
	s_waitcnt vmcnt(5)
	v_lshlrev_b32_e32 v158, 16, v128
	v_and_b32_e32 v159, 0xffff0000, v128
	v_rcp_f32_e32 v106, v106
	s_nop 0
	v_pk_fma_f32 v[106:107], v[106:107], v[156:157], v[158:159]
	v_pk_add_f32 v[112:113], v[112:113], 1.0 op_sel_hi:[1,0]
	v_rcp_f32_e32 v111, v111
	v_cvt_pk_bf16_f32 v156, v106, v107
	v_mul_f32_e32 v107, v107, v107
	v_lshlrev_b32_e32 v124, 16, v125
	v_and_b32_e32 v125, 0xffff0000, v125
	v_lshlrev_b32_e32 v128, 16, v129
	v_and_b32_e32 v129, 0xffff0000, v129
	v_rcp_f32_e32 v110, v110
	v_fmac_f32_e32 v107, v106, v106
	v_pk_fma_f32 v[110:111], v[110:111], v[124:125], v[128:129]
	v_cvt_pk_bf16_f32 v157, v110, v111
	v_mul_f32_e32 v111, v111, v111
	v_fmac_f32_e32 v111, v110, v110
	v_add_f32_e32 v128, v107, v111
	v_rcp_f32_e32 v111, v113
	v_mul_f32_e32 v106, v108, v149
	v_mul_f32_e32 v107, v109, v149
	v_mul_f32_e32 v106, 0xbfb8aa3b, v106
	v_mul_f32_e32 v107, 0xbfb8aa3b, v107
	v_exp_f32_e32 v106, v106
	v_exp_f32_e32 v107, v107
	v_rcp_f32_e32 v110, v112
	v_pk_add_f32 v[106:107], v[106:107], 1.0 op_sel_hi:[1,0]
	s_waitcnt vmcnt(4)
	v_lshlrev_b32_e32 v108, 16, v122
	v_and_b32_e32 v109, 0xffff0000, v122
	v_mul_f32_e32 v102, v102, v149
	v_mul_f32_e32 v103, v103, v149
	v_rcp_f32_e32 v107, v107
	v_mul_f32_e32 v102, 0xbfb8aa3b, v102
	v_mul_f32_e32 v103, 0xbfb8aa3b, v103
	v_exp_f32_e32 v102, v102
	v_exp_f32_e32 v103, v103
	v_rcp_f32_e32 v106, v106
	v_lshlrev_b32_e32 v112, 16, v123
	v_and_b32_e32 v113, 0xffff0000, v123
	s_waitcnt vmcnt(2)
	v_lshlrev_b32_e32 v122, 16, v150
	v_and_b32_e32 v123, 0xffff0000, v150
	v_pk_fma_f32 v[110:111], v[110:111], v[108:109], v[122:123]
	v_pk_add_f32 v[102:103], v[102:103], 1.0 op_sel_hi:[1,0]
	v_lshlrev_b32_e32 v124, 16, v151
	v_and_b32_e32 v125, 0xffff0000, v151
	v_cvt_pk_bf16_f32 v108, v110, v111
	v_mul_f32_e32 v109, v111, v111
	v_pk_fma_f32 v[106:107], v[106:107], v[112:113], v[124:125]
	v_fmac_f32_e32 v109, v110, v110
	v_mul_f32_e32 v110, v107, v107
	v_fmac_f32_e32 v110, v106, v106
	v_add_f32_e32 v109, v109, v110
	v_mul_f32_e32 v104, v104, v149
	v_mul_f32_e32 v105, v105, v149
	v_rcp_f32_e32 v103, v103
	v_mul_f32_e32 v104, 0xbfb8aa3b, v104
	v_mul_f32_e32 v105, 0xbfb8aa3b, v105
	v_exp_f32_e32 v104, v104
	v_exp_f32_e32 v105, v105
	s_nop 0
	v_pk_add_f32 v[104:105], v[104:105], 1.0 op_sel_hi:[1,0]
	v_rcp_f32_e32 v102, v102
	v_lshlrev_b32_e32 v110, 16, v126
	v_and_b32_e32 v111, 0xffff0000, v126
	v_rcp_f32_e32 v105, v105
	v_mul_f32_e32 v98, v98, v149
	s_waitcnt vmcnt(1)
; DI unsigned pk2(float lo, float hi) { f32x2 v = {lo, hi}; bf16x2_t b = __builtin_convertvector(v, bf16x2_t); return __builtin_bit_cast(unsigned, b); }
; DI float sigmoidf_(float x) { return 1.f / (1.f + __expf(-x)); }
;     DI void operator()(const f32x4 (&acc)[2][2][4][2], const Unit& u, int wr, int wc, int fr, int fq) const {
;     ...
;             for (int m = 0; m < 4; ++m) { const int row = row0 + ai * HALF + m * 16;
;                 const float* bp = (row < MP) ? base0 + (size_t)row * DM : base1 + (size_t)(row - MP) * DM;
;                 float r = 1.f; if (MODE == 1) r = __builtin_amdgcn_rsqf(ssin[row] * (1.f / DM) + EPS);
;                 float s = 0.f;
;     ...
;                         if (MODE == 1) { const u32x2 pw = *(const u32x2*)(PP + (size_t)row * DM + col);
;                             v[0] = sigmoidf_(v[0] * r) * bflo(pw.x); v[1] = sigmoidf_(v[1] * r) * bfhi(pw.x); v[2] = sigmoidf_(v[2] * r) * bflo(pw.y); v[3] = sigmoidf_(v[3] * r) * bfhi(pw.y); }
;                         f32x4 h;
;                         if (baseb) { const u32x2 bw = *(const u32x2*)(baseb + (size_t)row * DM + col); h = (f32x4){bflo(bw.x), bfhi(bw.x), bflo(bw.y), bfhi(bw.y)} + v; }
;                         else h = *(const f32x4*)(bp + col) + v;
;                         if (H) *(f32x4*)(H + (size_t)row * DM + col) = h;
;                         if (XB) { u32x2 w; w.x = pk2(h[0], h[1]); w.y = pk2(h[2], h[3]); *(u32x2*)(XB + (size_t)row * DM + col) = w; }
;                         s += (h[0] * h[0] + h[1] * h[1]) + (h[2] * h[2] + h[3] * h[3]); }
;                 if (ssout) { s += __shfl_xor(s, 16); s += __shfl_xor(s, 32); if (fq == 0) atomicAdd(ssout + row, s); } }
	v_lshlrev_b32_e32 v122, 16, v152
	v_and_b32_e32 v123, 0xffff0000, v152
	v_pk_fma_f32 v[102:103], v[102:103], v[110:111], v[122:123]
	global_load_dwordx2 v[110:111], v[118:119], off offset:288
	v_mul_f32_e32 v99, v99, v149
	v_mul_f32_e32 v98, 0xbfb8aa3b, v98
	v_mul_f32_e32 v99, 0xbfb8aa3b, v99
	v_exp_f32_e32 v98, v98
	v_exp_f32_e32 v99, v99
	v_rcp_f32_e32 v104, v104
	v_lshlrev_b32_e32 v112, 16, v127
	v_pk_add_f32 v[98:99], v[98:99], 1.0 op_sel_hi:[1,0]
	v_and_b32_e32 v113, 0xffff0000, v127
	v_lshlrev_b32_e32 v124, 16, v153
	v_and_b32_e32 v125, 0xffff0000, v153
	v_pk_fma_f32 v[104:105], v[104:105], v[112:113], v[124:125]
	v_mul_f32_e32 v112, v103, v103
	v_mul_f32_e32 v113, v105, v105
	v_fmac_f32_e32 v112, v102, v102
	v_fmac_f32_e32 v113, v104, v104
	v_add_f32_e32 v109, v128, v109
	v_add_f32_e32 v112, v112, v113
	v_add_f32_e32 v109, v109, v112
	v_mul_f32_e32 v100, v100, v149
	v_mul_f32_e32 v101, v101, v149
	v_mul_f32_e32 v100, 0xbfb8aa3b, v100
	v_mul_f32_e32 v101, 0xbfb8aa3b, v101
	v_rcp_f32_e32 v99, v99
	v_exp_f32_e32 v100, v100
	v_exp_f32_e32 v101, v101
	s_nop 0
	v_pk_add_f32 v[100:101], v[100:101], 1.0 op_sel_hi:[1,0]
	v_rcp_f32_e32 v98, v98
	s_waitcnt vmcnt(1)
	v_lshlrev_b32_e32 v112, 16, v120
	v_and_b32_e32 v113, 0xffff0000, v120
	v_rcp_f32_e32 v101, v101
	v_cvt_pk_bf16_f32 v102, v102, v103
	v_div_scale_f32 v118, vcc, 1.0, v100, 1.0
	v_rcp_f32_e32 v100, v100
	v_lshlrev_b32_e32 v118, 16, v121
	v_and_b32_e32 v119, 0xffff0000, v121
	s_waitcnt vmcnt(0)
	v_lshlrev_b32_e32 v120, 16, v110
	v_and_b32_e32 v121, 0xffff0000, v110
	v_lshlrev_b32_e32 v110, 16, v111
	v_and_b32_e32 v111, 0xffff0000, v111
	v_pk_fma_f32 v[100:101], v[100:101], v[118:119], v[110:111]
	v_pk_fma_f32 v[110:111], v[98:99], v[112:113], v[120:121]
	v_mul_f32_e32 v99, v101, v101
	v_mul_f32_e32 v98, v111, v111
	v_fmac_f32_e32 v98, v110, v110
	v_fmac_f32_e32 v99, v100, v100
	v_add_f32_e32 v98, v98, v99
	v_add_f32_e32 v98, v109, v98
	ds_bpermute_b32 v99, v154, v98
	v_cvt_pk_bf16_f32 v103, v104, v105
	v_cvt_pk_bf16_f32 v109, v106, v107
	global_store_dwordx2 v[116:117], v[102:103], off offset:256
	v_cvt_pk_bf16_f32 v102, v110, v111
	s_waitcnt lgkmcnt(0)
	v_add_f32_e32 v98, v98, v99
	ds_bpermute_b32 v99, v155, v98
	v_cvt_pk_bf16_f32 v103, v100, v101
	global_store_dwordx2 v[116:117], v[156:157], off
	global_store_dwordx2 v[116:117], v[108:109], off offset:32
	global_store_dwordx2 v[116:117], v[102:103], off offset:288
	s_and_saveexec_b64 s[4:5], s[0:1]
	s_cbranch_execz .LBB0_1427
	v_lshl_add_u64 v[100:101], v[114:115], 2, s[12:13]
	s_waitcnt lgkmcnt(0)
	v_add_f32_e32 v98, v98, v99
	global_atomic_add_f32 v[100:101], v98, off
.LBB0_1427:
	s_or_b64 exec, exec, s[4:5]
	v_or_b32_e32 v98, 32, v148
	s_waitcnt lgkmcnt(0)
	v_ashrrev_i32_e32 v99, 31, v98
	v_cmp_gt_i32_e32 vcc, s52, v98
	s_nop 1
	v_cndmask_b32_e32 v99, 0, v99, vcc
	v_lshl_add_u64 v[100:101], v[98:99], 2, s[16:17]
	global_load_dword v118, v[100:101], off
	v_lshlrev_b64 v[100:101], 11, v[98:99]
	v_lshl_add_u64 v[102:103], s[18:19], 0, v[100:101]
	v_lshl_add_u64 v[104:105], v[102:103], 0, v[146:147]
	v_lshl_add_u64 v[102:103], s[92:93], 0, v[100:101]
	v_lshl_add_u64 v[102:103], v[102:103], 0, v[146:147]
	global_load_dwordx2 v[108:109], v[104:105], off
	global_load_dwordx2 v[112:113], v[102:103], off
	global_load_dwordx2 v[106:107], v[104:105], off offset:32
	global_load_dwordx2 v[110:111], v[104:105], off offset:256
	global_load_dwordx2 v[114:115], v[102:103], off offset:32
	global_load_dwordx2 v[116:117], v[102:103], off offset:256
	s_nop 0
	global_load_dwordx2 v[104:105], v[104:105], off offset:288
	v_lshl_add_u64 v[100:101], s[14:15], 0, v[100:101]
	v_lshl_add_u64 v[100:101], v[100:101], 0, v[146:147]
	s_waitcnt vmcnt(7)
	v_fmamk_f32 v118, v118, 0x3a800000, v171
	v_rsq_f32_e32 v122, v118
	s_waitcnt vmcnt(6)
	v_lshlrev_b32_e32 v118, 16, v108
	v_mul_f32_e32 v94, v94, v122
	v_mul_f32_e32 v95, v95, v122
	v_mul_f32_e32 v90, v90, v122
	v_mul_f32_e32 v91, v91, v122
	v_mul_f32_e32 v94, 0xbfb8aa3b, v94
	v_mul_f32_e32 v95, 0xbfb8aa3b, v95
	v_mul_f32_e32 v123, 0xbfb8aa3b, v90
	v_mul_f32_e32 v124, 0xbfb8aa3b, v91
	v_exp_f32_e32 v90, v94
	v_exp_f32_e32 v91, v95
	v_mul_f32_e32 v96, v96, v122
	v_mul_f32_e32 v97, v97, v122
	v_mul_f32_e32 v96, 0xbfb8aa3b, v96
	v_mul_f32_e32 v97, 0xbfb8aa3b, v97
	v_exp_f32_e32 v94, v96
	v_exp_f32_e32 v95, v97
	v_pk_add_f32 v[90:91], v[90:91], 1.0 op_sel_hi:[1,0]
	v_exp_f32_e32 v96, v123
	v_pk_add_f32 v[94:95], v[94:95], 1.0 op_sel_hi:[1,0]
	v_exp_f32_e32 v97, v124
	v_rcp_f32_e32 v91, v91
	v_and_b32_e32 v119, 0xffff0000, v108
	s_waitcnt vmcnt(5)
	v_lshlrev_b32_e32 v120, 16, v112
	v_and_b32_e32 v121, 0xffff0000, v112
	v_rcp_f32_e32 v90, v90
	s_nop 0
	v_pk_fma_f32 v[90:91], v[90:91], v[118:119], v[120:121]
	v_pk_add_f32 v[96:97], v[96:97], 1.0 op_sel_hi:[1,0]
	v_rcp_f32_e32 v95, v95
	v_cvt_pk_bf16_f32 v118, v90, v91
	v_mul_f32_e32 v91, v91, v91
	v_lshlrev_b32_e32 v108, 16, v109
	v_and_b32_e32 v109, 0xffff0000, v109
	v_lshlrev_b32_e32 v112, 16, v113
	v_and_b32_e32 v113, 0xffff0000, v113
	v_rcp_f32_e32 v94, v94
	v_fmac_f32_e32 v91, v90, v90
	v_pk_fma_f32 v[94:95], v[94:95], v[108:109], v[112:113]
	v_cvt_pk_bf16_f32 v119, v94, v95
	v_mul_f32_e32 v95, v95, v95
	v_fmac_f32_e32 v95, v94, v94
	v_add_f32_e32 v112, v91, v95
	v_rcp_f32_e32 v95, v97
	v_mul_f32_e32 v90, v92, v122
	v_mul_f32_e32 v91, v93, v122
	v_mul_f32_e32 v90, 0xbfb8aa3b, v90
	v_mul_f32_e32 v91, 0xbfb8aa3b, v91
	v_exp_f32_e32 v90, v90
	v_exp_f32_e32 v91, v91
	v_rcp_f32_e32 v94, v96
	v_pk_add_f32 v[90:91], v[90:91], 1.0 op_sel_hi:[1,0]
	s_waitcnt vmcnt(4)
; DI unsigned pk2(float lo, float hi) { f32x2 v = {lo, hi}; bf16x2_t b = __builtin_convertvector(v, bf16x2_t); return __builtin_bit_cast(unsigned, b); }
; DI float sigmoidf_(float x) { return 1.f / (1.f + __expf(-x)); }
;     DI void operator()(const f32x4 (&acc)[2][2][4][2], const Unit& u, int wr, int wc, int fr, int fq) const {
;     ...
;             for (int m = 0; m < 4; ++m) { const int row = row0 + ai * HALF + m * 16;
;                 const float* bp = (row < MP) ? base0 + (size_t)row * DM : base1 + (size_t)(row - MP) * DM;
;                 float r = 1.f; if (MODE == 1) r = __builtin_amdgcn_rsqf(ssin[row] * (1.f / DM) + EPS);
;                 float s = 0.f;
;     ...
;                         if (MODE == 1) { const u32x2 pw = *(const u32x2*)(PP + (size_t)row * DM + col);
;                             v[0] = sigmoidf_(v[0] * r) * bflo(pw.x); v[1] = sigmoidf_(v[1] * r) * bfhi(pw.x); v[2] = sigmoidf_(v[2] * r) * bflo(pw.y); v[3] = sigmoidf_(v[3] * r) * bfhi(pw.y); }
;                         f32x4 h;
;                         if (baseb) { const u32x2 bw = *(const u32x2*)(baseb + (size_t)row * DM + col); h = (f32x4){bflo(bw.x), bfhi(bw.x), bflo(bw.y), bfhi(bw.y)} + v; }
;                         else h = *(const f32x4*)(bp + col) + v;
;                         if (H) *(f32x4*)(H + (size_t)row * DM + col) = h;
;                         if (XB) { u32x2 w; w.x = pk2(h[0], h[1]); w.y = pk2(h[2], h[3]); *(u32x2*)(XB + (size_t)row * DM + col) = w; }
;                         s += (h[0] * h[0] + h[1] * h[1]) + (h[2] * h[2] + h[3] * h[3]); }
;                 if (ssout) { s += __shfl_xor(s, 16); s += __shfl_xor(s, 32); if (fq == 0) atomicAdd(ssout + row, s); } }
	v_lshlrev_b32_e32 v92, 16, v106
	v_and_b32_e32 v93, 0xffff0000, v106
	v_mul_f32_e32 v86, v86, v122
	v_mul_f32_e32 v87, v87, v122
	v_rcp_f32_e32 v91, v91
	v_mul_f32_e32 v86, 0xbfb8aa3b, v86
	v_mul_f32_e32 v87, 0xbfb8aa3b, v87
	v_exp_f32_e32 v86, v86
	v_exp_f32_e32 v87, v87
	v_rcp_f32_e32 v90, v90
	v_lshlrev_b32_e32 v96, 16, v107
	v_and_b32_e32 v97, 0xffff0000, v107
	s_waitcnt vmcnt(2)
	v_lshlrev_b32_e32 v106, 16, v114
	v_and_b32_e32 v107, 0xffff0000, v114
	v_pk_fma_f32 v[94:95], v[94:95], v[92:93], v[106:107]
	v_pk_add_f32 v[86:87], v[86:87], 1.0 op_sel_hi:[1,0]
	v_lshlrev_b32_e32 v108, 16, v115
	v_and_b32_e32 v109, 0xffff0000, v115
	v_cvt_pk_bf16_f32 v92, v94, v95
	v_mul_f32_e32 v93, v95, v95
	v_pk_fma_f32 v[90:91], v[90:91], v[96:97], v[108:109]
	v_fmac_f32_e32 v93, v94, v94
	v_mul_f32_e32 v94, v91, v91
	v_fmac_f32_e32 v94, v90, v90
	v_add_f32_e32 v93, v93, v94
	v_mul_f32_e32 v88, v88, v122
	v_mul_f32_e32 v89, v89, v122
	v_rcp_f32_e32 v87, v87
	v_mul_f32_e32 v88, 0xbfb8aa3b, v88
	v_mul_f32_e32 v89, 0xbfb8aa3b, v89
	v_exp_f32_e32 v88, v88
	v_exp_f32_e32 v89, v89
	s_nop 0
	v_pk_add_f32 v[88:89], v[88:89], 1.0 op_sel_hi:[1,0]
	v_rcp_f32_e32 v86, v86
	v_lshlrev_b32_e32 v94, 16, v110
	v_and_b32_e32 v95, 0xffff0000, v110
	v_rcp_f32_e32 v89, v89
	v_mul_f32_e32 v82, v82, v122
	s_waitcnt vmcnt(1)
	v_lshlrev_b32_e32 v106, 16, v116
	v_and_b32_e32 v107, 0xffff0000, v116
	v_pk_fma_f32 v[86:87], v[86:87], v[94:95], v[106:107]
	global_load_dwordx2 v[94:95], v[102:103], off offset:288
	v_mul_f32_e32 v83, v83, v122
	v_mul_f32_e32 v82, 0xbfb8aa3b, v82
	v_mul_f32_e32 v83, 0xbfb8aa3b, v83
	v_exp_f32_e32 v82, v82
	v_exp_f32_e32 v83, v83
	v_rcp_f32_e32 v88, v88
	v_lshlrev_b32_e32 v96, 16, v111
	v_pk_add_f32 v[82:83], v[82:83], 1.0 op_sel_hi:[1,0]
	v_and_b32_e32 v97, 0xffff0000, v111
	v_lshlrev_b32_e32 v108, 16, v117
	v_and_b32_e32 v109, 0xffff0000, v117
	v_pk_fma_f32 v[88:89], v[88:89], v[96:97], v[108:109]
	v_mul_f32_e32 v96, v87, v87
	v_mul_f32_e32 v97, v89, v89
	v_fmac_f32_e32 v96, v86, v86
	v_fmac_f32_e32 v97, v88, v88
	v_add_f32_e32 v93, v112, v93
	v_add_f32_e32 v96, v96, v97
	v_add_f32_e32 v93, v93, v96
	v_mul_f32_e32 v84, v84, v122
	v_mul_f32_e32 v85, v85, v122
	v_mul_f32_e32 v84, 0xbfb8aa3b, v84
	v_mul_f32_e32 v85, 0xbfb8aa3b, v85
	v_rcp_f32_e32 v83, v83
	v_exp_f32_e32 v84, v84
	v_exp_f32_e32 v85, v85
	s_nop 0
	v_pk_add_f32 v[84:85], v[84:85], 1.0 op_sel_hi:[1,0]
	v_rcp_f32_e32 v82, v82
	s_waitcnt vmcnt(1)
	v_lshlrev_b32_e32 v96, 16, v104
	v_and_b32_e32 v97, 0xffff0000, v104
	v_rcp_f32_e32 v85, v85
	v_cvt_pk_bf16_f32 v86, v86, v87
	v_div_scale_f32 v102, vcc, 1.0, v84, 1.0
	v_rcp_f32_e32 v84, v84
	v_lshlrev_b32_e32 v102, 16, v105
	v_and_b32_e32 v103, 0xffff0000, v105
	s_waitcnt vmcnt(0)
	v_lshlrev_b32_e32 v104, 16, v94
	v_and_b32_e32 v105, 0xffff0000, v94
	v_lshlrev_b32_e32 v94, 16, v95
	v_and_b32_e32 v95, 0xffff0000, v95
	v_pk_fma_f32 v[84:85], v[84:85], v[102:103], v[94:95]
	v_pk_fma_f32 v[94:95], v[82:83], v[96:97], v[104:105]
	v_mul_f32_e32 v83, v85, v85
	v_mul_f32_e32 v82, v95, v95
	v_fmac_f32_e32 v82, v94, v94
	v_fmac_f32_e32 v83, v84, v84
	v_add_f32_e32 v82, v82, v83
	v_add_f32_e32 v82, v93, v82
	ds_bpermute_b32 v83, v154, v82
	v_cvt_pk_bf16_f32 v87, v88, v89
	v_cvt_pk_bf16_f32 v93, v90, v91
	global_store_dwordx2 v[100:101], v[86:87], off offset:256
	v_cvt_pk_bf16_f32 v86, v94, v95
	s_waitcnt lgkmcnt(0)
	v_add_f32_e32 v82, v82, v83
	ds_bpermute_b32 v83, v155, v82
	v_cvt_pk_bf16_f32 v87, v84, v85
	global_store_dwordx2 v[100:101], v[118:119], off
	global_store_dwordx2 v[100:101], v[92:93], off offset:32
	global_store_dwordx2 v[100:101], v[86:87], off offset:288
	s_and_saveexec_b64 s[4:5], s[0:1]
	s_cbranch_execz .LBB0_1429
	v_lshl_add_u64 v[84:85], v[98:99], 2, s[12:13]
	s_waitcnt lgkmcnt(0)
	v_add_f32_e32 v82, v82, v83
	global_atomic_add_f32 v[84:85], v82, off
.LBB0_1429:
	s_or_b64 exec, exec, s[4:5]
	v_or_b32_e32 v82, 48, v148
	s_waitcnt lgkmcnt(0)
	v_ashrrev_i32_e32 v83, 31, v82
	v_cmp_gt_i32_e32 vcc, s52, v82
	s_nop 1
	v_cndmask_b32_e32 v83, 0, v83, vcc
	v_lshl_add_u64 v[84:85], v[82:83], 2, s[16:17]
	global_load_dword v102, v[84:85], off
	v_lshlrev_b64 v[84:85], 11, v[82:83]
	v_lshl_add_u64 v[86:87], s[18:19], 0, v[84:85]
	v_lshl_add_u64 v[88:89], v[86:87], 0, v[146:147]
	v_lshl_add_u64 v[86:87], s[92:93], 0, v[84:85]
	v_lshl_add_u64 v[86:87], v[86:87], 0, v[146:147]
	global_load_dwordx2 v[92:93], v[88:89], off
	global_load_dwordx2 v[96:97], v[86:87], off
	global_load_dwordx2 v[90:91], v[88:89], off offset:32
	global_load_dwordx2 v[94:95], v[88:89], off offset:256
	global_load_dwordx2 v[98:99], v[86:87], off offset:32
	global_load_dwordx2 v[100:101], v[86:87], off offset:256
	s_nop 0
	global_load_dwordx2 v[88:89], v[88:89], off offset:288
	v_lshl_add_u64 v[84:85], s[14:15], 0, v[84:85]
	v_lshl_add_u64 v[84:85], v[84:85], 0, v[146:147]
	s_waitcnt vmcnt(7)
	v_fmamk_f32 v102, v102, 0x3a800000, v171
	v_rsq_f32_e32 v106, v102
	s_waitcnt vmcnt(6)
	v_lshlrev_b32_e32 v102, 16, v92
	v_mul_f32_e32 v78, v78, v106
	v_mul_f32_e32 v79, v79, v106
	v_mul_f32_e32 v74, v74, v106
	v_mul_f32_e32 v75, v75, v106
	v_mul_f32_e32 v78, 0xbfb8aa3b, v78
	v_mul_f32_e32 v79, 0xbfb8aa3b, v79
	v_mul_f32_e32 v107, 0xbfb8aa3b, v74
	v_mul_f32_e32 v108, 0xbfb8aa3b, v75
	v_exp_f32_e32 v74, v78
	v_exp_f32_e32 v75, v79
	v_mul_f32_e32 v80, v80, v106
	v_mul_f32_e32 v81, v81, v106
	v_mul_f32_e32 v80, 0xbfb8aa3b, v80
	v_mul_f32_e32 v81, 0xbfb8aa3b, v81
	v_exp_f32_e32 v78, v80
	v_exp_f32_e32 v79, v81
	v_pk_add_f32 v[74:75], v[74:75], 1.0 op_sel_hi:[1,0]
	v_exp_f32_e32 v80, v107
	v_pk_add_f32 v[78:79], v[78:79], 1.0 op_sel_hi:[1,0]
	v_exp_f32_e32 v81, v108
	v_rcp_f32_e32 v75, v75
	v_and_b32_e32 v103, 0xffff0000, v92
	s_waitcnt vmcnt(5)
; DI unsigned pk2(float lo, float hi) { f32x2 v = {lo, hi}; bf16x2_t b = __builtin_convertvector(v, bf16x2_t); return __builtin_bit_cast(unsigned, b); }
; DI float sigmoidf_(float x) { return 1.f / (1.f + __expf(-x)); }
;     DI void operator()(const f32x4 (&acc)[2][2][4][2], const Unit& u, int wr, int wc, int fr, int fq) const {
;     ...
;                         if (MODE == 1) { const u32x2 pw = *(const u32x2*)(PP + (size_t)row * DM + col);
;                             v[0] = sigmoidf_(v[0] * r) * bflo(pw.x); v[1] = sigmoidf_(v[1] * r) * bfhi(pw.x); v[2] = sigmoidf_(v[2] * r) * bflo(pw.y); v[3] = sigmoidf_(v[3] * r) * bfhi(pw.y); }
;                         f32x4 h;
;                         if (baseb) { const u32x2 bw = *(const u32x2*)(baseb + (size_t)row * DM + col); h = (f32x4){bflo(bw.x), bfhi(bw.x), bflo(bw.y), bfhi(bw.y)} + v; }
;                         else h = *(const f32x4*)(bp + col) + v;
;                         if (H) *(f32x4*)(H + (size_t)row * DM + col) = h;
;                         if (XB) { u32x2 w; w.x = pk2(h[0], h[1]); w.y = pk2(h[2], h[3]); *(u32x2*)(XB + (size_t)row * DM + col) = w; }
;                         s += (h[0] * h[0] + h[1] * h[1]) + (h[2] * h[2] + h[3] * h[3]); }
;                 if (ssout) { s += __shfl_xor(s, 16); s += __shfl_xor(s, 32); if (fq == 0) atomicAdd(ssout + row, s); } }
	v_lshlrev_b32_e32 v104, 16, v96
	v_and_b32_e32 v105, 0xffff0000, v96
	v_rcp_f32_e32 v74, v74
	s_nop 0
	v_pk_fma_f32 v[74:75], v[74:75], v[102:103], v[104:105]
	v_pk_add_f32 v[80:81], v[80:81], 1.0 op_sel_hi:[1,0]
	v_rcp_f32_e32 v79, v79
	v_cvt_pk_bf16_f32 v102, v74, v75
	v_mul_f32_e32 v75, v75, v75
	v_lshlrev_b32_e32 v92, 16, v93
	v_and_b32_e32 v93, 0xffff0000, v93
	v_lshlrev_b32_e32 v96, 16, v97
	v_and_b32_e32 v97, 0xffff0000, v97
	v_rcp_f32_e32 v78, v78
	v_fmac_f32_e32 v75, v74, v74
	v_pk_fma_f32 v[78:79], v[78:79], v[92:93], v[96:97]
	v_cvt_pk_bf16_f32 v103, v78, v79
	v_mul_f32_e32 v79, v79, v79
	v_fmac_f32_e32 v79, v78, v78
	v_add_f32_e32 v96, v75, v79
	v_rcp_f32_e32 v79, v81
	v_mul_f32_e32 v74, v76, v106
	v_mul_f32_e32 v75, v77, v106
	v_mul_f32_e32 v74, 0xbfb8aa3b, v74
	v_mul_f32_e32 v75, 0xbfb8aa3b, v75
	v_exp_f32_e32 v74, v74
	v_exp_f32_e32 v75, v75
	v_rcp_f32_e32 v78, v80
	v_pk_add_f32 v[74:75], v[74:75], 1.0 op_sel_hi:[1,0]
	s_waitcnt vmcnt(4)
	v_lshlrev_b32_e32 v76, 16, v90
	v_and_b32_e32 v77, 0xffff0000, v90
	v_mul_f32_e32 v70, v70, v106
	v_mul_f32_e32 v71, v71, v106
	v_rcp_f32_e32 v75, v75
	v_mul_f32_e32 v70, 0xbfb8aa3b, v70
	v_mul_f32_e32 v71, 0xbfb8aa3b, v71
	v_exp_f32_e32 v70, v70
	v_exp_f32_e32 v71, v71
	v_rcp_f32_e32 v74, v74
	v_lshlrev_b32_e32 v80, 16, v91
	v_and_b32_e32 v81, 0xffff0000, v91
	s_waitcnt vmcnt(2)
	v_lshlrev_b32_e32 v90, 16, v98
	v_and_b32_e32 v91, 0xffff0000, v98
	v_pk_fma_f32 v[78:79], v[78:79], v[76:77], v[90:91]
	v_pk_add_f32 v[70:71], v[70:71], 1.0 op_sel_hi:[1,0]
	v_lshlrev_b32_e32 v92, 16, v99
	v_and_b32_e32 v93, 0xffff0000, v99
	v_cvt_pk_bf16_f32 v76, v78, v79
	v_mul_f32_e32 v77, v79, v79
	v_pk_fma_f32 v[74:75], v[74:75], v[80:81], v[92:93]
	v_fmac_f32_e32 v77, v78, v78
	v_mul_f32_e32 v78, v75, v75
	v_fmac_f32_e32 v78, v74, v74
	v_add_f32_e32 v77, v77, v78
	v_mul_f32_e32 v72, v72, v106
	v_mul_f32_e32 v73, v73, v106
	v_rcp_f32_e32 v71, v71
	v_mul_f32_e32 v72, 0xbfb8aa3b, v72
	v_mul_f32_e32 v73, 0xbfb8aa3b, v73
	v_exp_f32_e32 v72, v72
	v_exp_f32_e32 v73, v73
	s_nop 0
	v_pk_add_f32 v[72:73], v[72:73], 1.0 op_sel_hi:[1,0]
	v_rcp_f32_e32 v70, v70
	v_lshlrev_b32_e32 v78, 16, v94
	v_and_b32_e32 v79, 0xffff0000, v94
	v_rcp_f32_e32 v73, v73
	v_mul_f32_e32 v66, v66, v106
	s_waitcnt vmcnt(1)
	v_lshlrev_b32_e32 v90, 16, v100
	v_and_b32_e32 v91, 0xffff0000, v100
	v_pk_fma_f32 v[70:71], v[70:71], v[78:79], v[90:91]
	global_load_dwordx2 v[78:79], v[86:87], off offset:288
	v_mul_f32_e32 v67, v67, v106
	v_mul_f32_e32 v66, 0xbfb8aa3b, v66
	v_mul_f32_e32 v67, 0xbfb8aa3b, v67
	v_exp_f32_e32 v66, v66
	v_exp_f32_e32 v67, v67
	v_rcp_f32_e32 v72, v72
	v_lshlrev_b32_e32 v80, 16, v95
	v_pk_add_f32 v[66:67], v[66:67], 1.0 op_sel_hi:[1,0]
	v_and_b32_e32 v81, 0xffff0000, v95
	v_lshlrev_b32_e32 v92, 16, v101
	v_and_b32_e32 v93, 0xffff0000, v101
	v_pk_fma_f32 v[72:73], v[72:73], v[80:81], v[92:93]
	v_mul_f32_e32 v80, v71, v71
	v_mul_f32_e32 v81, v73, v73
	v_fmac_f32_e32 v80, v70, v70
	v_fmac_f32_e32 v81, v72, v72
	v_add_f32_e32 v77, v96, v77
	v_add_f32_e32 v80, v80, v81
	v_add_f32_e32 v77, v77, v80
	v_mul_f32_e32 v68, v68, v106
	v_mul_f32_e32 v69, v69, v106
	v_mul_f32_e32 v68, 0xbfb8aa3b, v68
	v_mul_f32_e32 v69, 0xbfb8aa3b, v69
	v_rcp_f32_e32 v67, v67
	v_exp_f32_e32 v68, v68
	v_exp_f32_e32 v69, v69
	s_nop 0
	v_pk_add_f32 v[68:69], v[68:69], 1.0 op_sel_hi:[1,0]
	v_rcp_f32_e32 v66, v66
	s_waitcnt vmcnt(1)
	v_lshlrev_b32_e32 v80, 16, v88
	v_and_b32_e32 v81, 0xffff0000, v88
	v_rcp_f32_e32 v69, v69
	v_cvt_pk_bf16_f32 v70, v70, v71
	v_div_scale_f32 v86, vcc, 1.0, v68, 1.0
	v_rcp_f32_e32 v68, v68
	v_lshlrev_b32_e32 v86, 16, v89
	v_and_b32_e32 v87, 0xffff0000, v89
	s_waitcnt vmcnt(0)
	v_lshlrev_b32_e32 v88, 16, v78
	v_and_b32_e32 v89, 0xffff0000, v78
	v_lshlrev_b32_e32 v78, 16, v79
	v_and_b32_e32 v79, 0xffff0000, v79
	v_pk_fma_f32 v[68:69], v[68:69], v[86:87], v[78:79]
	v_pk_fma_f32 v[78:79], v[66:67], v[80:81], v[88:89]
	v_mul_f32_e32 v67, v69, v69
	v_mul_f32_e32 v66, v79, v79
	v_fmac_f32_e32 v66, v78, v78
	v_fmac_f32_e32 v67, v68, v68
	v_add_f32_e32 v66, v66, v67
	v_add_f32_e32 v66, v77, v66
	ds_bpermute_b32 v67, v154, v66
	v_cvt_pk_bf16_f32 v71, v72, v73
	v_cvt_pk_bf16_f32 v77, v74, v75
	global_store_dwordx2 v[84:85], v[70:71], off offset:256
	v_cvt_pk_bf16_f32 v70, v78, v79
	s_waitcnt lgkmcnt(0)
	v_add_f32_e32 v66, v66, v67
	ds_bpermute_b32 v67, v155, v66
	v_cvt_pk_bf16_f32 v71, v68, v69
	global_store_dwordx2 v[84:85], v[102:103], off
	global_store_dwordx2 v[84:85], v[76:77], off offset:32
	global_store_dwordx2 v[84:85], v[70:71], off offset:288
	s_and_saveexec_b64 s[4:5], s[0:1]
	s_cbranch_execz .LBB0_1431
	v_lshl_add_u64 v[68:69], v[82:83], 2, s[12:13]
	s_waitcnt lgkmcnt(0)
	v_add_f32_e32 v66, v66, v67
	global_atomic_add_f32 v[68:69], v66, off
; DI unsigned pk2(float lo, float hi) { f32x2 v = {lo, hi}; bf16x2_t b = __builtin_convertvector(v, bf16x2_t); return __builtin_bit_cast(unsigned, b); }
; DI float sigmoidf_(float x) { return 1.f / (1.f + __expf(-x)); }
;     DI void operator()(const f32x4 (&acc)[2][2][4][2], const Unit& u, int wr, int wc, int fr, int fq) const {
;     ...
;             for (int m = 0; m < 4; ++m) { const int row = row0 + ai * HALF + m * 16;
;                 const float* bp = (row < MP) ? base0 + (size_t)row * DM : base1 + (size_t)(row - MP) * DM;
;                 float r = 1.f; if (MODE == 1) r = __builtin_amdgcn_rsqf(ssin[row] * (1.f / DM) + EPS);
;                 float s = 0.f;
; #pragma unroll
;                 for (int bj = 0; bj < 2; ++bj)
; #pragma unroll
;                     for (int n = 0; n < 2; ++n) { const int col = col0 + bj * HALF + n * 16;
;                         f32x4 v = acc[ai][bj][m][n];
;                         if (MODE == 1) { const u32x2 pw = *(const u32x2*)(PP + (size_t)row * DM + col);
;                             v[0] = sigmoidf_(v[0] * r) * bflo(pw.x); v[1] = sigmoidf_(v[1] * r) * bfhi(pw.x); v[2] = sigmoidf_(v[2] * r) * bflo(pw.y); v[3] = sigmoidf_(v[3] * r) * bfhi(pw.y); }
;                         f32x4 h;
;                         if (baseb) { const u32x2 bw = *(const u32x2*)(baseb + (size_t)row * DM + col); h = (f32x4){bflo(bw.x), bfhi(bw.x), bflo(bw.y), bfhi(bw.y)} + v; }
;                         else h = *(const f32x4*)(bp + col) + v;
;                         if (H) *(f32x4*)(H + (size_t)row * DM + col) = h;
;                         if (XB) { u32x2 w; w.x = pk2(h[0], h[1]); w.y = pk2(h[2], h[3]); *(u32x2*)(XB + (size_t)row * DM + col) = w; }
;                         s += (h[0] * h[0] + h[1] * h[1]) + (h[2] * h[2] + h[3] * h[3]); }
;                 if (ssout) { s += __shfl_xor(s, 16); s += __shfl_xor(s, 32); if (fq == 0) atomicAdd(ssout + row, s); } }
.LBB0_1431:
	s_or_b64 exec, exec, s[4:5]
	v_add_u32_e32 v66, 0x80, v148
	s_waitcnt lgkmcnt(0)
	v_ashrrev_i32_e32 v67, 31, v66
	v_cmp_gt_i32_e32 vcc, s59, v148
	s_nop 1
	v_cndmask_b32_e32 v67, 0, v67, vcc
	v_lshl_add_u64 v[68:69], v[66:67], 2, s[16:17]
	global_load_dword v86, v[68:69], off
	v_lshlrev_b64 v[68:69], 11, v[66:67]
	v_lshl_add_u64 v[70:71], s[18:19], 0, v[68:69]
	v_lshl_add_u64 v[72:73], v[70:71], 0, v[146:147]
	v_lshl_add_u64 v[70:71], s[92:93], 0, v[68:69]
	v_lshl_add_u64 v[70:71], v[70:71], 0, v[146:147]
	global_load_dwordx2 v[76:77], v[72:73], off
	global_load_dwordx2 v[80:81], v[70:71], off
	global_load_dwordx2 v[74:75], v[72:73], off offset:32
	global_load_dwordx2 v[78:79], v[72:73], off offset:256
	global_load_dwordx2 v[82:83], v[70:71], off offset:32
	global_load_dwordx2 v[84:85], v[70:71], off offset:256
	s_nop 0
	global_load_dwordx2 v[72:73], v[72:73], off offset:288
	v_lshl_add_u64 v[68:69], s[14:15], 0, v[68:69]
	v_lshl_add_u64 v[68:69], v[68:69], 0, v[146:147]
	s_waitcnt vmcnt(7)
	v_fmamk_f32 v86, v86, 0x3a800000, v171
	v_rsq_f32_e32 v90, v86
	s_waitcnt vmcnt(6)
	v_lshlrev_b32_e32 v86, 16, v76
	v_mul_f32_e32 v62, v62, v90
	v_mul_f32_e32 v63, v63, v90
	v_mul_f32_e32 v58, v58, v90
	v_mul_f32_e32 v59, v59, v90
	v_mul_f32_e32 v62, 0xbfb8aa3b, v62
	v_mul_f32_e32 v63, 0xbfb8aa3b, v63
	v_mul_f32_e32 v91, 0xbfb8aa3b, v58
	v_mul_f32_e32 v92, 0xbfb8aa3b, v59
	v_exp_f32_e32 v58, v62
	v_exp_f32_e32 v59, v63
	v_mul_f32_e32 v64, v64, v90
	v_mul_f32_e32 v65, v65, v90
	v_mul_f32_e32 v64, 0xbfb8aa3b, v64
	v_mul_f32_e32 v65, 0xbfb8aa3b, v65
	v_exp_f32_e32 v62, v64
	v_exp_f32_e32 v63, v65
	v_pk_add_f32 v[58:59], v[58:59], 1.0 op_sel_hi:[1,0]
	v_exp_f32_e32 v64, v91
	v_pk_add_f32 v[62:63], v[62:63], 1.0 op_sel_hi:[1,0]
	v_exp_f32_e32 v65, v92
	v_rcp_f32_e32 v59, v59
	v_and_b32_e32 v87, 0xffff0000, v76
	s_waitcnt vmcnt(5)
	v_lshlrev_b32_e32 v88, 16, v80
	v_and_b32_e32 v89, 0xffff0000, v80
	v_rcp_f32_e32 v58, v58
	s_nop 0
	v_pk_fma_f32 v[58:59], v[58:59], v[86:87], v[88:89]
	v_pk_add_f32 v[64:65], v[64:65], 1.0 op_sel_hi:[1,0]
	v_rcp_f32_e32 v63, v63
	v_cvt_pk_bf16_f32 v86, v58, v59
	v_mul_f32_e32 v59, v59, v59
	v_lshlrev_b32_e32 v76, 16, v77
	v_and_b32_e32 v77, 0xffff0000, v77
	v_lshlrev_b32_e32 v80, 16, v81
	v_and_b32_e32 v81, 0xffff0000, v81
	v_rcp_f32_e32 v62, v62
	v_fmac_f32_e32 v59, v58, v58
	v_pk_fma_f32 v[62:63], v[62:63], v[76:77], v[80:81]
	v_cvt_pk_bf16_f32 v87, v62, v63
	v_mul_f32_e32 v63, v63, v63
	v_fmac_f32_e32 v63, v62, v62
	v_add_f32_e32 v80, v59, v63
	v_rcp_f32_e32 v63, v65
	v_mul_f32_e32 v58, v60, v90
	v_mul_f32_e32 v59, v61, v90
	v_mul_f32_e32 v58, 0xbfb8aa3b, v58
	v_mul_f32_e32 v59, 0xbfb8aa3b, v59
	v_exp_f32_e32 v58, v58
	v_exp_f32_e32 v59, v59
	v_rcp_f32_e32 v62, v64
	v_pk_add_f32 v[58:59], v[58:59], 1.0 op_sel_hi:[1,0]
	s_waitcnt vmcnt(4)
	v_lshlrev_b32_e32 v60, 16, v74
	v_and_b32_e32 v61, 0xffff0000, v74
	v_mul_f32_e32 v54, v54, v90
	v_mul_f32_e32 v55, v55, v90
	v_rcp_f32_e32 v59, v59
	v_mul_f32_e32 v54, 0xbfb8aa3b, v54
	v_mul_f32_e32 v55, 0xbfb8aa3b, v55
	v_exp_f32_e32 v54, v54
	v_exp_f32_e32 v55, v55
	v_rcp_f32_e32 v58, v58
	v_lshlrev_b32_e32 v64, 16, v75
	v_and_b32_e32 v65, 0xffff0000, v75
	s_waitcnt vmcnt(2)
	v_lshlrev_b32_e32 v74, 16, v82
	v_and_b32_e32 v75, 0xffff0000, v82
	v_pk_fma_f32 v[62:63], v[62:63], v[60:61], v[74:75]
	v_pk_add_f32 v[54:55], v[54:55], 1.0 op_sel_hi:[1,0]
	v_lshlrev_b32_e32 v76, 16, v83
	v_and_b32_e32 v77, 0xffff0000, v83
	v_cvt_pk_bf16_f32 v60, v62, v63
	v_mul_f32_e32 v61, v63, v63
	v_pk_fma_f32 v[58:59], v[58:59], v[64:65], v[76:77]
	v_fmac_f32_e32 v61, v62, v62
	v_mul_f32_e32 v62, v59, v59
	v_fmac_f32_e32 v62, v58, v58
	v_add_f32_e32 v61, v61, v62
	v_mul_f32_e32 v56, v56, v90
	v_mul_f32_e32 v57, v57, v90
	v_rcp_f32_e32 v55, v55
	v_mul_f32_e32 v56, 0xbfb8aa3b, v56
	v_mul_f32_e32 v57, 0xbfb8aa3b, v57
	v_exp_f32_e32 v56, v56
	v_exp_f32_e32 v57, v57
	s_nop 0
	v_pk_add_f32 v[56:57], v[56:57], 1.0 op_sel_hi:[1,0]
	v_rcp_f32_e32 v54, v54
	v_lshlrev_b32_e32 v62, 16, v78
	v_and_b32_e32 v63, 0xffff0000, v78
	v_rcp_f32_e32 v57, v57
	v_mul_f32_e32 v50, v50, v90
	s_waitcnt vmcnt(1)
	v_lshlrev_b32_e32 v74, 16, v84
	v_and_b32_e32 v75, 0xffff0000, v84
	v_pk_fma_f32 v[54:55], v[54:55], v[62:63], v[74:75]
	global_load_dwordx2 v[62:63], v[70:71], off offset:288
	v_mul_f32_e32 v51, v51, v90
	v_mul_f32_e32 v50, 0xbfb8aa3b, v50
	v_mul_f32_e32 v51, 0xbfb8aa3b, v51
	v_exp_f32_e32 v50, v50
	v_exp_f32_e32 v51, v51
	v_rcp_f32_e32 v56, v56
	v_lshlrev_b32_e32 v64, 16, v79
	v_pk_add_f32 v[50:51], v[50:51], 1.0 op_sel_hi:[1,0]
	v_and_b32_e32 v65, 0xffff0000, v79
	v_lshlrev_b32_e32 v76, 16, v85
	v_and_b32_e32 v77, 0xffff0000, v85
	v_pk_fma_f32 v[56:57], v[56:57], v[64:65], v[76:77]
	v_mul_f32_e32 v64, v55, v55
	v_mul_f32_e32 v65, v57, v57
	v_fmac_f32_e32 v64, v54, v54
	v_fmac_f32_e32 v65, v56, v56
	v_add_f32_e32 v61, v80, v61
	v_add_f32_e32 v64, v64, v65
	v_add_f32_e32 v61, v61, v64
	v_mul_f32_e32 v52, v52, v90
	v_mul_f32_e32 v53, v53, v90
	v_mul_f32_e32 v52, 0xbfb8aa3b, v52
	v_mul_f32_e32 v53, 0xbfb8aa3b, v53
	v_rcp_f32_e32 v51, v51
	v_exp_f32_e32 v52, v52
	v_exp_f32_e32 v53, v53
	s_nop 0
	v_pk_add_f32 v[52:53], v[52:53], 1.0 op_sel_hi:[1,0]
	v_rcp_f32_e32 v50, v50
	s_waitcnt vmcnt(1)
	v_lshlrev_b32_e32 v64, 16, v72
	v_and_b32_e32 v65, 0xffff0000, v72
	v_rcp_f32_e32 v53, v53
	v_cvt_pk_bf16_f32 v54, v54, v55
	v_div_scale_f32 v70, vcc, 1.0, v52, 1.0
	v_rcp_f32_e32 v52, v52
	v_lshlrev_b32_e32 v70, 16, v73
	v_and_b32_e32 v71, 0xffff0000, v73
	s_waitcnt vmcnt(0)
	v_lshlrev_b32_e32 v72, 16, v62
	v_and_b32_e32 v73, 0xffff0000, v62
	v_lshlrev_b32_e32 v62, 16, v63
	v_and_b32_e32 v63, 0xffff0000, v63
	v_pk_fma_f32 v[52:53], v[52:53], v[70:71], v[62:63]
	v_pk_fma_f32 v[62:63], v[50:51], v[64:65], v[72:73]
	v_mul_f32_e32 v51, v53, v53
	v_mul_f32_e32 v50, v63, v63
	v_fmac_f32_e32 v50, v62, v62
	v_fmac_f32_e32 v51, v52, v52
	v_add_f32_e32 v50, v50, v51
	v_add_f32_e32 v50, v61, v50
	ds_bpermute_b32 v51, v154, v50
	v_cvt_pk_bf16_f32 v55, v56, v57
	v_cvt_pk_bf16_f32 v61, v58, v59
	global_store_dwordx2 v[68:69], v[54:55], off offset:256
	v_cvt_pk_bf16_f32 v54, v62, v63
	s_waitcnt lgkmcnt(0)
	v_add_f32_e32 v50, v50, v51
	ds_bpermute_b32 v51, v155, v50
	v_cvt_pk_bf16_f32 v55, v52, v53
	global_store_dwordx2 v[68:69], v[86:87], off
	global_store_dwordx2 v[68:69], v[60:61], off offset:32
	global_store_dwordx2 v[68:69], v[54:55], off offset:288
	s_and_saveexec_b64 s[4:5], s[0:1]
	s_cbranch_execz .LBB0_1433
	v_lshl_add_u64 v[52:53], v[66:67], 2, s[12:13]
	s_waitcnt lgkmcnt(0)
	v_add_f32_e32 v50, v50, v51
	global_atomic_add_f32 v[52:53], v50, off
; DI unsigned pk2(float lo, float hi) { f32x2 v = {lo, hi}; bf16x2_t b = __builtin_convertvector(v, bf16x2_t); return __builtin_bit_cast(unsigned, b); }
; DI float sigmoidf_(float x) { return 1.f / (1.f + __expf(-x)); }
;     DI void operator()(const f32x4 (&acc)[2][2][4][2], const Unit& u, int wr, int wc, int fr, int fq) const {
;     ...
;             for (int m = 0; m < 4; ++m) { const int row = row0 + ai * HALF + m * 16;
;                 const float* bp = (row < MP) ? base0 + (size_t)row * DM : base1 + (size_t)(row - MP) * DM;
;                 float r = 1.f; if (MODE == 1) r = __builtin_amdgcn_rsqf(ssin[row] * (1.f / DM) + EPS);
;                 float s = 0.f;
; #pragma unroll
;                 for (int bj = 0; bj < 2; ++bj)
; #pragma unroll
;                     for (int n = 0; n < 2; ++n) { const int col = col0 + bj * HALF + n * 16;
;                         f32x4 v = acc[ai][bj][m][n];
;                         if (MODE == 1) { const u32x2 pw = *(const u32x2*)(PP + (size_t)row * DM + col);
;                             v[0] = sigmoidf_(v[0] * r) * bflo(pw.x); v[1] = sigmoidf_(v[1] * r) * bfhi(pw.x); v[2] = sigmoidf_(v[2] * r) * bflo(pw.y); v[3] = sigmoidf_(v[3] * r) * bfhi(pw.y); }
;                         f32x4 h;
;                         if (baseb) { const u32x2 bw = *(const u32x2*)(baseb + (size_t)row * DM + col); h = (f32x4){bflo(bw.x), bfhi(bw.x), bflo(bw.y), bfhi(bw.y)} + v; }
;                         else h = *(const f32x4*)(bp + col) + v;
;                         if (H) *(f32x4*)(H + (size_t)row * DM + col) = h;
;                         if (XB) { u32x2 w; w.x = pk2(h[0], h[1]); w.y = pk2(h[2], h[3]); *(u32x2*)(XB + (size_t)row * DM + col) = w; }
;                         s += (h[0] * h[0] + h[1] * h[1]) + (h[2] * h[2] + h[3] * h[3]); }
;                 if (ssout) { s += __shfl_xor(s, 16); s += __shfl_xor(s, 32); if (fq == 0) atomicAdd(ssout + row, s); } }
.LBB0_1433:
	s_or_b64 exec, exec, s[4:5]
	v_add_u32_e32 v50, 0x90, v148
	s_waitcnt lgkmcnt(0)
	v_ashrrev_i32_e32 v51, 31, v50
	v_cmp_gt_i32_e32 vcc, s60, v148
	s_nop 1
	v_cndmask_b32_e32 v51, 0, v51, vcc
	v_lshl_add_u64 v[52:53], v[50:51], 2, s[16:17]
	global_load_dword v70, v[52:53], off
	v_lshlrev_b64 v[52:53], 11, v[50:51]
	v_lshl_add_u64 v[54:55], s[18:19], 0, v[52:53]
	v_lshl_add_u64 v[56:57], v[54:55], 0, v[146:147]
	v_lshl_add_u64 v[54:55], s[92:93], 0, v[52:53]
	v_lshl_add_u64 v[54:55], v[54:55], 0, v[146:147]
	global_load_dwordx2 v[60:61], v[56:57], off
	global_load_dwordx2 v[64:65], v[54:55], off
	global_load_dwordx2 v[58:59], v[56:57], off offset:32
	global_load_dwordx2 v[62:63], v[56:57], off offset:256
	global_load_dwordx2 v[66:67], v[54:55], off offset:32
	global_load_dwordx2 v[68:69], v[54:55], off offset:256
	s_nop 0
	global_load_dwordx2 v[56:57], v[56:57], off offset:288
	v_lshl_add_u64 v[52:53], s[14:15], 0, v[52:53]
	v_lshl_add_u64 v[52:53], v[52:53], 0, v[146:147]
	s_waitcnt vmcnt(7)
	v_fmamk_f32 v70, v70, 0x3a800000, v171
	v_rsq_f32_e32 v74, v70
	s_waitcnt vmcnt(6)
	v_lshlrev_b32_e32 v70, 16, v60
	v_mul_f32_e32 v46, v46, v74
	v_mul_f32_e32 v47, v47, v74
	v_mul_f32_e32 v42, v42, v74
	v_mul_f32_e32 v43, v43, v74
	v_mul_f32_e32 v46, 0xbfb8aa3b, v46
	v_mul_f32_e32 v47, 0xbfb8aa3b, v47
	v_mul_f32_e32 v75, 0xbfb8aa3b, v42
	v_mul_f32_e32 v76, 0xbfb8aa3b, v43
	v_exp_f32_e32 v42, v46
	v_exp_f32_e32 v43, v47
	v_mul_f32_e32 v48, v48, v74
	v_mul_f32_e32 v49, v49, v74
	v_mul_f32_e32 v48, 0xbfb8aa3b, v48
	v_mul_f32_e32 v49, 0xbfb8aa3b, v49
	v_exp_f32_e32 v46, v48
	v_exp_f32_e32 v47, v49
	v_pk_add_f32 v[42:43], v[42:43], 1.0 op_sel_hi:[1,0]
	v_exp_f32_e32 v48, v75
	v_pk_add_f32 v[46:47], v[46:47], 1.0 op_sel_hi:[1,0]
	v_exp_f32_e32 v49, v76
	v_rcp_f32_e32 v43, v43
	v_and_b32_e32 v71, 0xffff0000, v60
	s_waitcnt vmcnt(5)
	v_lshlrev_b32_e32 v72, 16, v64
	v_and_b32_e32 v73, 0xffff0000, v64
	v_rcp_f32_e32 v42, v42
	s_nop 0
	v_pk_fma_f32 v[42:43], v[42:43], v[70:71], v[72:73]
	v_pk_add_f32 v[48:49], v[48:49], 1.0 op_sel_hi:[1,0]
	v_rcp_f32_e32 v47, v47
	v_cvt_pk_bf16_f32 v70, v42, v43
	v_mul_f32_e32 v43, v43, v43
	v_lshlrev_b32_e32 v60, 16, v61
	v_and_b32_e32 v61, 0xffff0000, v61
	v_lshlrev_b32_e32 v64, 16, v65
	v_and_b32_e32 v65, 0xffff0000, v65
	v_rcp_f32_e32 v46, v46
	v_fmac_f32_e32 v43, v42, v42
	v_pk_fma_f32 v[46:47], v[46:47], v[60:61], v[64:65]
	v_cvt_pk_bf16_f32 v71, v46, v47
	v_mul_f32_e32 v47, v47, v47
	v_fmac_f32_e32 v47, v46, v46
	v_add_f32_e32 v64, v43, v47
	v_rcp_f32_e32 v47, v49
	v_mul_f32_e32 v42, v44, v74
	v_mul_f32_e32 v43, v45, v74
	v_mul_f32_e32 v42, 0xbfb8aa3b, v42
	v_mul_f32_e32 v43, 0xbfb8aa3b, v43
	v_exp_f32_e32 v42, v42
	v_exp_f32_e32 v43, v43
	v_rcp_f32_e32 v46, v48
	v_pk_add_f32 v[42:43], v[42:43], 1.0 op_sel_hi:[1,0]
	s_waitcnt vmcnt(4)
	v_lshlrev_b32_e32 v44, 16, v58
	v_and_b32_e32 v45, 0xffff0000, v58
	v_mul_f32_e32 v38, v38, v74
	v_mul_f32_e32 v39, v39, v74
	v_rcp_f32_e32 v43, v43
	v_mul_f32_e32 v38, 0xbfb8aa3b, v38
	v_mul_f32_e32 v39, 0xbfb8aa3b, v39
	v_exp_f32_e32 v38, v38
	v_exp_f32_e32 v39, v39
	v_rcp_f32_e32 v42, v42
	v_lshlrev_b32_e32 v48, 16, v59
	v_and_b32_e32 v49, 0xffff0000, v59
	s_waitcnt vmcnt(2)
	v_lshlrev_b32_e32 v58, 16, v66
	v_and_b32_e32 v59, 0xffff0000, v66
	v_pk_fma_f32 v[46:47], v[46:47], v[44:45], v[58:59]
	v_pk_add_f32 v[38:39], v[38:39], 1.0 op_sel_hi:[1,0]
	v_lshlrev_b32_e32 v60, 16, v67
	v_and_b32_e32 v61, 0xffff0000, v67
	v_cvt_pk_bf16_f32 v44, v46, v47
	v_mul_f32_e32 v45, v47, v47
	v_pk_fma_f32 v[42:43], v[42:43], v[48:49], v[60:61]
	v_fmac_f32_e32 v45, v46, v46
	v_mul_f32_e32 v46, v43, v43
	v_fmac_f32_e32 v46, v42, v42
	v_add_f32_e32 v45, v45, v46
	v_mul_f32_e32 v40, v40, v74
	v_mul_f32_e32 v41, v41, v74
	v_rcp_f32_e32 v39, v39
	v_mul_f32_e32 v40, 0xbfb8aa3b, v40
	v_mul_f32_e32 v41, 0xbfb8aa3b, v41
	v_exp_f32_e32 v40, v40
	v_exp_f32_e32 v41, v41
	s_nop 0
	v_pk_add_f32 v[40:41], v[40:41], 1.0 op_sel_hi:[1,0]
	v_rcp_f32_e32 v38, v38
	v_lshlrev_b32_e32 v46, 16, v62
	v_and_b32_e32 v47, 0xffff0000, v62
	v_rcp_f32_e32 v41, v41
	v_mul_f32_e32 v34, v34, v74
	s_waitcnt vmcnt(1)
	v_lshlrev_b32_e32 v58, 16, v68
	v_and_b32_e32 v59, 0xffff0000, v68
	v_pk_fma_f32 v[38:39], v[38:39], v[46:47], v[58:59]
	global_load_dwordx2 v[46:47], v[54:55], off offset:288
	v_mul_f32_e32 v35, v35, v74
	v_mul_f32_e32 v34, 0xbfb8aa3b, v34
	v_mul_f32_e32 v35, 0xbfb8aa3b, v35
	v_exp_f32_e32 v34, v34
	v_exp_f32_e32 v35, v35
	v_rcp_f32_e32 v40, v40
	v_lshlrev_b32_e32 v48, 16, v63
	v_pk_add_f32 v[34:35], v[34:35], 1.0 op_sel_hi:[1,0]
	v_and_b32_e32 v49, 0xffff0000, v63
	v_lshlrev_b32_e32 v60, 16, v69
	v_and_b32_e32 v61, 0xffff0000, v69
	v_pk_fma_f32 v[40:41], v[40:41], v[48:49], v[60:61]
	v_mul_f32_e32 v48, v39, v39
	v_mul_f32_e32 v49, v41, v41
	v_fmac_f32_e32 v48, v38, v38
	v_fmac_f32_e32 v49, v40, v40
	v_add_f32_e32 v45, v64, v45
	v_add_f32_e32 v48, v48, v49
	v_add_f32_e32 v45, v45, v48
	v_mul_f32_e32 v36, v36, v74
	v_mul_f32_e32 v37, v37, v74
	v_mul_f32_e32 v36, 0xbfb8aa3b, v36
	v_mul_f32_e32 v37, 0xbfb8aa3b, v37
	v_rcp_f32_e32 v35, v35
	v_exp_f32_e32 v36, v36
	v_exp_f32_e32 v37, v37
	s_nop 0
	v_pk_add_f32 v[36:37], v[36:37], 1.0 op_sel_hi:[1,0]
	v_rcp_f32_e32 v34, v34
	s_waitcnt vmcnt(1)
	v_lshlrev_b32_e32 v48, 16, v56
	v_and_b32_e32 v49, 0xffff0000, v56
	v_rcp_f32_e32 v37, v37
	v_cvt_pk_bf16_f32 v38, v38, v39
	v_div_scale_f32 v54, vcc, 1.0, v36, 1.0
	v_rcp_f32_e32 v36, v36
	v_lshlrev_b32_e32 v54, 16, v57
	v_and_b32_e32 v55, 0xffff0000, v57
	s_waitcnt vmcnt(0)
	v_lshlrev_b32_e32 v56, 16, v46
	v_and_b32_e32 v57, 0xffff0000, v46
	v_lshlrev_b32_e32 v46, 16, v47
	v_and_b32_e32 v47, 0xffff0000, v47
	v_pk_fma_f32 v[36:37], v[36:37], v[54:55], v[46:47]
	v_pk_fma_f32 v[46:47], v[34:35], v[48:49], v[56:57]
	v_mul_f32_e32 v35, v37, v37
	v_mul_f32_e32 v34, v47, v47
	v_fmac_f32_e32 v34, v46, v46
	v_fmac_f32_e32 v35, v36, v36
	v_add_f32_e32 v34, v34, v35
	v_add_f32_e32 v34, v45, v34
	ds_bpermute_b32 v35, v154, v34
	v_cvt_pk_bf16_f32 v39, v40, v41
	v_cvt_pk_bf16_f32 v45, v42, v43
	global_store_dwordx2 v[52:53], v[38:39], off offset:256
	v_cvt_pk_bf16_f32 v38, v46, v47
	s_waitcnt lgkmcnt(0)
	v_add_f32_e32 v34, v34, v35
	ds_bpermute_b32 v35, v155, v34
	v_cvt_pk_bf16_f32 v39, v36, v37
	global_store_dwordx2 v[52:53], v[70:71], off
	global_store_dwordx2 v[52:53], v[44:45], off offset:32
	global_store_dwordx2 v[52:53], v[38:39], off offset:288
	s_and_saveexec_b64 s[4:5], s[0:1]
	s_cbranch_execz .LBB0_1435
	v_lshl_add_u64 v[36:37], v[50:51], 2, s[12:13]
	s_waitcnt lgkmcnt(0)
	v_add_f32_e32 v34, v34, v35
	global_atomic_add_f32 v[36:37], v34, off
; DI unsigned pk2(float lo, float hi) { f32x2 v = {lo, hi}; bf16x2_t b = __builtin_convertvector(v, bf16x2_t); return __builtin_bit_cast(unsigned, b); }
; DI float sigmoidf_(float x) { return 1.f / (1.f + __expf(-x)); }
;     DI void operator()(const f32x4 (&acc)[2][2][4][2], const Unit& u, int wr, int wc, int fr, int fq) const {
;     ...
;             for (int m = 0; m < 4; ++m) { const int row = row0 + ai * HALF + m * 16;
;                 const float* bp = (row < MP) ? base0 + (size_t)row * DM : base1 + (size_t)(row - MP) * DM;
;                 float r = 1.f; if (MODE == 1) r = __builtin_amdgcn_rsqf(ssin[row] * (1.f / DM) + EPS);
;                 float s = 0.f;
; #pragma unroll
;                 for (int bj = 0; bj < 2; ++bj)
; #pragma unroll
;                     for (int n = 0; n < 2; ++n) { const int col = col0 + bj * HALF + n * 16;
;                         f32x4 v = acc[ai][bj][m][n];
;                         if (MODE == 1) { const u32x2 pw = *(const u32x2*)(PP + (size_t)row * DM + col);
;                             v[0] = sigmoidf_(v[0] * r) * bflo(pw.x); v[1] = sigmoidf_(v[1] * r) * bfhi(pw.x); v[2] = sigmoidf_(v[2] * r) * bflo(pw.y); v[3] = sigmoidf_(v[3] * r) * bfhi(pw.y); }
;                         f32x4 h;
;                         if (baseb) { const u32x2 bw = *(const u32x2*)(baseb + (size_t)row * DM + col); h = (f32x4){bflo(bw.x), bfhi(bw.x), bflo(bw.y), bfhi(bw.y)} + v; }
;                         else h = *(const f32x4*)(bp + col) + v;
;                         if (H) *(f32x4*)(H + (size_t)row * DM + col) = h;
;                         if (XB) { u32x2 w; w.x = pk2(h[0], h[1]); w.y = pk2(h[2], h[3]); *(u32x2*)(XB + (size_t)row * DM + col) = w; }
;                         s += (h[0] * h[0] + h[1] * h[1]) + (h[2] * h[2] + h[3] * h[3]); }
;                 if (ssout) { s += __shfl_xor(s, 16); s += __shfl_xor(s, 32); if (fq == 0) atomicAdd(ssout + row, s); } }
.LBB0_1435:
	s_or_b64 exec, exec, s[4:5]
	v_add_u32_e32 v34, 0xa0, v148
	s_waitcnt lgkmcnt(0)
	v_ashrrev_i32_e32 v35, 31, v34
	v_cmp_gt_i32_e32 vcc, s61, v148
	s_nop 1
	v_cndmask_b32_e32 v35, 0, v35, vcc
	v_lshl_add_u64 v[36:37], v[34:35], 2, s[16:17]
	global_load_dword v54, v[36:37], off
	v_lshlrev_b64 v[36:37], 11, v[34:35]
	v_lshl_add_u64 v[38:39], s[18:19], 0, v[36:37]
	v_lshl_add_u64 v[40:41], v[38:39], 0, v[146:147]
	v_lshl_add_u64 v[38:39], s[92:93], 0, v[36:37]
	v_lshl_add_u64 v[38:39], v[38:39], 0, v[146:147]
	global_load_dwordx2 v[44:45], v[40:41], off
	global_load_dwordx2 v[48:49], v[38:39], off
	global_load_dwordx2 v[42:43], v[40:41], off offset:32
	global_load_dwordx2 v[46:47], v[40:41], off offset:256
	global_load_dwordx2 v[50:51], v[38:39], off offset:32
	global_load_dwordx2 v[52:53], v[38:39], off offset:256
	s_nop 0
	global_load_dwordx2 v[40:41], v[40:41], off offset:288
	v_lshl_add_u64 v[36:37], s[14:15], 0, v[36:37]
	v_lshl_add_u64 v[36:37], v[36:37], 0, v[146:147]
	s_waitcnt vmcnt(7)
	v_fmamk_f32 v54, v54, 0x3a800000, v171
	v_rsq_f32_e32 v58, v54
	s_waitcnt vmcnt(6)
	v_lshlrev_b32_e32 v54, 16, v44
	v_mul_f32_e32 v30, v30, v58
	v_mul_f32_e32 v31, v31, v58
	v_mul_f32_e32 v26, v26, v58
	v_mul_f32_e32 v27, v27, v58
	v_mul_f32_e32 v30, 0xbfb8aa3b, v30
	v_mul_f32_e32 v31, 0xbfb8aa3b, v31
	v_mul_f32_e32 v59, 0xbfb8aa3b, v26
	v_mul_f32_e32 v60, 0xbfb8aa3b, v27
	v_exp_f32_e32 v26, v30
	v_exp_f32_e32 v27, v31
	v_mul_f32_e32 v32, v32, v58
	v_mul_f32_e32 v33, v33, v58
	v_mul_f32_e32 v32, 0xbfb8aa3b, v32
	v_mul_f32_e32 v33, 0xbfb8aa3b, v33
	v_exp_f32_e32 v30, v32
	v_exp_f32_e32 v31, v33
	v_pk_add_f32 v[26:27], v[26:27], 1.0 op_sel_hi:[1,0]
	v_exp_f32_e32 v32, v59
	v_pk_add_f32 v[30:31], v[30:31], 1.0 op_sel_hi:[1,0]
	v_exp_f32_e32 v33, v60
	v_rcp_f32_e32 v27, v27
	v_and_b32_e32 v55, 0xffff0000, v44
	s_waitcnt vmcnt(5)
	v_lshlrev_b32_e32 v56, 16, v48
	v_and_b32_e32 v57, 0xffff0000, v48
	v_rcp_f32_e32 v26, v26
	s_nop 0
	v_pk_fma_f32 v[26:27], v[26:27], v[54:55], v[56:57]
	v_pk_add_f32 v[32:33], v[32:33], 1.0 op_sel_hi:[1,0]
	v_rcp_f32_e32 v31, v31
	v_cvt_pk_bf16_f32 v54, v26, v27
	v_mul_f32_e32 v27, v27, v27
	v_lshlrev_b32_e32 v44, 16, v45
	v_and_b32_e32 v45, 0xffff0000, v45
	v_lshlrev_b32_e32 v48, 16, v49
	v_and_b32_e32 v49, 0xffff0000, v49
	v_rcp_f32_e32 v30, v30
	v_fmac_f32_e32 v27, v26, v26
	v_pk_fma_f32 v[30:31], v[30:31], v[44:45], v[48:49]
	v_cvt_pk_bf16_f32 v55, v30, v31
	v_mul_f32_e32 v31, v31, v31
	v_fmac_f32_e32 v31, v30, v30
	v_add_f32_e32 v48, v27, v31
	v_rcp_f32_e32 v31, v33
	v_mul_f32_e32 v26, v28, v58
	v_mul_f32_e32 v27, v29, v58
	v_mul_f32_e32 v26, 0xbfb8aa3b, v26
	v_mul_f32_e32 v27, 0xbfb8aa3b, v27
	v_exp_f32_e32 v26, v26
	v_exp_f32_e32 v27, v27
	v_rcp_f32_e32 v30, v32
	v_pk_add_f32 v[26:27], v[26:27], 1.0 op_sel_hi:[1,0]
	s_waitcnt vmcnt(4)
	v_lshlrev_b32_e32 v28, 16, v42
	v_and_b32_e32 v29, 0xffff0000, v42
	v_mul_f32_e32 v22, v22, v58
	v_mul_f32_e32 v23, v23, v58
	v_rcp_f32_e32 v27, v27
	v_mul_f32_e32 v22, 0xbfb8aa3b, v22
	v_mul_f32_e32 v23, 0xbfb8aa3b, v23
	v_exp_f32_e32 v22, v22
	v_exp_f32_e32 v23, v23
	v_rcp_f32_e32 v26, v26
	v_lshlrev_b32_e32 v32, 16, v43
	v_and_b32_e32 v33, 0xffff0000, v43
	s_waitcnt vmcnt(2)
	v_lshlrev_b32_e32 v42, 16, v50
	v_and_b32_e32 v43, 0xffff0000, v50
	v_pk_fma_f32 v[30:31], v[30:31], v[28:29], v[42:43]
	v_pk_add_f32 v[22:23], v[22:23], 1.0 op_sel_hi:[1,0]
	v_lshlrev_b32_e32 v44, 16, v51
	v_and_b32_e32 v45, 0xffff0000, v51
	v_cvt_pk_bf16_f32 v28, v30, v31
	v_mul_f32_e32 v29, v31, v31
	v_pk_fma_f32 v[26:27], v[26:27], v[32:33], v[44:45]
	v_fmac_f32_e32 v29, v30, v30
	v_mul_f32_e32 v30, v27, v27
	v_fmac_f32_e32 v30, v26, v26
	v_add_f32_e32 v29, v29, v30
	v_mul_f32_e32 v24, v24, v58
	v_mul_f32_e32 v25, v25, v58
	v_rcp_f32_e32 v23, v23
	v_mul_f32_e32 v24, 0xbfb8aa3b, v24
	v_mul_f32_e32 v25, 0xbfb8aa3b, v25
	v_exp_f32_e32 v24, v24
	v_exp_f32_e32 v25, v25
	s_nop 0
	v_pk_add_f32 v[24:25], v[24:25], 1.0 op_sel_hi:[1,0]
	v_rcp_f32_e32 v22, v22
	v_lshlrev_b32_e32 v30, 16, v46
	v_and_b32_e32 v31, 0xffff0000, v46
	v_rcp_f32_e32 v25, v25
	v_mul_f32_e32 v18, v18, v58
	s_waitcnt vmcnt(1)
	v_lshlrev_b32_e32 v42, 16, v52
	v_and_b32_e32 v43, 0xffff0000, v52
	v_pk_fma_f32 v[22:23], v[22:23], v[30:31], v[42:43]
	global_load_dwordx2 v[30:31], v[38:39], off offset:288
	v_mul_f32_e32 v19, v19, v58
	v_mul_f32_e32 v18, 0xbfb8aa3b, v18
	v_mul_f32_e32 v19, 0xbfb8aa3b, v19
	v_exp_f32_e32 v18, v18
	v_exp_f32_e32 v19, v19
	v_rcp_f32_e32 v24, v24
	v_lshlrev_b32_e32 v32, 16, v47
	v_pk_add_f32 v[18:19], v[18:19], 1.0 op_sel_hi:[1,0]
	v_and_b32_e32 v33, 0xffff0000, v47
	v_lshlrev_b32_e32 v44, 16, v53
	v_and_b32_e32 v45, 0xffff0000, v53
	v_pk_fma_f32 v[24:25], v[24:25], v[32:33], v[44:45]
	v_mul_f32_e32 v32, v23, v23
	v_mul_f32_e32 v33, v25, v25
	v_fmac_f32_e32 v32, v22, v22
	v_fmac_f32_e32 v33, v24, v24
	v_add_f32_e32 v29, v48, v29
	v_add_f32_e32 v32, v32, v33
	v_add_f32_e32 v29, v29, v32
	v_mul_f32_e32 v20, v20, v58
	v_mul_f32_e32 v21, v21, v58
	v_mul_f32_e32 v20, 0xbfb8aa3b, v20
	v_mul_f32_e32 v21, 0xbfb8aa3b, v21
	v_rcp_f32_e32 v19, v19
	v_exp_f32_e32 v20, v20
	v_exp_f32_e32 v21, v21
	s_nop 0
	v_pk_add_f32 v[20:21], v[20:21], 1.0 op_sel_hi:[1,0]
	v_rcp_f32_e32 v18, v18
	s_waitcnt vmcnt(1)
	v_lshlrev_b32_e32 v32, 16, v40
	v_and_b32_e32 v33, 0xffff0000, v40
	v_rcp_f32_e32 v21, v21
	v_cvt_pk_bf16_f32 v22, v22, v23
	v_div_scale_f32 v38, vcc, 1.0, v20, 1.0
	v_rcp_f32_e32 v20, v20
	v_lshlrev_b32_e32 v38, 16, v41
	v_and_b32_e32 v39, 0xffff0000, v41
	s_waitcnt vmcnt(0)
	v_lshlrev_b32_e32 v40, 16, v30
	v_and_b32_e32 v41, 0xffff0000, v30
	v_lshlrev_b32_e32 v30, 16, v31
	v_and_b32_e32 v31, 0xffff0000, v31
	v_pk_fma_f32 v[20:21], v[20:21], v[38:39], v[30:31]
	v_pk_fma_f32 v[30:31], v[18:19], v[32:33], v[40:41]
	v_mul_f32_e32 v19, v21, v21
	v_mul_f32_e32 v18, v31, v31
	v_fmac_f32_e32 v18, v30, v30
	v_fmac_f32_e32 v19, v20, v20
	v_add_f32_e32 v18, v18, v19
	v_add_f32_e32 v18, v29, v18
	ds_bpermute_b32 v19, v154, v18
	v_cvt_pk_bf16_f32 v23, v24, v25
	v_cvt_pk_bf16_f32 v29, v26, v27
	global_store_dwordx2 v[36:37], v[22:23], off offset:256
	v_cvt_pk_bf16_f32 v22, v30, v31
	s_waitcnt lgkmcnt(0)
	v_add_f32_e32 v18, v18, v19
	ds_bpermute_b32 v19, v155, v18
	v_cvt_pk_bf16_f32 v23, v20, v21
	global_store_dwordx2 v[36:37], v[54:55], off
	global_store_dwordx2 v[36:37], v[28:29], off offset:32
	global_store_dwordx2 v[36:37], v[22:23], off offset:288
	s_and_saveexec_b64 s[4:5], s[0:1]
	s_cbranch_execz .LBB0_1437
	v_lshl_add_u64 v[20:21], v[34:35], 2, s[12:13]
	s_waitcnt lgkmcnt(0)
	v_add_f32_e32 v18, v18, v19
	global_atomic_add_f32 v[20:21], v18, off
; DI unsigned pk2(float lo, float hi) { f32x2 v = {lo, hi}; bf16x2_t b = __builtin_convertvector(v, bf16x2_t); return __builtin_bit_cast(unsigned, b); }
; DI float sigmoidf_(float x) { return 1.f / (1.f + __expf(-x)); }
;     DI void operator()(const f32x4 (&acc)[2][2][4][2], const Unit& u, int wr, int wc, int fr, int fq) const {
;     ...
;             for (int m = 0; m < 4; ++m) { const int row = row0 + ai * HALF + m * 16;
;                 const float* bp = (row < MP) ? base0 + (size_t)row * DM : base1 + (size_t)(row - MP) * DM;
;                 float r = 1.f; if (MODE == 1) r = __builtin_amdgcn_rsqf(ssin[row] * (1.f / DM) + EPS);
;                 float s = 0.f;
; #pragma unroll
;                 for (int bj = 0; bj < 2; ++bj)
; #pragma unroll
;                     for (int n = 0; n < 2; ++n) { const int col = col0 + bj * HALF + n * 16;
;                         f32x4 v = acc[ai][bj][m][n];
;                         if (MODE == 1) { const u32x2 pw = *(const u32x2*)(PP + (size_t)row * DM + col);
;                             v[0] = sigmoidf_(v[0] * r) * bflo(pw.x); v[1] = sigmoidf_(v[1] * r) * bfhi(pw.x); v[2] = sigmoidf_(v[2] * r) * bflo(pw.y); v[3] = sigmoidf_(v[3] * r) * bfhi(pw.y); }
;                         f32x4 h;
;                         if (baseb) { const u32x2 bw = *(const u32x2*)(baseb + (size_t)row * DM + col); h = (f32x4){bflo(bw.x), bfhi(bw.x), bflo(bw.y), bfhi(bw.y)} + v; }
;                         else h = *(const f32x4*)(bp + col) + v;
;                         if (H) *(f32x4*)(H + (size_t)row * DM + col) = h;
;                         if (XB) { u32x2 w; w.x = pk2(h[0], h[1]); w.y = pk2(h[2], h[3]); *(u32x2*)(XB + (size_t)row * DM + col) = w; }
;                         s += (h[0] * h[0] + h[1] * h[1]) + (h[2] * h[2] + h[3] * h[3]); }
;                 if (ssout) { s += __shfl_xor(s, 16); s += __shfl_xor(s, 32); if (fq == 0) atomicAdd(ssout + row, s); } }
.LBB0_1437:
	s_or_b64 exec, exec, s[4:5]
	v_add_u32_e32 v18, 0xb0, v148
	s_waitcnt lgkmcnt(0)
	v_ashrrev_i32_e32 v19, 31, v18
	v_cmp_gt_i32_e32 vcc, s62, v148
	s_nop 1
	v_cndmask_b32_e32 v19, 0, v19, vcc
	v_lshl_add_u64 v[20:21], v[18:19], 2, s[16:17]
	global_load_dword v38, v[20:21], off
	v_lshlrev_b64 v[20:21], 11, v[18:19]
	v_lshl_add_u64 v[22:23], s[18:19], 0, v[20:21]
	v_lshl_add_u64 v[24:25], v[22:23], 0, v[146:147]
	v_lshl_add_u64 v[22:23], s[92:93], 0, v[20:21]
	v_lshl_add_u64 v[22:23], v[22:23], 0, v[146:147]
	global_load_dwordx2 v[28:29], v[24:25], off
	global_load_dwordx2 v[32:33], v[22:23], off
	global_load_dwordx2 v[26:27], v[24:25], off offset:32
	global_load_dwordx2 v[30:31], v[24:25], off offset:256
	global_load_dwordx2 v[34:35], v[22:23], off offset:32
	global_load_dwordx2 v[36:37], v[22:23], off offset:256
	s_nop 0
	global_load_dwordx2 v[24:25], v[24:25], off offset:288
	v_lshl_add_u64 v[20:21], s[14:15], 0, v[20:21]
	v_lshl_add_u64 v[20:21], v[20:21], 0, v[146:147]
	s_waitcnt vmcnt(7)
	v_fmamk_f32 v38, v38, 0x3a800000, v171
	v_rsq_f32_e32 v42, v38
	s_waitcnt vmcnt(6)
	v_lshlrev_b32_e32 v38, 16, v28
	v_mul_f32_e32 v14, v14, v42
	v_mul_f32_e32 v15, v15, v42
	v_mul_f32_e32 v10, v10, v42
	v_mul_f32_e32 v11, v11, v42
	v_mul_f32_e32 v14, 0xbfb8aa3b, v14
	v_mul_f32_e32 v15, 0xbfb8aa3b, v15
	v_mul_f32_e32 v43, 0xbfb8aa3b, v10
	v_mul_f32_e32 v44, 0xbfb8aa3b, v11
	v_exp_f32_e32 v10, v14
	v_exp_f32_e32 v11, v15
	v_mul_f32_e32 v16, v16, v42
	v_mul_f32_e32 v17, v17, v42
	v_mul_f32_e32 v16, 0xbfb8aa3b, v16
	v_mul_f32_e32 v17, 0xbfb8aa3b, v17
	v_exp_f32_e32 v14, v16
	v_exp_f32_e32 v15, v17
	v_pk_add_f32 v[10:11], v[10:11], 1.0 op_sel_hi:[1,0]
	v_exp_f32_e32 v16, v43
	v_pk_add_f32 v[14:15], v[14:15], 1.0 op_sel_hi:[1,0]
	v_div_scale_f32 v47, s[6:7], v15, v15, 1.0
	v_rcp_f32_e32 v53, v47
	v_exp_f32_e32 v17, v44
	v_fma_f32 v57, -v47, v53, 1.0
	v_div_scale_f32 v48, s[6:7], 1.0, v15, 1.0
	v_fmac_f32_e32 v53, v57, v53
	v_mul_f32_e32 v57, v48, v53
	v_fma_f32 v61, -v47, v57, v48
	v_fmac_f32_e32 v57, v61, v53
	v_rcp_f32_e32 v11, v11
	v_and_b32_e32 v39, 0xffff0000, v28
	s_waitcnt vmcnt(5)
	v_lshlrev_b32_e32 v40, 16, v32
	v_and_b32_e32 v41, 0xffff0000, v32
	v_fma_f32 v45, -v47, v57, v48
	v_rcp_f32_e32 v10, v10
	s_nop 0
	v_pk_fma_f32 v[10:11], v[10:11], v[38:39], v[40:41]
	v_pk_add_f32 v[16:17], v[16:17], 1.0 op_sel_hi:[1,0]
	v_rcp_f32_e32 v15, v15
	v_cvt_pk_bf16_f32 v38, v10, v11
	v_mul_f32_e32 v11, v11, v11
	v_lshlrev_b32_e32 v28, 16, v29
	v_and_b32_e32 v29, 0xffff0000, v29
	v_lshlrev_b32_e32 v32, 16, v33
	v_and_b32_e32 v33, 0xffff0000, v33
	v_rcp_f32_e32 v14, v14
	v_fmac_f32_e32 v11, v10, v10
	v_pk_fma_f32 v[14:15], v[14:15], v[28:29], v[32:33]
	v_cvt_pk_bf16_f32 v39, v14, v15
	v_mul_f32_e32 v15, v15, v15
	v_fmac_f32_e32 v15, v14, v14
	v_add_f32_e32 v32, v11, v15
	v_rcp_f32_e32 v15, v17
	v_mul_f32_e32 v10, v12, v42
	v_mul_f32_e32 v11, v13, v42
	v_mul_f32_e32 v10, 0xbfb8aa3b, v10
	v_mul_f32_e32 v11, 0xbfb8aa3b, v11
	v_exp_f32_e32 v10, v10
	v_exp_f32_e32 v11, v11
	v_rcp_f32_e32 v14, v16
	v_pk_add_f32 v[10:11], v[10:11], 1.0 op_sel_hi:[1,0]
	s_waitcnt vmcnt(4)
	v_lshlrev_b32_e32 v12, 16, v26
	v_and_b32_e32 v13, 0xffff0000, v26
	v_mul_f32_e32 v6, v6, v42
	v_mul_f32_e32 v7, v7, v42
	v_rcp_f32_e32 v11, v11
	v_mul_f32_e32 v6, 0xbfb8aa3b, v6
	v_mul_f32_e32 v7, 0xbfb8aa3b, v7
	v_exp_f32_e32 v6, v6
	v_exp_f32_e32 v7, v7
	v_rcp_f32_e32 v10, v10
	v_lshlrev_b32_e32 v16, 16, v27
	v_and_b32_e32 v17, 0xffff0000, v27
	s_waitcnt vmcnt(2)
	v_lshlrev_b32_e32 v26, 16, v34
	v_and_b32_e32 v27, 0xffff0000, v34
	v_pk_fma_f32 v[14:15], v[14:15], v[12:13], v[26:27]
	v_pk_add_f32 v[6:7], v[6:7], 1.0 op_sel_hi:[1,0]
	v_lshlrev_b32_e32 v28, 16, v35
	v_and_b32_e32 v29, 0xffff0000, v35
	v_cvt_pk_bf16_f32 v12, v14, v15
	v_mul_f32_e32 v13, v15, v15
	v_pk_fma_f32 v[10:11], v[10:11], v[16:17], v[28:29]
	v_fmac_f32_e32 v13, v14, v14
	v_mul_f32_e32 v14, v11, v11
	v_fmac_f32_e32 v14, v10, v10
	v_add_f32_e32 v13, v13, v14
	v_mul_f32_e32 v8, v8, v42
	v_mul_f32_e32 v9, v9, v42
	v_rcp_f32_e32 v7, v7
	v_mul_f32_e32 v8, 0xbfb8aa3b, v8
	v_mul_f32_e32 v9, 0xbfb8aa3b, v9
	v_exp_f32_e32 v8, v8
	v_exp_f32_e32 v9, v9
	s_nop 0
	v_pk_add_f32 v[8:9], v[8:9], 1.0 op_sel_hi:[1,0]
	v_rcp_f32_e32 v6, v6
	v_lshlrev_b32_e32 v14, 16, v30
	v_and_b32_e32 v15, 0xffff0000, v30
	v_rcp_f32_e32 v9, v9
	v_mul_f32_e32 v2, v2, v42
	s_waitcnt vmcnt(1)
	v_lshlrev_b32_e32 v26, 16, v36
	v_and_b32_e32 v27, 0xffff0000, v36
	v_pk_fma_f32 v[6:7], v[6:7], v[14:15], v[26:27]
	global_load_dwordx2 v[14:15], v[22:23], off offset:288
	v_mul_f32_e32 v3, v3, v42
	v_mul_f32_e32 v2, 0xbfb8aa3b, v2
	v_mul_f32_e32 v3, 0xbfb8aa3b, v3
	v_exp_f32_e32 v2, v2
	v_exp_f32_e32 v3, v3
	v_rcp_f32_e32 v8, v8
	v_lshlrev_b32_e32 v16, 16, v31
	v_pk_add_f32 v[2:3], v[2:3], 1.0 op_sel_hi:[1,0]
	v_and_b32_e32 v17, 0xffff0000, v31
	v_lshlrev_b32_e32 v28, 16, v37
	v_and_b32_e32 v29, 0xffff0000, v37
	v_pk_fma_f32 v[8:9], v[8:9], v[16:17], v[28:29]
	v_mul_f32_e32 v16, v7, v7
	v_mul_f32_e32 v17, v9, v9
	v_fmac_f32_e32 v16, v6, v6
	v_fmac_f32_e32 v17, v8, v8
	v_add_f32_e32 v13, v32, v13
	v_add_f32_e32 v16, v16, v17
	v_add_f32_e32 v13, v13, v16
	v_mul_f32_e32 v4, v4, v42
	v_mul_f32_e32 v5, v5, v42
	v_mul_f32_e32 v4, 0xbfb8aa3b, v4
	v_mul_f32_e32 v5, 0xbfb8aa3b, v5
	v_rcp_f32_e32 v3, v3
	v_exp_f32_e32 v4, v4
	v_exp_f32_e32 v5, v5
	s_nop 0
	v_pk_add_f32 v[4:5], v[4:5], 1.0 op_sel_hi:[1,0]
	v_rcp_f32_e32 v2, v2
	s_waitcnt vmcnt(1)
	v_lshlrev_b32_e32 v16, 16, v24
	v_and_b32_e32 v17, 0xffff0000, v24
	v_rcp_f32_e32 v5, v5
	v_cvt_pk_bf16_f32 v6, v6, v7
	v_rcp_f32_e32 v4, v4
	v_lshlrev_b32_e32 v22, 16, v25
	v_and_b32_e32 v23, 0xffff0000, v25
	s_waitcnt vmcnt(0)
	v_lshlrev_b32_e32 v24, 16, v14
	v_and_b32_e32 v25, 0xffff0000, v14
	v_lshlrev_b32_e32 v14, 16, v15
	v_and_b32_e32 v15, 0xffff0000, v15
	v_pk_fma_f32 v[4:5], v[4:5], v[22:23], v[14:15]
	v_pk_fma_f32 v[14:15], v[2:3], v[16:17], v[24:25]
	v_mul_f32_e32 v3, v5, v5
	v_mul_f32_e32 v2, v15, v15
	v_fmac_f32_e32 v2, v14, v14
	v_fmac_f32_e32 v3, v4, v4
	v_add_f32_e32 v2, v2, v3
	v_add_f32_e32 v2, v13, v2
	ds_bpermute_b32 v3, v154, v2
	v_cvt_pk_bf16_f32 v7, v8, v9
	v_cvt_pk_bf16_f32 v13, v10, v11
	global_store_dwordx2 v[20:21], v[6:7], off offset:256
	v_cvt_pk_bf16_f32 v6, v14, v15
	s_waitcnt lgkmcnt(0)
	v_add_f32_e32 v2, v2, v3
	ds_bpermute_b32 v3, v155, v2
	v_cvt_pk_bf16_f32 v7, v4, v5
	global_store_dwordx2 v[20:21], v[38:39], off
	global_store_dwordx2 v[20:21], v[12:13], off offset:32
	global_store_dwordx2 v[20:21], v[6:7], off offset:288
	s_and_saveexec_b64 s[4:5], s[0:1]
	s_cbranch_execz .LBB0_1439
	v_lshl_add_u64 v[4:5], v[18:19], 2, s[12:13]
	s_waitcnt lgkmcnt(0)
	v_add_f32_e32 v2, v2, v3
	global_atomic_add_f32 v[4:5], v2, off

; #define LAS __attribute__((address_space(3)))
; DI unsigned pk2(float lo, float hi) { f32x2 v = {lo, hi}; bf16x2_t b = __builtin_convertvector(v, bf16x2_t); return __builtin_bit_cast(unsigned, b); }
; DI float sigmoidf_(float x) { return 1.f / (1.f + __expf(-x)); }
;     DI void operator()(LAS unsigned char*, int row, int tn, int ni, int fq, f32x4 v, int) const {
;         const int grow = MP + row, col = tn * 32 + 16 * ni + 4 * fq;
;         if (MODE == 1) { const float r = __builtin_amdgcn_rsqf(ssin[grow] * (1.f / DM) + EPS); const u32x2 pw = *(const u32x2*)(PP + (size_t)grow * DM + col);
;             v[0] = sigmoidf_(v[0] * r) * bflo(pw.x); v[1] = sigmoidf_(v[1] * r) * bfhi(pw.x); v[2] = sigmoidf_(v[2] * r) * bflo(pw.y); v[3] = sigmoidf_(v[3] * r) * bfhi(pw.y); }
;         f32x4 h;
;         if (baseb) { const u32x2 bw = *(const u32x2*)(baseb + (size_t)grow * DM + col); h = (f32x4){bflo(bw.x), bfhi(bw.x), bflo(bw.y), bfhi(bw.y)} + v; }
;         else h = *(const f32x4*)(basef + (size_t)row * DM + col) + v;
;         if (H) *(f32x4*)(H + (size_t)grow * DM + col) = h;
;         if (XB) { u32x2 w; w.x = pk2(h[0], h[1]); w.y = pk2(h[2], h[3]); *(u32x2*)(XB + (size_t)grow * DM + col) = w; }
;         if (ssout) { float s = (h[0] * h[0] + h[1] * h[1]) + (h[2] * h[2] + h[3] * h[3]); s += __shfl_xor(s, 16); s += __shfl_xor(s, 32); if (fq == 0) atomicAdd(ssout + grow, s); }
.LBB0_1458:
	v_or_b32_e32 v6, s4, v28
	v_lshlrev_b32_e32 v14, 2, v6
	global_load_dword v15, v14, s[16:17]
	v_add_u32_e32 v16, s5, v23
	v_lshlrev_b32_e32 v6, 11, v6
	v_ashrrev_i32_e32 v17, 31, v16
	v_lshl_add_u64 v[18:19], s[18:19], 0, v[6:7]
	v_lshlrev_b64 v[16:17], 1, v[16:17]
	v_lshl_add_u64 v[36:37], s[92:93], 0, v[6:7]
	v_lshl_add_u64 v[18:19], v[18:19], 0, v[16:17]
	v_lshl_add_u64 v[36:37], v[36:37], 0, v[16:17]
	global_load_dwordx2 v[18:19], v[18:19], off
	v_and_b32_e32 v39, 64, v35
	global_load_dwordx2 v[36:37], v[36:37], off
	v_xor_b32_e32 v38, 16, v35
	v_add_u32_e32 v42, 64, v39
	v_cmp_lt_i32_e32 vcc, v38, v42
	s_waitcnt vmcnt(0)
	v_fmamk_f32 v15, v15, 0x3a800000, v34
	v_rsq_f32_e32 v15, v15
	v_cndmask_b32_e32 v38, v35, v38, vcc
	v_lshlrev_b32_e32 v43, 2, v38
	v_mul_f32_e32 v2, v2, v15
	v_mul_f32_e32 v3, v3, v15
	v_mul_f32_e32 v2, 0xbfb8aa3b, v2
	v_mul_f32_e32 v3, 0xbfb8aa3b, v3
	v_mul_f32_e32 v4, v4, v15
	v_mul_f32_e32 v5, v5, v15
	v_exp_f32_e32 v2, v2
	v_exp_f32_e32 v3, v3
	v_mul_f32_e32 v4, 0xbfb8aa3b, v4
	v_mul_f32_e32 v5, 0xbfb8aa3b, v5
	v_exp_f32_e32 v4, v4
	v_exp_f32_e32 v5, v5
	v_pk_add_f32 v[2:3], v[2:3], 1.0 op_sel_hi:[1,0]
	v_lshlrev_b32_e32 v38, 16, v18
	v_pk_add_f32 v[4:5], v[4:5], 1.0 op_sel_hi:[1,0]
	v_div_scale_f32 v47, s[4:5], v5, v5, 1.0
	v_rcp_f32_e32 v53, v47
	s_nop 0
	v_fma_f32 v57, -v47, v53, 1.0
	v_div_scale_f32 v48, s[4:5], 1.0, v5, 1.0
	v_fmac_f32_e32 v53, v57, v53
	v_div_scale_f32 v50, s[6:7], 1.0, v4, 1.0
	v_mul_f32_e32 v57, v48, v53
	v_fma_f32 v61, -v47, v57, v48
	v_fmac_f32_e32 v57, v61, v53
	v_fma_f32 v45, -v47, v57, v48
	v_rcp_f32_e32 v3, v3
	v_rcp_f32_e32 v2, v2
	s_mov_b64 vcc, s[6:7]
	v_rcp_f32_e32 v5, v5
	v_and_b32_e32 v39, 0xffff0000, v18
	v_lshlrev_b32_e32 v18, 16, v19
	v_and_b32_e32 v19, 0xffff0000, v19
	v_lshlrev_b32_e32 v40, 16, v36
	v_and_b32_e32 v41, 0xffff0000, v36
	v_lshlrev_b32_e32 v36, 16, v37
	v_and_b32_e32 v37, 0xffff0000, v37
	v_rcp_f32_e32 v4, v4
	v_pk_fma_f32 v[2:3], v[2:3], v[38:39], v[40:41]
	v_pk_fma_f32 v[4:5], v[4:5], v[18:19], v[36:37]
	v_mul_f32_e32 v15, v3, v3
	v_mul_f32_e32 v18, v5, v5
	v_fmac_f32_e32 v15, v2, v2
	v_fmac_f32_e32 v18, v4, v4
	v_add_f32_e32 v15, v15, v18
	ds_bpermute_b32 v19, v43, v15
	v_xor_b32_e32 v18, 32, v35
	v_cmp_lt_i32_e32 vcc, v18, v42
	s_nop 1
	v_cndmask_b32_e32 v36, v35, v18, vcc
	v_cvt_pk_bf16_f32 v18, v2, v3
	s_waitcnt lgkmcnt(0)
	v_add_f32_e32 v2, v15, v19
	v_lshlrev_b32_e32 v3, 2, v36
	ds_bpermute_b32 v3, v3, v2
	v_cvt_pk_bf16_f32 v19, v4, v5
	v_lshl_add_u64 v[4:5], s[14:15], 0, v[6:7]
	v_lshl_add_u64 v[4:5], v[4:5], 0, v[16:17]
	global_store_dwordx2 v[4:5], v[18:19], off
	s_and_saveexec_b64 s[2:3], s[0:1]
	s_cbranch_execz .LBB0_1445
	s_waitcnt lgkmcnt(0)
	v_add_f32_e32 v2, v2, v3
	global_atomic_add_f32 v14, v2, s[12:13]
	s_branch .LBB0_1445

; #define LAS __attribute__((address_space(3)))
; DI unsigned f2bf(float f) { unsigned u = __builtin_bit_cast(unsigned, f); return (u + 0x7fffu + ((u >> 16) & 1u)) >> 16; }
; DI float gelu_tanh(float x) { const float u = 1.5957691216057308f * (x + 0.044715f * x * x * x); return x * sigmoidf_(u); }
; DI void s5_sample_phase(const Args& a, LAS unsigned char* lds, int gw, int NGW, int it_lo, int it_hi, int lane, int wave) {
;     ...
;         { const int t = lane >> 4, co = lane & 15; const LAS f32x2* cp = (const LAS f32x2*)(cs + co * 128);
;             float y = dd[g * 16 + co] * us[t * 16 + co];
; #pragma unroll 8
;             for (int p = 0; p < 64; ++p) { const f32x2 cc = cp[p]; y += cc.x * xr[t * 64 + p] - cc.y * xi[t * 64 + p]; }
;             GG[(row0 + t) * DM + g * 16 + co] = (bf16)f2bf(gelu_tanh(y)); }
.LBB0_1521:
	v_add_u32_e32 v40, s16, v53
	ds_read_b128 v[36:39], v35
	ds_read_b128 v[56:59], v35 offset:16
	ds_read_b128 v[60:63], v35 offset:32
	ds_read_b128 v[64:67], v35 offset:48
	ds_read_b128 v[68:71], v40
	ds_read_b128 v[72:75], v40 offset:1024
	ds_read_b128 v[76:79], v40 offset:16
	ds_read_b128 v[80:83], v40 offset:1040
	s_add_i32 s16, s16, 32
	s_waitcnt lgkmcnt(3)
	v_mov_b32_e32 v40, v68
	s_waitcnt lgkmcnt(2)
	v_mov_b32_e32 v41, v72
	v_mov_b32_e32 v72, v69
	v_pk_mul_f32 v[36:37], v[36:37], v[40:41]
	v_mov_b32_e32 v68, v70
	v_mov_b32_e32 v69, v74
	v_pk_mul_f32 v[38:39], v[38:39], v[72:73]
	v_sub_f32_e32 v36, v36, v37
	v_mov_b32_e32 v74, v71
	v_pk_mul_f32 v[40:41], v[56:57], v[68:69]
	v_sub_f32_e32 v37, v38, v39
	v_add_f32_e32 v34, v34, v36
	s_waitcnt lgkmcnt(1)
	v_mov_b32_e32 v70, v76
	s_waitcnt lgkmcnt(0)
	v_mov_b32_e32 v71, v80
	v_pk_mul_f32 v[56:57], v[58:59], v[74:75]
	v_sub_f32_e32 v38, v40, v41
	v_add_f32_e32 v34, v34, v37
	v_mov_b32_e32 v80, v77
	v_pk_mul_f32 v[58:59], v[60:61], v[70:71]
	v_sub_f32_e32 v39, v56, v57
	v_add_f32_e32 v34, v34, v38
	v_mov_b32_e32 v76, v78
	v_mov_b32_e32 v77, v82
	v_pk_mul_f32 v[60:61], v[62:63], v[80:81]
	v_sub_f32_e32 v40, v58, v59
	v_add_f32_e32 v34, v34, v39
	v_mov_b32_e32 v82, v79
	v_pk_mul_f32 v[62:63], v[64:65], v[76:77]
	v_sub_f32_e32 v41, v60, v61
	v_add_f32_e32 v34, v34, v40
	v_pk_mul_f32 v[64:65], v[66:67], v[82:83]
	v_sub_f32_e32 v42, v62, v63
	v_add_f32_e32 v34, v34, v41
	v_sub_f32_e32 v56, v64, v65
	v_add_f32_e32 v34, v34, v42
	v_add_u32_e32 v35, 64, v35
	s_cmpk_eq_i32 s16, 0x100
	v_add_f32_e32 v34, v34, v56
	s_cbranch_scc0 .LBB0_1521
	v_mul_f32_e32 v35, 0x3d372713, v34
	v_mul_f32_e32 v35, v34, v35
	v_fma_f32 v35, v34, v35, v34
	v_mul_f32_e32 v35, 0x3fcc422a, v35
	v_mul_f32_e32 v35, 0xbfb8aa3b, v35
	v_exp_f32_e32 v35, v35
	v_lshl_add_u64 v[36:37], v[50:51], 1, s[8:9]
	s_add_i32 s2, s2, s4
	s_cmp_ge_i32 s2, s52
	v_add_f32_e32 v35, 1.0, v35
	v_rcp_f32_e32 v35, v35
	s_nop 0
	v_mul_f32_e32 v34, v34, v35
	v_bfe_u32 v35, v34, 16, 1
	v_add3_u32 v34, v34, v35, s20
	global_store_short_d16_hi v[36:37], v34, off
	s_waitcnt lgkmcnt(0)
	s_cbranch_scc0 .LBB0_1516

; #define LAS __attribute__((address_space(3)))
; DI unsigned f2bf(float f) { unsigned u = __builtin_bit_cast(unsigned, f); return (u + 0x7fffu + ((u >> 16) & 1u)) >> 16; }
; DI float gelu_tanh(float x) { const float u = 1.5957691216057308f * (x + 0.044715f * x * x * x); return x * sigmoidf_(u); }
; DI void s5_sample_phase(const Args& a, LAS unsigned char* lds, int gw, int NGW, int it_lo, int it_hi, int lane, int wave) {
;     ...
;         { const int t = lane >> 4, co = lane & 15; const LAS f32x2* cp = (const LAS f32x2*)(cs + co * 128);
;             float y = dd[g * 16 + co] * us[t * 16 + co];
; #pragma unroll 8
;             for (int p = 0; p < 64; ++p) { const f32x2 cc = cp[p]; y += cc.x * xr[t * 64 + p] - cc.y * xi[t * 64 + p]; }
;             GG[(row0 + t) * DM + g * 16 + co] = (bf16)f2bf(gelu_tanh(y)); }
.LBB0_1602:
	v_add_u32_e32 v40, s10, v53
	ds_read_b128 v[36:39], v35
	ds_read_b128 v[56:59], v35 offset:16
	ds_read_b128 v[60:63], v35 offset:32
	ds_read_b128 v[64:67], v35 offset:48
	ds_read_b128 v[68:71], v40
	ds_read_b128 v[72:75], v40 offset:1024
	ds_read_b128 v[76:79], v40 offset:16
	ds_read_b128 v[80:83], v40 offset:1040
	s_add_i32 s10, s10, 32
	s_waitcnt lgkmcnt(3)
	v_mov_b32_e32 v40, v68
	s_waitcnt lgkmcnt(2)
	v_mov_b32_e32 v41, v72
	v_mov_b32_e32 v72, v69
	v_pk_mul_f32 v[36:37], v[36:37], v[40:41]
	v_mov_b32_e32 v68, v70
	v_mov_b32_e32 v69, v74
	v_pk_mul_f32 v[38:39], v[38:39], v[72:73]
	v_sub_f32_e32 v36, v36, v37
	v_mov_b32_e32 v74, v71
	v_pk_mul_f32 v[40:41], v[56:57], v[68:69]
	v_sub_f32_e32 v37, v38, v39
	v_add_f32_e32 v34, v34, v36
	s_waitcnt lgkmcnt(1)
	v_mov_b32_e32 v70, v76
	s_waitcnt lgkmcnt(0)
	v_mov_b32_e32 v71, v80
	v_pk_mul_f32 v[56:57], v[58:59], v[74:75]
	v_sub_f32_e32 v38, v40, v41
	v_add_f32_e32 v34, v34, v37
	v_mov_b32_e32 v80, v77
	v_pk_mul_f32 v[58:59], v[60:61], v[70:71]
	v_sub_f32_e32 v39, v56, v57
	v_add_f32_e32 v34, v34, v38
	v_mov_b32_e32 v76, v78
	v_mov_b32_e32 v77, v82
	v_pk_mul_f32 v[60:61], v[62:63], v[80:81]
	v_sub_f32_e32 v40, v58, v59
	v_add_f32_e32 v34, v34, v39
	v_mov_b32_e32 v82, v79
	v_pk_mul_f32 v[62:63], v[64:65], v[76:77]
	v_sub_f32_e32 v41, v60, v61
	v_add_f32_e32 v34, v34, v40
	v_pk_mul_f32 v[64:65], v[66:67], v[82:83]
	v_sub_f32_e32 v42, v62, v63
	v_add_f32_e32 v34, v34, v41
	v_sub_f32_e32 v56, v64, v65
	v_add_f32_e32 v34, v34, v42
	v_add_u32_e32 v35, 64, v35
	s_cmpk_eq_i32 s10, 0x100
	v_add_f32_e32 v34, v34, v56
	s_cbranch_scc0 .LBB0_1602
	v_mul_f32_e32 v35, 0x3d372713, v34
	v_mul_f32_e32 v35, v34, v35
	v_fma_f32 v35, v34, v35, v34
	v_mul_f32_e32 v35, 0x3fcc422a, v35
	v_mul_f32_e32 v35, 0xbfb8aa3b, v35
	v_exp_f32_e32 v35, v35
	v_lshl_add_u64 v[36:37], v[50:51], 1, s[6:7]
	s_add_i32 s16, s17, s16
	s_cmpk_gt_i32 s16, 0x1fff
	v_add_f32_e32 v35, 1.0, v35
	v_rcp_f32_e32 v35, v35
	s_nop 0
	v_mul_f32_e32 v34, v34, v35
	v_bfe_u32 v35, v34, 16, 1
	v_add3_u32 v34, v34, v35, s20
	global_store_short_d16_hi v[36:37], v34, off
	s_waitcnt lgkmcnt(0)
	s_cbranch_scc0 .LBB0_1597

; DI unsigned pk2(float lo, float hi) { f32x2 v = {lo, hi}; bf16x2_t b = __builtin_convertvector(v, bf16x2_t); return __builtin_bit_cast(unsigned, b); }
; DI float gelu_tanh(float x) { const float u = 1.5957691216057308f * (x + 0.044715f * x * x * x); return x * sigmoidf_(u); }
;     DI void operator()(const f32x4 (&acc)[2][2][4][2], const pg8::Unit& u, int wr, int wc, int fr, int fq) const {
;     ...
;             for (int m = 0; m < 4; ++m) { const int n = row0 + ai * 128 + m * 16;
; #pragma unroll
;                 for (int bj = 0; bj < 2; ++bj)
; #pragma unroll
;                     for (int nn = 0; nn < 2; ++nn) { const int col = col0 + bj * 128 + nn * 16, t = col >> 4, co = col & 15;
;                         const u32x2 uw = *(const u32x2*)(U2 + ((size_t)n * S5G + g) * S5K + col); const f32x4 d4 = *(const f32x4*)(D + g * 16 + co); const f32x4 v = acc[ai][bj][m][nn];
;                         const float y0 = gelu_tanh(v[0] + d4.x * bflo(uw.x)), y1 = gelu_tanh(v[1] + d4.y * bfhi(uw.x)), y2 = gelu_tanh(v[2] + d4.z * bflo(uw.y)), y3 = gelu_tanh(v[3] + d4.w * bfhi(uw.y));
;                         u32x2 w; w.x = pk2(y0, y1); w.y = pk2(y2, y3); *(u32x2*)(GG + ((size_t)n * S5T + t) * DM + g * 16 + co) = w; }
;                 asm volatile("" ::: "memory"); }
.LBB0_1677:
	s_mul_hi_u32 s2, s4, 0xaaaaaaaa
	s_mul_i32 s3, s4, 0xaaaaaaaa
	s_mul_i32 s7, s5, 0xaaaaaaab
	s_mul_hi_u32 s4, s4, 0xaaaaaaab
	s_mul_hi_u32 s6, s5, 0xaaaaaaab
	s_add_u32 s4, s7, s4
	s_addc_u32 s6, s6, 0
	s_add_u32 s3, s3, s4
	s_addc_u32 s2, s2, 0
	s_add_u32 s2, s6, s2
	s_addc_u32 s3, 0, 0
	s_mul_hi_u32 s4, s5, 0xaaaaaaaa
	s_mul_i32 s5, s5, 0xaaaaaaaa
	s_add_u32 s2, s5, s2
	s_addc_u32 s3, s4, s3
	v_lshl_add_u32 v164, s36, 8, v1
	s_lshr_b64 s[2:3], s[2:3], 9
	v_ashrrev_i32_e32 v165, 31, v164
	s_bfe_i64 s[36:37], s[2:3], 0x200000
	v_lshlrev_b64 v[162:163], 6, v[164:165]
	v_lshl_add_u64 v[162:163], v[162:163], 0, s[36:37]
	v_mad_u64_u32 v[166:167], s[4:5], v162, s46, v[146:147]
	s_lshl_b32 s34, s2, 4
	v_mad_i32_i24 v167, v163, s46, v167
	s_ashr_i32 s35, s34, 31
	global_load_dwordx2 v[174:175], v[166:167], off
	v_lshl_add_u64 v[162:163], s[34:35], 2, v[144:145]
	global_load_dwordx4 v[170:173], v[162:163], off
	v_lshlrev_b64 v[176:177], 15, v[164:165]
	s_lshl_b64 s[34:35], s[34:35], 1
	s_waitcnt vmcnt(0)
	v_lshlrev_b32_e32 v178, 16, v174
	v_and_b32_e32 v179, 0xffff0000, v174
	v_pk_fma_f32 v[170:171], v[170:171], v[178:179], v[126:127]
	v_lshlrev_b32_e32 v174, 16, v175
	v_and_b32_e32 v175, 0xffff0000, v175
	v_mul_f32_e32 v126, 0x3d372713, v170
	v_mul_f32_e32 v127, 0x3d372713, v171
	v_pk_fma_f32 v[128:129], v[172:173], v[174:175], v[128:129]
	v_mul_f32_e32 v126, v170, v126
	v_mul_f32_e32 v127, v171, v127
	v_mul_f32_e32 v157, 0x3d372713, v128
	v_mul_f32_e32 v159, 0x3d372713, v129
	v_fma_f32 v126, v170, v126, v170
	v_fma_f32 v127, v171, v127, v171
	v_mul_f32_e32 v157, v128, v157
	v_mul_f32_e32 v159, v129, v159
	v_mul_f32_e32 v126, 0x3fcc422a, v126
	v_mul_f32_e32 v127, 0x3fcc422a, v127
	v_fma_f32 v157, v128, v157, v128
	v_fma_f32 v159, v129, v159, v129
	v_mul_f32_e32 v126, 0xbfb8aa3b, v126
	v_mul_f32_e32 v127, 0xbfb8aa3b, v127
	v_mul_f32_e32 v157, 0x3fcc422a, v157
	v_mul_f32_e32 v159, 0x3fcc422a, v159
	v_exp_f32_e32 v172, v126
	v_exp_f32_e32 v173, v127
	v_mul_f32_e32 v157, 0xbfb8aa3b, v157
	v_mul_f32_e32 v159, 0xbfb8aa3b, v159
	v_exp_f32_e32 v174, v157
	v_exp_f32_e32 v175, v159
	v_pk_add_f32 v[172:173], v[172:173], 1.0 op_sel_hi:[1,0]
	v_lshl_add_u64 v[126:127], s[18:19], 0, v[176:177]
	v_pk_add_f32 v[174:175], v[174:175], 1.0 op_sel_hi:[1,0]
	v_rcp_f32_e32 v173, v173
	v_rcp_f32_e32 v172, v172
	s_nop 0
	v_pk_mul_f32 v[170:171], v[170:171], v[172:173]
	v_rcp_f32_e32 v173, v175
	v_rcp_f32_e32 v172, v174
	v_lshl_add_u64 v[176:177], v[126:127], 0, s[10:11]
	v_pk_mul_f32 v[128:129], v[128:129], v[172:173]
	v_cvt_pk_bf16_f32 v170, v170, v171
	v_cvt_pk_bf16_f32 v171, v128, v129
	v_lshl_add_u64 v[128:129], v[176:177], 0, s[34:35]
	v_lshl_add_u64 v[128:129], v[128:129], 0, v[138:139]
	global_store_dwordx2 v[128:129], v[170:171], off
	global_load_dwordx2 v[128:129], v[166:167], off offset:32
	s_nop 0
	global_load_dwordx4 v[170:173], v[162:163], off
	v_mov_b32_e32 v157, v139
	v_lshl_add_u64 v[174:175], v[126:127], 0, v[156:157]
	s_waitcnt vmcnt(0)
	v_lshlrev_b32_e32 v176, 16, v128
	v_and_b32_e32 v177, 0xffff0000, v128
	v_lshlrev_b32_e32 v128, 16, v129
	v_and_b32_e32 v129, 0xffff0000, v129
	v_pk_fma_f32 v[122:123], v[170:171], v[176:177], v[122:123]
	v_pk_fma_f32 v[124:125], v[172:173], v[128:129], v[124:125]
	v_mul_f32_e32 v128, 0x3d372713, v122
	v_mul_f32_e32 v129, 0x3d372713, v123
	v_mul_f32_e32 v128, v122, v128
	v_mul_f32_e32 v129, v123, v129
	v_mul_f32_e32 v159, 0x3d372713, v124
	v_mul_f32_e32 v161, 0x3d372713, v125
	v_fma_f32 v128, v122, v128, v122
	v_fma_f32 v129, v123, v129, v123
	v_mul_f32_e32 v159, v124, v159
	v_mul_f32_e32 v161, v125, v161
	v_mul_f32_e32 v128, 0x3fcc422a, v128
	v_mul_f32_e32 v129, 0x3fcc422a, v129
	v_fma_f32 v159, v124, v159, v124
	v_fma_f32 v161, v125, v161, v125
	v_mul_f32_e32 v128, 0xbfb8aa3b, v128
	v_mul_f32_e32 v129, 0xbfb8aa3b, v129
	v_mul_f32_e32 v159, 0x3fcc422a, v159
	v_mul_f32_e32 v161, 0x3fcc422a, v161
	v_exp_f32_e32 v128, v128
	v_exp_f32_e32 v129, v129
	v_mul_f32_e32 v159, 0xbfb8aa3b, v159
	v_mul_f32_e32 v161, 0xbfb8aa3b, v161
	v_exp_f32_e32 v170, v159
	v_exp_f32_e32 v171, v161
	v_pk_add_f32 v[128:129], v[128:129], 1.0 op_sel_hi:[1,0]
	v_lshl_add_u64 v[172:173], v[174:175], 0, s[34:35]
	v_pk_add_f32 v[170:171], v[170:171], 1.0 op_sel_hi:[1,0]
	v_rcp_f32_e32 v129, v129
	v_rcp_f32_e32 v128, v128
	s_nop 0
	v_pk_mul_f32 v[122:123], v[122:123], v[128:129]
	v_rcp_f32_e32 v129, v171
	v_rcp_f32_e32 v128, v170
	s_nop 0
	v_pk_mul_f32 v[124:125], v[124:125], v[128:129]
	v_lshl_add_u64 v[172:173], v[172:173], 0, v[138:139]
	v_cvt_pk_bf16_f32 v122, v122, v123
	v_cvt_pk_bf16_f32 v123, v124, v125
	global_store_dwordx2 v[172:173], v[122:123], off
	global_load_dwordx2 v[128:129], v[166:167], off offset:256
	s_nop 0
	global_load_dwordx4 v[122:125], v[162:163], off
	v_mov_b32_e32 v159, v139
	v_lshl_add_u64 v[170:171], v[126:127], 0, v[158:159]
	s_waitcnt vmcnt(0)
; DI unsigned pk2(float lo, float hi) { f32x2 v = {lo, hi}; bf16x2_t b = __builtin_convertvector(v, bf16x2_t); return __builtin_bit_cast(unsigned, b); }
; DI float gelu_tanh(float x) { const float u = 1.5957691216057308f * (x + 0.044715f * x * x * x); return x * sigmoidf_(u); }
;     DI void operator()(const f32x4 (&acc)[2][2][4][2], const pg8::Unit& u, int wr, int wc, int fr, int fq) const {
;     ...
;             for (int m = 0; m < 4; ++m) { const int n = row0 + ai * 128 + m * 16;
; #pragma unroll
;                 for (int bj = 0; bj < 2; ++bj)
; #pragma unroll
;                     for (int nn = 0; nn < 2; ++nn) { const int col = col0 + bj * 128 + nn * 16, t = col >> 4, co = col & 15;
;                         const u32x2 uw = *(const u32x2*)(U2 + ((size_t)n * S5G + g) * S5K + col); const f32x4 d4 = *(const f32x4*)(D + g * 16 + co); const f32x4 v = acc[ai][bj][m][nn];
;                         const float y0 = gelu_tanh(v[0] + d4.x * bflo(uw.x)), y1 = gelu_tanh(v[1] + d4.y * bfhi(uw.x)), y2 = gelu_tanh(v[2] + d4.z * bflo(uw.y)), y3 = gelu_tanh(v[3] + d4.w * bfhi(uw.y));
;                         u32x2 w; w.x = pk2(y0, y1); w.y = pk2(y2, y3); *(u32x2*)(GG + ((size_t)n * S5T + t) * DM + g * 16 + co) = w; }
;                 asm volatile("" ::: "memory"); }
	v_lshlrev_b32_e32 v172, 16, v128
	v_and_b32_e32 v173, 0xffff0000, v128
	v_pk_fma_f32 v[118:119], v[122:123], v[172:173], v[118:119]
	v_lshlrev_b32_e32 v128, 16, v129
	v_and_b32_e32 v129, 0xffff0000, v129
	v_mul_f32_e32 v122, 0x3d372713, v118
	v_mul_f32_e32 v123, 0x3d372713, v119
	v_pk_fma_f32 v[120:121], v[124:125], v[128:129], v[120:121]
	v_mul_f32_e32 v122, v118, v122
	v_mul_f32_e32 v123, v119, v123
	v_mul_f32_e32 v124, 0x3d372713, v120
	v_mul_f32_e32 v125, 0x3d372713, v121
	v_fma_f32 v122, v118, v122, v118
	v_fma_f32 v123, v119, v123, v119
	v_mul_f32_e32 v124, v120, v124
	v_mul_f32_e32 v125, v121, v125
	v_mul_f32_e32 v122, 0x3fcc422a, v122
	v_mul_f32_e32 v123, 0x3fcc422a, v123
	v_fma_f32 v124, v120, v124, v120
	v_fma_f32 v125, v121, v125, v121
	v_mul_f32_e32 v122, 0xbfb8aa3b, v122
	v_mul_f32_e32 v123, 0xbfb8aa3b, v123
	v_mul_f32_e32 v124, 0x3fcc422a, v124
	v_mul_f32_e32 v125, 0x3fcc422a, v125
	v_exp_f32_e32 v122, v122
	v_exp_f32_e32 v123, v123
	v_mul_f32_e32 v124, 0xbfb8aa3b, v124
	v_mul_f32_e32 v125, 0xbfb8aa3b, v125
	v_exp_f32_e32 v124, v124
	v_exp_f32_e32 v125, v125
	v_pk_add_f32 v[122:123], v[122:123], 1.0 op_sel_hi:[1,0]
	v_lshl_add_u64 v[128:129], v[170:171], 0, s[34:35]
	v_pk_add_f32 v[124:125], v[124:125], 1.0 op_sel_hi:[1,0]
	v_rcp_f32_e32 v123, v123
	v_rcp_f32_e32 v122, v122
	s_nop 0
	v_pk_mul_f32 v[118:119], v[118:119], v[122:123]
	v_rcp_f32_e32 v123, v125
	v_rcp_f32_e32 v122, v124
	s_nop 0
	v_pk_mul_f32 v[120:121], v[120:121], v[122:123]
	v_lshl_add_u64 v[128:129], v[128:129], 0, v[138:139]
	v_cvt_pk_bf16_f32 v118, v118, v119
	v_cvt_pk_bf16_f32 v119, v120, v121
	global_store_dwordx2 v[128:129], v[118:119], off
	global_load_dwordx2 v[124:125], v[166:167], off offset:288
	global_load_dwordx4 v[120:123], v[162:163], off
	v_mov_b32_e32 v161, v139
	v_or_b32_e32 v128, 16, v164
	v_ashrrev_i32_e32 v129, 31, v128
	v_lshl_add_u64 v[126:127], v[126:127], 0, v[160:161]
	v_lshlrev_b64 v[118:119], 6, v[128:129]
	v_lshl_add_u64 v[126:127], v[126:127], 0, s[34:35]
	v_lshl_add_u64 v[166:167], v[118:119], 0, s[36:37]
	v_mad_u64_u32 v[118:119], s[2:3], v166, s46, v[146:147]
	v_mad_i32_i24 v119, v167, s46, v119
	s_waitcnt vmcnt(0)
	v_lshlrev_b32_e32 v170, 16, v124
	v_and_b32_e32 v171, 0xffff0000, v124
	v_pk_fma_f32 v[114:115], v[120:121], v[170:171], v[114:115]
	v_lshlrev_b32_e32 v124, 16, v125
	v_and_b32_e32 v125, 0xffff0000, v125
	v_mul_f32_e32 v120, 0x3d372713, v114
	v_mul_f32_e32 v121, 0x3d372713, v115
	v_pk_fma_f32 v[116:117], v[122:123], v[124:125], v[116:117]
	v_mul_f32_e32 v120, v114, v120
	v_mul_f32_e32 v121, v115, v121
	v_mul_f32_e32 v122, 0x3d372713, v116
	v_mul_f32_e32 v123, 0x3d372713, v117
	v_fma_f32 v120, v114, v120, v114
	v_fma_f32 v121, v115, v121, v115
	v_mul_f32_e32 v122, v116, v122
	v_mul_f32_e32 v123, v117, v123
	v_mul_f32_e32 v120, 0x3fcc422a, v120
	v_mul_f32_e32 v121, 0x3fcc422a, v121
	v_fma_f32 v122, v116, v122, v116
	v_fma_f32 v123, v117, v123, v117
	v_mul_f32_e32 v120, 0xbfb8aa3b, v120
	v_mul_f32_e32 v121, 0xbfb8aa3b, v121
	v_mul_f32_e32 v122, 0x3fcc422a, v122
	v_mul_f32_e32 v123, 0x3fcc422a, v123
	v_exp_f32_e32 v120, v120
	v_exp_f32_e32 v121, v121
	v_mul_f32_e32 v122, 0xbfb8aa3b, v122
	v_mul_f32_e32 v123, 0xbfb8aa3b, v123
	v_exp_f32_e32 v122, v122
	v_exp_f32_e32 v123, v123
	v_pk_add_f32 v[120:121], v[120:121], 1.0 op_sel_hi:[1,0]
	v_lshl_add_u64 v[124:125], v[126:127], 0, v[138:139]
	v_pk_add_f32 v[122:123], v[122:123], 1.0 op_sel_hi:[1,0]
	v_rcp_f32_e32 v121, v121
	v_rcp_f32_e32 v120, v120
	s_nop 0
	v_pk_mul_f32 v[114:115], v[114:115], v[120:121]
	v_rcp_f32_e32 v121, v123
	v_rcp_f32_e32 v120, v122
	s_nop 0
	v_pk_mul_f32 v[116:117], v[116:117], v[120:121]
	v_cvt_pk_bf16_f32 v114, v114, v115
	v_cvt_pk_bf16_f32 v115, v116, v117
	global_store_dwordx2 v[124:125], v[114:115], off
	global_load_dwordx2 v[116:117], v[118:119], off
	global_load_dwordx4 v[120:123], v[162:163], off
	v_lshlrev_b64 v[114:115], 15, v[128:129]
	v_lshl_add_u64 v[114:115], s[18:19], 0, v[114:115]
	v_lshl_add_u64 v[124:125], v[114:115], 0, s[10:11]
	s_waitcnt vmcnt(0)
	v_lshlrev_b32_e32 v126, 16, v116
	v_and_b32_e32 v127, 0xffff0000, v116
	v_lshlrev_b32_e32 v116, 16, v117
	v_and_b32_e32 v117, 0xffff0000, v117
	v_pk_fma_f32 v[110:111], v[120:121], v[126:127], v[110:111]
	v_pk_fma_f32 v[112:113], v[122:123], v[116:117], v[112:113]
	v_mul_f32_e32 v116, 0x3d372713, v110
	v_mul_f32_e32 v117, 0x3d372713, v111
	v_mul_f32_e32 v116, v110, v116
	v_mul_f32_e32 v117, v111, v117
	v_mul_f32_e32 v120, 0x3d372713, v112
	v_mul_f32_e32 v121, 0x3d372713, v113
	v_fma_f32 v116, v110, v116, v110
	v_fma_f32 v117, v111, v117, v111
	v_mul_f32_e32 v120, v112, v120
	v_mul_f32_e32 v121, v113, v121
	v_mul_f32_e32 v116, 0x3fcc422a, v116
	v_mul_f32_e32 v117, 0x3fcc422a, v117
	v_fma_f32 v120, v112, v120, v112
	v_fma_f32 v121, v113, v121, v113
	v_mul_f32_e32 v116, 0xbfb8aa3b, v116
	v_mul_f32_e32 v117, 0xbfb8aa3b, v117
	v_mul_f32_e32 v120, 0x3fcc422a, v120
	v_mul_f32_e32 v121, 0x3fcc422a, v121
	v_exp_f32_e32 v116, v116
	v_exp_f32_e32 v117, v117
	v_mul_f32_e32 v120, 0xbfb8aa3b, v120
	v_mul_f32_e32 v121, 0xbfb8aa3b, v121
	v_exp_f32_e32 v120, v120
	v_exp_f32_e32 v121, v121
	v_pk_add_f32 v[116:117], v[116:117], 1.0 op_sel_hi:[1,0]
	v_lshl_add_u64 v[122:123], v[124:125], 0, s[34:35]
	v_pk_add_f32 v[120:121], v[120:121], 1.0 op_sel_hi:[1,0]
	v_rcp_f32_e32 v117, v117
	v_rcp_f32_e32 v116, v116
	s_nop 0
	v_pk_mul_f32 v[110:111], v[110:111], v[116:117]
	v_rcp_f32_e32 v117, v121
	v_rcp_f32_e32 v116, v120
	s_nop 0
	v_pk_mul_f32 v[112:113], v[112:113], v[116:117]
	v_lshl_add_u64 v[122:123], v[122:123], 0, v[138:139]
	v_cvt_pk_bf16_f32 v110, v110, v111
	v_cvt_pk_bf16_f32 v111, v112, v113
	global_store_dwordx2 v[122:123], v[110:111], off
	global_load_dwordx2 v[116:117], v[118:119], off offset:32
	s_nop 0
	global_load_dwordx4 v[110:113], v[162:163], off
	v_lshl_add_u64 v[120:121], v[114:115], 0, v[156:157]
	s_waitcnt vmcnt(0)
; DI unsigned pk2(float lo, float hi) { f32x2 v = {lo, hi}; bf16x2_t b = __builtin_convertvector(v, bf16x2_t); return __builtin_bit_cast(unsigned, b); }
; DI float gelu_tanh(float x) { const float u = 1.5957691216057308f * (x + 0.044715f * x * x * x); return x * sigmoidf_(u); }
;     DI void operator()(const f32x4 (&acc)[2][2][4][2], const pg8::Unit& u, int wr, int wc, int fr, int fq) const {
;     ...
;             for (int m = 0; m < 4; ++m) { const int n = row0 + ai * 128 + m * 16;
; #pragma unroll
;                 for (int bj = 0; bj < 2; ++bj)
; #pragma unroll
;                     for (int nn = 0; nn < 2; ++nn) { const int col = col0 + bj * 128 + nn * 16, t = col >> 4, co = col & 15;
;                         const u32x2 uw = *(const u32x2*)(U2 + ((size_t)n * S5G + g) * S5K + col); const f32x4 d4 = *(const f32x4*)(D + g * 16 + co); const f32x4 v = acc[ai][bj][m][nn];
;                         const float y0 = gelu_tanh(v[0] + d4.x * bflo(uw.x)), y1 = gelu_tanh(v[1] + d4.y * bfhi(uw.x)), y2 = gelu_tanh(v[2] + d4.z * bflo(uw.y)), y3 = gelu_tanh(v[3] + d4.w * bfhi(uw.y));
;                         u32x2 w; w.x = pk2(y0, y1); w.y = pk2(y2, y3); *(u32x2*)(GG + ((size_t)n * S5T + t) * DM + g * 16 + co) = w; }
;                 asm volatile("" ::: "memory"); }
	v_lshlrev_b32_e32 v122, 16, v116
	v_and_b32_e32 v123, 0xffff0000, v116
	v_pk_fma_f32 v[106:107], v[110:111], v[122:123], v[106:107]
	v_lshlrev_b32_e32 v116, 16, v117
	v_and_b32_e32 v117, 0xffff0000, v117
	v_mul_f32_e32 v110, 0x3d372713, v106
	v_mul_f32_e32 v111, 0x3d372713, v107
	v_pk_fma_f32 v[108:109], v[112:113], v[116:117], v[108:109]
	v_mul_f32_e32 v110, v106, v110
	v_mul_f32_e32 v111, v107, v111
	v_mul_f32_e32 v112, 0x3d372713, v108
	v_mul_f32_e32 v113, 0x3d372713, v109
	v_fma_f32 v110, v106, v110, v106
	v_fma_f32 v111, v107, v111, v107
	v_mul_f32_e32 v112, v108, v112
	v_mul_f32_e32 v113, v109, v113
	v_mul_f32_e32 v110, 0x3fcc422a, v110
	v_mul_f32_e32 v111, 0x3fcc422a, v111
	v_fma_f32 v112, v108, v112, v108
	v_fma_f32 v113, v109, v113, v109
	v_mul_f32_e32 v110, 0xbfb8aa3b, v110
	v_mul_f32_e32 v111, 0xbfb8aa3b, v111
	v_mul_f32_e32 v112, 0x3fcc422a, v112
	v_mul_f32_e32 v113, 0x3fcc422a, v113
	v_exp_f32_e32 v110, v110
	v_exp_f32_e32 v111, v111
	v_mul_f32_e32 v112, 0xbfb8aa3b, v112
	v_mul_f32_e32 v113, 0xbfb8aa3b, v113
	v_exp_f32_e32 v112, v112
	v_exp_f32_e32 v113, v113
	v_pk_add_f32 v[110:111], v[110:111], 1.0 op_sel_hi:[1,0]
	v_lshl_add_u64 v[116:117], v[120:121], 0, s[34:35]
	v_pk_add_f32 v[112:113], v[112:113], 1.0 op_sel_hi:[1,0]
	v_rcp_f32_e32 v111, v111
	v_rcp_f32_e32 v110, v110
	s_nop 0
	v_pk_mul_f32 v[106:107], v[106:107], v[110:111]
	v_rcp_f32_e32 v111, v113
	v_rcp_f32_e32 v110, v112
	s_nop 0
	v_pk_mul_f32 v[108:109], v[108:109], v[110:111]
	v_lshl_add_u64 v[116:117], v[116:117], 0, v[138:139]
	v_cvt_pk_bf16_f32 v106, v106, v107
	v_cvt_pk_bf16_f32 v107, v108, v109
	global_store_dwordx2 v[116:117], v[106:107], off
	global_load_dwordx2 v[110:111], v[118:119], off offset:256
	s_nop 0
	global_load_dwordx4 v[106:109], v[162:163], off
	v_lshl_add_u64 v[112:113], v[114:115], 0, v[158:159]
	s_waitcnt vmcnt(0)
	v_lshlrev_b32_e32 v116, 16, v110
	v_and_b32_e32 v117, 0xffff0000, v110
	v_pk_fma_f32 v[102:103], v[106:107], v[116:117], v[102:103]
	v_lshlrev_b32_e32 v110, 16, v111
	v_and_b32_e32 v111, 0xffff0000, v111
	v_mul_f32_e32 v106, 0x3d372713, v102
	v_mul_f32_e32 v107, 0x3d372713, v103
	v_pk_fma_f32 v[104:105], v[108:109], v[110:111], v[104:105]
	v_mul_f32_e32 v106, v102, v106
	v_mul_f32_e32 v107, v103, v107
	v_mul_f32_e32 v108, 0x3d372713, v104
	v_mul_f32_e32 v109, 0x3d372713, v105
	v_fma_f32 v106, v102, v106, v102
	v_fma_f32 v107, v103, v107, v103
	v_mul_f32_e32 v108, v104, v108
	v_mul_f32_e32 v109, v105, v109
	v_mul_f32_e32 v106, 0x3fcc422a, v106
	v_mul_f32_e32 v107, 0x3fcc422a, v107
	v_fma_f32 v108, v104, v108, v104
	v_fma_f32 v109, v105, v109, v105
	v_mul_f32_e32 v106, 0xbfb8aa3b, v106
	v_mul_f32_e32 v107, 0xbfb8aa3b, v107
	v_mul_f32_e32 v108, 0x3fcc422a, v108
	v_mul_f32_e32 v109, 0x3fcc422a, v109
	v_exp_f32_e32 v106, v106
	v_exp_f32_e32 v107, v107
	v_mul_f32_e32 v108, 0xbfb8aa3b, v108
	v_mul_f32_e32 v109, 0xbfb8aa3b, v109
	v_exp_f32_e32 v108, v108
	v_exp_f32_e32 v109, v109
	v_pk_add_f32 v[106:107], v[106:107], 1.0 op_sel_hi:[1,0]
	v_lshl_add_u64 v[110:111], v[112:113], 0, s[34:35]
	v_pk_add_f32 v[108:109], v[108:109], 1.0 op_sel_hi:[1,0]
	v_rcp_f32_e32 v107, v107
	v_rcp_f32_e32 v106, v106
	s_nop 0
	v_pk_mul_f32 v[102:103], v[102:103], v[106:107]
	v_rcp_f32_e32 v107, v109
	v_rcp_f32_e32 v106, v108
	s_nop 0
	v_pk_mul_f32 v[104:105], v[104:105], v[106:107]
	v_lshl_add_u64 v[110:111], v[110:111], 0, v[138:139]
	v_cvt_pk_bf16_f32 v102, v102, v103
	v_cvt_pk_bf16_f32 v103, v104, v105
	global_store_dwordx2 v[110:111], v[102:103], off
	global_load_dwordx2 v[108:109], v[118:119], off offset:288
	global_load_dwordx4 v[104:107], v[162:163], off
	v_or_b32_e32 v110, 32, v164
	v_ashrrev_i32_e32 v111, 31, v110
	v_lshl_add_u64 v[112:113], v[114:115], 0, v[160:161]
	v_lshlrev_b64 v[102:103], 6, v[110:111]
	v_lshl_add_u64 v[112:113], v[112:113], 0, s[34:35]
	v_lshl_add_u64 v[114:115], v[102:103], 0, s[36:37]
	v_mad_u64_u32 v[102:103], s[2:3], v114, s46, v[146:147]
	v_mad_i32_i24 v103, v115, s46, v103
	s_waitcnt vmcnt(0)
	v_lshlrev_b32_e32 v116, 16, v108
	v_and_b32_e32 v117, 0xffff0000, v108
	v_pk_fma_f32 v[98:99], v[104:105], v[116:117], v[98:99]
	v_lshlrev_b32_e32 v108, 16, v109
	v_and_b32_e32 v109, 0xffff0000, v109
	v_mul_f32_e32 v104, 0x3d372713, v98
	v_mul_f32_e32 v105, 0x3d372713, v99
	v_pk_fma_f32 v[100:101], v[106:107], v[108:109], v[100:101]
	v_mul_f32_e32 v104, v98, v104
	v_mul_f32_e32 v105, v99, v105
	v_mul_f32_e32 v106, 0x3d372713, v100
	v_mul_f32_e32 v107, 0x3d372713, v101
	v_fma_f32 v104, v98, v104, v98
	v_fma_f32 v105, v99, v105, v99
	v_mul_f32_e32 v106, v100, v106
	v_mul_f32_e32 v107, v101, v107
	v_mul_f32_e32 v104, 0x3fcc422a, v104
	v_mul_f32_e32 v105, 0x3fcc422a, v105
	v_fma_f32 v106, v100, v106, v100
	v_fma_f32 v107, v101, v107, v101
	v_mul_f32_e32 v104, 0xbfb8aa3b, v104
	v_mul_f32_e32 v105, 0xbfb8aa3b, v105
	v_mul_f32_e32 v106, 0x3fcc422a, v106
	v_mul_f32_e32 v107, 0x3fcc422a, v107
	v_exp_f32_e32 v104, v104
	v_exp_f32_e32 v105, v105
	v_mul_f32_e32 v106, 0xbfb8aa3b, v106
	v_mul_f32_e32 v107, 0xbfb8aa3b, v107
	v_exp_f32_e32 v106, v106
	v_exp_f32_e32 v107, v107
	v_pk_add_f32 v[104:105], v[104:105], 1.0 op_sel_hi:[1,0]
	v_lshl_add_u64 v[108:109], v[112:113], 0, v[138:139]
	v_pk_add_f32 v[106:107], v[106:107], 1.0 op_sel_hi:[1,0]
	v_rcp_f32_e32 v105, v105
	v_rcp_f32_e32 v104, v104
	s_nop 0
	v_pk_mul_f32 v[98:99], v[98:99], v[104:105]
	v_rcp_f32_e32 v105, v107
	v_rcp_f32_e32 v104, v106
	s_nop 0
	v_pk_mul_f32 v[100:101], v[100:101], v[104:105]
	v_cvt_pk_bf16_f32 v98, v98, v99
	v_cvt_pk_bf16_f32 v99, v100, v101
	global_store_dwordx2 v[108:109], v[98:99], off
	global_load_dwordx2 v[100:101], v[102:103], off
	global_load_dwordx4 v[104:107], v[162:163], off
	v_lshlrev_b64 v[98:99], 15, v[110:111]
	v_lshl_add_u64 v[98:99], s[18:19], 0, v[98:99]
	v_lshl_add_u64 v[108:109], v[98:99], 0, s[10:11]
	s_waitcnt vmcnt(0)
; DI unsigned pk2(float lo, float hi) { f32x2 v = {lo, hi}; bf16x2_t b = __builtin_convertvector(v, bf16x2_t); return __builtin_bit_cast(unsigned, b); }
; DI float gelu_tanh(float x) { const float u = 1.5957691216057308f * (x + 0.044715f * x * x * x); return x * sigmoidf_(u); }
;     DI void operator()(const f32x4 (&acc)[2][2][4][2], const pg8::Unit& u, int wr, int wc, int fr, int fq) const {
;     ...
;             for (int m = 0; m < 4; ++m) { const int n = row0 + ai * 128 + m * 16;
; #pragma unroll
;                 for (int bj = 0; bj < 2; ++bj)
; #pragma unroll
;                     for (int nn = 0; nn < 2; ++nn) { const int col = col0 + bj * 128 + nn * 16, t = col >> 4, co = col & 15;
;                         const u32x2 uw = *(const u32x2*)(U2 + ((size_t)n * S5G + g) * S5K + col); const f32x4 d4 = *(const f32x4*)(D + g * 16 + co); const f32x4 v = acc[ai][bj][m][nn];
;                         const float y0 = gelu_tanh(v[0] + d4.x * bflo(uw.x)), y1 = gelu_tanh(v[1] + d4.y * bfhi(uw.x)), y2 = gelu_tanh(v[2] + d4.z * bflo(uw.y)), y3 = gelu_tanh(v[3] + d4.w * bfhi(uw.y));
;                         u32x2 w; w.x = pk2(y0, y1); w.y = pk2(y2, y3); *(u32x2*)(GG + ((size_t)n * S5T + t) * DM + g * 16 + co) = w; }
;                 asm volatile("" ::: "memory"); }
	v_lshlrev_b32_e32 v110, 16, v100
	v_and_b32_e32 v111, 0xffff0000, v100
	v_lshlrev_b32_e32 v100, 16, v101
	v_and_b32_e32 v101, 0xffff0000, v101
	v_pk_fma_f32 v[94:95], v[104:105], v[110:111], v[94:95]
	v_pk_fma_f32 v[96:97], v[106:107], v[100:101], v[96:97]
	v_mul_f32_e32 v100, 0x3d372713, v94
	v_mul_f32_e32 v101, 0x3d372713, v95
	v_mul_f32_e32 v100, v94, v100
	v_mul_f32_e32 v101, v95, v101
	v_mul_f32_e32 v104, 0x3d372713, v96
	v_mul_f32_e32 v105, 0x3d372713, v97
	v_fma_f32 v100, v94, v100, v94
	v_fma_f32 v101, v95, v101, v95
	v_mul_f32_e32 v104, v96, v104
	v_mul_f32_e32 v105, v97, v105
	v_mul_f32_e32 v100, 0x3fcc422a, v100
	v_mul_f32_e32 v101, 0x3fcc422a, v101
	v_fma_f32 v104, v96, v104, v96
	v_fma_f32 v105, v97, v105, v97
	v_mul_f32_e32 v100, 0xbfb8aa3b, v100
	v_mul_f32_e32 v101, 0xbfb8aa3b, v101
	v_mul_f32_e32 v104, 0x3fcc422a, v104
	v_mul_f32_e32 v105, 0x3fcc422a, v105
	v_exp_f32_e32 v100, v100
	v_exp_f32_e32 v101, v101
	v_mul_f32_e32 v104, 0xbfb8aa3b, v104
	v_mul_f32_e32 v105, 0xbfb8aa3b, v105
	v_exp_f32_e32 v104, v104
	v_exp_f32_e32 v105, v105
	v_pk_add_f32 v[100:101], v[100:101], 1.0 op_sel_hi:[1,0]
	v_lshl_add_u64 v[106:107], v[108:109], 0, s[34:35]
	v_pk_add_f32 v[104:105], v[104:105], 1.0 op_sel_hi:[1,0]
	v_rcp_f32_e32 v101, v101
	v_rcp_f32_e32 v100, v100
	s_nop 0
	v_pk_mul_f32 v[94:95], v[94:95], v[100:101]
	v_rcp_f32_e32 v101, v105
	v_rcp_f32_e32 v100, v104
	s_nop 0
	v_pk_mul_f32 v[96:97], v[96:97], v[100:101]
	v_lshl_add_u64 v[106:107], v[106:107], 0, v[138:139]
	v_cvt_pk_bf16_f32 v94, v94, v95
	v_cvt_pk_bf16_f32 v95, v96, v97
	global_store_dwordx2 v[106:107], v[94:95], off
	global_load_dwordx2 v[100:101], v[102:103], off offset:32
	s_nop 0
	global_load_dwordx4 v[94:97], v[162:163], off
	v_lshl_add_u64 v[104:105], v[98:99], 0, v[156:157]
	s_waitcnt vmcnt(0)
	v_lshlrev_b32_e32 v106, 16, v100
	v_and_b32_e32 v107, 0xffff0000, v100
	v_pk_fma_f32 v[90:91], v[94:95], v[106:107], v[90:91]
	v_lshlrev_b32_e32 v100, 16, v101
	v_and_b32_e32 v101, 0xffff0000, v101
	v_mul_f32_e32 v94, 0x3d372713, v90
	v_mul_f32_e32 v95, 0x3d372713, v91
	v_pk_fma_f32 v[92:93], v[96:97], v[100:101], v[92:93]
	v_mul_f32_e32 v94, v90, v94
	v_mul_f32_e32 v95, v91, v95
	v_mul_f32_e32 v96, 0x3d372713, v92
	v_mul_f32_e32 v97, 0x3d372713, v93
	v_fma_f32 v94, v90, v94, v90
	v_fma_f32 v95, v91, v95, v91
	v_mul_f32_e32 v96, v92, v96
	v_mul_f32_e32 v97, v93, v97
	v_mul_f32_e32 v94, 0x3fcc422a, v94
	v_mul_f32_e32 v95, 0x3fcc422a, v95
	v_fma_f32 v96, v92, v96, v92
	v_fma_f32 v97, v93, v97, v93
	v_mul_f32_e32 v94, 0xbfb8aa3b, v94
	v_mul_f32_e32 v95, 0xbfb8aa3b, v95
	v_mul_f32_e32 v96, 0x3fcc422a, v96
	v_mul_f32_e32 v97, 0x3fcc422a, v97
	v_exp_f32_e32 v94, v94
	v_exp_f32_e32 v95, v95
	v_mul_f32_e32 v96, 0xbfb8aa3b, v96
	v_mul_f32_e32 v97, 0xbfb8aa3b, v97
	v_exp_f32_e32 v96, v96
	v_exp_f32_e32 v97, v97
	v_pk_add_f32 v[94:95], v[94:95], 1.0 op_sel_hi:[1,0]
	v_lshl_add_u64 v[100:101], v[104:105], 0, s[34:35]
	v_pk_add_f32 v[96:97], v[96:97], 1.0 op_sel_hi:[1,0]
	v_rcp_f32_e32 v95, v95
	v_rcp_f32_e32 v94, v94
	s_nop 0
	v_pk_mul_f32 v[90:91], v[90:91], v[94:95]
	v_rcp_f32_e32 v95, v97
	v_rcp_f32_e32 v94, v96
	s_nop 0
	v_pk_mul_f32 v[92:93], v[92:93], v[94:95]
	v_lshl_add_u64 v[100:101], v[100:101], 0, v[138:139]
	v_cvt_pk_bf16_f32 v90, v90, v91
	v_cvt_pk_bf16_f32 v91, v92, v93
	global_store_dwordx2 v[100:101], v[90:91], off
	global_load_dwordx2 v[94:95], v[102:103], off offset:256
	s_nop 0
	global_load_dwordx4 v[90:93], v[162:163], off
	v_lshl_add_u64 v[96:97], v[98:99], 0, v[158:159]
	s_waitcnt vmcnt(0)
	v_lshlrev_b32_e32 v100, 16, v94
	v_and_b32_e32 v101, 0xffff0000, v94
	v_pk_fma_f32 v[86:87], v[90:91], v[100:101], v[86:87]
	v_lshlrev_b32_e32 v94, 16, v95
	v_and_b32_e32 v95, 0xffff0000, v95
	v_mul_f32_e32 v90, 0x3d372713, v86
	v_mul_f32_e32 v91, 0x3d372713, v87
	v_pk_fma_f32 v[88:89], v[92:93], v[94:95], v[88:89]
	v_mul_f32_e32 v90, v86, v90
	v_mul_f32_e32 v91, v87, v91
	v_mul_f32_e32 v92, 0x3d372713, v88
	v_mul_f32_e32 v93, 0x3d372713, v89
	v_fma_f32 v90, v86, v90, v86
	v_fma_f32 v91, v87, v91, v87
	v_mul_f32_e32 v92, v88, v92
	v_mul_f32_e32 v93, v89, v93
	v_mul_f32_e32 v90, 0x3fcc422a, v90
	v_mul_f32_e32 v91, 0x3fcc422a, v91
	v_fma_f32 v92, v88, v92, v88
	v_fma_f32 v93, v89, v93, v89
	v_mul_f32_e32 v90, 0xbfb8aa3b, v90
	v_mul_f32_e32 v91, 0xbfb8aa3b, v91
	v_mul_f32_e32 v92, 0x3fcc422a, v92
	v_mul_f32_e32 v93, 0x3fcc422a, v93
	v_exp_f32_e32 v90, v90
	v_exp_f32_e32 v91, v91
	v_mul_f32_e32 v92, 0xbfb8aa3b, v92
	v_mul_f32_e32 v93, 0xbfb8aa3b, v93
	v_exp_f32_e32 v92, v92
	v_exp_f32_e32 v93, v93
	v_pk_add_f32 v[90:91], v[90:91], 1.0 op_sel_hi:[1,0]
	v_lshl_add_u64 v[94:95], v[96:97], 0, s[34:35]
	v_pk_add_f32 v[92:93], v[92:93], 1.0 op_sel_hi:[1,0]
	v_rcp_f32_e32 v91, v91
	v_rcp_f32_e32 v90, v90
	s_nop 0
	v_pk_mul_f32 v[86:87], v[86:87], v[90:91]
	v_rcp_f32_e32 v91, v93
	v_rcp_f32_e32 v90, v92
	s_nop 0
	v_pk_mul_f32 v[88:89], v[88:89], v[90:91]
	v_lshl_add_u64 v[94:95], v[94:95], 0, v[138:139]
	v_cvt_pk_bf16_f32 v86, v86, v87
	v_cvt_pk_bf16_f32 v87, v88, v89
	global_store_dwordx2 v[94:95], v[86:87], off
	global_load_dwordx2 v[92:93], v[102:103], off offset:288
	global_load_dwordx4 v[88:91], v[162:163], off
	v_or_b32_e32 v94, 48, v164
	v_ashrrev_i32_e32 v95, 31, v94
	v_lshl_add_u64 v[96:97], v[98:99], 0, v[160:161]
	v_lshlrev_b64 v[86:87], 6, v[94:95]
	v_lshl_add_u64 v[96:97], v[96:97], 0, s[34:35]
	v_lshl_add_u64 v[98:99], v[86:87], 0, s[36:37]
	v_mad_u64_u32 v[86:87], s[2:3], v98, s46, v[146:147]
	v_mad_i32_i24 v87, v99, s46, v87
	s_waitcnt vmcnt(0)
; DI unsigned pk2(float lo, float hi) { f32x2 v = {lo, hi}; bf16x2_t b = __builtin_convertvector(v, bf16x2_t); return __builtin_bit_cast(unsigned, b); }
; DI float gelu_tanh(float x) { const float u = 1.5957691216057308f * (x + 0.044715f * x * x * x); return x * sigmoidf_(u); }
;     DI void operator()(const f32x4 (&acc)[2][2][4][2], const pg8::Unit& u, int wr, int wc, int fr, int fq) const {
;     ...
;             for (int m = 0; m < 4; ++m) { const int n = row0 + ai * 128 + m * 16;
; #pragma unroll
;                 for (int bj = 0; bj < 2; ++bj)
; #pragma unroll
;                     for (int nn = 0; nn < 2; ++nn) { const int col = col0 + bj * 128 + nn * 16, t = col >> 4, co = col & 15;
;                         const u32x2 uw = *(const u32x2*)(U2 + ((size_t)n * S5G + g) * S5K + col); const f32x4 d4 = *(const f32x4*)(D + g * 16 + co); const f32x4 v = acc[ai][bj][m][nn];
;                         const float y0 = gelu_tanh(v[0] + d4.x * bflo(uw.x)), y1 = gelu_tanh(v[1] + d4.y * bfhi(uw.x)), y2 = gelu_tanh(v[2] + d4.z * bflo(uw.y)), y3 = gelu_tanh(v[3] + d4.w * bfhi(uw.y));
;                         u32x2 w; w.x = pk2(y0, y1); w.y = pk2(y2, y3); *(u32x2*)(GG + ((size_t)n * S5T + t) * DM + g * 16 + co) = w; }
;                 asm volatile("" ::: "memory"); }
	v_lshlrev_b32_e32 v100, 16, v92
	v_and_b32_e32 v101, 0xffff0000, v92
	v_pk_fma_f32 v[82:83], v[88:89], v[100:101], v[82:83]
	v_lshlrev_b32_e32 v92, 16, v93
	v_and_b32_e32 v93, 0xffff0000, v93
	v_mul_f32_e32 v88, 0x3d372713, v82
	v_mul_f32_e32 v89, 0x3d372713, v83
	v_pk_fma_f32 v[84:85], v[90:91], v[92:93], v[84:85]
	v_mul_f32_e32 v88, v82, v88
	v_mul_f32_e32 v89, v83, v89
	v_mul_f32_e32 v90, 0x3d372713, v84
	v_mul_f32_e32 v91, 0x3d372713, v85
	v_fma_f32 v88, v82, v88, v82
	v_fma_f32 v89, v83, v89, v83
	v_mul_f32_e32 v90, v84, v90
	v_mul_f32_e32 v91, v85, v91
	v_mul_f32_e32 v88, 0x3fcc422a, v88
	v_mul_f32_e32 v89, 0x3fcc422a, v89
	v_fma_f32 v90, v84, v90, v84
	v_fma_f32 v91, v85, v91, v85
	v_mul_f32_e32 v88, 0xbfb8aa3b, v88
	v_mul_f32_e32 v89, 0xbfb8aa3b, v89
	v_mul_f32_e32 v90, 0x3fcc422a, v90
	v_mul_f32_e32 v91, 0x3fcc422a, v91
	v_exp_f32_e32 v88, v88
	v_exp_f32_e32 v89, v89
	v_mul_f32_e32 v90, 0xbfb8aa3b, v90
	v_mul_f32_e32 v91, 0xbfb8aa3b, v91
	v_exp_f32_e32 v90, v90
	v_exp_f32_e32 v91, v91
	v_pk_add_f32 v[88:89], v[88:89], 1.0 op_sel_hi:[1,0]
	v_lshl_add_u64 v[92:93], v[96:97], 0, v[138:139]
	v_pk_add_f32 v[90:91], v[90:91], 1.0 op_sel_hi:[1,0]
	v_rcp_f32_e32 v89, v89
	v_rcp_f32_e32 v88, v88
	s_nop 0
	v_pk_mul_f32 v[82:83], v[82:83], v[88:89]
	v_rcp_f32_e32 v89, v91
	v_rcp_f32_e32 v88, v90
	s_nop 0
	v_pk_mul_f32 v[84:85], v[84:85], v[88:89]
	v_cvt_pk_bf16_f32 v82, v82, v83
	v_cvt_pk_bf16_f32 v83, v84, v85
	global_store_dwordx2 v[92:93], v[82:83], off
	global_load_dwordx2 v[84:85], v[86:87], off
	global_load_dwordx4 v[88:91], v[162:163], off
	v_lshlrev_b64 v[82:83], 15, v[94:95]
	v_lshl_add_u64 v[82:83], s[18:19], 0, v[82:83]
	v_lshl_add_u64 v[92:93], v[82:83], 0, s[10:11]
	s_waitcnt vmcnt(0)
	v_lshlrev_b32_e32 v94, 16, v84
	v_and_b32_e32 v95, 0xffff0000, v84
	v_lshlrev_b32_e32 v84, 16, v85
	v_and_b32_e32 v85, 0xffff0000, v85
	v_pk_fma_f32 v[78:79], v[88:89], v[94:95], v[78:79]
	v_pk_fma_f32 v[80:81], v[90:91], v[84:85], v[80:81]
	v_mul_f32_e32 v84, 0x3d372713, v78
	v_mul_f32_e32 v85, 0x3d372713, v79
	v_mul_f32_e32 v84, v78, v84
	v_mul_f32_e32 v85, v79, v85
	v_mul_f32_e32 v88, 0x3d372713, v80
	v_mul_f32_e32 v89, 0x3d372713, v81
	v_fma_f32 v84, v78, v84, v78
	v_fma_f32 v85, v79, v85, v79
	v_mul_f32_e32 v88, v80, v88
	v_mul_f32_e32 v89, v81, v89
	v_mul_f32_e32 v84, 0x3fcc422a, v84
	v_mul_f32_e32 v85, 0x3fcc422a, v85
	v_fma_f32 v88, v80, v88, v80
	v_fma_f32 v89, v81, v89, v81
	v_mul_f32_e32 v84, 0xbfb8aa3b, v84
	v_mul_f32_e32 v85, 0xbfb8aa3b, v85
	v_mul_f32_e32 v88, 0x3fcc422a, v88
	v_mul_f32_e32 v89, 0x3fcc422a, v89
	v_exp_f32_e32 v84, v84
	v_exp_f32_e32 v85, v85
	v_mul_f32_e32 v88, 0xbfb8aa3b, v88
	v_mul_f32_e32 v89, 0xbfb8aa3b, v89
	v_exp_f32_e32 v88, v88
	v_exp_f32_e32 v89, v89
	v_pk_add_f32 v[84:85], v[84:85], 1.0 op_sel_hi:[1,0]
	v_lshl_add_u64 v[90:91], v[92:93], 0, s[34:35]
	v_pk_add_f32 v[88:89], v[88:89], 1.0 op_sel_hi:[1,0]
	v_rcp_f32_e32 v85, v85
	v_rcp_f32_e32 v84, v84
	s_nop 0
	v_pk_mul_f32 v[78:79], v[78:79], v[84:85]
	v_rcp_f32_e32 v85, v89
	v_rcp_f32_e32 v84, v88
	s_nop 0
	v_pk_mul_f32 v[80:81], v[80:81], v[84:85]
	v_lshl_add_u64 v[90:91], v[90:91], 0, v[138:139]
	v_cvt_pk_bf16_f32 v78, v78, v79
	v_cvt_pk_bf16_f32 v79, v80, v81
	global_store_dwordx2 v[90:91], v[78:79], off
	global_load_dwordx2 v[84:85], v[86:87], off offset:32
	s_nop 0
	global_load_dwordx4 v[78:81], v[162:163], off
	v_lshl_add_u64 v[88:89], v[82:83], 0, v[156:157]
	s_waitcnt vmcnt(0)
	v_lshlrev_b32_e32 v90, 16, v84
	v_and_b32_e32 v91, 0xffff0000, v84
	v_pk_fma_f32 v[74:75], v[78:79], v[90:91], v[74:75]
	v_lshlrev_b32_e32 v84, 16, v85
	v_and_b32_e32 v85, 0xffff0000, v85
	v_mul_f32_e32 v78, 0x3d372713, v74
	v_mul_f32_e32 v79, 0x3d372713, v75
	v_pk_fma_f32 v[76:77], v[80:81], v[84:85], v[76:77]
	v_mul_f32_e32 v78, v74, v78
	v_mul_f32_e32 v79, v75, v79
	v_mul_f32_e32 v80, 0x3d372713, v76
	v_mul_f32_e32 v81, 0x3d372713, v77
	v_fma_f32 v78, v74, v78, v74
	v_fma_f32 v79, v75, v79, v75
	v_mul_f32_e32 v80, v76, v80
	v_mul_f32_e32 v81, v77, v81
	v_mul_f32_e32 v78, 0x3fcc422a, v78
	v_mul_f32_e32 v79, 0x3fcc422a, v79
	v_fma_f32 v80, v76, v80, v76
	v_fma_f32 v81, v77, v81, v77
	v_mul_f32_e32 v78, 0xbfb8aa3b, v78
	v_mul_f32_e32 v79, 0xbfb8aa3b, v79
	v_mul_f32_e32 v80, 0x3fcc422a, v80
	v_mul_f32_e32 v81, 0x3fcc422a, v81
	v_exp_f32_e32 v78, v78
	v_exp_f32_e32 v79, v79
	v_mul_f32_e32 v80, 0xbfb8aa3b, v80
	v_mul_f32_e32 v81, 0xbfb8aa3b, v81
	v_exp_f32_e32 v80, v80
	v_exp_f32_e32 v81, v81
	v_pk_add_f32 v[78:79], v[78:79], 1.0 op_sel_hi:[1,0]
	v_lshl_add_u64 v[84:85], v[88:89], 0, s[34:35]
	v_pk_add_f32 v[80:81], v[80:81], 1.0 op_sel_hi:[1,0]
	v_rcp_f32_e32 v79, v79
	v_rcp_f32_e32 v78, v78
	s_nop 0
	v_pk_mul_f32 v[74:75], v[74:75], v[78:79]
	v_rcp_f32_e32 v79, v81
	v_rcp_f32_e32 v78, v80
	s_nop 0
	v_pk_mul_f32 v[76:77], v[76:77], v[78:79]
	v_lshl_add_u64 v[84:85], v[84:85], 0, v[138:139]
	v_cvt_pk_bf16_f32 v74, v74, v75
	v_cvt_pk_bf16_f32 v75, v76, v77
	global_store_dwordx2 v[84:85], v[74:75], off
	global_load_dwordx2 v[78:79], v[86:87], off offset:256
	s_nop 0
	global_load_dwordx4 v[74:77], v[162:163], off
	v_lshl_add_u64 v[80:81], v[82:83], 0, v[158:159]
	s_waitcnt vmcnt(0)
; DI unsigned pk2(float lo, float hi) { f32x2 v = {lo, hi}; bf16x2_t b = __builtin_convertvector(v, bf16x2_t); return __builtin_bit_cast(unsigned, b); }
; DI float gelu_tanh(float x) { const float u = 1.5957691216057308f * (x + 0.044715f * x * x * x); return x * sigmoidf_(u); }
;     DI void operator()(const f32x4 (&acc)[2][2][4][2], const pg8::Unit& u, int wr, int wc, int fr, int fq) const {
;     ...
;             for (int m = 0; m < 4; ++m) { const int n = row0 + ai * 128 + m * 16;
; #pragma unroll
;                 for (int bj = 0; bj < 2; ++bj)
; #pragma unroll
;                     for (int nn = 0; nn < 2; ++nn) { const int col = col0 + bj * 128 + nn * 16, t = col >> 4, co = col & 15;
;                         const u32x2 uw = *(const u32x2*)(U2 + ((size_t)n * S5G + g) * S5K + col); const f32x4 d4 = *(const f32x4*)(D + g * 16 + co); const f32x4 v = acc[ai][bj][m][nn];
;                         const float y0 = gelu_tanh(v[0] + d4.x * bflo(uw.x)), y1 = gelu_tanh(v[1] + d4.y * bfhi(uw.x)), y2 = gelu_tanh(v[2] + d4.z * bflo(uw.y)), y3 = gelu_tanh(v[3] + d4.w * bfhi(uw.y));
;                         u32x2 w; w.x = pk2(y0, y1); w.y = pk2(y2, y3); *(u32x2*)(GG + ((size_t)n * S5T + t) * DM + g * 16 + co) = w; }
;                 asm volatile("" ::: "memory"); }
	v_lshlrev_b32_e32 v84, 16, v78
	v_and_b32_e32 v85, 0xffff0000, v78
	v_pk_fma_f32 v[70:71], v[74:75], v[84:85], v[70:71]
	v_lshlrev_b32_e32 v78, 16, v79
	v_and_b32_e32 v79, 0xffff0000, v79
	v_mul_f32_e32 v74, 0x3d372713, v70
	v_mul_f32_e32 v75, 0x3d372713, v71
	v_pk_fma_f32 v[72:73], v[76:77], v[78:79], v[72:73]
	v_mul_f32_e32 v74, v70, v74
	v_mul_f32_e32 v75, v71, v75
	v_mul_f32_e32 v76, 0x3d372713, v72
	v_mul_f32_e32 v77, 0x3d372713, v73
	v_fma_f32 v74, v70, v74, v70
	v_fma_f32 v75, v71, v75, v71
	v_mul_f32_e32 v76, v72, v76
	v_mul_f32_e32 v77, v73, v77
	v_mul_f32_e32 v74, 0x3fcc422a, v74
	v_mul_f32_e32 v75, 0x3fcc422a, v75
	v_fma_f32 v76, v72, v76, v72
	v_fma_f32 v77, v73, v77, v73
	v_mul_f32_e32 v74, 0xbfb8aa3b, v74
	v_mul_f32_e32 v75, 0xbfb8aa3b, v75
	v_mul_f32_e32 v76, 0x3fcc422a, v76
	v_mul_f32_e32 v77, 0x3fcc422a, v77
	v_exp_f32_e32 v74, v74
	v_exp_f32_e32 v75, v75
	v_mul_f32_e32 v76, 0xbfb8aa3b, v76
	v_mul_f32_e32 v77, 0xbfb8aa3b, v77
	v_exp_f32_e32 v76, v76
	v_exp_f32_e32 v77, v77
	v_pk_add_f32 v[74:75], v[74:75], 1.0 op_sel_hi:[1,0]
	v_lshl_add_u64 v[78:79], v[80:81], 0, s[34:35]
	v_pk_add_f32 v[76:77], v[76:77], 1.0 op_sel_hi:[1,0]
	v_rcp_f32_e32 v75, v75
	v_rcp_f32_e32 v74, v74
	s_nop 0
	v_pk_mul_f32 v[70:71], v[70:71], v[74:75]
	v_rcp_f32_e32 v75, v77
	v_rcp_f32_e32 v74, v76
	s_nop 0
	v_pk_mul_f32 v[72:73], v[72:73], v[74:75]
	v_lshl_add_u64 v[78:79], v[78:79], 0, v[138:139]
	v_cvt_pk_bf16_f32 v70, v70, v71
	v_cvt_pk_bf16_f32 v71, v72, v73
	global_store_dwordx2 v[78:79], v[70:71], off
	global_load_dwordx2 v[76:77], v[86:87], off offset:288
	global_load_dwordx4 v[72:75], v[162:163], off
	v_add_u32_e32 v78, 0x80, v164
	v_ashrrev_i32_e32 v79, 31, v78
	v_lshl_add_u64 v[80:81], v[82:83], 0, v[160:161]
	v_lshlrev_b64 v[70:71], 6, v[78:79]
	v_lshl_add_u64 v[80:81], v[80:81], 0, s[34:35]
	v_lshl_add_u64 v[82:83], v[70:71], 0, s[36:37]
	v_mad_u64_u32 v[70:71], s[2:3], v82, s46, v[146:147]
	v_mad_i32_i24 v71, v83, s46, v71
	s_waitcnt vmcnt(0)
	v_lshlrev_b32_e32 v84, 16, v76
	v_and_b32_e32 v85, 0xffff0000, v76
	v_pk_fma_f32 v[66:67], v[72:73], v[84:85], v[66:67]
	v_lshlrev_b32_e32 v76, 16, v77
	v_and_b32_e32 v77, 0xffff0000, v77
	v_mul_f32_e32 v72, 0x3d372713, v66
	v_mul_f32_e32 v73, 0x3d372713, v67
	v_pk_fma_f32 v[68:69], v[74:75], v[76:77], v[68:69]
	v_mul_f32_e32 v72, v66, v72
	v_mul_f32_e32 v73, v67, v73
	v_mul_f32_e32 v74, 0x3d372713, v68
	v_mul_f32_e32 v75, 0x3d372713, v69
	v_fma_f32 v72, v66, v72, v66
	v_fma_f32 v73, v67, v73, v67
	v_mul_f32_e32 v74, v68, v74
	v_mul_f32_e32 v75, v69, v75
	v_mul_f32_e32 v72, 0x3fcc422a, v72
	v_mul_f32_e32 v73, 0x3fcc422a, v73
	v_fma_f32 v74, v68, v74, v68
	v_fma_f32 v75, v69, v75, v69
	v_mul_f32_e32 v72, 0xbfb8aa3b, v72
	v_mul_f32_e32 v73, 0xbfb8aa3b, v73
	v_mul_f32_e32 v74, 0x3fcc422a, v74
	v_mul_f32_e32 v75, 0x3fcc422a, v75
	v_exp_f32_e32 v72, v72
	v_exp_f32_e32 v73, v73
	v_mul_f32_e32 v74, 0xbfb8aa3b, v74
	v_mul_f32_e32 v75, 0xbfb8aa3b, v75
	v_exp_f32_e32 v74, v74
	v_exp_f32_e32 v75, v75
	v_pk_add_f32 v[72:73], v[72:73], 1.0 op_sel_hi:[1,0]
	v_lshl_add_u64 v[76:77], v[80:81], 0, v[138:139]
	v_pk_add_f32 v[74:75], v[74:75], 1.0 op_sel_hi:[1,0]
	v_rcp_f32_e32 v73, v73
	v_rcp_f32_e32 v72, v72
	s_nop 0
	v_pk_mul_f32 v[66:67], v[66:67], v[72:73]
	v_rcp_f32_e32 v73, v75
	v_rcp_f32_e32 v72, v74
	s_nop 0
	v_pk_mul_f32 v[68:69], v[68:69], v[72:73]
	v_cvt_pk_bf16_f32 v66, v66, v67
	v_cvt_pk_bf16_f32 v67, v68, v69
	global_store_dwordx2 v[76:77], v[66:67], off
	global_load_dwordx2 v[68:69], v[70:71], off
	global_load_dwordx4 v[72:75], v[162:163], off
	v_lshlrev_b64 v[66:67], 15, v[78:79]
	v_lshl_add_u64 v[66:67], s[18:19], 0, v[66:67]
	v_lshl_add_u64 v[76:77], v[66:67], 0, s[10:11]
	s_waitcnt vmcnt(0)
	v_lshlrev_b32_e32 v78, 16, v68
	v_and_b32_e32 v79, 0xffff0000, v68
	v_lshlrev_b32_e32 v68, 16, v69
	v_and_b32_e32 v69, 0xffff0000, v69
	v_pk_fma_f32 v[62:63], v[72:73], v[78:79], v[62:63]
	v_pk_fma_f32 v[64:65], v[74:75], v[68:69], v[64:65]
	v_mul_f32_e32 v68, 0x3d372713, v62
	v_mul_f32_e32 v69, 0x3d372713, v63
	v_mul_f32_e32 v68, v62, v68
	v_mul_f32_e32 v69, v63, v69
	v_mul_f32_e32 v72, 0x3d372713, v64
	v_mul_f32_e32 v73, 0x3d372713, v65
	v_fma_f32 v68, v62, v68, v62
	v_fma_f32 v69, v63, v69, v63
	v_mul_f32_e32 v72, v64, v72
	v_mul_f32_e32 v73, v65, v73
	v_mul_f32_e32 v68, 0x3fcc422a, v68
	v_mul_f32_e32 v69, 0x3fcc422a, v69
	v_fma_f32 v72, v64, v72, v64
	v_fma_f32 v73, v65, v73, v65
	v_mul_f32_e32 v68, 0xbfb8aa3b, v68
	v_mul_f32_e32 v69, 0xbfb8aa3b, v69
	v_mul_f32_e32 v72, 0x3fcc422a, v72
	v_mul_f32_e32 v73, 0x3fcc422a, v73
	v_exp_f32_e32 v68, v68
	v_exp_f32_e32 v69, v69
	v_mul_f32_e32 v72, 0xbfb8aa3b, v72
	v_mul_f32_e32 v73, 0xbfb8aa3b, v73
	v_exp_f32_e32 v72, v72
	v_exp_f32_e32 v73, v73
	v_pk_add_f32 v[68:69], v[68:69], 1.0 op_sel_hi:[1,0]
	v_lshl_add_u64 v[74:75], v[76:77], 0, s[34:35]
	v_pk_add_f32 v[72:73], v[72:73], 1.0 op_sel_hi:[1,0]
	v_rcp_f32_e32 v69, v69
	v_rcp_f32_e32 v68, v68
	s_nop 0
	v_pk_mul_f32 v[62:63], v[62:63], v[68:69]
	v_rcp_f32_e32 v69, v73
	v_rcp_f32_e32 v68, v72
	s_nop 0
	v_pk_mul_f32 v[64:65], v[64:65], v[68:69]
	v_lshl_add_u64 v[74:75], v[74:75], 0, v[138:139]
	v_cvt_pk_bf16_f32 v62, v62, v63
	v_cvt_pk_bf16_f32 v63, v64, v65
	global_store_dwordx2 v[74:75], v[62:63], off
	global_load_dwordx2 v[68:69], v[70:71], off offset:32
	s_nop 0
	global_load_dwordx4 v[62:65], v[162:163], off
	v_lshl_add_u64 v[72:73], v[66:67], 0, v[156:157]
	s_waitcnt vmcnt(0)
; DI unsigned pk2(float lo, float hi) { f32x2 v = {lo, hi}; bf16x2_t b = __builtin_convertvector(v, bf16x2_t); return __builtin_bit_cast(unsigned, b); }
; DI float gelu_tanh(float x) { const float u = 1.5957691216057308f * (x + 0.044715f * x * x * x); return x * sigmoidf_(u); }
;     DI void operator()(const f32x4 (&acc)[2][2][4][2], const pg8::Unit& u, int wr, int wc, int fr, int fq) const {
;     ...
;             for (int m = 0; m < 4; ++m) { const int n = row0 + ai * 128 + m * 16;
; #pragma unroll
;                 for (int bj = 0; bj < 2; ++bj)
; #pragma unroll
;                     for (int nn = 0; nn < 2; ++nn) { const int col = col0 + bj * 128 + nn * 16, t = col >> 4, co = col & 15;
;                         const u32x2 uw = *(const u32x2*)(U2 + ((size_t)n * S5G + g) * S5K + col); const f32x4 d4 = *(const f32x4*)(D + g * 16 + co); const f32x4 v = acc[ai][bj][m][nn];
;                         const float y0 = gelu_tanh(v[0] + d4.x * bflo(uw.x)), y1 = gelu_tanh(v[1] + d4.y * bfhi(uw.x)), y2 = gelu_tanh(v[2] + d4.z * bflo(uw.y)), y3 = gelu_tanh(v[3] + d4.w * bfhi(uw.y));
;                         u32x2 w; w.x = pk2(y0, y1); w.y = pk2(y2, y3); *(u32x2*)(GG + ((size_t)n * S5T + t) * DM + g * 16 + co) = w; }
;                 asm volatile("" ::: "memory"); }
	v_lshlrev_b32_e32 v74, 16, v68
	v_and_b32_e32 v75, 0xffff0000, v68
	v_pk_fma_f32 v[58:59], v[62:63], v[74:75], v[58:59]
	v_lshlrev_b32_e32 v68, 16, v69
	v_and_b32_e32 v69, 0xffff0000, v69
	v_mul_f32_e32 v62, 0x3d372713, v58
	v_mul_f32_e32 v63, 0x3d372713, v59
	v_pk_fma_f32 v[60:61], v[64:65], v[68:69], v[60:61]
	v_mul_f32_e32 v62, v58, v62
	v_mul_f32_e32 v63, v59, v63
	v_mul_f32_e32 v64, 0x3d372713, v60
	v_mul_f32_e32 v65, 0x3d372713, v61
	v_fma_f32 v62, v58, v62, v58
	v_fma_f32 v63, v59, v63, v59
	v_mul_f32_e32 v64, v60, v64
	v_mul_f32_e32 v65, v61, v65
	v_mul_f32_e32 v62, 0x3fcc422a, v62
	v_mul_f32_e32 v63, 0x3fcc422a, v63
	v_fma_f32 v64, v60, v64, v60
	v_fma_f32 v65, v61, v65, v61
	v_mul_f32_e32 v62, 0xbfb8aa3b, v62
	v_mul_f32_e32 v63, 0xbfb8aa3b, v63
	v_mul_f32_e32 v64, 0x3fcc422a, v64
	v_mul_f32_e32 v65, 0x3fcc422a, v65
	v_exp_f32_e32 v62, v62
	v_exp_f32_e32 v63, v63
	v_mul_f32_e32 v64, 0xbfb8aa3b, v64
	v_mul_f32_e32 v65, 0xbfb8aa3b, v65
	v_exp_f32_e32 v64, v64
	v_exp_f32_e32 v65, v65
	v_pk_add_f32 v[62:63], v[62:63], 1.0 op_sel_hi:[1,0]
	v_lshl_add_u64 v[68:69], v[72:73], 0, s[34:35]
	v_pk_add_f32 v[64:65], v[64:65], 1.0 op_sel_hi:[1,0]
	v_rcp_f32_e32 v63, v63
	v_rcp_f32_e32 v62, v62
	s_nop 0
	v_pk_mul_f32 v[58:59], v[58:59], v[62:63]
	v_rcp_f32_e32 v63, v65
	v_rcp_f32_e32 v62, v64
	s_nop 0
	v_pk_mul_f32 v[60:61], v[60:61], v[62:63]
	v_lshl_add_u64 v[68:69], v[68:69], 0, v[138:139]
	v_cvt_pk_bf16_f32 v58, v58, v59
	v_cvt_pk_bf16_f32 v59, v60, v61
	global_store_dwordx2 v[68:69], v[58:59], off
	global_load_dwordx2 v[62:63], v[70:71], off offset:256
	s_nop 0
	global_load_dwordx4 v[58:61], v[162:163], off
	v_lshl_add_u64 v[64:65], v[66:67], 0, v[158:159]
	s_waitcnt vmcnt(0)
	v_lshlrev_b32_e32 v68, 16, v62
	v_and_b32_e32 v69, 0xffff0000, v62
	v_pk_fma_f32 v[54:55], v[58:59], v[68:69], v[54:55]
	v_lshlrev_b32_e32 v62, 16, v63
	v_and_b32_e32 v63, 0xffff0000, v63
	v_mul_f32_e32 v58, 0x3d372713, v54
	v_mul_f32_e32 v59, 0x3d372713, v55
	v_pk_fma_f32 v[56:57], v[60:61], v[62:63], v[56:57]
	v_mul_f32_e32 v58, v54, v58
	v_mul_f32_e32 v59, v55, v59
	v_mul_f32_e32 v60, 0x3d372713, v56
	v_mul_f32_e32 v61, 0x3d372713, v57
	v_fma_f32 v58, v54, v58, v54
	v_fma_f32 v59, v55, v59, v55
	v_mul_f32_e32 v60, v56, v60
	v_mul_f32_e32 v61, v57, v61
	v_mul_f32_e32 v58, 0x3fcc422a, v58
	v_mul_f32_e32 v59, 0x3fcc422a, v59
	v_fma_f32 v60, v56, v60, v56
	v_fma_f32 v61, v57, v61, v57
	v_mul_f32_e32 v58, 0xbfb8aa3b, v58
	v_mul_f32_e32 v59, 0xbfb8aa3b, v59
	v_mul_f32_e32 v60, 0x3fcc422a, v60
	v_mul_f32_e32 v61, 0x3fcc422a, v61
	v_exp_f32_e32 v58, v58
	v_exp_f32_e32 v59, v59
	v_mul_f32_e32 v60, 0xbfb8aa3b, v60
	v_mul_f32_e32 v61, 0xbfb8aa3b, v61
	v_exp_f32_e32 v60, v60
	v_exp_f32_e32 v61, v61
	v_pk_add_f32 v[58:59], v[58:59], 1.0 op_sel_hi:[1,0]
	v_lshl_add_u64 v[62:63], v[64:65], 0, s[34:35]
	v_pk_add_f32 v[60:61], v[60:61], 1.0 op_sel_hi:[1,0]
	v_rcp_f32_e32 v59, v59
	v_rcp_f32_e32 v58, v58
	s_nop 0
	v_pk_mul_f32 v[54:55], v[54:55], v[58:59]
	v_rcp_f32_e32 v59, v61
	v_rcp_f32_e32 v58, v60
	s_nop 0
	v_pk_mul_f32 v[56:57], v[56:57], v[58:59]
	v_lshl_add_u64 v[62:63], v[62:63], 0, v[138:139]
	v_cvt_pk_bf16_f32 v54, v54, v55
	v_cvt_pk_bf16_f32 v55, v56, v57
	global_store_dwordx2 v[62:63], v[54:55], off
	global_load_dwordx2 v[60:61], v[70:71], off offset:288
	global_load_dwordx4 v[56:59], v[162:163], off
	v_add_u32_e32 v62, 0x90, v164
	v_ashrrev_i32_e32 v63, 31, v62
	v_lshl_add_u64 v[64:65], v[66:67], 0, v[160:161]
	v_lshlrev_b64 v[54:55], 6, v[62:63]
	v_lshl_add_u64 v[64:65], v[64:65], 0, s[34:35]
	v_lshl_add_u64 v[66:67], v[54:55], 0, s[36:37]
	v_mad_u64_u32 v[54:55], s[2:3], v66, s46, v[146:147]
	v_mad_i32_i24 v55, v67, s46, v55
	s_waitcnt vmcnt(0)
	v_lshlrev_b32_e32 v68, 16, v60
	v_and_b32_e32 v69, 0xffff0000, v60
	v_pk_fma_f32 v[50:51], v[56:57], v[68:69], v[50:51]
	v_lshlrev_b32_e32 v60, 16, v61
	v_and_b32_e32 v61, 0xffff0000, v61
	v_mul_f32_e32 v56, 0x3d372713, v50
	v_mul_f32_e32 v57, 0x3d372713, v51
	v_pk_fma_f32 v[52:53], v[58:59], v[60:61], v[52:53]
	v_mul_f32_e32 v56, v50, v56
	v_mul_f32_e32 v57, v51, v57
	v_mul_f32_e32 v58, 0x3d372713, v52
	v_mul_f32_e32 v59, 0x3d372713, v53
	v_fma_f32 v56, v50, v56, v50
	v_fma_f32 v57, v51, v57, v51
	v_mul_f32_e32 v58, v52, v58
	v_mul_f32_e32 v59, v53, v59
	v_mul_f32_e32 v56, 0x3fcc422a, v56
	v_mul_f32_e32 v57, 0x3fcc422a, v57
	v_fma_f32 v58, v52, v58, v52
	v_fma_f32 v59, v53, v59, v53
	v_mul_f32_e32 v56, 0xbfb8aa3b, v56
	v_mul_f32_e32 v57, 0xbfb8aa3b, v57
	v_mul_f32_e32 v58, 0x3fcc422a, v58
	v_mul_f32_e32 v59, 0x3fcc422a, v59
	v_exp_f32_e32 v56, v56
	v_exp_f32_e32 v57, v57
	v_mul_f32_e32 v58, 0xbfb8aa3b, v58
	v_mul_f32_e32 v59, 0xbfb8aa3b, v59
	v_exp_f32_e32 v58, v58
	v_exp_f32_e32 v59, v59
	v_pk_add_f32 v[56:57], v[56:57], 1.0 op_sel_hi:[1,0]
	v_lshl_add_u64 v[60:61], v[64:65], 0, v[138:139]
	v_pk_add_f32 v[58:59], v[58:59], 1.0 op_sel_hi:[1,0]
	v_rcp_f32_e32 v57, v57
	v_rcp_f32_e32 v56, v56
	s_nop 0
	v_pk_mul_f32 v[50:51], v[50:51], v[56:57]
	v_rcp_f32_e32 v57, v59
	v_rcp_f32_e32 v56, v58
	s_nop 0
	v_pk_mul_f32 v[52:53], v[52:53], v[56:57]
	v_cvt_pk_bf16_f32 v50, v50, v51
	v_cvt_pk_bf16_f32 v51, v52, v53
	global_store_dwordx2 v[60:61], v[50:51], off
	global_load_dwordx2 v[52:53], v[54:55], off
	global_load_dwordx4 v[56:59], v[162:163], off
	v_lshlrev_b64 v[50:51], 15, v[62:63]
	v_lshl_add_u64 v[50:51], s[18:19], 0, v[50:51]
	v_lshl_add_u64 v[60:61], v[50:51], 0, s[10:11]
	s_waitcnt vmcnt(0)
; DI unsigned pk2(float lo, float hi) { f32x2 v = {lo, hi}; bf16x2_t b = __builtin_convertvector(v, bf16x2_t); return __builtin_bit_cast(unsigned, b); }
; DI float gelu_tanh(float x) { const float u = 1.5957691216057308f * (x + 0.044715f * x * x * x); return x * sigmoidf_(u); }
;     DI void operator()(const f32x4 (&acc)[2][2][4][2], const pg8::Unit& u, int wr, int wc, int fr, int fq) const {
;     ...
;             for (int m = 0; m < 4; ++m) { const int n = row0 + ai * 128 + m * 16;
; #pragma unroll
;                 for (int bj = 0; bj < 2; ++bj)
; #pragma unroll
;                     for (int nn = 0; nn < 2; ++nn) { const int col = col0 + bj * 128 + nn * 16, t = col >> 4, co = col & 15;
;                         const u32x2 uw = *(const u32x2*)(U2 + ((size_t)n * S5G + g) * S5K + col); const f32x4 d4 = *(const f32x4*)(D + g * 16 + co); const f32x4 v = acc[ai][bj][m][nn];
;                         const float y0 = gelu_tanh(v[0] + d4.x * bflo(uw.x)), y1 = gelu_tanh(v[1] + d4.y * bfhi(uw.x)), y2 = gelu_tanh(v[2] + d4.z * bflo(uw.y)), y3 = gelu_tanh(v[3] + d4.w * bfhi(uw.y));
;                         u32x2 w; w.x = pk2(y0, y1); w.y = pk2(y2, y3); *(u32x2*)(GG + ((size_t)n * S5T + t) * DM + g * 16 + co) = w; }
;                 asm volatile("" ::: "memory"); }
	v_lshlrev_b32_e32 v62, 16, v52
	v_and_b32_e32 v63, 0xffff0000, v52
	v_lshlrev_b32_e32 v52, 16, v53
	v_and_b32_e32 v53, 0xffff0000, v53
	v_pk_fma_f32 v[46:47], v[56:57], v[62:63], v[46:47]
	v_pk_fma_f32 v[48:49], v[58:59], v[52:53], v[48:49]
	v_mul_f32_e32 v52, 0x3d372713, v46
	v_mul_f32_e32 v53, 0x3d372713, v47
	v_mul_f32_e32 v52, v46, v52
	v_mul_f32_e32 v53, v47, v53
	v_mul_f32_e32 v56, 0x3d372713, v48
	v_mul_f32_e32 v57, 0x3d372713, v49
	v_fma_f32 v52, v46, v52, v46
	v_fma_f32 v53, v47, v53, v47
	v_mul_f32_e32 v56, v48, v56
	v_mul_f32_e32 v57, v49, v57
	v_mul_f32_e32 v52, 0x3fcc422a, v52
	v_mul_f32_e32 v53, 0x3fcc422a, v53
	v_fma_f32 v56, v48, v56, v48
	v_fma_f32 v57, v49, v57, v49
	v_mul_f32_e32 v52, 0xbfb8aa3b, v52
	v_mul_f32_e32 v53, 0xbfb8aa3b, v53
	v_mul_f32_e32 v56, 0x3fcc422a, v56
	v_mul_f32_e32 v57, 0x3fcc422a, v57
	v_exp_f32_e32 v52, v52
	v_exp_f32_e32 v53, v53
	v_mul_f32_e32 v56, 0xbfb8aa3b, v56
	v_mul_f32_e32 v57, 0xbfb8aa3b, v57
	v_exp_f32_e32 v56, v56
	v_exp_f32_e32 v57, v57
	v_pk_add_f32 v[52:53], v[52:53], 1.0 op_sel_hi:[1,0]
	v_lshl_add_u64 v[58:59], v[60:61], 0, s[34:35]
	v_pk_add_f32 v[56:57], v[56:57], 1.0 op_sel_hi:[1,0]
	v_rcp_f32_e32 v53, v53
	v_rcp_f32_e32 v52, v52
	s_nop 0
	v_pk_mul_f32 v[46:47], v[46:47], v[52:53]
	v_rcp_f32_e32 v53, v57
	v_rcp_f32_e32 v52, v56
	s_nop 0
	v_pk_mul_f32 v[48:49], v[48:49], v[52:53]
	v_lshl_add_u64 v[58:59], v[58:59], 0, v[138:139]
	v_cvt_pk_bf16_f32 v46, v46, v47
	v_cvt_pk_bf16_f32 v47, v48, v49
	global_store_dwordx2 v[58:59], v[46:47], off
	global_load_dwordx2 v[52:53], v[54:55], off offset:32
	s_nop 0
	global_load_dwordx4 v[46:49], v[162:163], off
	v_lshl_add_u64 v[56:57], v[50:51], 0, v[156:157]
	s_waitcnt vmcnt(0)
	v_lshlrev_b32_e32 v58, 16, v52
	v_and_b32_e32 v59, 0xffff0000, v52
	v_pk_fma_f32 v[42:43], v[46:47], v[58:59], v[42:43]
	v_lshlrev_b32_e32 v52, 16, v53
	v_and_b32_e32 v53, 0xffff0000, v53
	v_mul_f32_e32 v46, 0x3d372713, v42
	v_mul_f32_e32 v47, 0x3d372713, v43
	v_pk_fma_f32 v[44:45], v[48:49], v[52:53], v[44:45]
	v_mul_f32_e32 v46, v42, v46
	v_mul_f32_e32 v47, v43, v47
	v_mul_f32_e32 v48, 0x3d372713, v44
	v_mul_f32_e32 v49, 0x3d372713, v45
	v_fma_f32 v46, v42, v46, v42
	v_fma_f32 v47, v43, v47, v43
	v_mul_f32_e32 v48, v44, v48
	v_mul_f32_e32 v49, v45, v49
	v_mul_f32_e32 v46, 0x3fcc422a, v46
	v_mul_f32_e32 v47, 0x3fcc422a, v47
	v_fma_f32 v48, v44, v48, v44
	v_fma_f32 v49, v45, v49, v45
	v_mul_f32_e32 v46, 0xbfb8aa3b, v46
	v_mul_f32_e32 v47, 0xbfb8aa3b, v47
	v_mul_f32_e32 v48, 0x3fcc422a, v48
	v_mul_f32_e32 v49, 0x3fcc422a, v49
	v_exp_f32_e32 v46, v46
	v_exp_f32_e32 v47, v47
	v_mul_f32_e32 v48, 0xbfb8aa3b, v48
	v_mul_f32_e32 v49, 0xbfb8aa3b, v49
	v_exp_f32_e32 v48, v48
	v_exp_f32_e32 v49, v49
	v_pk_add_f32 v[46:47], v[46:47], 1.0 op_sel_hi:[1,0]
	v_lshl_add_u64 v[52:53], v[56:57], 0, s[34:35]
	v_pk_add_f32 v[48:49], v[48:49], 1.0 op_sel_hi:[1,0]
	v_rcp_f32_e32 v47, v47
	v_rcp_f32_e32 v46, v46
	s_nop 0
	v_pk_mul_f32 v[42:43], v[42:43], v[46:47]
	v_rcp_f32_e32 v47, v49
	v_rcp_f32_e32 v46, v48
	s_nop 0
	v_pk_mul_f32 v[44:45], v[44:45], v[46:47]
	v_lshl_add_u64 v[52:53], v[52:53], 0, v[138:139]
	v_cvt_pk_bf16_f32 v42, v42, v43
	v_cvt_pk_bf16_f32 v43, v44, v45
	global_store_dwordx2 v[52:53], v[42:43], off
	global_load_dwordx2 v[46:47], v[54:55], off offset:256
	s_nop 0
	global_load_dwordx4 v[42:45], v[162:163], off
	v_lshl_add_u64 v[48:49], v[50:51], 0, v[158:159]
	s_waitcnt vmcnt(0)
	v_lshlrev_b32_e32 v52, 16, v46
	v_and_b32_e32 v53, 0xffff0000, v46
	v_pk_fma_f32 v[38:39], v[42:43], v[52:53], v[38:39]
	v_lshlrev_b32_e32 v46, 16, v47
	v_and_b32_e32 v47, 0xffff0000, v47
	v_mul_f32_e32 v42, 0x3d372713, v38
	v_mul_f32_e32 v43, 0x3d372713, v39
	v_pk_fma_f32 v[40:41], v[44:45], v[46:47], v[40:41]
	v_mul_f32_e32 v42, v38, v42
	v_mul_f32_e32 v43, v39, v43
	v_mul_f32_e32 v44, 0x3d372713, v40
	v_mul_f32_e32 v45, 0x3d372713, v41
	v_fma_f32 v42, v38, v42, v38
	v_fma_f32 v43, v39, v43, v39
	v_mul_f32_e32 v44, v40, v44
	v_mul_f32_e32 v45, v41, v45
	v_mul_f32_e32 v42, 0x3fcc422a, v42
	v_mul_f32_e32 v43, 0x3fcc422a, v43
	v_fma_f32 v44, v40, v44, v40
	v_fma_f32 v45, v41, v45, v41
	v_mul_f32_e32 v42, 0xbfb8aa3b, v42
	v_mul_f32_e32 v43, 0xbfb8aa3b, v43
	v_mul_f32_e32 v44, 0x3fcc422a, v44
	v_mul_f32_e32 v45, 0x3fcc422a, v45
	v_exp_f32_e32 v42, v42
	v_exp_f32_e32 v43, v43
	v_mul_f32_e32 v44, 0xbfb8aa3b, v44
	v_mul_f32_e32 v45, 0xbfb8aa3b, v45
	v_exp_f32_e32 v44, v44
	v_exp_f32_e32 v45, v45
	v_pk_add_f32 v[42:43], v[42:43], 1.0 op_sel_hi:[1,0]
	v_lshl_add_u64 v[46:47], v[48:49], 0, s[34:35]
	v_pk_add_f32 v[44:45], v[44:45], 1.0 op_sel_hi:[1,0]
	v_rcp_f32_e32 v43, v43
	v_rcp_f32_e32 v42, v42
	s_nop 0
	v_pk_mul_f32 v[38:39], v[38:39], v[42:43]
	v_rcp_f32_e32 v43, v45
	v_rcp_f32_e32 v42, v44
	s_nop 0
	v_pk_mul_f32 v[40:41], v[40:41], v[42:43]
	v_lshl_add_u64 v[46:47], v[46:47], 0, v[138:139]
	v_cvt_pk_bf16_f32 v38, v38, v39
	v_cvt_pk_bf16_f32 v39, v40, v41
	global_store_dwordx2 v[46:47], v[38:39], off
	global_load_dwordx2 v[44:45], v[54:55], off offset:288
	global_load_dwordx4 v[40:43], v[162:163], off
	v_add_u32_e32 v46, 0xa0, v164
	v_ashrrev_i32_e32 v47, 31, v46
	v_lshl_add_u64 v[48:49], v[50:51], 0, v[160:161]
	v_lshlrev_b64 v[38:39], 6, v[46:47]
	v_lshl_add_u64 v[48:49], v[48:49], 0, s[34:35]
	v_lshl_add_u64 v[50:51], v[38:39], 0, s[36:37]
	v_mad_u64_u32 v[38:39], s[2:3], v50, s46, v[146:147]
	v_mad_i32_i24 v39, v51, s46, v39
	s_waitcnt vmcnt(0)
; DI unsigned pk2(float lo, float hi) { f32x2 v = {lo, hi}; bf16x2_t b = __builtin_convertvector(v, bf16x2_t); return __builtin_bit_cast(unsigned, b); }
; DI float gelu_tanh(float x) { const float u = 1.5957691216057308f * (x + 0.044715f * x * x * x); return x * sigmoidf_(u); }
;     DI void operator()(const f32x4 (&acc)[2][2][4][2], const pg8::Unit& u, int wr, int wc, int fr, int fq) const {
;     ...
;             for (int m = 0; m < 4; ++m) { const int n = row0 + ai * 128 + m * 16;
; #pragma unroll
;                 for (int bj = 0; bj < 2; ++bj)
; #pragma unroll
;                     for (int nn = 0; nn < 2; ++nn) { const int col = col0 + bj * 128 + nn * 16, t = col >> 4, co = col & 15;
;                         const u32x2 uw = *(const u32x2*)(U2 + ((size_t)n * S5G + g) * S5K + col); const f32x4 d4 = *(const f32x4*)(D + g * 16 + co); const f32x4 v = acc[ai][bj][m][nn];
;                         const float y0 = gelu_tanh(v[0] + d4.x * bflo(uw.x)), y1 = gelu_tanh(v[1] + d4.y * bfhi(uw.x)), y2 = gelu_tanh(v[2] + d4.z * bflo(uw.y)), y3 = gelu_tanh(v[3] + d4.w * bfhi(uw.y));
;                         u32x2 w; w.x = pk2(y0, y1); w.y = pk2(y2, y3); *(u32x2*)(GG + ((size_t)n * S5T + t) * DM + g * 16 + co) = w; }
;                 asm volatile("" ::: "memory"); }
	v_lshlrev_b32_e32 v52, 16, v44
	v_and_b32_e32 v53, 0xffff0000, v44
	v_pk_fma_f32 v[34:35], v[40:41], v[52:53], v[34:35]
	v_lshlrev_b32_e32 v44, 16, v45
	v_and_b32_e32 v45, 0xffff0000, v45
	v_mul_f32_e32 v40, 0x3d372713, v34
	v_mul_f32_e32 v41, 0x3d372713, v35
	v_pk_fma_f32 v[36:37], v[42:43], v[44:45], v[36:37]
	v_mul_f32_e32 v40, v34, v40
	v_mul_f32_e32 v41, v35, v41
	v_mul_f32_e32 v42, 0x3d372713, v36
	v_mul_f32_e32 v43, 0x3d372713, v37
	v_fma_f32 v40, v34, v40, v34
	v_fma_f32 v41, v35, v41, v35
	v_mul_f32_e32 v42, v36, v42
	v_mul_f32_e32 v43, v37, v43
	v_mul_f32_e32 v40, 0x3fcc422a, v40
	v_mul_f32_e32 v41, 0x3fcc422a, v41
	v_fma_f32 v42, v36, v42, v36
	v_fma_f32 v43, v37, v43, v37
	v_mul_f32_e32 v40, 0xbfb8aa3b, v40
	v_mul_f32_e32 v41, 0xbfb8aa3b, v41
	v_mul_f32_e32 v42, 0x3fcc422a, v42
	v_mul_f32_e32 v43, 0x3fcc422a, v43
	v_exp_f32_e32 v40, v40
	v_exp_f32_e32 v41, v41
	v_mul_f32_e32 v42, 0xbfb8aa3b, v42
	v_mul_f32_e32 v43, 0xbfb8aa3b, v43
	v_exp_f32_e32 v42, v42
	v_exp_f32_e32 v43, v43
	v_pk_add_f32 v[40:41], v[40:41], 1.0 op_sel_hi:[1,0]
	v_lshl_add_u64 v[44:45], v[48:49], 0, v[138:139]
	v_pk_add_f32 v[42:43], v[42:43], 1.0 op_sel_hi:[1,0]
	v_rcp_f32_e32 v41, v41
	v_rcp_f32_e32 v40, v40
	s_nop 0
	v_pk_mul_f32 v[34:35], v[34:35], v[40:41]
	v_rcp_f32_e32 v41, v43
	v_rcp_f32_e32 v40, v42
	s_nop 0
	v_pk_mul_f32 v[36:37], v[36:37], v[40:41]
	v_cvt_pk_bf16_f32 v34, v34, v35
	v_cvt_pk_bf16_f32 v35, v36, v37
	global_store_dwordx2 v[44:45], v[34:35], off
	global_load_dwordx2 v[36:37], v[38:39], off
	global_load_dwordx4 v[40:43], v[162:163], off
	v_lshlrev_b64 v[34:35], 15, v[46:47]
	v_lshl_add_u64 v[34:35], s[18:19], 0, v[34:35]
	v_lshl_add_u64 v[44:45], v[34:35], 0, s[10:11]
	s_waitcnt vmcnt(0)
	v_lshlrev_b32_e32 v46, 16, v36
	v_and_b32_e32 v47, 0xffff0000, v36
	v_lshlrev_b32_e32 v36, 16, v37
	v_and_b32_e32 v37, 0xffff0000, v37
	v_pk_fma_f32 v[30:31], v[40:41], v[46:47], v[30:31]
	v_pk_fma_f32 v[32:33], v[42:43], v[36:37], v[32:33]
	v_mul_f32_e32 v36, 0x3d372713, v30
	v_mul_f32_e32 v37, 0x3d372713, v31
	v_mul_f32_e32 v36, v30, v36
	v_mul_f32_e32 v37, v31, v37
	v_mul_f32_e32 v40, 0x3d372713, v32
	v_mul_f32_e32 v41, 0x3d372713, v33
	v_fma_f32 v36, v30, v36, v30
	v_fma_f32 v37, v31, v37, v31
	v_mul_f32_e32 v40, v32, v40
	v_mul_f32_e32 v41, v33, v41
	v_mul_f32_e32 v36, 0x3fcc422a, v36
	v_mul_f32_e32 v37, 0x3fcc422a, v37
	v_fma_f32 v40, v32, v40, v32
	v_fma_f32 v41, v33, v41, v33
	v_mul_f32_e32 v36, 0xbfb8aa3b, v36
	v_mul_f32_e32 v37, 0xbfb8aa3b, v37
	v_mul_f32_e32 v40, 0x3fcc422a, v40
	v_mul_f32_e32 v41, 0x3fcc422a, v41
	v_exp_f32_e32 v36, v36
	v_exp_f32_e32 v37, v37
	v_mul_f32_e32 v40, 0xbfb8aa3b, v40
	v_mul_f32_e32 v41, 0xbfb8aa3b, v41
	v_exp_f32_e32 v40, v40
	v_exp_f32_e32 v41, v41
	v_pk_add_f32 v[36:37], v[36:37], 1.0 op_sel_hi:[1,0]
	v_lshl_add_u64 v[42:43], v[44:45], 0, s[34:35]
	v_pk_add_f32 v[40:41], v[40:41], 1.0 op_sel_hi:[1,0]
	v_rcp_f32_e32 v37, v37
	v_rcp_f32_e32 v36, v36
	s_nop 0
	v_pk_mul_f32 v[30:31], v[30:31], v[36:37]
	v_rcp_f32_e32 v37, v41
	v_rcp_f32_e32 v36, v40
	s_nop 0
	v_pk_mul_f32 v[32:33], v[32:33], v[36:37]
	v_lshl_add_u64 v[42:43], v[42:43], 0, v[138:139]
	v_cvt_pk_bf16_f32 v30, v30, v31
	v_cvt_pk_bf16_f32 v31, v32, v33
	global_store_dwordx2 v[42:43], v[30:31], off
	global_load_dwordx2 v[36:37], v[38:39], off offset:32
	s_nop 0
	global_load_dwordx4 v[30:33], v[162:163], off
	v_lshl_add_u64 v[40:41], v[34:35], 0, v[156:157]
	s_waitcnt vmcnt(0)
	v_lshlrev_b32_e32 v42, 16, v36
	v_and_b32_e32 v43, 0xffff0000, v36
	v_pk_fma_f32 v[26:27], v[30:31], v[42:43], v[26:27]
	v_lshlrev_b32_e32 v36, 16, v37
	v_and_b32_e32 v37, 0xffff0000, v37
	v_mul_f32_e32 v30, 0x3d372713, v26
	v_mul_f32_e32 v31, 0x3d372713, v27
	v_pk_fma_f32 v[28:29], v[32:33], v[36:37], v[28:29]
	v_mul_f32_e32 v30, v26, v30
	v_mul_f32_e32 v31, v27, v31
	v_mul_f32_e32 v32, 0x3d372713, v28
	v_mul_f32_e32 v33, 0x3d372713, v29
	v_fma_f32 v30, v26, v30, v26
	v_fma_f32 v31, v27, v31, v27
	v_mul_f32_e32 v32, v28, v32
	v_mul_f32_e32 v33, v29, v33
	v_mul_f32_e32 v30, 0x3fcc422a, v30
	v_mul_f32_e32 v31, 0x3fcc422a, v31
	v_fma_f32 v32, v28, v32, v28
	v_fma_f32 v33, v29, v33, v29
	v_mul_f32_e32 v30, 0xbfb8aa3b, v30
	v_mul_f32_e32 v31, 0xbfb8aa3b, v31
	v_mul_f32_e32 v32, 0x3fcc422a, v32
	v_mul_f32_e32 v33, 0x3fcc422a, v33
	v_exp_f32_e32 v30, v30
	v_exp_f32_e32 v31, v31
	v_mul_f32_e32 v32, 0xbfb8aa3b, v32
	v_mul_f32_e32 v33, 0xbfb8aa3b, v33
	v_exp_f32_e32 v32, v32
	v_exp_f32_e32 v33, v33
	v_pk_add_f32 v[30:31], v[30:31], 1.0 op_sel_hi:[1,0]
	v_lshl_add_u64 v[36:37], v[40:41], 0, s[34:35]
	v_pk_add_f32 v[32:33], v[32:33], 1.0 op_sel_hi:[1,0]
	v_rcp_f32_e32 v31, v31
	v_rcp_f32_e32 v30, v30
	s_nop 0
	v_pk_mul_f32 v[26:27], v[26:27], v[30:31]
	v_rcp_f32_e32 v31, v33
	v_rcp_f32_e32 v30, v32
	s_nop 0
	v_pk_mul_f32 v[28:29], v[28:29], v[30:31]
	v_lshl_add_u64 v[36:37], v[36:37], 0, v[138:139]
	v_cvt_pk_bf16_f32 v26, v26, v27
	v_cvt_pk_bf16_f32 v27, v28, v29
	global_store_dwordx2 v[36:37], v[26:27], off
	global_load_dwordx2 v[30:31], v[38:39], off offset:256
	s_nop 0
	global_load_dwordx4 v[26:29], v[162:163], off
	v_lshl_add_u64 v[32:33], v[34:35], 0, v[158:159]
	s_waitcnt vmcnt(0)
; DI unsigned pk2(float lo, float hi) { f32x2 v = {lo, hi}; bf16x2_t b = __builtin_convertvector(v, bf16x2_t); return __builtin_bit_cast(unsigned, b); }
; DI float gelu_tanh(float x) { const float u = 1.5957691216057308f * (x + 0.044715f * x * x * x); return x * sigmoidf_(u); }
;     DI void operator()(const f32x4 (&acc)[2][2][4][2], const pg8::Unit& u, int wr, int wc, int fr, int fq) const {
;     ...
;             for (int m = 0; m < 4; ++m) { const int n = row0 + ai * 128 + m * 16;
; #pragma unroll
;                 for (int bj = 0; bj < 2; ++bj)
; #pragma unroll
;                     for (int nn = 0; nn < 2; ++nn) { const int col = col0 + bj * 128 + nn * 16, t = col >> 4, co = col & 15;
;                         const u32x2 uw = *(const u32x2*)(U2 + ((size_t)n * S5G + g) * S5K + col); const f32x4 d4 = *(const f32x4*)(D + g * 16 + co); const f32x4 v = acc[ai][bj][m][nn];
;                         const float y0 = gelu_tanh(v[0] + d4.x * bflo(uw.x)), y1 = gelu_tanh(v[1] + d4.y * bfhi(uw.x)), y2 = gelu_tanh(v[2] + d4.z * bflo(uw.y)), y3 = gelu_tanh(v[3] + d4.w * bfhi(uw.y));
;                         u32x2 w; w.x = pk2(y0, y1); w.y = pk2(y2, y3); *(u32x2*)(GG + ((size_t)n * S5T + t) * DM + g * 16 + co) = w; }
;                 asm volatile("" ::: "memory"); }
	v_lshlrev_b32_e32 v36, 16, v30
	v_and_b32_e32 v37, 0xffff0000, v30
	v_pk_fma_f32 v[22:23], v[26:27], v[36:37], v[22:23]
	v_lshlrev_b32_e32 v30, 16, v31
	v_and_b32_e32 v31, 0xffff0000, v31
	v_mul_f32_e32 v26, 0x3d372713, v22
	v_mul_f32_e32 v27, 0x3d372713, v23
	v_pk_fma_f32 v[24:25], v[28:29], v[30:31], v[24:25]
	v_mul_f32_e32 v26, v22, v26
	v_mul_f32_e32 v27, v23, v27
	v_mul_f32_e32 v28, 0x3d372713, v24
	v_mul_f32_e32 v29, 0x3d372713, v25
	v_fma_f32 v26, v22, v26, v22
	v_fma_f32 v27, v23, v27, v23
	v_mul_f32_e32 v28, v24, v28
	v_mul_f32_e32 v29, v25, v29
	v_mul_f32_e32 v26, 0x3fcc422a, v26
	v_mul_f32_e32 v27, 0x3fcc422a, v27
	v_fma_f32 v28, v24, v28, v24
	v_fma_f32 v29, v25, v29, v25
	v_mul_f32_e32 v26, 0xbfb8aa3b, v26
	v_mul_f32_e32 v27, 0xbfb8aa3b, v27
	v_mul_f32_e32 v28, 0x3fcc422a, v28
	v_mul_f32_e32 v29, 0x3fcc422a, v29
	v_exp_f32_e32 v26, v26
	v_exp_f32_e32 v27, v27
	v_mul_f32_e32 v28, 0xbfb8aa3b, v28
	v_mul_f32_e32 v29, 0xbfb8aa3b, v29
	v_exp_f32_e32 v28, v28
	v_exp_f32_e32 v29, v29
	v_pk_add_f32 v[26:27], v[26:27], 1.0 op_sel_hi:[1,0]
	v_lshl_add_u64 v[30:31], v[32:33], 0, s[34:35]
	v_pk_add_f32 v[28:29], v[28:29], 1.0 op_sel_hi:[1,0]
	v_rcp_f32_e32 v27, v27
	v_rcp_f32_e32 v26, v26
	s_nop 0
	v_pk_mul_f32 v[22:23], v[22:23], v[26:27]
	v_rcp_f32_e32 v27, v29
	v_rcp_f32_e32 v26, v28
	s_nop 0
	v_pk_mul_f32 v[24:25], v[24:25], v[26:27]
	v_lshl_add_u64 v[30:31], v[30:31], 0, v[138:139]
	v_cvt_pk_bf16_f32 v22, v22, v23
	v_cvt_pk_bf16_f32 v23, v24, v25
	global_store_dwordx2 v[30:31], v[22:23], off
	global_load_dwordx2 v[28:29], v[38:39], off offset:288
	global_load_dwordx4 v[24:27], v[162:163], off
	v_add_u32_e32 v30, 0xb0, v164
	v_ashrrev_i32_e32 v31, 31, v30
	v_lshl_add_u64 v[32:33], v[34:35], 0, v[160:161]
	v_lshlrev_b64 v[22:23], 6, v[30:31]
	v_lshl_add_u64 v[32:33], v[32:33], 0, s[34:35]
	v_lshl_add_u64 v[34:35], v[22:23], 0, s[36:37]
	v_mad_u64_u32 v[22:23], s[2:3], v34, s46, v[146:147]
	v_mad_i32_i24 v23, v35, s46, v23
	s_waitcnt vmcnt(0)
	v_lshlrev_b32_e32 v36, 16, v28
	v_and_b32_e32 v37, 0xffff0000, v28
	v_pk_fma_f32 v[18:19], v[24:25], v[36:37], v[18:19]
	v_lshlrev_b32_e32 v28, 16, v29
	v_and_b32_e32 v29, 0xffff0000, v29
	v_mul_f32_e32 v24, 0x3d372713, v18
	v_mul_f32_e32 v25, 0x3d372713, v19
	v_pk_fma_f32 v[20:21], v[26:27], v[28:29], v[20:21]
	v_mul_f32_e32 v24, v18, v24
	v_mul_f32_e32 v25, v19, v25
	v_mul_f32_e32 v26, 0x3d372713, v20
	v_mul_f32_e32 v27, 0x3d372713, v21
	v_fma_f32 v24, v18, v24, v18
	v_fma_f32 v25, v19, v25, v19
	v_mul_f32_e32 v26, v20, v26
	v_mul_f32_e32 v27, v21, v27
	v_mul_f32_e32 v24, 0x3fcc422a, v24
	v_mul_f32_e32 v25, 0x3fcc422a, v25
	v_fma_f32 v26, v20, v26, v20
	v_fma_f32 v27, v21, v27, v21
	v_mul_f32_e32 v24, 0xbfb8aa3b, v24
	v_mul_f32_e32 v25, 0xbfb8aa3b, v25
	v_mul_f32_e32 v26, 0x3fcc422a, v26
	v_mul_f32_e32 v27, 0x3fcc422a, v27
	v_exp_f32_e32 v24, v24
	v_exp_f32_e32 v25, v25
	v_mul_f32_e32 v26, 0xbfb8aa3b, v26
	v_mul_f32_e32 v27, 0xbfb8aa3b, v27
	v_exp_f32_e32 v26, v26
	v_exp_f32_e32 v27, v27
	v_pk_add_f32 v[24:25], v[24:25], 1.0 op_sel_hi:[1,0]
	v_lshl_add_u64 v[28:29], v[32:33], 0, v[138:139]
	v_pk_add_f32 v[26:27], v[26:27], 1.0 op_sel_hi:[1,0]
	v_rcp_f32_e32 v25, v25
	v_rcp_f32_e32 v24, v24
	s_nop 0
	v_pk_mul_f32 v[18:19], v[18:19], v[24:25]
	v_rcp_f32_e32 v25, v27
	v_rcp_f32_e32 v24, v26
	s_nop 0
	v_pk_mul_f32 v[20:21], v[20:21], v[24:25]
	v_cvt_pk_bf16_f32 v18, v18, v19
	v_cvt_pk_bf16_f32 v19, v20, v21
	global_store_dwordx2 v[28:29], v[18:19], off
	global_load_dwordx2 v[20:21], v[22:23], off
	global_load_dwordx4 v[24:27], v[162:163], off
	v_lshlrev_b64 v[18:19], 15, v[30:31]
	v_lshl_add_u64 v[18:19], s[18:19], 0, v[18:19]
	v_lshl_add_u64 v[28:29], v[18:19], 0, s[10:11]
	s_waitcnt vmcnt(0)
	v_lshlrev_b32_e32 v30, 16, v20
	v_and_b32_e32 v31, 0xffff0000, v20
	v_lshlrev_b32_e32 v20, 16, v21
	v_and_b32_e32 v21, 0xffff0000, v21
	v_pk_fma_f32 v[14:15], v[24:25], v[30:31], v[14:15]
	v_pk_fma_f32 v[16:17], v[26:27], v[20:21], v[16:17]
	v_mul_f32_e32 v20, 0x3d372713, v14
	v_mul_f32_e32 v21, 0x3d372713, v15
	v_mul_f32_e32 v20, v14, v20
	v_mul_f32_e32 v21, v15, v21
	v_mul_f32_e32 v24, 0x3d372713, v16
	v_mul_f32_e32 v25, 0x3d372713, v17
	v_fma_f32 v20, v14, v20, v14
	v_fma_f32 v21, v15, v21, v15
	v_mul_f32_e32 v24, v16, v24
	v_mul_f32_e32 v25, v17, v25
	v_mul_f32_e32 v20, 0x3fcc422a, v20
	v_mul_f32_e32 v21, 0x3fcc422a, v21
	v_fma_f32 v24, v16, v24, v16
	v_fma_f32 v25, v17, v25, v17
	v_mul_f32_e32 v20, 0xbfb8aa3b, v20
	v_mul_f32_e32 v21, 0xbfb8aa3b, v21
	v_mul_f32_e32 v24, 0x3fcc422a, v24
	v_mul_f32_e32 v25, 0x3fcc422a, v25
	v_exp_f32_e32 v20, v20
	v_exp_f32_e32 v21, v21
	v_mul_f32_e32 v24, 0xbfb8aa3b, v24
	v_mul_f32_e32 v25, 0xbfb8aa3b, v25
	v_exp_f32_e32 v24, v24
	v_exp_f32_e32 v25, v25
	v_pk_add_f32 v[20:21], v[20:21], 1.0 op_sel_hi:[1,0]
	v_lshl_add_u64 v[26:27], v[28:29], 0, s[34:35]
	v_pk_add_f32 v[24:25], v[24:25], 1.0 op_sel_hi:[1,0]
	v_rcp_f32_e32 v21, v21
	v_rcp_f32_e32 v20, v20
	s_nop 0
	v_pk_mul_f32 v[14:15], v[14:15], v[20:21]
	v_rcp_f32_e32 v21, v25
	v_rcp_f32_e32 v20, v24
	s_nop 0
	v_pk_mul_f32 v[16:17], v[16:17], v[20:21]
	v_lshl_add_u64 v[26:27], v[26:27], 0, v[138:139]
	v_cvt_pk_bf16_f32 v14, v14, v15
	v_cvt_pk_bf16_f32 v15, v16, v17
	global_store_dwordx2 v[26:27], v[14:15], off
	global_load_dwordx2 v[20:21], v[22:23], off offset:32
	s_nop 0
	global_load_dwordx4 v[14:17], v[162:163], off
	v_lshl_add_u64 v[24:25], v[18:19], 0, v[156:157]
	s_waitcnt vmcnt(0)
; DI unsigned pk2(float lo, float hi) { f32x2 v = {lo, hi}; bf16x2_t b = __builtin_convertvector(v, bf16x2_t); return __builtin_bit_cast(unsigned, b); }
; DI float gelu_tanh(float x) { const float u = 1.5957691216057308f * (x + 0.044715f * x * x * x); return x * sigmoidf_(u); }
;     DI void operator()(const f32x4 (&acc)[2][2][4][2], const pg8::Unit& u, int wr, int wc, int fr, int fq) const {
;     ...
;             for (int m = 0; m < 4; ++m) { const int n = row0 + ai * 128 + m * 16;
; #pragma unroll
;                 for (int bj = 0; bj < 2; ++bj)
; #pragma unroll
;                     for (int nn = 0; nn < 2; ++nn) { const int col = col0 + bj * 128 + nn * 16, t = col >> 4, co = col & 15;
;                         const u32x2 uw = *(const u32x2*)(U2 + ((size_t)n * S5G + g) * S5K + col); const f32x4 d4 = *(const f32x4*)(D + g * 16 + co); const f32x4 v = acc[ai][bj][m][nn];
;                         const float y0 = gelu_tanh(v[0] + d4.x * bflo(uw.x)), y1 = gelu_tanh(v[1] + d4.y * bfhi(uw.x)), y2 = gelu_tanh(v[2] + d4.z * bflo(uw.y)), y3 = gelu_tanh(v[3] + d4.w * bfhi(uw.y));
;                         u32x2 w; w.x = pk2(y0, y1); w.y = pk2(y2, y3); *(u32x2*)(GG + ((size_t)n * S5T + t) * DM + g * 16 + co) = w; }
;                 asm volatile("" ::: "memory"); }
	v_lshlrev_b32_e32 v26, 16, v20
	v_and_b32_e32 v27, 0xffff0000, v20
	v_pk_fma_f32 v[10:11], v[14:15], v[26:27], v[10:11]
	v_lshlrev_b32_e32 v20, 16, v21
	v_and_b32_e32 v21, 0xffff0000, v21
	v_mul_f32_e32 v14, 0x3d372713, v10
	v_mul_f32_e32 v15, 0x3d372713, v11
	v_pk_fma_f32 v[12:13], v[16:17], v[20:21], v[12:13]
	v_mul_f32_e32 v14, v10, v14
	v_mul_f32_e32 v15, v11, v15
	v_mul_f32_e32 v16, 0x3d372713, v12
	v_mul_f32_e32 v17, 0x3d372713, v13
	v_fma_f32 v14, v10, v14, v10
	v_fma_f32 v15, v11, v15, v11
	v_mul_f32_e32 v16, v12, v16
	v_mul_f32_e32 v17, v13, v17
	v_mul_f32_e32 v14, 0x3fcc422a, v14
	v_mul_f32_e32 v15, 0x3fcc422a, v15
	v_fma_f32 v16, v12, v16, v12
	v_fma_f32 v17, v13, v17, v13
	v_mul_f32_e32 v14, 0xbfb8aa3b, v14
	v_mul_f32_e32 v15, 0xbfb8aa3b, v15
	v_mul_f32_e32 v16, 0x3fcc422a, v16
	v_mul_f32_e32 v17, 0x3fcc422a, v17
	v_exp_f32_e32 v14, v14
	v_exp_f32_e32 v15, v15
	v_mul_f32_e32 v16, 0xbfb8aa3b, v16
	v_mul_f32_e32 v17, 0xbfb8aa3b, v17
	v_exp_f32_e32 v16, v16
	v_exp_f32_e32 v17, v17
	v_pk_add_f32 v[14:15], v[14:15], 1.0 op_sel_hi:[1,0]
	v_lshl_add_u64 v[20:21], v[24:25], 0, s[34:35]
	v_pk_add_f32 v[16:17], v[16:17], 1.0 op_sel_hi:[1,0]
	v_rcp_f32_e32 v15, v15
	v_rcp_f32_e32 v14, v14
	s_nop 0
	v_pk_mul_f32 v[10:11], v[10:11], v[14:15]
	v_rcp_f32_e32 v15, v17
	v_rcp_f32_e32 v14, v16
	s_nop 0
	v_pk_mul_f32 v[12:13], v[12:13], v[14:15]
	v_lshl_add_u64 v[20:21], v[20:21], 0, v[138:139]
	v_cvt_pk_bf16_f32 v10, v10, v11
	v_cvt_pk_bf16_f32 v11, v12, v13
	global_store_dwordx2 v[20:21], v[10:11], off
	global_load_dwordx2 v[14:15], v[22:23], off offset:256
	s_nop 0
	global_load_dwordx4 v[10:13], v[162:163], off
	v_lshl_add_u64 v[16:17], v[18:19], 0, v[158:159]
	s_waitcnt vmcnt(0)
	v_lshlrev_b32_e32 v20, 16, v14
	v_and_b32_e32 v21, 0xffff0000, v14
	v_pk_fma_f32 v[6:7], v[10:11], v[20:21], v[6:7]
	v_lshlrev_b32_e32 v14, 16, v15
	v_and_b32_e32 v15, 0xffff0000, v15
	v_mul_f32_e32 v10, 0x3d372713, v6
	v_mul_f32_e32 v11, 0x3d372713, v7
	v_pk_fma_f32 v[8:9], v[12:13], v[14:15], v[8:9]
	v_mul_f32_e32 v10, v6, v10
	v_mul_f32_e32 v11, v7, v11
	v_mul_f32_e32 v12, 0x3d372713, v8
	v_mul_f32_e32 v13, 0x3d372713, v9
	v_fma_f32 v10, v6, v10, v6
	v_fma_f32 v11, v7, v11, v7
	v_mul_f32_e32 v12, v8, v12
	v_mul_f32_e32 v13, v9, v13
	v_mul_f32_e32 v10, 0x3fcc422a, v10
	v_mul_f32_e32 v11, 0x3fcc422a, v11
	v_fma_f32 v12, v8, v12, v8
	v_fma_f32 v13, v9, v13, v9
	v_mul_f32_e32 v10, 0xbfb8aa3b, v10
	v_mul_f32_e32 v11, 0xbfb8aa3b, v11
	v_mul_f32_e32 v12, 0x3fcc422a, v12
	v_mul_f32_e32 v13, 0x3fcc422a, v13
	v_exp_f32_e32 v10, v10
	v_exp_f32_e32 v11, v11
	v_mul_f32_e32 v12, 0xbfb8aa3b, v12
	v_mul_f32_e32 v13, 0xbfb8aa3b, v13
	v_exp_f32_e32 v12, v12
	v_exp_f32_e32 v13, v13
	v_pk_add_f32 v[10:11], v[10:11], 1.0 op_sel_hi:[1,0]
	v_lshl_add_u64 v[14:15], v[16:17], 0, s[34:35]
	v_pk_add_f32 v[12:13], v[12:13], 1.0 op_sel_hi:[1,0]
	v_rcp_f32_e32 v11, v11
	v_rcp_f32_e32 v10, v10
	s_nop 0
	v_pk_mul_f32 v[6:7], v[6:7], v[10:11]
	v_rcp_f32_e32 v11, v13
	v_rcp_f32_e32 v10, v12
	s_nop 0
	v_pk_mul_f32 v[8:9], v[8:9], v[10:11]
	v_lshl_add_u64 v[14:15], v[14:15], 0, v[138:139]
	v_cvt_pk_bf16_f32 v6, v6, v7
	v_cvt_pk_bf16_f32 v7, v8, v9
	global_store_dwordx2 v[14:15], v[6:7], off
	global_load_dwordx2 v[10:11], v[22:23], off offset:288
	s_nop 0
	global_load_dwordx4 v[6:9], v[162:163], off
	s_waitcnt vmcnt(0)
	v_lshlrev_b32_e32 v12, 16, v10
	v_and_b32_e32 v13, 0xffff0000, v10
	v_pk_fma_f32 v[2:3], v[6:7], v[12:13], v[2:3]
	v_lshlrev_b32_e32 v10, 16, v11
	v_and_b32_e32 v11, 0xffff0000, v11
	v_mul_f32_e32 v6, 0x3d372713, v2
	v_mul_f32_e32 v7, 0x3d372713, v3
	v_pk_fma_f32 v[4:5], v[8:9], v[10:11], v[4:5]
	v_mul_f32_e32 v6, v2, v6
	v_mul_f32_e32 v7, v3, v7
	v_mul_f32_e32 v8, 0x3d372713, v4
	v_mul_f32_e32 v9, 0x3d372713, v5
	v_fma_f32 v6, v2, v6, v2
	v_fma_f32 v7, v3, v7, v3
	v_mul_f32_e32 v8, v4, v8
	v_mul_f32_e32 v9, v5, v9
	v_mul_f32_e32 v6, 0x3fcc422a, v6
	v_mul_f32_e32 v7, 0x3fcc422a, v7
	v_fma_f32 v8, v4, v8, v4
	v_fma_f32 v9, v5, v9, v5
	v_mul_f32_e32 v6, 0xbfb8aa3b, v6
	v_mul_f32_e32 v7, 0xbfb8aa3b, v7
	v_mul_f32_e32 v8, 0x3fcc422a, v8
	v_mul_f32_e32 v9, 0x3fcc422a, v9
	v_exp_f32_e32 v6, v6
	v_exp_f32_e32 v7, v7
	v_mul_f32_e32 v8, 0xbfb8aa3b, v8
	v_mul_f32_e32 v9, 0xbfb8aa3b, v9
	v_exp_f32_e32 v8, v8
	v_exp_f32_e32 v9, v9
	v_pk_add_f32 v[6:7], v[6:7], 1.0 op_sel_hi:[1,0]
	v_lshl_add_u64 v[10:11], v[18:19], 0, v[160:161]
	v_pk_add_f32 v[8:9], v[8:9], 1.0 op_sel_hi:[1,0]
	v_rcp_f32_e32 v7, v7
	v_rcp_f32_e32 v6, v6
	s_nop 0
	v_pk_mul_f32 v[2:3], v[2:3], v[6:7]
	v_rcp_f32_e32 v7, v9
	v_rcp_f32_e32 v6, v8
	v_lshl_add_u64 v[10:11], v[10:11], 0, s[34:35]
	v_pk_mul_f32 v[4:5], v[4:5], v[6:7]
	v_cvt_pk_bf16_f32 v2, v2, v3
	v_cvt_pk_bf16_f32 v3, v4, v5
	v_lshl_add_u64 v[4:5], v[10:11], 0, v[138:139]
	global_store_dwordx2 v[4:5], v[2:3], off
	s_and_b64 vcc, exec, s[0:1]
	s_mov_b64 s[0:1], -1
	s_cbranch_vccnz .LBB0_1667
	s_andn2_b64 vcc, exec, s[12:13]
	s_cbranch_vccnz .LBB0_1666
	s_barrier
	s_branch .LBB0_1666

; DI unsigned pk2(float lo, float hi) { f32x2 v = {lo, hi}; bf16x2_t b = __builtin_convertvector(v, bf16x2_t); return __builtin_bit_cast(unsigned, b); }
; DI float sigmoidf_(float x) { return 1.f / (1.f + __expf(-x)); }
;     DI void operator()(const f32x4 (&acc)[2][2][4][2], const Unit& u, int wr, int wc, int fr, int fq) const {
;     ...
;             for (int m = 0; m < 4; ++m) { const int row = row0 + ai * HALF + m * 16; float s = 0.f;
; #pragma unroll
;                 for (int n = 0; n < 2; ++n) { const int col = col0 + n * 16; const f32x4 v = acc[ai][0][m][n], gt = acc[ai][1][m][n];
;                     const u32x2 bw = *(const u32x2*)(baseb + (size_t)row * DM + col); f32x4 h = {bflo(bw.x), bfhi(bw.x), bflo(bw.y), bfhi(bw.y)};
; #pragma unroll
;                     for (int j = 0; j < 4; ++j) h[j] += v[j] * sigmoidf_(gt[j]);
;                     u32x2 w; w.x = pk2(h[0], h[1]); w.y = pk2(h[2], h[3]); *(u32x2*)(XB + (size_t)row * DM + col) = w;
;                     s += (h[0] * h[0] + h[1] * h[1]) + (h[2] * h[2] + h[3] * h[3]); }
;                 s += __shfl_xor(s, 16); s += __shfl_xor(s, 32); if (fq == 0) atomicAdd(ssout + row, s); }
.LBB0_1755:
	v_lshl_add_u32 v148, s4, 8, v1
	v_lshl_or_b32 v146, s6, 7, v143
	v_ashrrev_i32_e32 v149, 31, v148
	v_lshlrev_b64 v[150:151], 11, v[148:149]
	v_ashrrev_i32_e32 v147, 31, v146
	v_lshl_add_u64 v[156:157], s[14:15], 0, v[150:151]
	v_lshlrev_b64 v[146:147], 1, v[146:147]
	v_lshl_add_u64 v[156:157], v[156:157], 0, v[146:147]
	global_load_dwordx2 v[158:159], v[156:157], off
	v_mul_f32_e32 v126, 0xbfb8aa3b, v126
	global_load_dwordx2 v[156:157], v[156:157], off offset:32
	v_mul_f32_e32 v127, 0xbfb8aa3b, v127
	v_and_b32_e32 v160, 64, v155
	v_mul_f32_e32 v161, 0xbfb8aa3b, v128
	v_mul_f32_e32 v164, 0xbfb8aa3b, v129
	v_exp_f32_e32 v128, v126
	v_exp_f32_e32 v129, v127
	v_xor_b32_e32 v162, 16, v155
	v_add_u32_e32 v165, 64, v160
	v_xor_b32_e32 v163, 32, v155
	v_exp_f32_e32 v160, v161
	v_exp_f32_e32 v161, v164
	v_cmp_lt_i32_e32 vcc, v162, v165
	v_pk_add_f32 v[128:129], v[128:129], 1.0 op_sel_hi:[1,0]
	v_mul_f32_e32 v118, 0xbfb8aa3b, v118
	v_cndmask_b32_e32 v126, v155, v162, vcc
	v_cmp_lt_i32_e32 vcc, v163, v165
	v_lshlrev_b32_e32 v127, 2, v126
	v_pk_add_f32 v[160:161], v[160:161], 1.0 op_sel_hi:[1,0]
	v_cndmask_b32_e32 v162, v155, v163, vcc
	v_lshlrev_b32_e32 v126, 2, v162
	v_mul_f32_e32 v119, 0xbfb8aa3b, v119
	v_exp_f32_e32 v118, v118
	v_exp_f32_e32 v119, v119
	v_rcp_f32_e32 v129, v129
	v_rcp_f32_e32 v128, v128
	v_rcp_f32_e32 v161, v161
	v_pk_add_f32 v[118:119], v[118:119], 1.0 op_sel_hi:[1,0]
	v_mul_f32_e32 v120, 0xbfb8aa3b, v120
	s_waitcnt vmcnt(0)
	v_lshlrev_b32_e32 v162, 16, v158
	v_and_b32_e32 v163, 0xffff0000, v158
	v_pk_fma_f32 v[122:123], v[122:123], v[128:129], v[162:163]
	v_lshlrev_b32_e32 v158, 16, v159
	v_and_b32_e32 v159, 0xffff0000, v159
	v_rcp_f32_e32 v160, v160
	s_nop 0
	v_pk_fma_f32 v[124:125], v[124:125], v[160:161], v[158:159]
	v_lshlrev_b32_e32 v160, 16, v156
	v_and_b32_e32 v161, 0xffff0000, v156
	v_rcp_f32_e32 v119, v119
	v_mul_f32_e32 v121, 0xbfb8aa3b, v121
	v_exp_f32_e32 v120, v120
	v_exp_f32_e32 v121, v121
	s_nop 0
	v_pk_add_f32 v[120:121], v[120:121], 1.0 op_sel_hi:[1,0]
	v_rcp_f32_e32 v118, v118
	s_nop 0
	v_pk_fma_f32 v[118:119], v[114:115], v[118:119], v[160:161]
	v_lshlrev_b32_e32 v114, 16, v157
	v_and_b32_e32 v115, 0xffff0000, v157
	v_rcp_f32_e32 v121, v121
	v_pk_mul_f32 v[128:129], v[122:123], v[122:123]
	v_rcp_f32_e32 v120, v120
	s_nop 0
	v_pk_fma_f32 v[116:117], v[116:117], v[120:121], v[114:115]
	v_pk_mul_f32 v[114:115], v[118:119], v[118:119]
	v_pk_mul_f32 v[120:121], v[116:117], v[116:117]
	v_pk_mul_f32 v[158:159], v[124:125], v[124:125]
	v_add_f32_e32 v120, v120, v121
	v_add_f32_e32 v114, v114, v115
	v_add_f32_e32 v114, v114, v120
	v_add_f32_e32 v115, v158, v159
	v_add_f32_e32 v120, v128, v129
	v_add_f32_e32 v115, v120, v115
	v_add_f32_e32 v128, v115, v114
	ds_bpermute_b32 v129, v127, v128
	v_lshl_add_u64 v[114:115], s[92:93], 0, v[150:151]
	v_cvt_pk_bf16_f32 v120, v122, v123
	v_lshl_add_u64 v[122:123], v[114:115], 0, v[146:147]
	v_cvt_pk_bf16_f32 v121, v124, v125
	s_waitcnt lgkmcnt(0)
	v_add_f32_e32 v114, v128, v129
	ds_bpermute_b32 v115, v126, v114
	v_cvt_pk_bf16_f32 v118, v118, v119
	v_cvt_pk_bf16_f32 v119, v116, v117
	global_store_dwordx2 v[122:123], v[120:121], off
	global_store_dwordx2 v[122:123], v[118:119], off offset:32
	s_and_saveexec_b64 s[4:5], s[0:1]
	s_cbranch_execz .LBB0_1757
	v_lshl_add_u64 v[116:117], v[148:149], 2, s[12:13]
	s_waitcnt lgkmcnt(0)
	v_add_f32_e32 v114, v114, v115
	global_atomic_add_f32 v[116:117], v114, off
.LBB0_1757:
	s_or_b64 exec, exec, s[4:5]
	v_or_b32_e32 v114, 16, v148
	s_waitcnt lgkmcnt(0)
	v_ashrrev_i32_e32 v115, 31, v114
	v_lshlrev_b64 v[116:117], 11, v[114:115]
	v_lshl_add_u64 v[118:119], s[14:15], 0, v[116:117]
	v_lshl_add_u64 v[118:119], v[118:119], 0, v[146:147]
	global_load_dwordx2 v[120:121], v[118:119], off
	v_mul_f32_e32 v122, 0xbfb8aa3b, v110
	v_mul_f32_e32 v123, 0xbfb8aa3b, v111
	global_load_dwordx2 v[110:111], v[118:119], off offset:32
	v_mul_f32_e32 v118, 0xbfb8aa3b, v102
	v_mul_f32_e32 v119, 0xbfb8aa3b, v103
	v_exp_f32_e32 v102, v122
	v_exp_f32_e32 v103, v123
	v_mul_f32_e32 v112, 0xbfb8aa3b, v112
	v_mul_f32_e32 v113, 0xbfb8aa3b, v113
	v_exp_f32_e32 v112, v112
	v_exp_f32_e32 v113, v113
	v_pk_add_f32 v[102:103], v[102:103], 1.0 op_sel_hi:[1,0]
	v_exp_f32_e32 v118, v118
	v_pk_add_f32 v[112:113], v[112:113], 1.0 op_sel_hi:[1,0]
	v_exp_f32_e32 v119, v119
	s_nop 0
	v_pk_add_f32 v[118:119], v[118:119], 1.0 op_sel_hi:[1,0]
	v_rcp_f32_e32 v103, v103
	v_rcp_f32_e32 v102, v102
	v_rcp_f32_e32 v113, v113
	v_rcp_f32_e32 v112, v112
	v_mul_f32_e32 v104, 0xbfb8aa3b, v104
	v_mul_f32_e32 v105, 0xbfb8aa3b, v105
	v_exp_f32_e32 v104, v104
	v_exp_f32_e32 v105, v105
	s_waitcnt vmcnt(1)
	v_lshlrev_b32_e32 v122, 16, v120
	v_and_b32_e32 v123, 0xffff0000, v120
	v_lshlrev_b32_e32 v120, 16, v121
	v_and_b32_e32 v121, 0xffff0000, v121
	v_pk_fma_f32 v[102:103], v[106:107], v[102:103], v[122:123]
	v_pk_fma_f32 v[106:107], v[108:109], v[112:113], v[120:121]
	s_waitcnt vmcnt(0)
	v_lshlrev_b32_e32 v120, 16, v110
	v_and_b32_e32 v121, 0xffff0000, v110
	v_rcp_f32_e32 v119, v119
	v_pk_add_f32 v[104:105], v[104:105], 1.0 op_sel_hi:[1,0]
	v_rcp_f32_e32 v118, v118
	s_nop 0
	v_pk_fma_f32 v[118:119], v[98:99], v[118:119], v[120:121]
	v_lshlrev_b32_e32 v98, 16, v111
	v_and_b32_e32 v99, 0xffff0000, v111
	v_rcp_f32_e32 v105, v105
	v_pk_mul_f32 v[108:109], v[102:103], v[102:103]
	v_rcp_f32_e32 v104, v104
	s_nop 0
	v_pk_fma_f32 v[100:101], v[100:101], v[104:105], v[98:99]
	v_pk_mul_f32 v[98:99], v[118:119], v[118:119]
	v_pk_mul_f32 v[104:105], v[100:101], v[100:101]
	v_pk_mul_f32 v[112:113], v[106:107], v[106:107]
	v_add_f32_e32 v104, v104, v105
	v_add_f32_e32 v98, v98, v99
	v_add_f32_e32 v98, v98, v104
	v_add_f32_e32 v99, v112, v113
	v_add_f32_e32 v104, v108, v109
	v_add_f32_e32 v99, v104, v99
	v_add_f32_e32 v108, v99, v98
	ds_bpermute_b32 v109, v127, v108
	v_lshl_add_u64 v[98:99], s[92:93], 0, v[116:117]
	v_lshl_add_u64 v[104:105], v[98:99], 0, v[146:147]
	v_cvt_pk_bf16_f32 v102, v102, v103
	v_cvt_pk_bf16_f32 v103, v106, v107
	s_waitcnt lgkmcnt(0)
	v_add_f32_e32 v98, v108, v109
	ds_bpermute_b32 v99, v126, v98
	global_store_dwordx2 v[104:105], v[102:103], off
	v_cvt_pk_bf16_f32 v102, v118, v119
	v_cvt_pk_bf16_f32 v103, v100, v101
	global_store_dwordx2 v[104:105], v[102:103], off offset:32
	s_and_saveexec_b64 s[4:5], s[0:1]
	s_cbranch_execz .LBB0_1759
	v_lshl_add_u64 v[100:101], v[114:115], 2, s[12:13]
	s_waitcnt lgkmcnt(0)
	v_add_f32_e32 v98, v98, v99
	global_atomic_add_f32 v[100:101], v98, off
; DI unsigned pk2(float lo, float hi) { f32x2 v = {lo, hi}; bf16x2_t b = __builtin_convertvector(v, bf16x2_t); return __builtin_bit_cast(unsigned, b); }
; DI float sigmoidf_(float x) { return 1.f / (1.f + __expf(-x)); }
;     DI void operator()(const f32x4 (&acc)[2][2][4][2], const Unit& u, int wr, int wc, int fr, int fq) const {
;     ...
;             for (int m = 0; m < 4; ++m) { const int row = row0 + ai * HALF + m * 16; float s = 0.f;
; #pragma unroll
;                 for (int n = 0; n < 2; ++n) { const int col = col0 + n * 16; const f32x4 v = acc[ai][0][m][n], gt = acc[ai][1][m][n];
;                     const u32x2 bw = *(const u32x2*)(baseb + (size_t)row * DM + col); f32x4 h = {bflo(bw.x), bfhi(bw.x), bflo(bw.y), bfhi(bw.y)};
; #pragma unroll
;                     for (int j = 0; j < 4; ++j) h[j] += v[j] * sigmoidf_(gt[j]);
;                     u32x2 w; w.x = pk2(h[0], h[1]); w.y = pk2(h[2], h[3]); *(u32x2*)(XB + (size_t)row * DM + col) = w;
;                     s += (h[0] * h[0] + h[1] * h[1]) + (h[2] * h[2] + h[3] * h[3]); }
;                 s += __shfl_xor(s, 16); s += __shfl_xor(s, 32); if (fq == 0) atomicAdd(ssout + row, s); }
.LBB0_1759:
	s_or_b64 exec, exec, s[4:5]
	v_or_b32_e32 v98, 32, v148
	s_waitcnt lgkmcnt(0)
	v_ashrrev_i32_e32 v99, 31, v98
	v_lshlrev_b64 v[100:101], 11, v[98:99]
	v_lshl_add_u64 v[102:103], s[14:15], 0, v[100:101]
	v_lshl_add_u64 v[102:103], v[102:103], 0, v[146:147]
	global_load_dwordx2 v[104:105], v[102:103], off
	v_mul_f32_e32 v106, 0xbfb8aa3b, v94
	v_mul_f32_e32 v107, 0xbfb8aa3b, v95
	global_load_dwordx2 v[94:95], v[102:103], off offset:32
	v_mul_f32_e32 v102, 0xbfb8aa3b, v86
	v_mul_f32_e32 v103, 0xbfb8aa3b, v87
	v_exp_f32_e32 v86, v106
	v_exp_f32_e32 v87, v107
	v_mul_f32_e32 v96, 0xbfb8aa3b, v96
	v_mul_f32_e32 v97, 0xbfb8aa3b, v97
	v_exp_f32_e32 v96, v96
	v_exp_f32_e32 v97, v97
	v_pk_add_f32 v[86:87], v[86:87], 1.0 op_sel_hi:[1,0]
	v_exp_f32_e32 v102, v102
	v_pk_add_f32 v[96:97], v[96:97], 1.0 op_sel_hi:[1,0]
	v_exp_f32_e32 v103, v103
	s_nop 0
	v_pk_add_f32 v[102:103], v[102:103], 1.0 op_sel_hi:[1,0]
	v_rcp_f32_e32 v87, v87
	v_rcp_f32_e32 v86, v86
	v_rcp_f32_e32 v97, v97
	v_rcp_f32_e32 v96, v96
	v_mul_f32_e32 v88, 0xbfb8aa3b, v88
	v_mul_f32_e32 v89, 0xbfb8aa3b, v89
	v_exp_f32_e32 v88, v88
	v_exp_f32_e32 v89, v89
	s_waitcnt vmcnt(1)
	v_lshlrev_b32_e32 v106, 16, v104
	v_and_b32_e32 v107, 0xffff0000, v104
	v_lshlrev_b32_e32 v104, 16, v105
	v_and_b32_e32 v105, 0xffff0000, v105
	v_pk_fma_f32 v[86:87], v[90:91], v[86:87], v[106:107]
	v_pk_fma_f32 v[90:91], v[92:93], v[96:97], v[104:105]
	s_waitcnt vmcnt(0)
	v_lshlrev_b32_e32 v104, 16, v94
	v_and_b32_e32 v105, 0xffff0000, v94
	v_rcp_f32_e32 v103, v103
	v_pk_add_f32 v[88:89], v[88:89], 1.0 op_sel_hi:[1,0]
	v_rcp_f32_e32 v102, v102
	s_nop 0
	v_pk_fma_f32 v[102:103], v[82:83], v[102:103], v[104:105]
	v_lshlrev_b32_e32 v82, 16, v95
	v_and_b32_e32 v83, 0xffff0000, v95
	v_rcp_f32_e32 v89, v89
	v_pk_mul_f32 v[92:93], v[86:87], v[86:87]
	v_rcp_f32_e32 v88, v88
	s_nop 0
	v_pk_fma_f32 v[84:85], v[84:85], v[88:89], v[82:83]
	v_pk_mul_f32 v[82:83], v[102:103], v[102:103]
	v_pk_mul_f32 v[88:89], v[84:85], v[84:85]
	v_pk_mul_f32 v[96:97], v[90:91], v[90:91]
	v_add_f32_e32 v88, v88, v89
	v_add_f32_e32 v82, v82, v83
	v_add_f32_e32 v82, v82, v88
	v_add_f32_e32 v83, v96, v97
	v_add_f32_e32 v88, v92, v93
	v_add_f32_e32 v83, v88, v83
	v_add_f32_e32 v92, v83, v82
	ds_bpermute_b32 v93, v127, v92
	v_lshl_add_u64 v[82:83], s[92:93], 0, v[100:101]
	v_lshl_add_u64 v[88:89], v[82:83], 0, v[146:147]
	v_cvt_pk_bf16_f32 v86, v86, v87
	v_cvt_pk_bf16_f32 v87, v90, v91
	s_waitcnt lgkmcnt(0)
	v_add_f32_e32 v82, v92, v93
	ds_bpermute_b32 v83, v126, v82
	global_store_dwordx2 v[88:89], v[86:87], off
	v_cvt_pk_bf16_f32 v86, v102, v103
	v_cvt_pk_bf16_f32 v87, v84, v85
	global_store_dwordx2 v[88:89], v[86:87], off offset:32
	s_and_saveexec_b64 s[4:5], s[0:1]
	s_cbranch_execz .LBB0_1761
	v_lshl_add_u64 v[84:85], v[98:99], 2, s[12:13]
	s_waitcnt lgkmcnt(0)
	v_add_f32_e32 v82, v82, v83
	global_atomic_add_f32 v[84:85], v82, off
.LBB0_1761:
	s_or_b64 exec, exec, s[4:5]
	v_or_b32_e32 v82, 48, v148
	s_waitcnt lgkmcnt(0)
	v_ashrrev_i32_e32 v83, 31, v82
	v_lshlrev_b64 v[84:85], 11, v[82:83]
	v_lshl_add_u64 v[86:87], s[14:15], 0, v[84:85]
	v_lshl_add_u64 v[86:87], v[86:87], 0, v[146:147]
	global_load_dwordx2 v[88:89], v[86:87], off
	v_mul_f32_e32 v90, 0xbfb8aa3b, v78
	v_mul_f32_e32 v91, 0xbfb8aa3b, v79
	global_load_dwordx2 v[78:79], v[86:87], off offset:32
	v_mul_f32_e32 v86, 0xbfb8aa3b, v70
	v_mul_f32_e32 v87, 0xbfb8aa3b, v71
	v_exp_f32_e32 v70, v90
	v_exp_f32_e32 v71, v91
	v_mul_f32_e32 v80, 0xbfb8aa3b, v80
	v_mul_f32_e32 v81, 0xbfb8aa3b, v81
	v_exp_f32_e32 v80, v80
	v_exp_f32_e32 v81, v81
	v_pk_add_f32 v[70:71], v[70:71], 1.0 op_sel_hi:[1,0]
	v_exp_f32_e32 v86, v86
	v_pk_add_f32 v[80:81], v[80:81], 1.0 op_sel_hi:[1,0]
	v_exp_f32_e32 v87, v87
	s_nop 0
	v_pk_add_f32 v[86:87], v[86:87], 1.0 op_sel_hi:[1,0]
	v_rcp_f32_e32 v71, v71
	v_rcp_f32_e32 v70, v70
	v_rcp_f32_e32 v81, v81
	v_rcp_f32_e32 v80, v80
	v_mul_f32_e32 v72, 0xbfb8aa3b, v72
	v_mul_f32_e32 v73, 0xbfb8aa3b, v73
	v_exp_f32_e32 v72, v72
	v_exp_f32_e32 v73, v73
	s_waitcnt vmcnt(1)
	v_lshlrev_b32_e32 v90, 16, v88
	v_and_b32_e32 v91, 0xffff0000, v88
	v_lshlrev_b32_e32 v88, 16, v89
	v_and_b32_e32 v89, 0xffff0000, v89
	v_pk_fma_f32 v[70:71], v[74:75], v[70:71], v[90:91]
	v_pk_fma_f32 v[74:75], v[76:77], v[80:81], v[88:89]
	s_waitcnt vmcnt(0)
	v_lshlrev_b32_e32 v88, 16, v78
	v_and_b32_e32 v89, 0xffff0000, v78
	v_rcp_f32_e32 v87, v87
	v_pk_add_f32 v[72:73], v[72:73], 1.0 op_sel_hi:[1,0]
	v_rcp_f32_e32 v86, v86
	s_nop 0
	v_pk_fma_f32 v[86:87], v[66:67], v[86:87], v[88:89]
	v_lshlrev_b32_e32 v66, 16, v79
	v_and_b32_e32 v67, 0xffff0000, v79
	v_rcp_f32_e32 v73, v73
	v_pk_mul_f32 v[76:77], v[70:71], v[70:71]
	v_rcp_f32_e32 v72, v72
	s_nop 0
	v_pk_fma_f32 v[68:69], v[68:69], v[72:73], v[66:67]
	v_pk_mul_f32 v[66:67], v[86:87], v[86:87]
	v_pk_mul_f32 v[72:73], v[68:69], v[68:69]
	v_pk_mul_f32 v[80:81], v[74:75], v[74:75]
	v_add_f32_e32 v72, v72, v73
	v_add_f32_e32 v66, v66, v67
	v_add_f32_e32 v66, v66, v72
	v_add_f32_e32 v67, v80, v81
	v_add_f32_e32 v72, v76, v77
	v_add_f32_e32 v67, v72, v67
	v_add_f32_e32 v76, v67, v66
	ds_bpermute_b32 v77, v127, v76
	v_lshl_add_u64 v[66:67], s[92:93], 0, v[84:85]
	v_lshl_add_u64 v[72:73], v[66:67], 0, v[146:147]
	v_cvt_pk_bf16_f32 v70, v70, v71
	v_cvt_pk_bf16_f32 v71, v74, v75
	s_waitcnt lgkmcnt(0)
	v_add_f32_e32 v66, v76, v77
	ds_bpermute_b32 v67, v126, v66
	global_store_dwordx2 v[72:73], v[70:71], off
	v_cvt_pk_bf16_f32 v70, v86, v87
	v_cvt_pk_bf16_f32 v71, v68, v69
	global_store_dwordx2 v[72:73], v[70:71], off offset:32
	s_and_saveexec_b64 s[4:5], s[0:1]
	s_cbranch_execz .LBB0_1763
	v_lshl_add_u64 v[68:69], v[82:83], 2, s[12:13]
	s_waitcnt lgkmcnt(0)
	v_add_f32_e32 v66, v66, v67
	global_atomic_add_f32 v[68:69], v66, off
; DI unsigned pk2(float lo, float hi) { f32x2 v = {lo, hi}; bf16x2_t b = __builtin_convertvector(v, bf16x2_t); return __builtin_bit_cast(unsigned, b); }
; DI float sigmoidf_(float x) { return 1.f / (1.f + __expf(-x)); }
;     DI void operator()(const f32x4 (&acc)[2][2][4][2], const Unit& u, int wr, int wc, int fr, int fq) const {
;     ...
;             for (int m = 0; m < 4; ++m) { const int row = row0 + ai * HALF + m * 16; float s = 0.f;
; #pragma unroll
;                 for (int n = 0; n < 2; ++n) { const int col = col0 + n * 16; const f32x4 v = acc[ai][0][m][n], gt = acc[ai][1][m][n];
;                     const u32x2 bw = *(const u32x2*)(baseb + (size_t)row * DM + col); f32x4 h = {bflo(bw.x), bfhi(bw.x), bflo(bw.y), bfhi(bw.y)};
; #pragma unroll
;                     for (int j = 0; j < 4; ++j) h[j] += v[j] * sigmoidf_(gt[j]);
;                     u32x2 w; w.x = pk2(h[0], h[1]); w.y = pk2(h[2], h[3]); *(u32x2*)(XB + (size_t)row * DM + col) = w;
;                     s += (h[0] * h[0] + h[1] * h[1]) + (h[2] * h[2] + h[3] * h[3]); }
;                 s += __shfl_xor(s, 16); s += __shfl_xor(s, 32); if (fq == 0) atomicAdd(ssout + row, s); }
.LBB0_1763:
	s_or_b64 exec, exec, s[4:5]
	v_add_u32_e32 v66, 0x80, v148
	s_waitcnt lgkmcnt(0)
	v_ashrrev_i32_e32 v67, 31, v66
	v_lshlrev_b64 v[68:69], 11, v[66:67]
	v_lshl_add_u64 v[70:71], s[14:15], 0, v[68:69]
	v_lshl_add_u64 v[70:71], v[70:71], 0, v[146:147]
	global_load_dwordx2 v[72:73], v[70:71], off
	v_mul_f32_e32 v74, 0xbfb8aa3b, v62
	v_mul_f32_e32 v75, 0xbfb8aa3b, v63
	global_load_dwordx2 v[62:63], v[70:71], off offset:32
	v_mul_f32_e32 v70, 0xbfb8aa3b, v54
	v_mul_f32_e32 v71, 0xbfb8aa3b, v55
	v_exp_f32_e32 v54, v74
	v_exp_f32_e32 v55, v75
	v_mul_f32_e32 v64, 0xbfb8aa3b, v64
	v_mul_f32_e32 v65, 0xbfb8aa3b, v65
	v_exp_f32_e32 v64, v64
	v_exp_f32_e32 v65, v65
	v_pk_add_f32 v[54:55], v[54:55], 1.0 op_sel_hi:[1,0]
	v_exp_f32_e32 v70, v70
	v_pk_add_f32 v[64:65], v[64:65], 1.0 op_sel_hi:[1,0]
	v_exp_f32_e32 v71, v71
	s_nop 0
	v_pk_add_f32 v[70:71], v[70:71], 1.0 op_sel_hi:[1,0]
	v_rcp_f32_e32 v55, v55
	v_rcp_f32_e32 v54, v54
	v_rcp_f32_e32 v65, v65
	v_rcp_f32_e32 v64, v64
	v_mul_f32_e32 v56, 0xbfb8aa3b, v56
	v_mul_f32_e32 v57, 0xbfb8aa3b, v57
	v_exp_f32_e32 v56, v56
	v_exp_f32_e32 v57, v57
	s_waitcnt vmcnt(1)
	v_lshlrev_b32_e32 v74, 16, v72
	v_and_b32_e32 v75, 0xffff0000, v72
	v_lshlrev_b32_e32 v72, 16, v73
	v_and_b32_e32 v73, 0xffff0000, v73
	v_pk_fma_f32 v[54:55], v[58:59], v[54:55], v[74:75]
	v_pk_fma_f32 v[58:59], v[60:61], v[64:65], v[72:73]
	s_waitcnt vmcnt(0)
	v_lshlrev_b32_e32 v72, 16, v62
	v_and_b32_e32 v73, 0xffff0000, v62
	v_rcp_f32_e32 v71, v71
	v_pk_add_f32 v[56:57], v[56:57], 1.0 op_sel_hi:[1,0]
	v_rcp_f32_e32 v70, v70
	s_nop 0
	v_pk_fma_f32 v[70:71], v[50:51], v[70:71], v[72:73]
	v_lshlrev_b32_e32 v50, 16, v63
	v_and_b32_e32 v51, 0xffff0000, v63
	v_rcp_f32_e32 v57, v57
	v_pk_mul_f32 v[60:61], v[54:55], v[54:55]
	v_rcp_f32_e32 v56, v56
	s_nop 0
	v_pk_fma_f32 v[52:53], v[52:53], v[56:57], v[50:51]
	v_pk_mul_f32 v[50:51], v[70:71], v[70:71]
	v_pk_mul_f32 v[56:57], v[52:53], v[52:53]
	v_pk_mul_f32 v[64:65], v[58:59], v[58:59]
	v_add_f32_e32 v56, v56, v57
	v_add_f32_e32 v50, v50, v51
	v_add_f32_e32 v50, v50, v56
	v_add_f32_e32 v51, v64, v65
	v_add_f32_e32 v56, v60, v61
	v_add_f32_e32 v51, v56, v51
	v_add_f32_e32 v60, v51, v50
	ds_bpermute_b32 v61, v127, v60
	v_lshl_add_u64 v[50:51], s[92:93], 0, v[68:69]
	v_lshl_add_u64 v[56:57], v[50:51], 0, v[146:147]
	v_cvt_pk_bf16_f32 v54, v54, v55
	v_cvt_pk_bf16_f32 v55, v58, v59
	s_waitcnt lgkmcnt(0)
	v_add_f32_e32 v50, v60, v61
	ds_bpermute_b32 v51, v126, v50
	global_store_dwordx2 v[56:57], v[54:55], off
	v_cvt_pk_bf16_f32 v54, v70, v71
	v_cvt_pk_bf16_f32 v55, v52, v53
	global_store_dwordx2 v[56:57], v[54:55], off offset:32
	s_and_saveexec_b64 s[4:5], s[0:1]
	s_cbranch_execz .LBB0_1765
	v_lshl_add_u64 v[52:53], v[66:67], 2, s[12:13]
	s_waitcnt lgkmcnt(0)
	v_add_f32_e32 v50, v50, v51
	global_atomic_add_f32 v[52:53], v50, off
.LBB0_1765:
	s_or_b64 exec, exec, s[4:5]
	v_add_u32_e32 v50, 0x90, v148
	s_waitcnt lgkmcnt(0)
	v_ashrrev_i32_e32 v51, 31, v50
	v_lshlrev_b64 v[52:53], 11, v[50:51]
	v_lshl_add_u64 v[54:55], s[14:15], 0, v[52:53]
	v_lshl_add_u64 v[54:55], v[54:55], 0, v[146:147]
	global_load_dwordx2 v[56:57], v[54:55], off
	v_mul_f32_e32 v58, 0xbfb8aa3b, v46
	v_mul_f32_e32 v59, 0xbfb8aa3b, v47
	global_load_dwordx2 v[46:47], v[54:55], off offset:32
	v_mul_f32_e32 v54, 0xbfb8aa3b, v38
	v_mul_f32_e32 v55, 0xbfb8aa3b, v39
	v_exp_f32_e32 v38, v58
	v_exp_f32_e32 v39, v59
	v_mul_f32_e32 v48, 0xbfb8aa3b, v48
	v_mul_f32_e32 v49, 0xbfb8aa3b, v49
	v_exp_f32_e32 v48, v48
	v_exp_f32_e32 v49, v49
	v_pk_add_f32 v[38:39], v[38:39], 1.0 op_sel_hi:[1,0]
	v_exp_f32_e32 v54, v54
	v_pk_add_f32 v[48:49], v[48:49], 1.0 op_sel_hi:[1,0]
	v_exp_f32_e32 v55, v55
	s_nop 0
	v_pk_add_f32 v[54:55], v[54:55], 1.0 op_sel_hi:[1,0]
	v_rcp_f32_e32 v39, v39
	v_rcp_f32_e32 v38, v38
	v_rcp_f32_e32 v49, v49
	v_rcp_f32_e32 v48, v48
	v_mul_f32_e32 v40, 0xbfb8aa3b, v40
	v_mul_f32_e32 v41, 0xbfb8aa3b, v41
	v_exp_f32_e32 v40, v40
	v_exp_f32_e32 v41, v41
	s_waitcnt vmcnt(1)
	v_lshlrev_b32_e32 v58, 16, v56
	v_and_b32_e32 v59, 0xffff0000, v56
	v_lshlrev_b32_e32 v56, 16, v57
	v_and_b32_e32 v57, 0xffff0000, v57
	v_pk_fma_f32 v[38:39], v[42:43], v[38:39], v[58:59]
	v_pk_fma_f32 v[42:43], v[44:45], v[48:49], v[56:57]
	s_waitcnt vmcnt(0)
	v_lshlrev_b32_e32 v56, 16, v46
	v_and_b32_e32 v57, 0xffff0000, v46
	v_rcp_f32_e32 v55, v55
	v_pk_add_f32 v[40:41], v[40:41], 1.0 op_sel_hi:[1,0]
	v_rcp_f32_e32 v54, v54
	s_nop 0
	v_pk_fma_f32 v[54:55], v[34:35], v[54:55], v[56:57]
	v_lshlrev_b32_e32 v34, 16, v47
	v_and_b32_e32 v35, 0xffff0000, v47
	v_rcp_f32_e32 v41, v41
	v_pk_mul_f32 v[44:45], v[38:39], v[38:39]
	v_rcp_f32_e32 v40, v40
	s_nop 0
	v_pk_fma_f32 v[36:37], v[36:37], v[40:41], v[34:35]
	v_pk_mul_f32 v[34:35], v[54:55], v[54:55]
	v_pk_mul_f32 v[40:41], v[36:37], v[36:37]
	v_pk_mul_f32 v[48:49], v[42:43], v[42:43]
	v_add_f32_e32 v40, v40, v41
	v_add_f32_e32 v34, v34, v35
	v_add_f32_e32 v34, v34, v40
	v_add_f32_e32 v35, v48, v49
	v_add_f32_e32 v40, v44, v45
	v_add_f32_e32 v35, v40, v35
	v_add_f32_e32 v44, v35, v34
	ds_bpermute_b32 v45, v127, v44
	v_lshl_add_u64 v[34:35], s[92:93], 0, v[52:53]
	v_lshl_add_u64 v[40:41], v[34:35], 0, v[146:147]
	v_cvt_pk_bf16_f32 v38, v38, v39
	v_cvt_pk_bf16_f32 v39, v42, v43
	s_waitcnt lgkmcnt(0)
	v_add_f32_e32 v34, v44, v45
	ds_bpermute_b32 v35, v126, v34
	global_store_dwordx2 v[40:41], v[38:39], off
	v_cvt_pk_bf16_f32 v38, v54, v55
	v_cvt_pk_bf16_f32 v39, v36, v37
	global_store_dwordx2 v[40:41], v[38:39], off offset:32
	s_and_saveexec_b64 s[4:5], s[0:1]
	s_cbranch_execz .LBB0_1767
	v_lshl_add_u64 v[36:37], v[50:51], 2, s[12:13]
	s_waitcnt lgkmcnt(0)
	v_add_f32_e32 v34, v34, v35
	global_atomic_add_f32 v[36:37], v34, off
; DI unsigned pk2(float lo, float hi) { f32x2 v = {lo, hi}; bf16x2_t b = __builtin_convertvector(v, bf16x2_t); return __builtin_bit_cast(unsigned, b); }
; DI float sigmoidf_(float x) { return 1.f / (1.f + __expf(-x)); }
;     DI void operator()(const f32x4 (&acc)[2][2][4][2], const Unit& u, int wr, int wc, int fr, int fq) const {
;     ...
;             for (int m = 0; m < 4; ++m) { const int row = row0 + ai * HALF + m * 16; float s = 0.f;
; #pragma unroll
;                 for (int n = 0; n < 2; ++n) { const int col = col0 + n * 16; const f32x4 v = acc[ai][0][m][n], gt = acc[ai][1][m][n];
;                     const u32x2 bw = *(const u32x2*)(baseb + (size_t)row * DM + col); f32x4 h = {bflo(bw.x), bfhi(bw.x), bflo(bw.y), bfhi(bw.y)};
; #pragma unroll
;                     for (int j = 0; j < 4; ++j) h[j] += v[j] * sigmoidf_(gt[j]);
;                     u32x2 w; w.x = pk2(h[0], h[1]); w.y = pk2(h[2], h[3]); *(u32x2*)(XB + (size_t)row * DM + col) = w;
;                     s += (h[0] * h[0] + h[1] * h[1]) + (h[2] * h[2] + h[3] * h[3]); }
;                 s += __shfl_xor(s, 16); s += __shfl_xor(s, 32); if (fq == 0) atomicAdd(ssout + row, s); }
.LBB0_1767:
	s_or_b64 exec, exec, s[4:5]
	v_add_u32_e32 v34, 0xa0, v148
	s_waitcnt lgkmcnt(0)
	v_ashrrev_i32_e32 v35, 31, v34
	v_lshlrev_b64 v[36:37], 11, v[34:35]
	v_lshl_add_u64 v[38:39], s[14:15], 0, v[36:37]
	v_lshl_add_u64 v[38:39], v[38:39], 0, v[146:147]
	global_load_dwordx2 v[40:41], v[38:39], off
	v_mul_f32_e32 v42, 0xbfb8aa3b, v30
	v_mul_f32_e32 v43, 0xbfb8aa3b, v31
	global_load_dwordx2 v[30:31], v[38:39], off offset:32
	v_mul_f32_e32 v38, 0xbfb8aa3b, v22
	v_mul_f32_e32 v39, 0xbfb8aa3b, v23
	v_exp_f32_e32 v22, v42
	v_exp_f32_e32 v23, v43
	v_mul_f32_e32 v32, 0xbfb8aa3b, v32
	v_mul_f32_e32 v33, 0xbfb8aa3b, v33
	v_exp_f32_e32 v32, v32
	v_exp_f32_e32 v33, v33
	v_pk_add_f32 v[22:23], v[22:23], 1.0 op_sel_hi:[1,0]
	v_exp_f32_e32 v38, v38
	v_pk_add_f32 v[32:33], v[32:33], 1.0 op_sel_hi:[1,0]
	v_exp_f32_e32 v39, v39
	s_nop 0
	v_pk_add_f32 v[38:39], v[38:39], 1.0 op_sel_hi:[1,0]
	v_rcp_f32_e32 v23, v23
	v_rcp_f32_e32 v22, v22
	v_rcp_f32_e32 v33, v33
	v_rcp_f32_e32 v32, v32
	v_mul_f32_e32 v24, 0xbfb8aa3b, v24
	v_mul_f32_e32 v25, 0xbfb8aa3b, v25
	v_exp_f32_e32 v24, v24
	v_exp_f32_e32 v25, v25
	s_waitcnt vmcnt(1)
	v_lshlrev_b32_e32 v42, 16, v40
	v_and_b32_e32 v43, 0xffff0000, v40
	v_lshlrev_b32_e32 v40, 16, v41
	v_and_b32_e32 v41, 0xffff0000, v41
	v_pk_fma_f32 v[22:23], v[26:27], v[22:23], v[42:43]
	v_pk_fma_f32 v[26:27], v[28:29], v[32:33], v[40:41]
	s_waitcnt vmcnt(0)
	v_lshlrev_b32_e32 v40, 16, v30
	v_and_b32_e32 v41, 0xffff0000, v30
	v_rcp_f32_e32 v39, v39
	v_pk_add_f32 v[24:25], v[24:25], 1.0 op_sel_hi:[1,0]
	v_rcp_f32_e32 v38, v38
	s_nop 0
	v_pk_fma_f32 v[38:39], v[18:19], v[38:39], v[40:41]
	v_lshlrev_b32_e32 v18, 16, v31
	v_and_b32_e32 v19, 0xffff0000, v31
	v_rcp_f32_e32 v25, v25
	v_pk_mul_f32 v[28:29], v[22:23], v[22:23]
	v_rcp_f32_e32 v24, v24
	s_nop 0
	v_pk_fma_f32 v[20:21], v[20:21], v[24:25], v[18:19]
	v_pk_mul_f32 v[18:19], v[38:39], v[38:39]
	v_pk_mul_f32 v[24:25], v[20:21], v[20:21]
	v_pk_mul_f32 v[32:33], v[26:27], v[26:27]
	v_add_f32_e32 v24, v24, v25
	v_add_f32_e32 v18, v18, v19
	v_add_f32_e32 v18, v18, v24
	v_add_f32_e32 v19, v32, v33
	v_add_f32_e32 v24, v28, v29
	v_add_f32_e32 v19, v24, v19
	v_add_f32_e32 v28, v19, v18
	ds_bpermute_b32 v29, v127, v28
	v_lshl_add_u64 v[18:19], s[92:93], 0, v[36:37]
	v_lshl_add_u64 v[24:25], v[18:19], 0, v[146:147]
	v_cvt_pk_bf16_f32 v22, v22, v23
	v_cvt_pk_bf16_f32 v23, v26, v27
	s_waitcnt lgkmcnt(0)
	v_add_f32_e32 v18, v28, v29
	ds_bpermute_b32 v19, v126, v18
	global_store_dwordx2 v[24:25], v[22:23], off
	v_cvt_pk_bf16_f32 v22, v38, v39
	v_cvt_pk_bf16_f32 v23, v20, v21
	global_store_dwordx2 v[24:25], v[22:23], off offset:32
	s_and_saveexec_b64 s[4:5], s[0:1]
	s_cbranch_execz .LBB0_1769
	v_lshl_add_u64 v[20:21], v[34:35], 2, s[12:13]
	s_waitcnt lgkmcnt(0)
	v_add_f32_e32 v18, v18, v19
	global_atomic_add_f32 v[20:21], v18, off
.LBB0_1769:
	s_or_b64 exec, exec, s[4:5]
	v_add_u32_e32 v18, 0xb0, v148
	s_waitcnt lgkmcnt(0)
	v_ashrrev_i32_e32 v19, 31, v18
	v_lshlrev_b64 v[20:21], 11, v[18:19]
	v_lshl_add_u64 v[22:23], s[14:15], 0, v[20:21]
	v_lshl_add_u64 v[22:23], v[22:23], 0, v[146:147]
	global_load_dwordx2 v[24:25], v[22:23], off
	v_mul_f32_e32 v26, 0xbfb8aa3b, v14
	v_mul_f32_e32 v27, 0xbfb8aa3b, v15
	global_load_dwordx2 v[14:15], v[22:23], off offset:32
	v_mul_f32_e32 v22, 0xbfb8aa3b, v6
	v_mul_f32_e32 v23, 0xbfb8aa3b, v7
	v_exp_f32_e32 v6, v26
	v_exp_f32_e32 v7, v27
	v_mul_f32_e32 v16, 0xbfb8aa3b, v16
	v_mul_f32_e32 v17, 0xbfb8aa3b, v17
	v_exp_f32_e32 v16, v16
	v_exp_f32_e32 v17, v17
	v_pk_add_f32 v[6:7], v[6:7], 1.0 op_sel_hi:[1,0]
	v_exp_f32_e32 v22, v22
	v_pk_add_f32 v[16:17], v[16:17], 1.0 op_sel_hi:[1,0]
	v_exp_f32_e32 v23, v23
	s_nop 0
	v_pk_add_f32 v[22:23], v[22:23], 1.0 op_sel_hi:[1,0]
	v_rcp_f32_e32 v7, v7
	v_rcp_f32_e32 v6, v6
	v_rcp_f32_e32 v17, v17
	v_rcp_f32_e32 v16, v16
	v_mul_f32_e32 v8, 0xbfb8aa3b, v8
	v_mul_f32_e32 v9, 0xbfb8aa3b, v9
	v_exp_f32_e32 v8, v8
	v_exp_f32_e32 v9, v9
	s_waitcnt vmcnt(1)
	v_lshlrev_b32_e32 v26, 16, v24
	v_and_b32_e32 v27, 0xffff0000, v24
	v_lshlrev_b32_e32 v24, 16, v25
	v_and_b32_e32 v25, 0xffff0000, v25
	v_pk_fma_f32 v[6:7], v[10:11], v[6:7], v[26:27]
	v_pk_fma_f32 v[10:11], v[12:13], v[16:17], v[24:25]
	s_waitcnt vmcnt(0)
	v_lshlrev_b32_e32 v24, 16, v14
	v_and_b32_e32 v25, 0xffff0000, v14
	v_rcp_f32_e32 v23, v23
	v_pk_add_f32 v[8:9], v[8:9], 1.0 op_sel_hi:[1,0]
	v_rcp_f32_e32 v22, v22
	s_nop 0
	v_pk_fma_f32 v[22:23], v[2:3], v[22:23], v[24:25]
	v_lshlrev_b32_e32 v2, 16, v15
	v_and_b32_e32 v3, 0xffff0000, v15
	v_rcp_f32_e32 v9, v9
	v_pk_mul_f32 v[12:13], v[6:7], v[6:7]
	v_rcp_f32_e32 v8, v8
	s_nop 0
	v_pk_fma_f32 v[4:5], v[4:5], v[8:9], v[2:3]
	v_pk_mul_f32 v[2:3], v[22:23], v[22:23]
	v_pk_mul_f32 v[8:9], v[4:5], v[4:5]
	v_pk_mul_f32 v[16:17], v[10:11], v[10:11]
	v_add_f32_e32 v8, v8, v9
	v_add_f32_e32 v2, v2, v3
	v_add_f32_e32 v2, v2, v8
	v_add_f32_e32 v3, v16, v17
	v_add_f32_e32 v8, v12, v13
	v_add_f32_e32 v3, v8, v3
	v_add_f32_e32 v12, v3, v2
	ds_bpermute_b32 v13, v127, v12
	v_lshl_add_u64 v[2:3], s[92:93], 0, v[20:21]
	v_lshl_add_u64 v[8:9], v[2:3], 0, v[146:147]
	v_cvt_pk_bf16_f32 v6, v6, v7
	v_cvt_pk_bf16_f32 v7, v10, v11
	s_waitcnt lgkmcnt(0)
	v_add_f32_e32 v2, v12, v13
	ds_bpermute_b32 v3, v126, v2
	global_store_dwordx2 v[8:9], v[6:7], off
	v_cvt_pk_bf16_f32 v6, v22, v23
	v_cvt_pk_bf16_f32 v7, v4, v5
	global_store_dwordx2 v[8:9], v[6:7], off offset:32
	s_and_saveexec_b64 s[4:5], s[0:1]
	s_cbranch_execz .LBB0_1771
	v_lshl_add_u64 v[4:5], v[18:19], 2, s[12:13]
	s_waitcnt lgkmcnt(0)
	v_add_f32_e32 v2, v2, v3
	global_atomic_add_f32 v[4:5], v2, off

; #define LAS __attribute__((address_space(3)))
; DI unsigned pk2(float lo, float hi) { f32x2 v = {lo, hi}; bf16x2_t b = __builtin_convertvector(v, bf16x2_t); return __builtin_bit_cast(unsigned, b); }
; DI float sigmoidf_(float x) { return 1.f / (1.f + __expf(-x)); }
;     DI void operator()(LAS unsigned char* lds, int row, int tn, int ni, int fq, f32x4 v, int tid) const {
;         LAS f32x4* X = (LAS f32x4*)(lds + 4 * SLOT);
;         const int lr = row & 63;
;         if (ni == 1) X[lr * 4 + fq] = v;
;         asm volatile("s_waitcnt lgkmcnt(0)\n\ts_barrier" ::: "memory");
;         if (ni == 0) { const f32x4 gt = X[lr * 4 + fq]; const int grow = MP + row, col = tn * 16 + 4 * fq;
;             const u32x2 bw = *(const u32x2*)(baseb + (size_t)grow * DM + col); f32x4 h = {bflo(bw.x), bfhi(bw.x), bflo(bw.y), bfhi(bw.y)};
; #pragma unroll
;             for (int j = 0; j < 4; ++j) h[j] += v[j] * sigmoidf_(gt[j]);
;             u32x2 w; w.x = pk2(h[0], h[1]); w.y = pk2(h[2], h[3]); *(u32x2*)(XB + (size_t)grow * DM + col) = w;
;             float s = (h[0] * h[0] + h[1] * h[1]) + (h[2] * h[2] + h[3] * h[3]); s += __shfl_xor(s, 16); s += __shfl_xor(s, 32); if (fq == 0) atomicAdd(ssout + grow, s); }
;     }
.LBB0_1793:
	s_waitcnt lgkmcnt(0)
	s_barrier
	s_andn2_b64 vcc, exec, s[0:1]
	s_cbranch_vccnz .LBB0_1778
	v_or_b32_e32 v14, s6, v28
	v_or_b32_e32 v16, s7, v23
	v_lshlrev_b32_e32 v6, 11, v14
	v_ashrrev_i32_e32 v17, 31, v16
	v_lshl_add_u64 v[18:19], s[14:15], 0, v[6:7]
	v_lshlrev_b64 v[36:37], 1, v[16:17]
	v_lshl_add_u64 v[16:17], v[18:19], 0, v[36:37]
	global_load_dwordx2 v[38:39], v[16:17], off
	ds_read_b128 v[16:19], v34
	v_and_b32_e32 v40, 64, v35
	v_add_u32_e32 v42, 64, v40
	v_xor_b32_e32 v15, 16, v35
	s_waitcnt lgkmcnt(0)
	v_mul_f32_e32 v16, 0xbfb8aa3b, v16
	v_mul_f32_e32 v17, 0xbfb8aa3b, v17
	v_exp_f32_e32 v16, v16
	v_exp_f32_e32 v17, v17
	v_mul_f32_e32 v18, 0xbfb8aa3b, v18
	v_mul_f32_e32 v19, 0xbfb8aa3b, v19
	v_exp_f32_e32 v18, v18
	v_exp_f32_e32 v19, v19
	v_pk_add_f32 v[16:17], v[16:17], 1.0 op_sel_hi:[1,0]
	v_pk_add_f32 v[18:19], v[18:19], 1.0 op_sel_hi:[1,0]
	v_div_scale_f32 v48, s[8:9], 1.0, v18, 1.0
	v_rcp_f32_e32 v17, v17
	v_rcp_f32_e32 v16, v16
	s_mov_b64 vcc, s[8:9]
	v_rcp_f32_e32 v19, v19
	v_rcp_f32_e32 v18, v18
	v_cmp_lt_i32_e32 vcc, v15, v42
	s_waitcnt vmcnt(0)
	v_lshlrev_b32_e32 v40, 16, v38
	v_and_b32_e32 v41, 0xffff0000, v38
	v_lshlrev_b32_e32 v38, 16, v39
	v_and_b32_e32 v39, 0xffff0000, v39
	v_pk_fma_f32 v[2:3], v[2:3], v[16:17], v[40:41]
	v_pk_fma_f32 v[4:5], v[4:5], v[18:19], v[38:39]
	v_pk_mul_f32 v[16:17], v[2:3], v[2:3]
	v_pk_mul_f32 v[18:19], v[4:5], v[4:5]
	v_add_f32_e32 v16, v16, v17
	v_add_f32_e32 v18, v18, v19
	v_cndmask_b32_e32 v15, v35, v15, vcc
	v_add_f32_e32 v17, v16, v18
	v_lshlrev_b32_e32 v15, 2, v15
	ds_bpermute_b32 v15, v15, v17
	v_cvt_pk_bf16_f32 v16, v2, v3
	v_xor_b32_e32 v3, 32, v35
	v_cmp_lt_i32_e32 vcc, v3, v42
	s_waitcnt lgkmcnt(0)
	v_add_f32_e32 v2, v17, v15
	v_cndmask_b32_e32 v3, v35, v3, vcc
	v_lshlrev_b32_e32 v3, 2, v3
	ds_bpermute_b32 v3, v3, v2
	v_cvt_pk_bf16_f32 v17, v4, v5
	v_lshl_add_u64 v[4:5], s[92:93], 0, v[6:7]
	v_lshl_add_u64 v[4:5], v[4:5], 0, v[36:37]
	global_store_dwordx2 v[4:5], v[16:17], off
	s_and_saveexec_b64 s[4:5], s[2:3]
	s_cbranch_execz .LBB0_1777
	v_lshlrev_b32_e32 v4, 2, v14
	s_waitcnt lgkmcnt(0)
	v_add_f32_e32 v2, v2, v3
	global_atomic_add_f32 v4, v2, s[12:13]
	s_branch .LBB0_1777

; DI float sigmoidf_(float x) { return 1.f / (1.f + __expf(-x)); }
;     DI void operator()(const f32x4 (&acc)[2][2][4][2], const Unit& u, int wr, int wc, int fr, int fq) const {
;     ...
;             for (int m = 0; m < 4; ++m) { const int row = row0 + ai * HALF + m * 16;
;                 const float* bp = (row < MP) ? base0 + (size_t)row * DM : base1 + (size_t)(row - MP) * DM;
;                 float r = 1.f; if (MODE == 1) r = __builtin_amdgcn_rsqf(ssin[row] * (1.f / DM) + EPS);
;                 float s = 0.f;
; #pragma unroll
;                 for (int bj = 0; bj < 2; ++bj)
; #pragma unroll
;                     for (int n = 0; n < 2; ++n) { const int col = col0 + bj * HALF + n * 16;
;                         f32x4 v = acc[ai][bj][m][n];
;                         if (MODE == 1) { const u32x2 pw = *(const u32x2*)(PP + (size_t)row * DM + col);
;                             v[0] = sigmoidf_(v[0] * r) * bflo(pw.x); v[1] = sigmoidf_(v[1] * r) * bfhi(pw.x); v[2] = sigmoidf_(v[2] * r) * bflo(pw.y); v[3] = sigmoidf_(v[3] * r) * bfhi(pw.y); }
;                         f32x4 h;
;                         if (baseb) { const u32x2 bw = *(const u32x2*)(baseb + (size_t)row * DM + col); h = (f32x4){bflo(bw.x), bfhi(bw.x), bflo(bw.y), bfhi(bw.y)} + v; }
;                         else h = *(const f32x4*)(bp + col) + v;
;                         if (H) *(f32x4*)(H + (size_t)row * DM + col) = h;
.LBB0_2067:
	s_andn2_b64 vcc, exec, s[24:25]
	s_cbranch_vccnz .LBB0_2069
	v_lshl_add_u32 v150, s2, 8, v1
	v_ashrrev_i32_e32 v146, 31, v150
	v_cmp_gt_i32_e32 vcc, s45, v150
	v_lshl_or_b32 v148, s3, 8, v143
	v_ashrrev_i32_e32 v149, 31, v148
	v_cndmask_b32_e32 v151, 0, v146, vcc
	v_lshl_add_u64 v[146:147], v[150:151], 2, s[10:11]
	global_load_dword v166, v[146:147], off
	v_lshlrev_b64 v[152:153], 11, v[150:151]
	v_lshl_add_u64 v[154:155], s[12:13], 0, v[152:153]
	v_lshlrev_b64 v[146:147], 1, v[148:149]
	v_lshl_add_u64 v[152:153], s[14:15], 0, v[152:153]
	v_lshl_add_u64 v[156:157], v[154:155], 0, v[146:147]
	v_lshl_add_u64 v[154:155], v[152:153], 0, v[146:147]
	global_load_dwordx2 v[162:163], v[156:157], off
	global_load_dwordx2 v[164:165], v[154:155], off
	v_lshlrev_b64 v[152:153], 12, v[150:151]
	v_lshlrev_b64 v[148:149], 2, v[148:149]
	v_lshl_add_u64 v[152:153], s[48:49], 0, v[152:153]
	v_lshl_add_u64 v[152:153], v[152:153], 0, v[148:149]
	s_waitcnt vmcnt(0)
	v_fmamk_f32 v151, v166, 0x3a800000, v161
	v_rsq_f32_e32 v151, v151
	v_lshlrev_b32_e32 v166, 16, v162
	v_mul_f32_e32 v126, v126, v151
	v_mul_f32_e32 v127, v127, v151
	v_mul_f32_e32 v126, 0xbfb8aa3b, v126
	v_mul_f32_e32 v127, 0xbfb8aa3b, v127
	v_mul_f32_e32 v128, v128, v151
	v_mul_f32_e32 v129, v129, v151
	v_exp_f32_e32 v126, v126
	v_exp_f32_e32 v127, v127
	v_mul_f32_e32 v128, 0xbfb8aa3b, v128
	v_mul_f32_e32 v129, 0xbfb8aa3b, v129
	v_exp_f32_e32 v128, v128
	v_exp_f32_e32 v129, v129
	v_pk_add_f32 v[126:127], v[126:127], 1.0 op_sel_hi:[1,0]
	v_and_b32_e32 v167, 0xffff0000, v162
	v_pk_add_f32 v[128:129], v[128:129], 1.0 op_sel_hi:[1,0]
	v_rcp_f32_e32 v127, v127
	v_rcp_f32_e32 v126, v126
	v_rcp_f32_e32 v129, v129
	v_lshlrev_b32_e32 v162, 16, v163
	v_and_b32_e32 v163, 0xffff0000, v163
	v_lshlrev_b32_e32 v168, 16, v164
	v_and_b32_e32 v169, 0xffff0000, v164
	v_lshlrev_b32_e32 v164, 16, v165
	v_and_b32_e32 v165, 0xffff0000, v165
	v_rcp_f32_e32 v128, v128
	v_pk_fma_f32 v[126:127], v[126:127], v[166:167], v[168:169]
	v_pk_fma_f32 v[128:129], v[128:129], v[162:163], v[164:165]
	global_store_dwordx4 v[152:153], v[126:129], off
	global_load_dwordx2 v[126:127], v[156:157], off offset:32
	s_nop 0
	global_load_dwordx2 v[128:129], v[154:155], off offset:32
	v_mul_f32_e32 v122, v122, v151
	v_mul_f32_e32 v123, v123, v151
	v_mul_f32_e32 v122, 0xbfb8aa3b, v122
	v_mul_f32_e32 v123, 0xbfb8aa3b, v123
	v_mul_f32_e32 v124, v124, v151
	v_mul_f32_e32 v125, v125, v151
	v_exp_f32_e32 v122, v122
	v_exp_f32_e32 v123, v123
	v_mul_f32_e32 v124, 0xbfb8aa3b, v124
	v_mul_f32_e32 v125, 0xbfb8aa3b, v125
	v_exp_f32_e32 v124, v124
	v_exp_f32_e32 v125, v125
	v_pk_add_f32 v[122:123], v[122:123], 1.0 op_sel_hi:[1,0]
	v_mul_f32_e32 v118, v118, v151
	v_pk_add_f32 v[124:125], v[124:125], 1.0 op_sel_hi:[1,0]
	v_rcp_f32_e32 v123, v123
	v_rcp_f32_e32 v122, v122
	v_rcp_f32_e32 v125, v125
	v_rcp_f32_e32 v124, v124
	v_mul_f32_e32 v119, v119, v151
	v_mul_f32_e32 v118, 0xbfb8aa3b, v118
	v_mul_f32_e32 v119, 0xbfb8aa3b, v119
	v_mul_f32_e32 v120, v120, v151
	v_mul_f32_e32 v121, v121, v151
	v_exp_f32_e32 v118, v118
	v_exp_f32_e32 v119, v119
	v_mul_f32_e32 v120, 0xbfb8aa3b, v120
	s_waitcnt vmcnt(1)
	v_lshlrev_b32_e32 v162, 16, v126
	v_and_b32_e32 v163, 0xffff0000, v126
	v_lshlrev_b32_e32 v126, 16, v127
	v_and_b32_e32 v127, 0xffff0000, v127
	s_waitcnt vmcnt(0)
	v_lshlrev_b32_e32 v164, 16, v128
	v_and_b32_e32 v165, 0xffff0000, v128
	v_lshlrev_b32_e32 v128, 16, v129
	v_and_b32_e32 v129, 0xffff0000, v129
	v_pk_fma_f32 v[124:125], v[124:125], v[126:127], v[128:129]
	v_pk_fma_f32 v[122:123], v[122:123], v[162:163], v[164:165]
	global_store_dwordx4 v[152:153], v[122:125], off offset:64
	global_load_dwordx2 v[122:123], v[156:157], off offset:256
	s_nop 0
	global_load_dwordx2 v[124:125], v[154:155], off offset:256
	v_mul_f32_e32 v121, 0xbfb8aa3b, v121
	v_exp_f32_e32 v120, v120
	v_exp_f32_e32 v121, v121
	v_pk_add_f32 v[118:119], v[118:119], 1.0 op_sel_hi:[1,0]
	v_mul_f32_e32 v114, v114, v151
	v_pk_add_f32 v[120:121], v[120:121], 1.0 op_sel_hi:[1,0]
	v_div_scale_f32 v165, s[6:7], 1.0, v120, 1.0
	v_rcp_f32_e32 v119, v119
	v_rcp_f32_e32 v118, v118
	s_mov_b64 vcc, s[6:7]
	v_rcp_f32_e32 v121, v121
	v_rcp_f32_e32 v120, v120
	v_mul_f32_e32 v115, v115, v151
	v_mul_f32_e32 v114, 0xbfb8aa3b, v114
	v_mul_f32_e32 v115, 0xbfb8aa3b, v115
	v_mul_f32_e32 v116, v116, v151
	v_mul_f32_e32 v117, v117, v151
	v_exp_f32_e32 v114, v114
	v_exp_f32_e32 v115, v115
	v_mul_f32_e32 v116, 0xbfb8aa3b, v116
	v_mul_f32_e32 v117, 0xbfb8aa3b, v117
	v_pk_add_f32 v[114:115], v[114:115], 1.0 op_sel_hi:[1,0]
	s_nop 0
	s_waitcnt vmcnt(1)
	v_lshlrev_b32_e32 v126, 16, v122
	v_and_b32_e32 v127, 0xffff0000, v122
	v_lshlrev_b32_e32 v122, 16, v123
	v_and_b32_e32 v123, 0xffff0000, v123
	s_waitcnt vmcnt(0)
	v_lshlrev_b32_e32 v128, 16, v124
	v_and_b32_e32 v129, 0xffff0000, v124
	v_lshlrev_b32_e32 v124, 16, v125
	v_and_b32_e32 v125, 0xffff0000, v125
	v_pk_fma_f32 v[120:121], v[120:121], v[122:123], v[124:125]
	v_pk_fma_f32 v[118:119], v[118:119], v[126:127], v[128:129]
	global_store_dwordx4 v[152:153], v[118:121], off offset:512
	global_load_dwordx2 v[118:119], v[156:157], off offset:288
	v_exp_f32_e32 v128, v116
	global_load_dwordx2 v[120:121], v[154:155], off offset:288
	v_exp_f32_e32 v129, v117
	s_nop 0
	v_pk_add_f32 v[128:129], v[128:129], 1.0 op_sel_hi:[1,0]
	v_or_b32_e32 v122, 16, v150
	v_ashrrev_i32_e32 v123, 31, v122
	v_cmp_gt_i32_e32 vcc, s45, v122
	v_cndmask_b32_e32 v123, 0, v123, vcc
	v_rcp_f32_e32 v115, v115
	v_rcp_f32_e32 v114, v114
	v_rcp_f32_e32 v129, v129
	v_rcp_f32_e32 v128, v128
	v_lshlrev_b64 v[124:125], 11, v[122:123]
	v_lshl_add_u64 v[126:127], v[122:123], 2, s[10:11]
	v_lshl_add_u64 v[116:117], s[12:13], 0, v[124:125]
	v_lshl_add_u64 v[116:117], v[116:117], 0, v[146:147]
	s_waitcnt vmcnt(1)
; DI float sigmoidf_(float x) { return 1.f / (1.f + __expf(-x)); }
;     DI void operator()(const f32x4 (&acc)[2][2][4][2], const Unit& u, int wr, int wc, int fr, int fq) const {
;     ...
;             for (int m = 0; m < 4; ++m) { const int row = row0 + ai * HALF + m * 16;
;                 const float* bp = (row < MP) ? base0 + (size_t)row * DM : base1 + (size_t)(row - MP) * DM;
;                 float r = 1.f; if (MODE == 1) r = __builtin_amdgcn_rsqf(ssin[row] * (1.f / DM) + EPS);
;                 float s = 0.f;
; #pragma unroll
;                 for (int bj = 0; bj < 2; ++bj)
; #pragma unroll
;                     for (int n = 0; n < 2; ++n) { const int col = col0 + bj * HALF + n * 16;
;                         f32x4 v = acc[ai][bj][m][n];
;                         if (MODE == 1) { const u32x2 pw = *(const u32x2*)(PP + (size_t)row * DM + col);
;                             v[0] = sigmoidf_(v[0] * r) * bflo(pw.x); v[1] = sigmoidf_(v[1] * r) * bfhi(pw.x); v[2] = sigmoidf_(v[2] * r) * bflo(pw.y); v[3] = sigmoidf_(v[3] * r) * bfhi(pw.y); }
;                         f32x4 h;
;                         if (baseb) { const u32x2 bw = *(const u32x2*)(baseb + (size_t)row * DM + col); h = (f32x4){bflo(bw.x), bfhi(bw.x), bflo(bw.y), bfhi(bw.y)} + v; }
;                         else h = *(const f32x4*)(bp + col) + v;
;                         if (H) *(f32x4*)(H + (size_t)row * DM + col) = h;
	v_lshlrev_b32_e32 v154, 16, v118
	v_and_b32_e32 v155, 0xffff0000, v118
	v_lshlrev_b32_e32 v118, 16, v119
	v_and_b32_e32 v119, 0xffff0000, v119
	s_waitcnt vmcnt(0)
	v_lshlrev_b32_e32 v156, 16, v120
	v_and_b32_e32 v157, 0xffff0000, v120
	v_lshlrev_b32_e32 v120, 16, v121
	v_and_b32_e32 v121, 0xffff0000, v121
	v_pk_fma_f32 v[120:121], v[128:129], v[118:119], v[120:121]
	v_pk_fma_f32 v[118:119], v[114:115], v[154:155], v[156:157]
	global_store_dwordx4 v[152:153], v[118:121], off offset:576
	global_load_dword v126, v[126:127], off
	s_nop 0
	global_load_dwordx2 v[120:121], v[116:117], off
	v_lshl_add_u64 v[114:115], s[14:15], 0, v[124:125]
	v_lshl_add_u64 v[118:119], v[114:115], 0, v[146:147]
	global_load_dwordx2 v[124:125], v[118:119], off
	v_lshlrev_b64 v[114:115], 12, v[122:123]
	v_lshl_add_u64 v[114:115], s[48:49], 0, v[114:115]
	v_lshl_add_u64 v[114:115], v[114:115], 0, v[148:149]
	s_waitcnt vmcnt(2)
	v_fmamk_f32 v127, v126, 0x3a800000, v161
	s_waitcnt vmcnt(1)
	v_lshlrev_b32_e32 v122, 16, v120
	v_and_b32_e32 v123, 0xffff0000, v120
	v_rsq_f32_e32 v120, v127
	v_lshlrev_b32_e32 v126, 16, v121
	v_and_b32_e32 v127, 0xffff0000, v121
	s_waitcnt vmcnt(0)
	v_lshlrev_b32_e32 v128, 16, v124
	v_mul_f32_e32 v110, v110, v120
	v_mul_f32_e32 v111, v111, v120
	v_mul_f32_e32 v110, 0xbfb8aa3b, v110
	v_mul_f32_e32 v111, 0xbfb8aa3b, v111
	v_mul_f32_e32 v112, v112, v120
	v_mul_f32_e32 v113, v113, v120
	v_exp_f32_e32 v110, v110
	v_exp_f32_e32 v111, v111
	v_mul_f32_e32 v112, 0xbfb8aa3b, v112
	v_mul_f32_e32 v113, 0xbfb8aa3b, v113
	v_exp_f32_e32 v112, v112
	v_exp_f32_e32 v113, v113
	v_pk_add_f32 v[110:111], v[110:111], 1.0 op_sel_hi:[1,0]
	v_and_b32_e32 v129, 0xffff0000, v124
	v_pk_add_f32 v[112:113], v[112:113], 1.0 op_sel_hi:[1,0]
	v_rcp_f32_e32 v111, v111
	v_rcp_f32_e32 v110, v110
	v_rcp_f32_e32 v113, v113
	v_lshlrev_b32_e32 v124, 16, v125
	v_and_b32_e32 v125, 0xffff0000, v125
	v_rcp_f32_e32 v112, v112
	v_pk_fma_f32 v[110:111], v[110:111], v[122:123], v[128:129]
	v_pk_fma_f32 v[112:113], v[112:113], v[126:127], v[124:125]
	global_store_dwordx4 v[114:115], v[110:113], off
	global_load_dwordx2 v[110:111], v[116:117], off offset:32
	s_nop 0
	global_load_dwordx2 v[112:113], v[118:119], off offset:32
	v_mul_f32_e32 v106, v106, v120
	v_mul_f32_e32 v107, v107, v120
	v_mul_f32_e32 v106, 0xbfb8aa3b, v106
	v_mul_f32_e32 v107, 0xbfb8aa3b, v107
	v_mul_f32_e32 v108, v108, v120
	v_mul_f32_e32 v109, v109, v120
	v_exp_f32_e32 v106, v106
	v_exp_f32_e32 v107, v107
	v_mul_f32_e32 v108, 0xbfb8aa3b, v108
	v_mul_f32_e32 v109, 0xbfb8aa3b, v109
	v_exp_f32_e32 v108, v108
	v_exp_f32_e32 v109, v109
	v_pk_add_f32 v[106:107], v[106:107], 1.0 op_sel_hi:[1,0]
	v_mul_f32_e32 v102, v102, v120
	v_pk_add_f32 v[108:109], v[108:109], 1.0 op_sel_hi:[1,0]
	v_rcp_f32_e32 v107, v107
	v_rcp_f32_e32 v106, v106
	v_rcp_f32_e32 v109, v109
	v_rcp_f32_e32 v108, v108
	v_mul_f32_e32 v103, v103, v120
	v_mul_f32_e32 v102, 0xbfb8aa3b, v102
	v_mul_f32_e32 v103, 0xbfb8aa3b, v103
	v_mul_f32_e32 v104, v104, v120
	v_mul_f32_e32 v105, v105, v120
	v_exp_f32_e32 v102, v102
	v_exp_f32_e32 v103, v103
	v_mul_f32_e32 v104, 0xbfb8aa3b, v104
	s_waitcnt vmcnt(1)
	v_lshlrev_b32_e32 v122, 16, v110
	v_and_b32_e32 v123, 0xffff0000, v110
	v_lshlrev_b32_e32 v110, 16, v111
	v_and_b32_e32 v111, 0xffff0000, v111
	s_waitcnt vmcnt(0)
	v_lshlrev_b32_e32 v124, 16, v112
	v_and_b32_e32 v125, 0xffff0000, v112
	v_lshlrev_b32_e32 v112, 16, v113
	v_and_b32_e32 v113, 0xffff0000, v113
	v_pk_fma_f32 v[108:109], v[108:109], v[110:111], v[112:113]
	v_pk_fma_f32 v[106:107], v[106:107], v[122:123], v[124:125]
	global_store_dwordx4 v[114:115], v[106:109], off offset:64
	global_load_dwordx2 v[106:107], v[116:117], off offset:256
	s_nop 0
	global_load_dwordx2 v[108:109], v[118:119], off offset:256
	v_mul_f32_e32 v105, 0xbfb8aa3b, v105
	v_exp_f32_e32 v104, v104
	v_exp_f32_e32 v105, v105
	v_pk_add_f32 v[102:103], v[102:103], 1.0 op_sel_hi:[1,0]
	v_mul_f32_e32 v98, v98, v120
	v_pk_add_f32 v[104:105], v[104:105], 1.0 op_sel_hi:[1,0]
	v_div_scale_f32 v124, s[6:7], 1.0, v104, 1.0
	v_rcp_f32_e32 v103, v103
	v_rcp_f32_e32 v102, v102
	s_mov_b64 vcc, s[6:7]
	v_rcp_f32_e32 v105, v105
	v_rcp_f32_e32 v104, v104
	v_mul_f32_e32 v99, v99, v120
	v_mul_f32_e32 v98, 0xbfb8aa3b, v98
	v_mul_f32_e32 v99, 0xbfb8aa3b, v99
	v_mul_f32_e32 v100, v100, v120
	v_mul_f32_e32 v101, v101, v120
	v_exp_f32_e32 v98, v98
	v_exp_f32_e32 v99, v99
	v_mul_f32_e32 v100, 0xbfb8aa3b, v100
	v_mul_f32_e32 v101, 0xbfb8aa3b, v101
	v_pk_add_f32 v[98:99], v[98:99], 1.0 op_sel_hi:[1,0]
	s_waitcnt vmcnt(1)
	v_lshlrev_b32_e32 v110, 16, v106
	v_and_b32_e32 v111, 0xffff0000, v106
	v_lshlrev_b32_e32 v106, 16, v107
	v_and_b32_e32 v107, 0xffff0000, v107
	s_waitcnt vmcnt(0)
	v_lshlrev_b32_e32 v112, 16, v108
	v_and_b32_e32 v113, 0xffff0000, v108
	v_lshlrev_b32_e32 v108, 16, v109
	v_and_b32_e32 v109, 0xffff0000, v109
	v_pk_fma_f32 v[104:105], v[104:105], v[106:107], v[108:109]
	v_pk_fma_f32 v[102:103], v[102:103], v[110:111], v[112:113]
	global_store_dwordx4 v[114:115], v[102:105], off offset:512
	global_load_dwordx2 v[102:103], v[116:117], off offset:288
	v_exp_f32_e32 v112, v100
	global_load_dwordx2 v[104:105], v[118:119], off offset:288
	v_exp_f32_e32 v113, v101
	s_nop 0
	v_pk_add_f32 v[112:113], v[112:113], 1.0 op_sel_hi:[1,0]
	v_or_b32_e32 v106, 32, v150
	v_ashrrev_i32_e32 v107, 31, v106
	v_cmp_gt_i32_e32 vcc, s45, v106
	v_cndmask_b32_e32 v107, 0, v107, vcc
	v_rcp_f32_e32 v99, v99
	v_rcp_f32_e32 v98, v98
	v_rcp_f32_e32 v113, v113
	v_rcp_f32_e32 v112, v112
	v_lshlrev_b64 v[108:109], 11, v[106:107]
	v_lshl_add_u64 v[110:111], v[106:107], 2, s[10:11]
	v_lshl_add_u64 v[100:101], s[12:13], 0, v[108:109]
	v_lshl_add_u64 v[100:101], v[100:101], 0, v[146:147]
	s_waitcnt vmcnt(1)
; DI float sigmoidf_(float x) { return 1.f / (1.f + __expf(-x)); }
;     DI void operator()(const f32x4 (&acc)[2][2][4][2], const Unit& u, int wr, int wc, int fr, int fq) const {
;     ...
;             for (int m = 0; m < 4; ++m) { const int row = row0 + ai * HALF + m * 16;
;                 const float* bp = (row < MP) ? base0 + (size_t)row * DM : base1 + (size_t)(row - MP) * DM;
;                 float r = 1.f; if (MODE == 1) r = __builtin_amdgcn_rsqf(ssin[row] * (1.f / DM) + EPS);
;                 float s = 0.f;
; #pragma unroll
;                 for (int bj = 0; bj < 2; ++bj)
; #pragma unroll
;                     for (int n = 0; n < 2; ++n) { const int col = col0 + bj * HALF + n * 16;
;                         f32x4 v = acc[ai][bj][m][n];
;                         if (MODE == 1) { const u32x2 pw = *(const u32x2*)(PP + (size_t)row * DM + col);
;                             v[0] = sigmoidf_(v[0] * r) * bflo(pw.x); v[1] = sigmoidf_(v[1] * r) * bfhi(pw.x); v[2] = sigmoidf_(v[2] * r) * bflo(pw.y); v[3] = sigmoidf_(v[3] * r) * bfhi(pw.y); }
;                         f32x4 h;
;                         if (baseb) { const u32x2 bw = *(const u32x2*)(baseb + (size_t)row * DM + col); h = (f32x4){bflo(bw.x), bfhi(bw.x), bflo(bw.y), bfhi(bw.y)} + v; }
;                         else h = *(const f32x4*)(bp + col) + v;
;                         if (H) *(f32x4*)(H + (size_t)row * DM + col) = h;
	v_lshlrev_b32_e32 v116, 16, v102
	v_and_b32_e32 v117, 0xffff0000, v102
	v_lshlrev_b32_e32 v102, 16, v103
	v_and_b32_e32 v103, 0xffff0000, v103
	s_waitcnt vmcnt(0)
	v_lshlrev_b32_e32 v118, 16, v104
	v_and_b32_e32 v119, 0xffff0000, v104
	v_lshlrev_b32_e32 v104, 16, v105
	v_and_b32_e32 v105, 0xffff0000, v105
	v_pk_fma_f32 v[104:105], v[112:113], v[102:103], v[104:105]
	v_pk_fma_f32 v[102:103], v[98:99], v[116:117], v[118:119]
	global_store_dwordx4 v[114:115], v[102:105], off offset:576
	global_load_dword v110, v[110:111], off
	s_nop 0
	global_load_dwordx2 v[104:105], v[100:101], off
	v_lshl_add_u64 v[98:99], s[14:15], 0, v[108:109]
	v_lshl_add_u64 v[102:103], v[98:99], 0, v[146:147]
	global_load_dwordx2 v[108:109], v[102:103], off
	v_lshlrev_b64 v[98:99], 12, v[106:107]
	v_lshl_add_u64 v[98:99], s[48:49], 0, v[98:99]
	v_lshl_add_u64 v[98:99], v[98:99], 0, v[148:149]
	s_waitcnt vmcnt(2)
	v_fmamk_f32 v111, v110, 0x3a800000, v161
	s_waitcnt vmcnt(1)
	v_lshlrev_b32_e32 v106, 16, v104
	v_and_b32_e32 v107, 0xffff0000, v104
	v_rsq_f32_e32 v104, v111
	v_lshlrev_b32_e32 v110, 16, v105
	v_and_b32_e32 v111, 0xffff0000, v105
	s_waitcnt vmcnt(0)
	v_lshlrev_b32_e32 v112, 16, v108
	v_mul_f32_e32 v94, v94, v104
	v_mul_f32_e32 v95, v95, v104
	v_mul_f32_e32 v94, 0xbfb8aa3b, v94
	v_mul_f32_e32 v95, 0xbfb8aa3b, v95
	v_mul_f32_e32 v96, v96, v104
	v_mul_f32_e32 v97, v97, v104
	v_exp_f32_e32 v94, v94
	v_exp_f32_e32 v95, v95
	v_mul_f32_e32 v96, 0xbfb8aa3b, v96
	v_mul_f32_e32 v97, 0xbfb8aa3b, v97
	v_exp_f32_e32 v96, v96
	v_exp_f32_e32 v97, v97
	v_pk_add_f32 v[94:95], v[94:95], 1.0 op_sel_hi:[1,0]
	v_and_b32_e32 v113, 0xffff0000, v108
	v_pk_add_f32 v[96:97], v[96:97], 1.0 op_sel_hi:[1,0]
	v_rcp_f32_e32 v95, v95
	v_rcp_f32_e32 v94, v94
	v_rcp_f32_e32 v97, v97
	v_lshlrev_b32_e32 v108, 16, v109
	v_and_b32_e32 v109, 0xffff0000, v109
	v_rcp_f32_e32 v96, v96
	v_pk_fma_f32 v[94:95], v[94:95], v[106:107], v[112:113]
	v_pk_fma_f32 v[96:97], v[96:97], v[110:111], v[108:109]
	global_store_dwordx4 v[98:99], v[94:97], off
	global_load_dwordx2 v[94:95], v[100:101], off offset:32
	s_nop 0
	global_load_dwordx2 v[96:97], v[102:103], off offset:32
	v_mul_f32_e32 v90, v90, v104
	v_mul_f32_e32 v91, v91, v104
	v_mul_f32_e32 v90, 0xbfb8aa3b, v90
	v_mul_f32_e32 v91, 0xbfb8aa3b, v91
	v_mul_f32_e32 v92, v92, v104
	v_mul_f32_e32 v93, v93, v104
	v_exp_f32_e32 v90, v90
	v_exp_f32_e32 v91, v91
	v_mul_f32_e32 v92, 0xbfb8aa3b, v92
	v_mul_f32_e32 v93, 0xbfb8aa3b, v93
	v_exp_f32_e32 v92, v92
	v_exp_f32_e32 v93, v93
	v_pk_add_f32 v[90:91], v[90:91], 1.0 op_sel_hi:[1,0]
	v_mul_f32_e32 v86, v86, v104
	v_pk_add_f32 v[92:93], v[92:93], 1.0 op_sel_hi:[1,0]
	v_rcp_f32_e32 v91, v91
	v_rcp_f32_e32 v90, v90
	v_rcp_f32_e32 v93, v93
	v_rcp_f32_e32 v92, v92
	v_mul_f32_e32 v87, v87, v104
	v_mul_f32_e32 v86, 0xbfb8aa3b, v86
	v_mul_f32_e32 v87, 0xbfb8aa3b, v87
	v_mul_f32_e32 v88, v88, v104
	v_mul_f32_e32 v89, v89, v104
	v_exp_f32_e32 v86, v86
	v_exp_f32_e32 v87, v87
	v_mul_f32_e32 v88, 0xbfb8aa3b, v88
	s_waitcnt vmcnt(1)
	v_lshlrev_b32_e32 v106, 16, v94
	v_and_b32_e32 v107, 0xffff0000, v94
	v_lshlrev_b32_e32 v94, 16, v95
	v_and_b32_e32 v95, 0xffff0000, v95
	s_waitcnt vmcnt(0)
	v_lshlrev_b32_e32 v108, 16, v96
	v_and_b32_e32 v109, 0xffff0000, v96
	v_lshlrev_b32_e32 v96, 16, v97
	v_and_b32_e32 v97, 0xffff0000, v97
	v_pk_fma_f32 v[92:93], v[92:93], v[94:95], v[96:97]
	v_pk_fma_f32 v[90:91], v[90:91], v[106:107], v[108:109]
	global_store_dwordx4 v[98:99], v[90:93], off offset:64
	global_load_dwordx2 v[90:91], v[100:101], off offset:256
	s_nop 0
	global_load_dwordx2 v[92:93], v[102:103], off offset:256
	v_mul_f32_e32 v89, 0xbfb8aa3b, v89
	v_exp_f32_e32 v88, v88
	v_exp_f32_e32 v89, v89
	v_pk_add_f32 v[86:87], v[86:87], 1.0 op_sel_hi:[1,0]
	v_mul_f32_e32 v82, v82, v104
	v_pk_add_f32 v[88:89], v[88:89], 1.0 op_sel_hi:[1,0]
	v_div_scale_f32 v108, s[6:7], 1.0, v88, 1.0
	v_rcp_f32_e32 v87, v87
	v_rcp_f32_e32 v86, v86
	s_mov_b64 vcc, s[6:7]
	v_rcp_f32_e32 v89, v89
	v_rcp_f32_e32 v88, v88
	v_mul_f32_e32 v83, v83, v104
	v_mul_f32_e32 v82, 0xbfb8aa3b, v82
	v_mul_f32_e32 v83, 0xbfb8aa3b, v83
	v_mul_f32_e32 v84, v84, v104
	v_mul_f32_e32 v85, v85, v104
	v_exp_f32_e32 v82, v82
	v_exp_f32_e32 v83, v83
	v_mul_f32_e32 v84, 0xbfb8aa3b, v84
	v_mul_f32_e32 v85, 0xbfb8aa3b, v85
	v_pk_add_f32 v[82:83], v[82:83], 1.0 op_sel_hi:[1,0]
	s_waitcnt vmcnt(1)
	v_lshlrev_b32_e32 v94, 16, v90
	v_and_b32_e32 v95, 0xffff0000, v90
	v_lshlrev_b32_e32 v90, 16, v91
	v_and_b32_e32 v91, 0xffff0000, v91
	s_waitcnt vmcnt(0)
	v_lshlrev_b32_e32 v96, 16, v92
	v_and_b32_e32 v97, 0xffff0000, v92
	v_lshlrev_b32_e32 v92, 16, v93
	v_and_b32_e32 v93, 0xffff0000, v93
	v_pk_fma_f32 v[88:89], v[88:89], v[90:91], v[92:93]
	v_pk_fma_f32 v[86:87], v[86:87], v[94:95], v[96:97]
	global_store_dwordx4 v[98:99], v[86:89], off offset:512
	global_load_dwordx2 v[86:87], v[100:101], off offset:288
	v_exp_f32_e32 v96, v84
	global_load_dwordx2 v[88:89], v[102:103], off offset:288
	v_exp_f32_e32 v97, v85
	s_nop 0
	v_pk_add_f32 v[96:97], v[96:97], 1.0 op_sel_hi:[1,0]
	v_or_b32_e32 v90, 48, v150
	v_ashrrev_i32_e32 v91, 31, v90
	v_cmp_gt_i32_e32 vcc, s45, v90
	v_cndmask_b32_e32 v91, 0, v91, vcc
	v_rcp_f32_e32 v83, v83
	v_rcp_f32_e32 v82, v82
	v_rcp_f32_e32 v97, v97
	v_rcp_f32_e32 v96, v96
	v_lshlrev_b64 v[92:93], 11, v[90:91]
	v_lshl_add_u64 v[94:95], v[90:91], 2, s[10:11]
	v_lshl_add_u64 v[84:85], s[12:13], 0, v[92:93]
	v_lshl_add_u64 v[84:85], v[84:85], 0, v[146:147]
	s_waitcnt vmcnt(1)
	v_lshlrev_b32_e32 v100, 16, v86
	v_and_b32_e32 v101, 0xffff0000, v86
	v_lshlrev_b32_e32 v86, 16, v87
	v_and_b32_e32 v87, 0xffff0000, v87
	s_waitcnt vmcnt(0)
; DI float sigmoidf_(float x) { return 1.f / (1.f + __expf(-x)); }
;     DI void operator()(const f32x4 (&acc)[2][2][4][2], const Unit& u, int wr, int wc, int fr, int fq) const {
;     ...
;             for (int m = 0; m < 4; ++m) { const int row = row0 + ai * HALF + m * 16;
;                 const float* bp = (row < MP) ? base0 + (size_t)row * DM : base1 + (size_t)(row - MP) * DM;
;                 float r = 1.f; if (MODE == 1) r = __builtin_amdgcn_rsqf(ssin[row] * (1.f / DM) + EPS);
;                 float s = 0.f;
; #pragma unroll
;                 for (int bj = 0; bj < 2; ++bj)
; #pragma unroll
;                     for (int n = 0; n < 2; ++n) { const int col = col0 + bj * HALF + n * 16;
;                         f32x4 v = acc[ai][bj][m][n];
;                         if (MODE == 1) { const u32x2 pw = *(const u32x2*)(PP + (size_t)row * DM + col);
;                             v[0] = sigmoidf_(v[0] * r) * bflo(pw.x); v[1] = sigmoidf_(v[1] * r) * bfhi(pw.x); v[2] = sigmoidf_(v[2] * r) * bflo(pw.y); v[3] = sigmoidf_(v[3] * r) * bfhi(pw.y); }
;                         f32x4 h;
;                         if (baseb) { const u32x2 bw = *(const u32x2*)(baseb + (size_t)row * DM + col); h = (f32x4){bflo(bw.x), bfhi(bw.x), bflo(bw.y), bfhi(bw.y)} + v; }
;                         else h = *(const f32x4*)(bp + col) + v;
;                         if (H) *(f32x4*)(H + (size_t)row * DM + col) = h;
	v_lshlrev_b32_e32 v102, 16, v88
	v_and_b32_e32 v103, 0xffff0000, v88
	v_lshlrev_b32_e32 v88, 16, v89
	v_and_b32_e32 v89, 0xffff0000, v89
	v_pk_fma_f32 v[88:89], v[96:97], v[86:87], v[88:89]
	v_pk_fma_f32 v[86:87], v[82:83], v[100:101], v[102:103]
	global_store_dwordx4 v[98:99], v[86:89], off offset:576
	global_load_dword v94, v[94:95], off
	s_nop 0
	global_load_dwordx2 v[88:89], v[84:85], off
	v_lshl_add_u64 v[82:83], s[14:15], 0, v[92:93]
	v_lshl_add_u64 v[86:87], v[82:83], 0, v[146:147]
	global_load_dwordx2 v[92:93], v[86:87], off
	v_lshlrev_b64 v[82:83], 12, v[90:91]
	v_lshl_add_u64 v[82:83], s[48:49], 0, v[82:83]
	v_lshl_add_u64 v[82:83], v[82:83], 0, v[148:149]
	s_waitcnt vmcnt(2)
	v_fmamk_f32 v95, v94, 0x3a800000, v161
	s_waitcnt vmcnt(1)
	v_lshlrev_b32_e32 v90, 16, v88
	v_and_b32_e32 v91, 0xffff0000, v88
	v_rsq_f32_e32 v88, v95
	v_lshlrev_b32_e32 v94, 16, v89
	v_and_b32_e32 v95, 0xffff0000, v89
	s_waitcnt vmcnt(0)
	v_lshlrev_b32_e32 v96, 16, v92
	v_mul_f32_e32 v78, v78, v88
	v_mul_f32_e32 v79, v79, v88
	v_mul_f32_e32 v78, 0xbfb8aa3b, v78
	v_mul_f32_e32 v79, 0xbfb8aa3b, v79
	v_mul_f32_e32 v80, v80, v88
	v_mul_f32_e32 v81, v81, v88
	v_exp_f32_e32 v78, v78
	v_exp_f32_e32 v79, v79
	v_mul_f32_e32 v80, 0xbfb8aa3b, v80
	v_mul_f32_e32 v81, 0xbfb8aa3b, v81
	v_exp_f32_e32 v80, v80
	v_exp_f32_e32 v81, v81
	v_pk_add_f32 v[78:79], v[78:79], 1.0 op_sel_hi:[1,0]
	v_and_b32_e32 v97, 0xffff0000, v92
	v_pk_add_f32 v[80:81], v[80:81], 1.0 op_sel_hi:[1,0]
	v_rcp_f32_e32 v79, v79
	v_rcp_f32_e32 v78, v78
	v_rcp_f32_e32 v81, v81
	v_lshlrev_b32_e32 v92, 16, v93
	v_and_b32_e32 v93, 0xffff0000, v93
	v_rcp_f32_e32 v80, v80
	v_pk_fma_f32 v[78:79], v[78:79], v[90:91], v[96:97]
	v_pk_fma_f32 v[80:81], v[80:81], v[94:95], v[92:93]
	global_store_dwordx4 v[82:83], v[78:81], off
	global_load_dwordx2 v[78:79], v[84:85], off offset:32
	s_nop 0
	global_load_dwordx2 v[80:81], v[86:87], off offset:32
	v_mul_f32_e32 v74, v74, v88
	v_mul_f32_e32 v75, v75, v88
	v_mul_f32_e32 v74, 0xbfb8aa3b, v74
	v_mul_f32_e32 v75, 0xbfb8aa3b, v75
	v_mul_f32_e32 v76, v76, v88
	v_mul_f32_e32 v77, v77, v88
	v_exp_f32_e32 v74, v74
	v_exp_f32_e32 v75, v75
	v_mul_f32_e32 v76, 0xbfb8aa3b, v76
	v_mul_f32_e32 v77, 0xbfb8aa3b, v77
	v_exp_f32_e32 v76, v76
	v_exp_f32_e32 v77, v77
	v_pk_add_f32 v[74:75], v[74:75], 1.0 op_sel_hi:[1,0]
	v_mul_f32_e32 v70, v70, v88
	v_pk_add_f32 v[76:77], v[76:77], 1.0 op_sel_hi:[1,0]
	v_rcp_f32_e32 v75, v75
	v_rcp_f32_e32 v74, v74
	v_rcp_f32_e32 v77, v77
	v_rcp_f32_e32 v76, v76
	v_mul_f32_e32 v71, v71, v88
	v_mul_f32_e32 v70, 0xbfb8aa3b, v70
	v_mul_f32_e32 v71, 0xbfb8aa3b, v71
	v_mul_f32_e32 v72, v72, v88
	v_mul_f32_e32 v73, v73, v88
	v_exp_f32_e32 v70, v70
	v_exp_f32_e32 v71, v71
	v_mul_f32_e32 v72, 0xbfb8aa3b, v72
	s_waitcnt vmcnt(1)
	v_lshlrev_b32_e32 v90, 16, v78
	v_and_b32_e32 v91, 0xffff0000, v78
	v_lshlrev_b32_e32 v78, 16, v79
	v_and_b32_e32 v79, 0xffff0000, v79
	s_waitcnt vmcnt(0)
	v_lshlrev_b32_e32 v92, 16, v80
	v_and_b32_e32 v93, 0xffff0000, v80
	v_lshlrev_b32_e32 v80, 16, v81
	v_and_b32_e32 v81, 0xffff0000, v81
	v_pk_fma_f32 v[76:77], v[76:77], v[78:79], v[80:81]
	v_pk_fma_f32 v[74:75], v[74:75], v[90:91], v[92:93]
	global_store_dwordx4 v[82:83], v[74:77], off offset:64
	global_load_dwordx2 v[74:75], v[84:85], off offset:256
	s_nop 0
	global_load_dwordx2 v[76:77], v[86:87], off offset:256
	v_mul_f32_e32 v73, 0xbfb8aa3b, v73
	v_exp_f32_e32 v72, v72
	v_exp_f32_e32 v73, v73
	v_pk_add_f32 v[70:71], v[70:71], 1.0 op_sel_hi:[1,0]
	v_mul_f32_e32 v66, v66, v88
	v_pk_add_f32 v[72:73], v[72:73], 1.0 op_sel_hi:[1,0]
	v_div_scale_f32 v92, s[6:7], 1.0, v72, 1.0
	v_rcp_f32_e32 v71, v71
	v_rcp_f32_e32 v70, v70
	s_mov_b64 vcc, s[6:7]
	v_rcp_f32_e32 v73, v73
	v_rcp_f32_e32 v72, v72
	v_mul_f32_e32 v67, v67, v88
	v_mul_f32_e32 v66, 0xbfb8aa3b, v66
	v_mul_f32_e32 v67, 0xbfb8aa3b, v67
	v_mul_f32_e32 v68, v68, v88
	v_mul_f32_e32 v69, v69, v88
	v_exp_f32_e32 v66, v66
	v_exp_f32_e32 v67, v67
	v_mul_f32_e32 v68, 0xbfb8aa3b, v68
	v_mul_f32_e32 v69, 0xbfb8aa3b, v69
	v_cmp_gt_i32_e32 vcc, s55, v150
	v_pk_add_f32 v[66:67], v[66:67], 1.0 op_sel_hi:[1,0]
	s_waitcnt vmcnt(1)
	v_lshlrev_b32_e32 v78, 16, v74
	v_and_b32_e32 v79, 0xffff0000, v74
	v_lshlrev_b32_e32 v74, 16, v75
	v_and_b32_e32 v75, 0xffff0000, v75
	s_waitcnt vmcnt(0)
	v_lshlrev_b32_e32 v80, 16, v76
	v_and_b32_e32 v81, 0xffff0000, v76
	v_lshlrev_b32_e32 v76, 16, v77
	v_and_b32_e32 v77, 0xffff0000, v77
	v_pk_fma_f32 v[72:73], v[72:73], v[74:75], v[76:77]
	v_pk_fma_f32 v[70:71], v[70:71], v[78:79], v[80:81]
	global_store_dwordx4 v[82:83], v[70:73], off offset:512
	global_load_dwordx2 v[70:71], v[84:85], off offset:288
	v_exp_f32_e32 v80, v68
	global_load_dwordx2 v[72:73], v[86:87], off offset:288
	v_exp_f32_e32 v81, v69
	s_nop 0
	v_pk_add_f32 v[80:81], v[80:81], 1.0 op_sel_hi:[1,0]
	v_add_u32_e32 v74, 0x80, v150
	v_ashrrev_i32_e32 v75, 31, v74
	v_cndmask_b32_e32 v75, 0, v75, vcc
	v_rcp_f32_e32 v67, v67
	v_rcp_f32_e32 v66, v66
	v_rcp_f32_e32 v81, v81
	v_rcp_f32_e32 v80, v80
	v_lshlrev_b64 v[76:77], 11, v[74:75]
	v_lshl_add_u64 v[78:79], v[74:75], 2, s[10:11]
	v_lshl_add_u64 v[68:69], s[12:13], 0, v[76:77]
	v_lshl_add_u64 v[68:69], v[68:69], 0, v[146:147]
	s_waitcnt vmcnt(1)
	v_lshlrev_b32_e32 v84, 16, v70
	v_and_b32_e32 v85, 0xffff0000, v70
	v_lshlrev_b32_e32 v70, 16, v71
	v_and_b32_e32 v71, 0xffff0000, v71
	s_waitcnt vmcnt(0)
; DI float sigmoidf_(float x) { return 1.f / (1.f + __expf(-x)); }
;     DI void operator()(const f32x4 (&acc)[2][2][4][2], const Unit& u, int wr, int wc, int fr, int fq) const {
;     ...
;             for (int m = 0; m < 4; ++m) { const int row = row0 + ai * HALF + m * 16;
;                 const float* bp = (row < MP) ? base0 + (size_t)row * DM : base1 + (size_t)(row - MP) * DM;
;                 float r = 1.f; if (MODE == 1) r = __builtin_amdgcn_rsqf(ssin[row] * (1.f / DM) + EPS);
;                 float s = 0.f;
; #pragma unroll
;                 for (int bj = 0; bj < 2; ++bj)
; #pragma unroll
;                     for (int n = 0; n < 2; ++n) { const int col = col0 + bj * HALF + n * 16;
;                         f32x4 v = acc[ai][bj][m][n];
;                         if (MODE == 1) { const u32x2 pw = *(const u32x2*)(PP + (size_t)row * DM + col);
;                             v[0] = sigmoidf_(v[0] * r) * bflo(pw.x); v[1] = sigmoidf_(v[1] * r) * bfhi(pw.x); v[2] = sigmoidf_(v[2] * r) * bflo(pw.y); v[3] = sigmoidf_(v[3] * r) * bfhi(pw.y); }
;                         f32x4 h;
;                         if (baseb) { const u32x2 bw = *(const u32x2*)(baseb + (size_t)row * DM + col); h = (f32x4){bflo(bw.x), bfhi(bw.x), bflo(bw.y), bfhi(bw.y)} + v; }
;                         else h = *(const f32x4*)(bp + col) + v;
;                         if (H) *(f32x4*)(H + (size_t)row * DM + col) = h;
	v_lshlrev_b32_e32 v86, 16, v72
	v_and_b32_e32 v87, 0xffff0000, v72
	v_lshlrev_b32_e32 v72, 16, v73
	v_and_b32_e32 v73, 0xffff0000, v73
	v_pk_fma_f32 v[72:73], v[80:81], v[70:71], v[72:73]
	v_pk_fma_f32 v[70:71], v[66:67], v[84:85], v[86:87]
	global_store_dwordx4 v[82:83], v[70:73], off offset:576
	global_load_dword v78, v[78:79], off
	s_nop 0
	global_load_dwordx2 v[72:73], v[68:69], off
	v_lshl_add_u64 v[66:67], s[14:15], 0, v[76:77]
	v_lshl_add_u64 v[70:71], v[66:67], 0, v[146:147]
	global_load_dwordx2 v[76:77], v[70:71], off
	v_lshlrev_b64 v[66:67], 12, v[74:75]
	v_lshl_add_u64 v[66:67], s[48:49], 0, v[66:67]
	v_lshl_add_u64 v[66:67], v[66:67], 0, v[148:149]
	s_waitcnt vmcnt(2)
	v_fmamk_f32 v79, v78, 0x3a800000, v161
	s_waitcnt vmcnt(1)
	v_lshlrev_b32_e32 v74, 16, v72
	v_and_b32_e32 v75, 0xffff0000, v72
	v_rsq_f32_e32 v72, v79
	v_lshlrev_b32_e32 v78, 16, v73
	v_and_b32_e32 v79, 0xffff0000, v73
	s_waitcnt vmcnt(0)
	v_lshlrev_b32_e32 v80, 16, v76
	v_mul_f32_e32 v62, v62, v72
	v_mul_f32_e32 v63, v63, v72
	v_mul_f32_e32 v62, 0xbfb8aa3b, v62
	v_mul_f32_e32 v63, 0xbfb8aa3b, v63
	v_mul_f32_e32 v64, v64, v72
	v_mul_f32_e32 v65, v65, v72
	v_exp_f32_e32 v62, v62
	v_exp_f32_e32 v63, v63
	v_mul_f32_e32 v64, 0xbfb8aa3b, v64
	v_mul_f32_e32 v65, 0xbfb8aa3b, v65
	v_exp_f32_e32 v64, v64
	v_exp_f32_e32 v65, v65
	v_pk_add_f32 v[62:63], v[62:63], 1.0 op_sel_hi:[1,0]
	v_and_b32_e32 v81, 0xffff0000, v76
	v_pk_add_f32 v[64:65], v[64:65], 1.0 op_sel_hi:[1,0]
	v_rcp_f32_e32 v63, v63
	v_rcp_f32_e32 v62, v62
	v_rcp_f32_e32 v65, v65
	v_lshlrev_b32_e32 v76, 16, v77
	v_and_b32_e32 v77, 0xffff0000, v77
	v_rcp_f32_e32 v64, v64
	v_pk_fma_f32 v[62:63], v[62:63], v[74:75], v[80:81]
	v_pk_fma_f32 v[64:65], v[64:65], v[78:79], v[76:77]
	global_store_dwordx4 v[66:67], v[62:65], off
	global_load_dwordx2 v[62:63], v[68:69], off offset:32
	s_nop 0
	global_load_dwordx2 v[64:65], v[70:71], off offset:32
	v_mul_f32_e32 v58, v58, v72
	v_mul_f32_e32 v59, v59, v72
	v_mul_f32_e32 v58, 0xbfb8aa3b, v58
	v_mul_f32_e32 v59, 0xbfb8aa3b, v59
	v_mul_f32_e32 v60, v60, v72
	v_mul_f32_e32 v61, v61, v72
	v_exp_f32_e32 v58, v58
	v_exp_f32_e32 v59, v59
	v_mul_f32_e32 v60, 0xbfb8aa3b, v60
	v_mul_f32_e32 v61, 0xbfb8aa3b, v61
	v_exp_f32_e32 v60, v60
	v_exp_f32_e32 v61, v61
	v_pk_add_f32 v[58:59], v[58:59], 1.0 op_sel_hi:[1,0]
	v_mul_f32_e32 v54, v54, v72
	v_pk_add_f32 v[60:61], v[60:61], 1.0 op_sel_hi:[1,0]
	v_rcp_f32_e32 v59, v59
	v_rcp_f32_e32 v58, v58
	v_rcp_f32_e32 v61, v61
	v_rcp_f32_e32 v60, v60
	v_mul_f32_e32 v55, v55, v72
	v_mul_f32_e32 v54, 0xbfb8aa3b, v54
	v_mul_f32_e32 v55, 0xbfb8aa3b, v55
	v_mul_f32_e32 v56, v56, v72
	v_mul_f32_e32 v57, v57, v72
	v_exp_f32_e32 v54, v54
	v_exp_f32_e32 v55, v55
	v_mul_f32_e32 v56, 0xbfb8aa3b, v56
	s_waitcnt vmcnt(1)
	v_lshlrev_b32_e32 v74, 16, v62
	v_and_b32_e32 v75, 0xffff0000, v62
	v_lshlrev_b32_e32 v62, 16, v63
	v_and_b32_e32 v63, 0xffff0000, v63
	s_waitcnt vmcnt(0)
	v_lshlrev_b32_e32 v76, 16, v64
	v_and_b32_e32 v77, 0xffff0000, v64
	v_lshlrev_b32_e32 v64, 16, v65
	v_and_b32_e32 v65, 0xffff0000, v65
	v_pk_fma_f32 v[60:61], v[60:61], v[62:63], v[64:65]
	v_pk_fma_f32 v[58:59], v[58:59], v[74:75], v[76:77]
	global_store_dwordx4 v[66:67], v[58:61], off offset:64
	global_load_dwordx2 v[58:59], v[68:69], off offset:256
	s_nop 0
	global_load_dwordx2 v[60:61], v[70:71], off offset:256
	v_mul_f32_e32 v57, 0xbfb8aa3b, v57
	v_exp_f32_e32 v56, v56
	v_exp_f32_e32 v57, v57
	v_pk_add_f32 v[54:55], v[54:55], 1.0 op_sel_hi:[1,0]
	v_mul_f32_e32 v50, v50, v72
	v_pk_add_f32 v[56:57], v[56:57], 1.0 op_sel_hi:[1,0]
	v_div_scale_f32 v76, s[6:7], 1.0, v56, 1.0
	v_rcp_f32_e32 v55, v55
	v_rcp_f32_e32 v54, v54
	s_mov_b64 vcc, s[6:7]
	v_rcp_f32_e32 v57, v57
	v_rcp_f32_e32 v56, v56
	v_mul_f32_e32 v51, v51, v72
	v_mul_f32_e32 v50, 0xbfb8aa3b, v50
	v_mul_f32_e32 v51, 0xbfb8aa3b, v51
	v_mul_f32_e32 v52, v52, v72
	v_mul_f32_e32 v53, v53, v72
	v_exp_f32_e32 v50, v50
	v_exp_f32_e32 v51, v51
	v_mul_f32_e32 v52, 0xbfb8aa3b, v52
	v_mul_f32_e32 v53, 0xbfb8aa3b, v53
	v_cmp_gt_i32_e32 vcc, s56, v150
	v_pk_add_f32 v[50:51], v[50:51], 1.0 op_sel_hi:[1,0]
	s_waitcnt vmcnt(1)
	v_lshlrev_b32_e32 v62, 16, v58
	v_and_b32_e32 v63, 0xffff0000, v58
	v_lshlrev_b32_e32 v58, 16, v59
	v_and_b32_e32 v59, 0xffff0000, v59
	s_waitcnt vmcnt(0)
	v_lshlrev_b32_e32 v64, 16, v60
	v_and_b32_e32 v65, 0xffff0000, v60
	v_lshlrev_b32_e32 v60, 16, v61
	v_and_b32_e32 v61, 0xffff0000, v61
	v_pk_fma_f32 v[56:57], v[56:57], v[58:59], v[60:61]
	v_pk_fma_f32 v[54:55], v[54:55], v[62:63], v[64:65]
	global_store_dwordx4 v[66:67], v[54:57], off offset:512
	global_load_dwordx2 v[54:55], v[68:69], off offset:288
	v_exp_f32_e32 v64, v52
	global_load_dwordx2 v[56:57], v[70:71], off offset:288
	v_exp_f32_e32 v65, v53
	s_nop 0
	v_pk_add_f32 v[64:65], v[64:65], 1.0 op_sel_hi:[1,0]
	v_add_u32_e32 v58, 0x90, v150
	v_ashrrev_i32_e32 v59, 31, v58
	v_cndmask_b32_e32 v59, 0, v59, vcc
	v_rcp_f32_e32 v51, v51
	v_rcp_f32_e32 v50, v50
	v_rcp_f32_e32 v65, v65
	v_rcp_f32_e32 v64, v64
	v_lshlrev_b64 v[60:61], 11, v[58:59]
	v_lshl_add_u64 v[62:63], v[58:59], 2, s[10:11]
	v_lshl_add_u64 v[52:53], s[12:13], 0, v[60:61]
	v_lshl_add_u64 v[52:53], v[52:53], 0, v[146:147]
	s_waitcnt vmcnt(1)
	v_lshlrev_b32_e32 v68, 16, v54
	v_and_b32_e32 v69, 0xffff0000, v54
	v_lshlrev_b32_e32 v54, 16, v55
	v_and_b32_e32 v55, 0xffff0000, v55
	s_waitcnt vmcnt(0)
; DI float sigmoidf_(float x) { return 1.f / (1.f + __expf(-x)); }
;     DI void operator()(const f32x4 (&acc)[2][2][4][2], const Unit& u, int wr, int wc, int fr, int fq) const {
;     ...
;             for (int m = 0; m < 4; ++m) { const int row = row0 + ai * HALF + m * 16;
;                 const float* bp = (row < MP) ? base0 + (size_t)row * DM : base1 + (size_t)(row - MP) * DM;
;                 float r = 1.f; if (MODE == 1) r = __builtin_amdgcn_rsqf(ssin[row] * (1.f / DM) + EPS);
;                 float s = 0.f;
; #pragma unroll
;                 for (int bj = 0; bj < 2; ++bj)
; #pragma unroll
;                     for (int n = 0; n < 2; ++n) { const int col = col0 + bj * HALF + n * 16;
;                         f32x4 v = acc[ai][bj][m][n];
;                         if (MODE == 1) { const u32x2 pw = *(const u32x2*)(PP + (size_t)row * DM + col);
;                             v[0] = sigmoidf_(v[0] * r) * bflo(pw.x); v[1] = sigmoidf_(v[1] * r) * bfhi(pw.x); v[2] = sigmoidf_(v[2] * r) * bflo(pw.y); v[3] = sigmoidf_(v[3] * r) * bfhi(pw.y); }
;                         f32x4 h;
;                         if (baseb) { const u32x2 bw = *(const u32x2*)(baseb + (size_t)row * DM + col); h = (f32x4){bflo(bw.x), bfhi(bw.x), bflo(bw.y), bfhi(bw.y)} + v; }
;                         else h = *(const f32x4*)(bp + col) + v;
;                         if (H) *(f32x4*)(H + (size_t)row * DM + col) = h;
	v_lshlrev_b32_e32 v70, 16, v56
	v_and_b32_e32 v71, 0xffff0000, v56
	v_lshlrev_b32_e32 v56, 16, v57
	v_and_b32_e32 v57, 0xffff0000, v57
	v_pk_fma_f32 v[56:57], v[64:65], v[54:55], v[56:57]
	v_pk_fma_f32 v[54:55], v[50:51], v[68:69], v[70:71]
	global_store_dwordx4 v[66:67], v[54:57], off offset:576
	global_load_dword v62, v[62:63], off
	s_nop 0
	global_load_dwordx2 v[56:57], v[52:53], off
	v_lshl_add_u64 v[50:51], s[14:15], 0, v[60:61]
	v_lshl_add_u64 v[54:55], v[50:51], 0, v[146:147]
	global_load_dwordx2 v[60:61], v[54:55], off
	v_lshlrev_b64 v[50:51], 12, v[58:59]
	v_lshl_add_u64 v[50:51], s[48:49], 0, v[50:51]
	v_lshl_add_u64 v[50:51], v[50:51], 0, v[148:149]
	s_waitcnt vmcnt(2)
	v_fmamk_f32 v63, v62, 0x3a800000, v161
	s_waitcnt vmcnt(1)
	v_lshlrev_b32_e32 v58, 16, v56
	v_and_b32_e32 v59, 0xffff0000, v56
	v_rsq_f32_e32 v56, v63
	v_lshlrev_b32_e32 v62, 16, v57
	v_and_b32_e32 v63, 0xffff0000, v57
	s_waitcnt vmcnt(0)
	v_lshlrev_b32_e32 v64, 16, v60
	v_mul_f32_e32 v46, v46, v56
	v_mul_f32_e32 v47, v47, v56
	v_mul_f32_e32 v46, 0xbfb8aa3b, v46
	v_mul_f32_e32 v47, 0xbfb8aa3b, v47
	v_mul_f32_e32 v48, v48, v56
	v_mul_f32_e32 v49, v49, v56
	v_exp_f32_e32 v46, v46
	v_exp_f32_e32 v47, v47
	v_mul_f32_e32 v48, 0xbfb8aa3b, v48
	v_mul_f32_e32 v49, 0xbfb8aa3b, v49
	v_exp_f32_e32 v48, v48
	v_exp_f32_e32 v49, v49
	v_pk_add_f32 v[46:47], v[46:47], 1.0 op_sel_hi:[1,0]
	v_and_b32_e32 v65, 0xffff0000, v60
	v_pk_add_f32 v[48:49], v[48:49], 1.0 op_sel_hi:[1,0]
	v_rcp_f32_e32 v47, v47
	v_rcp_f32_e32 v46, v46
	v_rcp_f32_e32 v49, v49
	v_lshlrev_b32_e32 v60, 16, v61
	v_and_b32_e32 v61, 0xffff0000, v61
	v_rcp_f32_e32 v48, v48
	v_pk_fma_f32 v[46:47], v[46:47], v[58:59], v[64:65]
	v_pk_fma_f32 v[48:49], v[48:49], v[62:63], v[60:61]
	global_store_dwordx4 v[50:51], v[46:49], off
	global_load_dwordx2 v[46:47], v[52:53], off offset:32
	s_nop 0
	global_load_dwordx2 v[48:49], v[54:55], off offset:32
	v_mul_f32_e32 v42, v42, v56
	v_mul_f32_e32 v43, v43, v56
	v_mul_f32_e32 v42, 0xbfb8aa3b, v42
	v_mul_f32_e32 v43, 0xbfb8aa3b, v43
	v_mul_f32_e32 v44, v44, v56
	v_mul_f32_e32 v45, v45, v56
	v_exp_f32_e32 v42, v42
	v_exp_f32_e32 v43, v43
	v_mul_f32_e32 v44, 0xbfb8aa3b, v44
	v_mul_f32_e32 v45, 0xbfb8aa3b, v45
	v_exp_f32_e32 v44, v44
	v_exp_f32_e32 v45, v45
	v_pk_add_f32 v[42:43], v[42:43], 1.0 op_sel_hi:[1,0]
	v_mul_f32_e32 v38, v38, v56
	v_pk_add_f32 v[44:45], v[44:45], 1.0 op_sel_hi:[1,0]
	v_rcp_f32_e32 v43, v43
	v_rcp_f32_e32 v42, v42
	v_rcp_f32_e32 v45, v45
	v_rcp_f32_e32 v44, v44
	v_mul_f32_e32 v39, v39, v56
	v_mul_f32_e32 v38, 0xbfb8aa3b, v38
	v_mul_f32_e32 v39, 0xbfb8aa3b, v39
	v_mul_f32_e32 v40, v40, v56
	v_mul_f32_e32 v41, v41, v56
	v_exp_f32_e32 v38, v38
	v_exp_f32_e32 v39, v39
	v_mul_f32_e32 v40, 0xbfb8aa3b, v40
	s_waitcnt vmcnt(1)
	v_lshlrev_b32_e32 v58, 16, v46
	v_and_b32_e32 v59, 0xffff0000, v46
	v_lshlrev_b32_e32 v46, 16, v47
	v_and_b32_e32 v47, 0xffff0000, v47
	s_waitcnt vmcnt(0)
	v_lshlrev_b32_e32 v60, 16, v48
	v_and_b32_e32 v61, 0xffff0000, v48
	v_lshlrev_b32_e32 v48, 16, v49
	v_and_b32_e32 v49, 0xffff0000, v49
	v_pk_fma_f32 v[44:45], v[44:45], v[46:47], v[48:49]
	v_pk_fma_f32 v[42:43], v[42:43], v[58:59], v[60:61]
	global_store_dwordx4 v[50:51], v[42:45], off offset:64
	global_load_dwordx2 v[42:43], v[52:53], off offset:256
	s_nop 0
	global_load_dwordx2 v[44:45], v[54:55], off offset:256
	v_mul_f32_e32 v41, 0xbfb8aa3b, v41
	v_exp_f32_e32 v40, v40
	v_exp_f32_e32 v41, v41
	v_pk_add_f32 v[38:39], v[38:39], 1.0 op_sel_hi:[1,0]
	v_mul_f32_e32 v34, v34, v56
	v_pk_add_f32 v[40:41], v[40:41], 1.0 op_sel_hi:[1,0]
	v_div_scale_f32 v60, s[6:7], 1.0, v40, 1.0
	v_rcp_f32_e32 v39, v39
	v_rcp_f32_e32 v38, v38
	s_mov_b64 vcc, s[6:7]
	v_rcp_f32_e32 v41, v41
	v_rcp_f32_e32 v40, v40
	v_mul_f32_e32 v35, v35, v56
	v_mul_f32_e32 v34, 0xbfb8aa3b, v34
	v_mul_f32_e32 v35, 0xbfb8aa3b, v35
	v_mul_f32_e32 v36, v36, v56
	v_mul_f32_e32 v37, v37, v56
	v_exp_f32_e32 v34, v34
	v_exp_f32_e32 v35, v35
	v_mul_f32_e32 v36, 0xbfb8aa3b, v36
	v_mul_f32_e32 v37, 0xbfb8aa3b, v37
	v_cmp_gt_i32_e32 vcc, s57, v150
	v_pk_add_f32 v[34:35], v[34:35], 1.0 op_sel_hi:[1,0]
	s_waitcnt vmcnt(1)
	v_lshlrev_b32_e32 v46, 16, v42
	v_and_b32_e32 v47, 0xffff0000, v42
	v_lshlrev_b32_e32 v42, 16, v43
	v_and_b32_e32 v43, 0xffff0000, v43
	s_waitcnt vmcnt(0)
	v_lshlrev_b32_e32 v48, 16, v44
	v_and_b32_e32 v49, 0xffff0000, v44
	v_lshlrev_b32_e32 v44, 16, v45
	v_and_b32_e32 v45, 0xffff0000, v45
	v_pk_fma_f32 v[40:41], v[40:41], v[42:43], v[44:45]
	v_pk_fma_f32 v[38:39], v[38:39], v[46:47], v[48:49]
	global_store_dwordx4 v[50:51], v[38:41], off offset:512
	global_load_dwordx2 v[38:39], v[52:53], off offset:288
	v_exp_f32_e32 v48, v36
	global_load_dwordx2 v[40:41], v[54:55], off offset:288
	v_exp_f32_e32 v49, v37
	s_nop 0
	v_pk_add_f32 v[48:49], v[48:49], 1.0 op_sel_hi:[1,0]
	v_add_u32_e32 v42, 0xa0, v150
	v_ashrrev_i32_e32 v43, 31, v42
	v_cndmask_b32_e32 v43, 0, v43, vcc
	v_rcp_f32_e32 v35, v35
	v_rcp_f32_e32 v34, v34
	v_rcp_f32_e32 v49, v49
	v_rcp_f32_e32 v48, v48
	v_lshlrev_b64 v[44:45], 11, v[42:43]
	v_lshl_add_u64 v[46:47], v[42:43], 2, s[10:11]
	v_lshl_add_u64 v[36:37], s[12:13], 0, v[44:45]
	v_lshl_add_u64 v[36:37], v[36:37], 0, v[146:147]
	s_waitcnt vmcnt(1)
	v_lshlrev_b32_e32 v52, 16, v38
	v_and_b32_e32 v53, 0xffff0000, v38
	v_lshlrev_b32_e32 v38, 16, v39
	v_and_b32_e32 v39, 0xffff0000, v39
	s_waitcnt vmcnt(0)
; DI float sigmoidf_(float x) { return 1.f / (1.f + __expf(-x)); }
;     DI void operator()(const f32x4 (&acc)[2][2][4][2], const Unit& u, int wr, int wc, int fr, int fq) const {
;     ...
;                 const float* bp = (row < MP) ? base0 + (size_t)row * DM : base1 + (size_t)(row - MP) * DM;
;                 float r = 1.f; if (MODE == 1) r = __builtin_amdgcn_rsqf(ssin[row] * (1.f / DM) + EPS);
;                 float s = 0.f;
; #pragma unroll
;                 for (int bj = 0; bj < 2; ++bj)
; #pragma unroll
;                     for (int n = 0; n < 2; ++n) { const int col = col0 + bj * HALF + n * 16;
;                         f32x4 v = acc[ai][bj][m][n];
;                         if (MODE == 1) { const u32x2 pw = *(const u32x2*)(PP + (size_t)row * DM + col);
;                             v[0] = sigmoidf_(v[0] * r) * bflo(pw.x); v[1] = sigmoidf_(v[1] * r) * bfhi(pw.x); v[2] = sigmoidf_(v[2] * r) * bflo(pw.y); v[3] = sigmoidf_(v[3] * r) * bfhi(pw.y); }
;                         f32x4 h;
;                         if (baseb) { const u32x2 bw = *(const u32x2*)(baseb + (size_t)row * DM + col); h = (f32x4){bflo(bw.x), bfhi(bw.x), bflo(bw.y), bfhi(bw.y)} + v; }
;                         else h = *(const f32x4*)(bp + col) + v;
;                         if (H) *(f32x4*)(H + (size_t)row * DM + col) = h;
	v_lshlrev_b32_e32 v54, 16, v40
	v_and_b32_e32 v55, 0xffff0000, v40
	v_lshlrev_b32_e32 v40, 16, v41
	v_and_b32_e32 v41, 0xffff0000, v41
	v_pk_fma_f32 v[40:41], v[48:49], v[38:39], v[40:41]
	v_pk_fma_f32 v[38:39], v[34:35], v[52:53], v[54:55]
	global_store_dwordx4 v[50:51], v[38:41], off offset:576
	global_load_dword v46, v[46:47], off
	s_nop 0
	global_load_dwordx2 v[40:41], v[36:37], off
	v_lshl_add_u64 v[34:35], s[14:15], 0, v[44:45]
	v_lshl_add_u64 v[38:39], v[34:35], 0, v[146:147]
	global_load_dwordx2 v[44:45], v[38:39], off
	v_lshlrev_b64 v[34:35], 12, v[42:43]
	v_lshl_add_u64 v[34:35], s[48:49], 0, v[34:35]
	v_lshl_add_u64 v[34:35], v[34:35], 0, v[148:149]
	s_waitcnt vmcnt(2)
	v_fmamk_f32 v47, v46, 0x3a800000, v161
	s_waitcnt vmcnt(1)
	v_lshlrev_b32_e32 v42, 16, v40
	v_and_b32_e32 v43, 0xffff0000, v40
	v_rsq_f32_e32 v40, v47
	v_lshlrev_b32_e32 v46, 16, v41
	v_and_b32_e32 v47, 0xffff0000, v41
	s_waitcnt vmcnt(0)
	v_lshlrev_b32_e32 v48, 16, v44
	v_mul_f32_e32 v30, v30, v40
	v_mul_f32_e32 v31, v31, v40
	v_mul_f32_e32 v30, 0xbfb8aa3b, v30
	v_mul_f32_e32 v31, 0xbfb8aa3b, v31
	v_mul_f32_e32 v32, v32, v40
	v_mul_f32_e32 v33, v33, v40
	v_exp_f32_e32 v30, v30
	v_exp_f32_e32 v31, v31
	v_mul_f32_e32 v32, 0xbfb8aa3b, v32
	v_mul_f32_e32 v33, 0xbfb8aa3b, v33
	v_exp_f32_e32 v32, v32
	v_exp_f32_e32 v33, v33
	v_pk_add_f32 v[30:31], v[30:31], 1.0 op_sel_hi:[1,0]
	v_and_b32_e32 v49, 0xffff0000, v44
	v_pk_add_f32 v[32:33], v[32:33], 1.0 op_sel_hi:[1,0]
	v_rcp_f32_e32 v31, v31
	v_rcp_f32_e32 v30, v30
	v_rcp_f32_e32 v33, v33
	v_lshlrev_b32_e32 v44, 16, v45
	v_and_b32_e32 v45, 0xffff0000, v45
	v_rcp_f32_e32 v32, v32
	v_pk_fma_f32 v[30:31], v[30:31], v[42:43], v[48:49]
	v_pk_fma_f32 v[32:33], v[32:33], v[46:47], v[44:45]
	global_store_dwordx4 v[34:35], v[30:33], off
	global_load_dwordx2 v[30:31], v[36:37], off offset:32
	s_nop 0
	global_load_dwordx2 v[32:33], v[38:39], off offset:32
	v_mul_f32_e32 v26, v26, v40
	v_mul_f32_e32 v27, v27, v40
	v_mul_f32_e32 v26, 0xbfb8aa3b, v26
	v_mul_f32_e32 v27, 0xbfb8aa3b, v27
	v_mul_f32_e32 v28, v28, v40
	v_mul_f32_e32 v29, v29, v40
	v_exp_f32_e32 v26, v26
	v_exp_f32_e32 v27, v27
	v_mul_f32_e32 v28, 0xbfb8aa3b, v28
	v_mul_f32_e32 v29, 0xbfb8aa3b, v29
	v_exp_f32_e32 v28, v28
	v_exp_f32_e32 v29, v29
	v_pk_add_f32 v[26:27], v[26:27], 1.0 op_sel_hi:[1,0]
	v_mul_f32_e32 v22, v22, v40
	v_pk_add_f32 v[28:29], v[28:29], 1.0 op_sel_hi:[1,0]
	v_rcp_f32_e32 v27, v27
	v_rcp_f32_e32 v26, v26
	v_rcp_f32_e32 v29, v29
	v_rcp_f32_e32 v28, v28
	v_mul_f32_e32 v23, v23, v40
	v_mul_f32_e32 v22, 0xbfb8aa3b, v22
	v_mul_f32_e32 v23, 0xbfb8aa3b, v23
	v_mul_f32_e32 v24, v24, v40
	v_mul_f32_e32 v25, v25, v40
	v_exp_f32_e32 v22, v22
	v_exp_f32_e32 v23, v23
	v_mul_f32_e32 v24, 0xbfb8aa3b, v24
	s_waitcnt vmcnt(1)
	v_lshlrev_b32_e32 v42, 16, v30
	v_and_b32_e32 v43, 0xffff0000, v30
	v_lshlrev_b32_e32 v30, 16, v31
	v_and_b32_e32 v31, 0xffff0000, v31
	s_waitcnt vmcnt(0)
	v_lshlrev_b32_e32 v44, 16, v32
	v_and_b32_e32 v45, 0xffff0000, v32
	v_lshlrev_b32_e32 v32, 16, v33
	v_and_b32_e32 v33, 0xffff0000, v33
	v_pk_fma_f32 v[28:29], v[28:29], v[30:31], v[32:33]
	v_pk_fma_f32 v[26:27], v[26:27], v[42:43], v[44:45]
	global_store_dwordx4 v[34:35], v[26:29], off offset:64
	global_load_dwordx2 v[26:27], v[36:37], off offset:256
	s_nop 0
	global_load_dwordx2 v[28:29], v[38:39], off offset:256
	v_mul_f32_e32 v25, 0xbfb8aa3b, v25
	v_exp_f32_e32 v24, v24
	v_exp_f32_e32 v25, v25
	v_pk_add_f32 v[22:23], v[22:23], 1.0 op_sel_hi:[1,0]
	v_mul_f32_e32 v18, v18, v40
	v_pk_add_f32 v[24:25], v[24:25], 1.0 op_sel_hi:[1,0]
	v_div_scale_f32 v44, s[6:7], 1.0, v24, 1.0
	v_rcp_f32_e32 v23, v23
	v_rcp_f32_e32 v22, v22
	s_mov_b64 vcc, s[6:7]
	v_rcp_f32_e32 v25, v25
	v_rcp_f32_e32 v24, v24
	v_mul_f32_e32 v19, v19, v40
	v_mul_f32_e32 v18, 0xbfb8aa3b, v18
	v_mul_f32_e32 v19, 0xbfb8aa3b, v19
	v_mul_f32_e32 v20, v20, v40
	v_mul_f32_e32 v21, v21, v40
	v_exp_f32_e32 v18, v18
	v_exp_f32_e32 v19, v19
	v_mul_f32_e32 v20, 0xbfb8aa3b, v20
	v_mul_f32_e32 v21, 0xbfb8aa3b, v21
	v_cmp_gt_i32_e32 vcc, s58, v150
	v_pk_add_f32 v[18:19], v[18:19], 1.0 op_sel_hi:[1,0]
	s_waitcnt vmcnt(1)
	v_lshlrev_b32_e32 v30, 16, v26
	v_and_b32_e32 v31, 0xffff0000, v26
	v_lshlrev_b32_e32 v26, 16, v27
	v_and_b32_e32 v27, 0xffff0000, v27
	s_waitcnt vmcnt(0)
	v_lshlrev_b32_e32 v32, 16, v28
	v_and_b32_e32 v33, 0xffff0000, v28
	v_lshlrev_b32_e32 v28, 16, v29
	v_and_b32_e32 v29, 0xffff0000, v29
	v_pk_fma_f32 v[24:25], v[24:25], v[26:27], v[28:29]
	v_pk_fma_f32 v[22:23], v[22:23], v[30:31], v[32:33]
	global_store_dwordx4 v[34:35], v[22:25], off offset:512
	global_load_dwordx2 v[22:23], v[36:37], off offset:288
	v_exp_f32_e32 v32, v20
	global_load_dwordx2 v[24:25], v[38:39], off offset:288
	v_exp_f32_e32 v33, v21
	s_nop 0
	v_pk_add_f32 v[32:33], v[32:33], 1.0 op_sel_hi:[1,0]
	v_add_u32_e32 v26, 0xb0, v150
	v_ashrrev_i32_e32 v27, 31, v26
	v_cndmask_b32_e32 v27, 0, v27, vcc
	v_rcp_f32_e32 v19, v19
	v_rcp_f32_e32 v18, v18
	v_rcp_f32_e32 v33, v33
	v_rcp_f32_e32 v32, v32
	v_lshlrev_b64 v[28:29], 11, v[26:27]
	v_lshl_add_u64 v[30:31], v[26:27], 2, s[10:11]
	v_lshl_add_u64 v[20:21], s[12:13], 0, v[28:29]
	v_lshl_add_u64 v[20:21], v[20:21], 0, v[146:147]
	s_waitcnt vmcnt(1)
; DI float sigmoidf_(float x) { return 1.f / (1.f + __expf(-x)); }
;     DI void operator()(const f32x4 (&acc)[2][2][4][2], const Unit& u, int wr, int wc, int fr, int fq) const {
;     ...
;                 const float* bp = (row < MP) ? base0 + (size_t)row * DM : base1 + (size_t)(row - MP) * DM;
;                 float r = 1.f; if (MODE == 1) r = __builtin_amdgcn_rsqf(ssin[row] * (1.f / DM) + EPS);
;                 float s = 0.f;
; #pragma unroll
;                 for (int bj = 0; bj < 2; ++bj)
; #pragma unroll
;                     for (int n = 0; n < 2; ++n) { const int col = col0 + bj * HALF + n * 16;
;                         f32x4 v = acc[ai][bj][m][n];
;                         if (MODE == 1) { const u32x2 pw = *(const u32x2*)(PP + (size_t)row * DM + col);
;                             v[0] = sigmoidf_(v[0] * r) * bflo(pw.x); v[1] = sigmoidf_(v[1] * r) * bfhi(pw.x); v[2] = sigmoidf_(v[2] * r) * bflo(pw.y); v[3] = sigmoidf_(v[3] * r) * bfhi(pw.y); }
;                         f32x4 h;
;                         if (baseb) { const u32x2 bw = *(const u32x2*)(baseb + (size_t)row * DM + col); h = (f32x4){bflo(bw.x), bfhi(bw.x), bflo(bw.y), bfhi(bw.y)} + v; }
;                         else h = *(const f32x4*)(bp + col) + v;
;                         if (H) *(f32x4*)(H + (size_t)row * DM + col) = h;
	v_lshlrev_b32_e32 v36, 16, v22
	v_and_b32_e32 v37, 0xffff0000, v22
	v_lshlrev_b32_e32 v22, 16, v23
	v_and_b32_e32 v23, 0xffff0000, v23
	s_waitcnt vmcnt(0)
	v_lshlrev_b32_e32 v38, 16, v24
	v_and_b32_e32 v39, 0xffff0000, v24
	v_lshlrev_b32_e32 v24, 16, v25
	v_and_b32_e32 v25, 0xffff0000, v25
	v_pk_fma_f32 v[24:25], v[32:33], v[22:23], v[24:25]
	v_pk_fma_f32 v[22:23], v[18:19], v[36:37], v[38:39]
	global_store_dwordx4 v[34:35], v[22:25], off offset:576
	global_load_dword v30, v[30:31], off
	s_nop 0
	global_load_dwordx2 v[24:25], v[20:21], off
	v_lshl_add_u64 v[18:19], s[14:15], 0, v[28:29]
	v_lshl_add_u64 v[22:23], v[18:19], 0, v[146:147]
	global_load_dwordx2 v[28:29], v[22:23], off
	v_lshlrev_b64 v[18:19], 12, v[26:27]
	v_lshl_add_u64 v[18:19], s[48:49], 0, v[18:19]
	v_lshl_add_u64 v[18:19], v[18:19], 0, v[148:149]
	s_waitcnt vmcnt(2)
	v_fmamk_f32 v31, v30, 0x3a800000, v161
	s_waitcnt vmcnt(1)
	v_lshlrev_b32_e32 v26, 16, v24
	v_and_b32_e32 v27, 0xffff0000, v24
	v_rsq_f32_e32 v24, v31
	v_lshlrev_b32_e32 v30, 16, v25
	v_and_b32_e32 v31, 0xffff0000, v25
	s_waitcnt vmcnt(0)
	v_lshlrev_b32_e32 v32, 16, v28
	v_mul_f32_e32 v14, v14, v24
	v_mul_f32_e32 v15, v15, v24
	v_mul_f32_e32 v14, 0xbfb8aa3b, v14
	v_mul_f32_e32 v15, 0xbfb8aa3b, v15
	v_mul_f32_e32 v16, v16, v24
	v_mul_f32_e32 v17, v17, v24
	v_exp_f32_e32 v14, v14
	v_exp_f32_e32 v15, v15
	v_mul_f32_e32 v16, 0xbfb8aa3b, v16
	v_mul_f32_e32 v17, 0xbfb8aa3b, v17
	v_exp_f32_e32 v16, v16
	v_exp_f32_e32 v17, v17
	v_pk_add_f32 v[14:15], v[14:15], 1.0 op_sel_hi:[1,0]
	v_and_b32_e32 v33, 0xffff0000, v28
	v_pk_add_f32 v[16:17], v[16:17], 1.0 op_sel_hi:[1,0]
	v_rcp_f32_e32 v15, v15
	v_rcp_f32_e32 v14, v14
	v_rcp_f32_e32 v17, v17
	v_lshlrev_b32_e32 v28, 16, v29
	v_and_b32_e32 v29, 0xffff0000, v29
	v_rcp_f32_e32 v16, v16
	v_pk_fma_f32 v[14:15], v[14:15], v[26:27], v[32:33]
	v_pk_fma_f32 v[16:17], v[16:17], v[30:31], v[28:29]
	global_store_dwordx4 v[18:19], v[14:17], off
	global_load_dwordx2 v[14:15], v[20:21], off offset:32
	s_nop 0
	global_load_dwordx2 v[16:17], v[22:23], off offset:32
	v_mul_f32_e32 v10, v10, v24
	v_mul_f32_e32 v11, v11, v24
	v_mul_f32_e32 v10, 0xbfb8aa3b, v10
	v_mul_f32_e32 v11, 0xbfb8aa3b, v11
	v_mul_f32_e32 v12, v12, v24
	v_mul_f32_e32 v13, v13, v24
	v_exp_f32_e32 v10, v10
	v_exp_f32_e32 v11, v11
	v_mul_f32_e32 v12, 0xbfb8aa3b, v12
	v_mul_f32_e32 v13, 0xbfb8aa3b, v13
	v_exp_f32_e32 v12, v12
	v_exp_f32_e32 v13, v13
	v_pk_add_f32 v[10:11], v[10:11], 1.0 op_sel_hi:[1,0]
	v_mul_f32_e32 v6, v6, v24
	v_pk_add_f32 v[12:13], v[12:13], 1.0 op_sel_hi:[1,0]
	v_rcp_f32_e32 v11, v11
	v_rcp_f32_e32 v10, v10
	v_rcp_f32_e32 v13, v13
	v_rcp_f32_e32 v12, v12
	v_mul_f32_e32 v7, v7, v24
	v_mul_f32_e32 v6, 0xbfb8aa3b, v6
	v_mul_f32_e32 v7, 0xbfb8aa3b, v7
	v_mul_f32_e32 v8, v8, v24
	v_mul_f32_e32 v9, v9, v24
	v_exp_f32_e32 v6, v6
	v_exp_f32_e32 v7, v7
	v_mul_f32_e32 v8, 0xbfb8aa3b, v8
	s_waitcnt vmcnt(1)
	v_lshlrev_b32_e32 v26, 16, v14
	v_and_b32_e32 v27, 0xffff0000, v14
	v_lshlrev_b32_e32 v14, 16, v15
	v_and_b32_e32 v15, 0xffff0000, v15
	s_waitcnt vmcnt(0)
	v_lshlrev_b32_e32 v28, 16, v16
	v_and_b32_e32 v29, 0xffff0000, v16
	v_lshlrev_b32_e32 v16, 16, v17
	v_and_b32_e32 v17, 0xffff0000, v17
	v_pk_fma_f32 v[12:13], v[12:13], v[14:15], v[16:17]
	v_pk_fma_f32 v[10:11], v[10:11], v[26:27], v[28:29]
	global_store_dwordx4 v[18:19], v[10:13], off offset:64
	global_load_dwordx2 v[10:11], v[20:21], off offset:256
	s_nop 0
	global_load_dwordx2 v[12:13], v[22:23], off offset:256
	v_mul_f32_e32 v9, 0xbfb8aa3b, v9
	v_exp_f32_e32 v8, v8
	v_exp_f32_e32 v9, v9
	v_pk_add_f32 v[6:7], v[6:7], 1.0 op_sel_hi:[1,0]
	v_mul_f32_e32 v2, v2, v24
	v_pk_add_f32 v[8:9], v[8:9], 1.0 op_sel_hi:[1,0]
	v_rcp_f32_e32 v7, v7
	v_rcp_f32_e32 v6, v6
	v_rcp_f32_e32 v9, v9
	v_rcp_f32_e32 v8, v8
	v_mul_f32_e32 v3, v3, v24
	v_mul_f32_e32 v2, 0xbfb8aa3b, v2
	v_mul_f32_e32 v3, 0xbfb8aa3b, v3
	v_mul_f32_e32 v4, v4, v24
	v_mul_f32_e32 v5, v5, v24
	v_exp_f32_e32 v2, v2
	v_exp_f32_e32 v3, v3
	v_mul_f32_e32 v4, 0xbfb8aa3b, v4
	v_mul_f32_e32 v5, 0xbfb8aa3b, v5
	v_exp_f32_e32 v4, v4
	v_exp_f32_e32 v5, v5
	v_pk_add_f32 v[2:3], v[2:3], 1.0 op_sel_hi:[1,0]
	v_pk_add_f32 v[4:5], v[4:5], 1.0 op_sel_hi:[1,0]
	s_waitcnt vmcnt(1)
	v_lshlrev_b32_e32 v14, 16, v10
	v_and_b32_e32 v15, 0xffff0000, v10
	v_lshlrev_b32_e32 v10, 16, v11
	v_and_b32_e32 v11, 0xffff0000, v11
	s_waitcnt vmcnt(0)
	v_lshlrev_b32_e32 v16, 16, v12
	v_and_b32_e32 v17, 0xffff0000, v12
	v_lshlrev_b32_e32 v12, 16, v13
	v_and_b32_e32 v13, 0xffff0000, v13
	v_pk_fma_f32 v[8:9], v[8:9], v[10:11], v[12:13]
	v_pk_fma_f32 v[6:7], v[6:7], v[14:15], v[16:17]
	global_store_dwordx4 v[18:19], v[6:9], off offset:512
	global_load_dwordx2 v[6:7], v[20:21], off offset:288
	s_nop 0
	global_load_dwordx2 v[8:9], v[22:23], off offset:288
	v_rcp_f32_e32 v3, v3
	v_rcp_f32_e32 v2, v2
	v_rcp_f32_e32 v5, v5
	v_rcp_f32_e32 v4, v4
	s_waitcnt vmcnt(1)
	v_lshlrev_b32_e32 v10, 16, v6
	v_and_b32_e32 v11, 0xffff0000, v6
	v_lshlrev_b32_e32 v6, 16, v7
	v_and_b32_e32 v7, 0xffff0000, v7
	s_waitcnt vmcnt(0)
	v_lshlrev_b32_e32 v12, 16, v8
	v_and_b32_e32 v13, 0xffff0000, v8
	v_lshlrev_b32_e32 v8, 16, v9
	v_and_b32_e32 v9, 0xffff0000, v9
	v_pk_fma_f32 v[4:5], v[4:5], v[6:7], v[8:9]
	v_pk_fma_f32 v[2:3], v[2:3], v[10:11], v[12:13]
	global_store_dwordx4 v[18:19], v[2:5], off offset:576

; DI float sigmoidf_(float x) { return 1.f / (1.f + __expf(-x)); }
;     DI void operator()(const f32x4 (&acc)[2][2][4][2], const Unit& u, int wr, int wc, int fr, int fq) const {
;     ...
;                 const float* bp = (row < MP) ? base0 + (size_t)row * DM : base1 + (size_t)(row - MP) * DM;
;                 float r = 1.f; if (MODE == 1) r = __builtin_amdgcn_rsqf(ssin[row] * (1.f / DM) + EPS);
;                 float s = 0.f;
; #pragma unroll
;                 for (int bj = 0; bj < 2; ++bj)
; #pragma unroll
;                     for (int n = 0; n < 2; ++n) { const int col = col0 + bj * HALF + n * 16;
;                         f32x4 v = acc[ai][bj][m][n];
;                         if (MODE == 1) { const u32x2 pw = *(const u32x2*)(PP + (size_t)row * DM + col);
;                             v[0] = sigmoidf_(v[0] * r) * bflo(pw.x); v[1] = sigmoidf_(v[1] * r) * bfhi(pw.x); v[2] = sigmoidf_(v[2] * r) * bflo(pw.y); v[3] = sigmoidf_(v[3] * r) * bfhi(pw.y); }
;                         f32x4 h;
;                         if (baseb) { const u32x2 bw = *(const u32x2*)(baseb + (size_t)row * DM + col); h = (f32x4){bflo(bw.x), bfhi(bw.x), bflo(bw.y), bfhi(bw.y)} + v; }
;                         else h = *(const f32x4*)(bp + col) + v;
;                         if (H) *(f32x4*)(H + (size_t)row * DM + col) = h;
.LBB0_2088:
	s_andn2_b64 vcc, exec, s[6:7]
	s_cbranch_vccnz .LBB0_2075
	v_or_b32_e32 v18, s2, v28
	v_lshlrev_b32_e32 v6, 12, v18
	v_lshl_add_u64 v[14:15], s[48:49], 0, v[6:7]
	v_lshlrev_b32_e32 v6, 2, v18
	global_load_dword v35, v6, s[10:11]
	v_add_u32_e32 v16, s3, v23
	v_ashrrev_i32_e32 v17, 31, v16
	v_lshlrev_b32_e32 v6, 11, v18
	v_lshl_add_u64 v[18:19], s[12:13], 0, v[6:7]
	v_lshlrev_b64 v[36:37], 1, v[16:17]
	v_lshl_add_u64 v[38:39], s[14:15], 0, v[6:7]
	v_lshl_add_u64 v[18:19], v[18:19], 0, v[36:37]
	v_lshl_add_u64 v[36:37], v[38:39], 0, v[36:37]
	global_load_dwordx2 v[18:19], v[18:19], off
	v_lshl_add_u64 v[14:15], v[16:17], 2, v[14:15]
	global_load_dwordx2 v[36:37], v[36:37], off
	s_waitcnt vmcnt(0)
	v_fmamk_f32 v6, v35, 0x3a800000, v34
	v_rsq_f32_e32 v6, v6
	v_lshlrev_b32_e32 v16, 16, v18
	v_mul_f32_e32 v2, v2, v6
	v_mul_f32_e32 v3, v3, v6
	v_mul_f32_e32 v2, 0xbfb8aa3b, v2
	v_mul_f32_e32 v3, 0xbfb8aa3b, v3
	v_mul_f32_e32 v4, v4, v6
	v_mul_f32_e32 v5, v5, v6
	v_exp_f32_e32 v2, v2
	v_exp_f32_e32 v3, v3
	v_mul_f32_e32 v4, 0xbfb8aa3b, v4
	v_mul_f32_e32 v5, 0xbfb8aa3b, v5
	v_exp_f32_e32 v4, v4
	v_exp_f32_e32 v5, v5
	v_pk_add_f32 v[2:3], v[2:3], 1.0 op_sel_hi:[1,0]
	v_and_b32_e32 v17, 0xffff0000, v18
	v_pk_add_f32 v[4:5], v[4:5], 1.0 op_sel_hi:[1,0]
	v_rcp_f32_e32 v3, v3
	v_rcp_f32_e32 v2, v2
	v_rcp_f32_e32 v5, v5
	v_lshlrev_b32_e32 v18, 16, v19
	v_and_b32_e32 v19, 0xffff0000, v19
	v_lshlrev_b32_e32 v38, 16, v36
	v_and_b32_e32 v39, 0xffff0000, v36
	v_lshlrev_b32_e32 v36, 16, v37
	v_and_b32_e32 v37, 0xffff0000, v37
	v_rcp_f32_e32 v4, v4
	s_nop 0
	v_pk_fma_f32 v[4:5], v[4:5], v[18:19], v[36:37]
	v_pk_fma_f32 v[2:3], v[2:3], v[16:17], v[38:39]
	global_store_dwordx4 v[14:15], v[2:5], off
	s_branch .LBB0_2075

; #define LAS __attribute__((address_space(3)))
; __global__ void __launch_bounds__(NTHR, 2) mega_fwd(Args args) {
;     extern __shared__ __attribute__((aligned(16))) unsigned char lds_raw[];
;     LAS unsigned char* lds = (LAS unsigned char*)lds_raw;
;     volatile LAS unsigned* MISC = (volatile LAS unsigned*)(lds + MISC_OFF);
;     const int tid = threadIdx.x, lane = tid & 63, wave = __builtin_amdgcn_readfirstlane(tid >> 6);
	.amdhsa_kernel _Z8mega_fwd4Args
		.amdhsa_group_segment_fixed_size 0
		.amdhsa_private_segment_fixed_size 0
		.amdhsa_kernarg_size 584
		.amdhsa_user_sgpr_count 2
		.amdhsa_user_sgpr_dispatch_ptr 0
		.amdhsa_user_sgpr_queue_ptr 0
		.amdhsa_user_sgpr_kernarg_segment_ptr 1
		.amdhsa_user_sgpr_dispatch_id 0
		.amdhsa_user_sgpr_kernarg_preload_length 0
		.amdhsa_user_sgpr_kernarg_preload_offset 0
		.amdhsa_user_sgpr_private_segment_size 0
		.amdhsa_uses_dynamic_stack 0
		.amdhsa_enable_private_segment 0
		.amdhsa_system_sgpr_workgroup_id_x 1
		.amdhsa_system_sgpr_workgroup_id_y 0
		.amdhsa_system_sgpr_workgroup_id_z 0
		.amdhsa_system_sgpr_workgroup_info 0
		.amdhsa_system_vgpr_workitem_id 0
		.amdhsa_next_free_vgpr 246
		.amdhsa_next_free_sgpr 100
		.amdhsa_accum_offset 248
		.amdhsa_reserve_vcc 1
		.amdhsa_float_round_mode_32 0
		.amdhsa_float_round_mode_16_64 0
		.amdhsa_float_denorm_mode_32 3
		.amdhsa_float_denorm_mode_16_64 3
		.amdhsa_dx10_clamp 1
		.amdhsa_ieee_mode 1
		.amdhsa_fp16_overflow 0
		.amdhsa_tg_split 0
		.amdhsa_exception_fp_ieee_invalid_op 0
		.amdhsa_exception_fp_denorm_src 0
		.amdhsa_exception_fp_ieee_div_zero 0
		.amdhsa_exception_fp_ieee_overflow 0
		.amdhsa_exception_fp_ieee_underflow 0
		.amdhsa_exception_fp_ieee_inexact 0
		.amdhsa_exception_int_div_zero 0
	.end_amdhsa_kernel

; __global__ void __launch_bounds__(NTHR, 2) mega_fwd(Args args) {
amdhsa.kernels:
  - .agpr_count:     0
    .args:
      - .offset:         0
        .size:           328
        .value_kind:     by_value
      - .offset:         328
        .size:           4
        .value_kind:     hidden_block_count_x
      - .offset:         332
        .size:           4
        .value_kind:     hidden_block_count_y
      - .offset:         336
        .size:           4
        .value_kind:     hidden_block_count_z
      - .offset:         340
        .size:           2
        .value_kind:     hidden_group_size_x
      - .offset:         342
        .size:           2
        .value_kind:     hidden_group_size_y
      - .offset:         344
        .size:           2
        .value_kind:     hidden_group_size_z
      - .offset:         346
        .size:           2
        .value_kind:     hidden_remainder_x
      - .offset:         348
        .size:           2
        .value_kind:     hidden_remainder_y
      - .offset:         350
        .size:           2
        .value_kind:     hidden_remainder_z
      - .offset:         368
        .size:           8
        .value_kind:     hidden_global_offset_x
      - .offset:         376
        .size:           8
        .value_kind:     hidden_global_offset_y
      - .offset:         384
        .size:           8
        .value_kind:     hidden_global_offset_z
      - .offset:         392
        .size:           2
        .value_kind:     hidden_grid_dims
      - .offset:         448
        .size:           4
        .value_kind:     hidden_dynamic_lds_size
    .group_segment_fixed_size: 0
    .kernarg_segment_align: 8
    .kernarg_segment_size: 584
    .language:       OpenCL C
    .language_version:
      - 2
      - 0
    .max_flat_workgroup_size: 512
    .name:           _Z8mega_fwd4Args
    .private_segment_fixed_size: 0
    .sgpr_count:     106
    .sgpr_spill_count: 85
    .symbol:         _Z8mega_fwd4Args.kd
    .uniform_work_group_size: 1
    .uses_dynamic_stack: false
    .vgpr_count:     246
    .vgpr_spill_count: 0
    .wavefront_size: 64
